# GEMM epilogue stores: sc1 nt (streaming) so the write-through outputs do not displace A/B lines in L2
# speedup vs baseline: 1.0201x; 1.0087x over previous
; #define GCOMPUTE(AS, BS) GCOMPUTE_KS(AS, BS, 0) GCOMPUTE_KS(AS, BS, 1)
; template <int EPI>
; DI void gemm_phase(const P& p, int l, const u16* __restrict__ A, const u16* __restrict__ Bt, int mpx, char* lds) {
;     ...
;   __syncthreads();
;   __builtin_amdgcn_sched_barrier(0);
;   GCOMPUTE(As1, Bs1)
;   __builtin_amdgcn_sched_barrier(0);
;   }
;   __syncthreads();
;   GSTORE(As0, Bs0)
.Lgemm_out_exit:
	v_mfma_f32_16x16x32_bf16 v[134:137], v[246:249], v[162:165], v[134:137]
	v_mfma_f32_16x16x32_bf16 v[138:141], v[246:249], v[166:169], v[138:141]
	v_mfma_f32_16x16x32_bf16 v[142:145], v[246:249], v[170:173], v[142:145]
	v_mfma_f32_16x16x32_bf16 v[146:149], v[246:249], v[174:177], v[146:149]
	v_mfma_f32_16x16x32_bf16 v[150:153], v[250:253], v[162:165], v[150:153]
	v_mfma_f32_16x16x32_bf16 v[154:157], v[250:253], v[166:169], v[154:157]
	v_mfma_f32_16x16x32_bf16 v[158:161], v[250:253], v[170:173], v[158:161]
	v_mfma_f32_16x16x32_bf16 v[2:5], v[250:253], v[174:177], v[2:5]
	s_barrier
	ds_read_b128 v[162:165], v231
	ds_read_b128 v[166:169], v230
	ds_read_b128 v[170:173], v230 offset:2048
	ds_read_b128 v[174:177], v230 offset:4096
	ds_read_b128 v[178:181], v230 offset:6144
	s_waitcnt lgkmcnt(3)
	v_mfma_f32_16x16x32_bf16 v[6:9], v[162:165], v[166:169], v[6:9]
	s_waitcnt lgkmcnt(2)
	v_mfma_f32_16x16x32_bf16 v[10:13], v[162:165], v[170:173], v[10:13]
	s_waitcnt lgkmcnt(1)
	v_mfma_f32_16x16x32_bf16 v[14:17], v[162:165], v[174:177], v[14:17]
	s_waitcnt lgkmcnt(0)
	v_mfma_f32_16x16x32_bf16 v[22:25], v[162:165], v[178:181], v[22:25]
	ds_read_b128 v[162:165], v231 offset:2048
	s_waitcnt lgkmcnt(0)
	v_mfma_f32_16x16x32_bf16 v[26:29], v[162:165], v[166:169], v[26:29]
	v_mfma_f32_16x16x32_bf16 v[30:33], v[162:165], v[170:173], v[30:33]
	v_mfma_f32_16x16x32_bf16 v[34:37], v[162:165], v[174:177], v[34:37]
	v_mfma_f32_16x16x32_bf16 v[38:41], v[162:165], v[178:181], v[38:41]
	ds_read_b128 v[162:165], v231 offset:4096
	s_waitcnt lgkmcnt(0)
	v_mfma_f32_16x16x32_bf16 v[42:45], v[162:165], v[166:169], v[42:45]
	v_mfma_f32_16x16x32_bf16 v[46:49], v[162:165], v[170:173], v[46:49]
	v_mfma_f32_16x16x32_bf16 v[50:53], v[162:165], v[174:177], v[50:53]
	v_mfma_f32_16x16x32_bf16 v[54:57], v[162:165], v[178:181], v[54:57]
	ds_read_b128 v[162:165], v231 offset:6144
	s_waitcnt lgkmcnt(0)
	v_mfma_f32_16x16x32_bf16 v[58:61], v[162:165], v[166:169], v[58:61]
	v_mfma_f32_16x16x32_bf16 v[62:65], v[162:165], v[170:173], v[62:65]
	v_mfma_f32_16x16x32_bf16 v[66:69], v[162:165], v[174:177], v[66:69]
	v_mfma_f32_16x16x32_bf16 v[162:165], v[162:165], v[178:181], v[70:73]
	s_nop 2
	ds_read_b128 v[70:73], v231 offset:8192
	s_waitcnt lgkmcnt(0)
	v_mfma_f32_16x16x32_bf16 v[182:185], v[70:73], v[166:169], v[74:77]
	s_nop 2
	ds_read_b128 v[74:77], v233
	v_mfma_f32_16x16x32_bf16 v[186:189], v[70:73], v[170:173], v[78:81]
	v_mfma_f32_16x16x32_bf16 v[190:193], v[70:73], v[174:177], v[82:85]
	v_mfma_f32_16x16x32_bf16 v[212:215], v[70:73], v[178:181], v[114:117]
	ds_read_b128 v[70:73], v231 offset:10240
	s_waitcnt lgkmcnt(0)
	v_mfma_f32_16x16x32_bf16 v[216:219], v[70:73], v[166:169], v[118:121]
	v_mfma_f32_16x16x32_bf16 v[220:223], v[70:73], v[170:173], v[122:125]
	v_mfma_f32_16x16x32_bf16 v[234:237], v[70:73], v[174:177], v[126:129]
	v_mfma_f32_16x16x32_bf16 v[238:241], v[70:73], v[178:181], v[130:133]
	ds_read_b128 v[70:73], v231 offset:12288
	s_waitcnt lgkmcnt(0)
	v_mfma_f32_16x16x32_bf16 v[242:245], v[70:73], v[166:169], v[134:137]
	v_mfma_f32_16x16x32_bf16 v[246:249], v[70:73], v[170:173], v[138:141]
	v_mfma_f32_16x16x32_bf16 v[250:253], v[70:73], v[174:177], v[142:145]
	v_mfma_f32_16x16x32_bf16 v[208:211], v[70:73], v[178:181], v[146:149]
	ds_read_b128 v[70:73], v231 offset:14336
	s_waitcnt lgkmcnt(0)
	v_mfma_f32_16x16x32_bf16 v[178:181], v[70:73], v[178:181], v[2:5]
	s_nop 2
	ds_read_b128 v[2:5], v232
	s_waitcnt lgkmcnt(0)
	v_mfma_f32_16x16x32_bf16 v[146:149], v[74:77], v[2:5], v[6:9]
	s_nop 2
	ds_read_b128 v[6:9], v232 offset:2048
	v_mfma_f32_16x16x32_bf16 v[170:173], v[70:73], v[170:173], v[154:157]
	s_waitcnt lgkmcnt(0)
	v_mfma_f32_16x16x32_bf16 v[154:157], v[74:77], v[6:9], v[10:13]
	s_nop 2
	ds_read_b128 v[10:13], v232 offset:4096
	v_mfma_f32_16x16x32_bf16 v[166:169], v[70:73], v[166:169], v[150:153]
	s_waitcnt lgkmcnt(0)
	v_mfma_f32_16x16x32_bf16 v[150:153], v[74:77], v[10:13], v[14:17]
	s_nop 2
	ds_read_b128 v[14:17], v232 offset:6144
	v_mfma_f32_16x16x32_bf16 v[174:177], v[70:73], v[174:177], v[158:161]
	s_waitcnt lgkmcnt(0)
	v_mfma_f32_16x16x32_bf16 v[158:161], v[74:77], v[14:17], v[22:25]
	s_nop 2
	ds_read_b128 v[22:25], v233 offset:2048
	s_waitcnt lgkmcnt(0)
	v_mfma_f32_16x16x32_bf16 v[138:141], v[22:25], v[2:5], v[26:29]
	s_nop 2
	ds_read_b128 v[26:29], v233 offset:12288
	v_mfma_f32_16x16x32_bf16 v[142:145], v[22:25], v[6:9], v[30:33]
	v_mfma_f32_16x16x32_bf16 v[130:133], v[22:25], v[10:13], v[34:37]
	v_mfma_f32_16x16x32_bf16 v[134:137], v[22:25], v[14:17], v[38:41]
	ds_read_b128 v[22:25], v233 offset:4096
	s_waitcnt lgkmcnt(0)
	v_mfma_f32_16x16x32_bf16 v[122:125], v[22:25], v[2:5], v[42:45]
	v_mfma_f32_16x16x32_bf16 v[126:129], v[22:25], v[6:9], v[46:49]
	v_mfma_f32_16x16x32_bf16 v[114:117], v[22:25], v[10:13], v[50:53]
	v_mfma_f32_16x16x32_bf16 v[118:121], v[22:25], v[14:17], v[54:57]
	ds_read_b128 v[22:25], v233 offset:6144
	s_waitcnt lgkmcnt(0)
	v_mfma_f32_16x16x32_bf16 v[78:81], v[22:25], v[2:5], v[58:61]
	v_mfma_f32_16x16x32_bf16 v[82:85], v[22:25], v[6:9], v[62:65]
	v_mfma_f32_16x16x32_bf16 v[70:73], v[22:25], v[10:13], v[66:69]
	v_mfma_f32_16x16x32_bf16 v[74:77], v[22:25], v[14:17], v[162:165]
	ds_read_b128 v[22:25], v233 offset:8192
	s_nop 1
	ds_read_b128 v[162:165], v233 offset:14336
	s_waitcnt lgkmcnt(1)
	v_mfma_f32_16x16x32_bf16 v[62:65], v[22:25], v[2:5], v[182:185]
	v_mfma_f32_16x16x32_bf16 v[66:69], v[22:25], v[6:9], v[186:189]
	v_mfma_f32_16x16x32_bf16 v[54:57], v[22:25], v[10:13], v[190:193]
	v_mfma_f32_16x16x32_bf16 v[58:61], v[22:25], v[14:17], v[212:215]
	ds_read_b128 v[22:25], v233 offset:10240
	s_waitcnt lgkmcnt(0)
	v_mfma_f32_16x16x32_bf16 v[46:49], v[22:25], v[2:5], v[216:219]
	v_mfma_f32_16x16x32_bf16 v[50:53], v[22:25], v[6:9], v[220:223]
	v_mfma_f32_16x16x32_bf16 v[38:41], v[22:25], v[10:13], v[234:237]
	v_mfma_f32_16x16x32_bf16 v[42:45], v[22:25], v[14:17], v[238:241]
	v_mfma_f32_16x16x32_bf16 v[30:33], v[26:29], v[2:5], v[242:245]
	v_mfma_f32_16x16x32_bf16 v[34:37], v[26:29], v[6:9], v[246:249]
	v_mfma_f32_16x16x32_bf16 v[22:25], v[26:29], v[10:13], v[250:253]
	v_mfma_f32_16x16x32_bf16 v[26:29], v[26:29], v[14:17], v[208:211]
	v_mfma_f32_16x16x32_bf16 v[166:169], v[162:165], v[2:5], v[166:169]
	v_mfma_f32_16x16x32_bf16 v[170:173], v[162:165], v[6:9], v[170:173]
	v_mfma_f32_16x16x32_bf16 v[2:5], v[162:165], v[10:13], v[174:177]
	v_mfma_f32_16x16x32_bf16 v[6:9], v[162:165], v[14:17], v[178:181]
	v_mov_b32_e32 v14, v195
	s_barrier
; DI int tidx() { int t = threadIdx.x; asm volatile("" : "+v"(t)); return t; }
; template <int EPI>
; DI void gemm_phase(const P& p, int l, const u16* __restrict__ A, const u16* __restrict__ Bt, int mpx, char* lds) {
;     ...
;   __syncthreads();
;   GSTORE(As0, Bs0)
;   const int tid_e = tidx();
;   const int lane = tid_e & 63, w = tid_e >> 6, r = lane & 15, g = lane >> 4, wm = w >> 2, wn = w & 3;
;   if constexpr (EPI == 1) {
;     const float alpha = 1.4142135623730951f;
;     float* Cw = (float*)(lds + 65536) + w * (16 * 68);
;     const int mr = m0 < MLAT ? (m0 >> 11) : 16;
;     const int colw = n0 + wn * 64;
;     const float* gate = p.mod + (size_t)(l * 17 + mr) * 3072 + 2048 + colw;
;     const float* xr = ((l == 0) ? (m0 < MLAT ? p.x + (size_t)m0 * 1024 : p.ctx + (size_t)(m0 - MLAT) * 1024)
;                                 : p.out + (size_t)m0 * 1024) + (size_t)(wm * 128) * 1024 + colw;
;     float* Z = (float*)p.slab + (size_t)(m0 + wm * 128) * 1024 + colw;
;     const int c4 = (lane & 15) * 4, rr0 = lane >> 4;
;     const float4 gt = *(const float4*)(gate + c4);
;     float4 xn[4];
; #pragma unroll
;     for (int i = 0; i < 4; ++i) xn[i] = *(const float4*)(xr + (size_t)(rr0 + 4 * i) * 1024 + c4);
; #pragma unroll
;     for (int mi = 0; mi < 8; ++mi) {
;       float4 xv[4];
; #pragma unroll
;       for (int i = 0; i < 4; ++i) xv[i] = xn[i];
;       if (mi < 7) {
; #pragma unroll
;         for (int i = 0; i < 4; ++i) xn[i] = *(const float4*)(xr + (size_t)((mi + 1) * 16 + rr0 + 4 * i) * 1024 + c4);
;       }
; #pragma unroll
;       for (int ni = 0; ni < 4; ++ni)
; #pragma unroll
;         for (int j = 0; j < 4; ++j) Cw[(g * 4 + j) * 68 + ni * 16 + r] = acc[mi][ni][j];
;       __builtin_amdgcn_fence(__ATOMIC_RELEASE, "wavefront");
; #pragma unroll
;       for (int i = 0; i < 4; ++i) {
;         const int row = rr0 + 4 * i;
;         const float4 a = *(const float4*)&Cw[row * 68 + c4];
;         float4 z;
;         z.x = alpha * xv[i].x + gt.x * a.x;
;         z.y = alpha * xv[i].y + gt.y * a.y;
;         z.z = alpha * xv[i].z + gt.z * a.z;
;         z.w = alpha * xv[i].w + gt.w * a.w;
;         *(float4*)(Z + (size_t)(mi * 16 + row) * 1024 + c4) = z;
	s_waitcnt vmcnt(7)
	ds_write_b128 v198, v[18:21]
	s_waitcnt vmcnt(5)
	ds_write_b128 v198, v[86:89] offset:8192
	s_waitcnt vmcnt(4)
	ds_write_b128 v198, v[90:93] offset:16384
	s_waitcnt vmcnt(3)
	ds_write_b128 v198, v[94:97] offset:24576
	ds_write_b128 v198, v[98:101] offset:32768
	s_waitcnt vmcnt(2)
	ds_write_b128 v198, v[102:105] offset:40960
	s_waitcnt vmcnt(1)
	ds_write_b128 v198, v[106:109] offset:49152
	s_waitcnt vmcnt(0)
	ds_write_b128 v198, v[110:113] offset:57344
	s_movk_i32 s2, 0x1100
	v_lshrrev_b32_e32 v0, 6, v14
	v_mul_lo_u32 v19, v0, s2
	s_min_i32 s2, s60, 0x8000
	s_lshr_b32 s2, s2, 11
	s_mul_i32 s46, s50, 17
	v_and_b32_e32 v0, 0xc0, v14
	s_add_i32 s2, s2, s46
	v_readlane_b32 s64, v255, 28
	v_or_b32_e32 v0, s61, v0
	s_mul_hi_i32 s47, s2, 0x3000
	s_mulk_i32 s2, 0x3000
	v_readlane_b32 s66, v255, 30
	v_readlane_b32 s67, v255, 31
	s_add_u32 s46, s66, s2
	v_lshlrev_b64 v[10:11], 2, v[0:1]
	v_mov_b32_e32 v0, 0x8000
	s_addc_u32 s47, s67, s47
	v_sub_co_u32_e32 v0, vcc, s60, v0
	v_lshl_add_u64 v[12:13], s[46:47], 0, v[10:11]
	s_and_b64 s[46:47], vcc, exec
	v_readfirstlane_b32 s2, v0
	s_cselect_b32 s2, s60, s2
	s_cselect_b32 s48, 0, 16
	s_and_b64 s[46:47], s[0:1], exec
	s_cselect_b32 s46, s48, 0x88
	s_cselect_b32 s2, s2, s60
	s_add_u32 s46, s96, s46
	s_addc_u32 s47, s97, 0
	s_load_dwordx2 s[46:47], s[46:47], 0x0
	v_ashrrev_i32_e32 v0, 1, v14
	v_and_b32_e32 v18, 15, v14
	v_bfe_u32 v88, v14, 4, 2
	s_lshl_b64 s[48:49], s[2:3], 12
	v_and_b32_e32 v14, 0xffffff80, v0
	s_waitcnt lgkmcnt(0)
	s_add_u32 s46, s46, s48
	v_ashrrev_i32_e32 v15, 31, v14
	s_addc_u32 s47, s47, s49
	v_lshlrev_b64 v[16:17], 12, v[14:15]
	v_lshl_add_u64 v[16:17], s[46:47], 0, v[16:17]
	v_add_u32_e32 v14, s60, v14
	v_lshl_add_u64 v[16:17], v[16:17], 0, v[10:11]
	v_ashrrev_i32_e32 v15, 31, v14
	v_lshlrev_b32_e32 v0, 4, v18
	v_lshlrev_b64 v[14:15], 12, v[14:15]
	v_lshlrev_b32_e32 v20, 2, v18
	v_lshl_add_u64 v[16:17], v[16:17], 0, v[0:1]
	v_lshlrev_b32_e32 v86, 12, v88
	v_mov_b32_e32 v87, v1
	v_lshl_add_u64 v[14:15], s[18:19], 0, v[14:15]
	v_lshl_add_u64 v[162:163], v[16:17], 0, v[86:87]
	v_add3_u32 v16, s78, v19, v20
	s_movk_i32 s2, 0x440
	v_lshl_add_u64 v[12:13], v[12:13], 0, v[0:1]
	v_lshl_add_u64 v[10:11], v[14:15], 0, v[10:11]
	v_mad_u32_u24 v165, v88, s2, v16
	s_movk_i32 s2, 0x2000
	v_lshl_add_u64 v[14:15], v[10:11], 0, v[0:1]
	v_add_co_u32_e32 v10, vcc, s2, v12
	ds_write2_b32 v165, v146, v154 offset1:16
	ds_write2_b32 v165, v147, v155 offset0:68 offset1:84
	ds_write2_b32 v165, v148, v156 offset0:136 offset1:152
	ds_write2_b32 v165, v149, v157 offset0:204 offset1:220
	ds_write2_b32 v165, v150, v158 offset0:32 offset1:48
	ds_write2_b32 v165, v151, v159 offset0:100 offset1:116
	ds_write2_b32 v165, v152, v160 offset0:168 offset1:184
	ds_write2_b32 v165, v153, v161 offset0:236 offset1:252
	v_addc_co_u32_e32 v11, vcc, 0, v13, vcc
	v_mad_u32_u24 v17, v18, 12, v16
	global_load_dwordx4 v[18:21], v[10:11], off
	s_nop 0
	global_load_dwordx4 v[10:13], v[162:163], off
	v_or_b32_e32 v0, 4, v88
	v_add_co_u32_e32 v16, vcc, s94, v162
	v_mad_u32_u24 v164, v88, s79, v17
	v_mad_u32_u24 v158, v0, s79, v17
	v_addc_co_u32_e32 v17, vcc, 0, v163, vcc
	global_load_dwordx4 v[102:105], v[16:17], off
	v_add_co_u32_e32 v16, vcc, s21, v162
	v_lshlrev_b32_e32 v0, 12, v0
	s_nop 0
	v_addc_co_u32_e32 v17, vcc, 0, v163, vcc
	global_load_dwordx4 v[94:97], v[16:17], off
	v_lshl_add_u64 v[156:157], v[14:15], 0, v[0:1]
	v_or_b32_e32 v0, 0x8000, v86
	v_lshl_add_u64 v[154:155], v[14:15], 0, v[0:1]
	v_or_b32_e32 v0, 0xc000, v86
	s_mov_b32 s2, 0xc000
	v_lshl_add_u64 v[152:153], v[14:15], 0, v[86:87]
	v_lshl_add_u64 v[150:151], v[14:15], 0, v[0:1]
	v_add_co_u32_e32 v14, vcc, s2, v162
	s_mov_b32 s2, 0x14000
	s_nop 0
	v_addc_co_u32_e32 v15, vcc, 0, v163, vcc
	global_load_dwordx4 v[86:89], v[14:15], off
	v_add_co_u32_e32 v14, vcc, s85, v162
	s_mov_b32 s46, 0x30000
	s_nop 0
	v_addc_co_u32_e32 v15, vcc, 0, v163, vcc
	global_load_dwordx4 v[146:149], v[14:15], off
	v_add_co_u32_e32 v14, vcc, s2, v162
	s_mov_b32 s2, 0x18000
	s_nop 0
	v_addc_co_u32_e32 v15, vcc, 0, v163, vcc
	global_load_dwordx4 v[106:109], v[14:15], off
	v_add_co_u32_e32 v14, vcc, s2, v162
	s_mov_b32 s2, 0x1c000
	s_nop 0
	v_addc_co_u32_e32 v15, vcc, 0, v163, vcc
	global_load_dwordx4 v[98:101], v[14:15], off
	v_add_co_u32_e32 v14, vcc, s2, v162
	s_mov_b32 s2, 0x24000
	s_nop 0
	v_addc_co_u32_e32 v15, vcc, 0, v163, vcc
	global_load_dwordx4 v[90:93], v[14:15], off
	ds_read_b128 v[14:17], v164
	s_mov_b32 s60, s58
	s_mov_b32 s61, s59
	s_mov_b64 s[48:49], s[42:43]
	v_readlane_b32 s65, v255, 29
	v_readlane_b32 s68, v255, 32
	v_readlane_b32 s69, v255, 33
	v_readlane_b32 s70, v255, 34
	v_readlane_b32 s71, v255, 35
	s_waitcnt vmcnt(8) lgkmcnt(0)
	v_pk_mul_f32 v[14:15], v[18:19], v[14:15]
	s_waitcnt vmcnt(7)
	v_pk_fma_f32 v[10:11], v[10:11], s[34:35], v[14:15] op_sel_hi:[1,0,1]
	v_pk_mul_f32 v[14:15], v[20:21], v[16:17]
	s_nop 0
	v_pk_fma_f32 v[12:13], v[12:13], s[34:35], v[14:15] op_sel_hi:[1,0,1]
	global_store_dwordx4 v[152:153], v[10:13], off sc1 nt
	ds_read_b128 v[10:13], v158
	s_waitcnt lgkmcnt(0)
	v_pk_mul_f32 v[10:11], v[18:19], v[10:11]
	v_pk_mul_f32 v[12:13], v[20:21], v[12:13]
	s_waitcnt vmcnt(7)
	v_pk_fma_f32 v[10:11], v[102:103], s[34:35], v[10:11] op_sel_hi:[1,0,1]
	v_pk_fma_f32 v[12:13], v[104:105], s[34:35], v[12:13] op_sel_hi:[1,0,1]
	global_store_dwordx4 v[156:157], v[10:13], off sc1 nt
	ds_read_b128 v[10:13], v158 offset:1088
	s_waitcnt lgkmcnt(0)
	v_pk_mul_f32 v[10:11], v[18:19], v[10:11]
	v_pk_mul_f32 v[12:13], v[20:21], v[12:13]
	s_waitcnt vmcnt(7)
; template <int EPI>
; DI void gemm_phase(const P& p, int l, const u16* __restrict__ A, const u16* __restrict__ Bt, int mpx, char* lds) {
;     ...
;     for (int mi = 0; mi < 8; ++mi) {
;       float4 xv[4];
; #pragma unroll
;       for (int i = 0; i < 4; ++i) xv[i] = xn[i];
;       if (mi < 7) {
; #pragma unroll
;         for (int i = 0; i < 4; ++i) xn[i] = *(const float4*)(xr + (size_t)((mi + 1) * 16 + rr0 + 4 * i) * 1024 + c4);
;       }
; #pragma unroll
;       for (int ni = 0; ni < 4; ++ni)
; #pragma unroll
;         for (int j = 0; j < 4; ++j) Cw[(g * 4 + j) * 68 + ni * 16 + r] = acc[mi][ni][j];
;       __builtin_amdgcn_fence(__ATOMIC_RELEASE, "wavefront");
; #pragma unroll
;       for (int i = 0; i < 4; ++i) {
;         const int row = rr0 + 4 * i;
;         const float4 a = *(const float4*)&Cw[row * 68 + c4];
;         float4 z;
;         z.x = alpha * xv[i].x + gt.x * a.x;
;         z.y = alpha * xv[i].y + gt.y * a.y;
;         z.z = alpha * xv[i].z + gt.z * a.z;
;         z.w = alpha * xv[i].w + gt.w * a.w;
;         *(float4*)(Z + (size_t)(mi * 16 + row) * 1024 + c4) = z;
;       }
;       __builtin_amdgcn_fence(__ATOMIC_RELEASE, "wavefront");
	v_pk_fma_f32 v[10:11], v[94:95], s[34:35], v[10:11] op_sel_hi:[1,0,1]
	v_pk_fma_f32 v[12:13], v[96:97], s[34:35], v[12:13] op_sel_hi:[1,0,1]
	global_store_dwordx4 v[154:155], v[10:13], off sc1 nt
	ds_read_b128 v[10:13], v158 offset:2176
	s_waitcnt lgkmcnt(0)
	v_pk_mul_f32 v[10:11], v[18:19], v[10:11]
	v_pk_mul_f32 v[12:13], v[20:21], v[12:13]
	s_waitcnt vmcnt(7)
	v_pk_fma_f32 v[10:11], v[86:87], s[34:35], v[10:11] op_sel_hi:[1,0,1]
	v_pk_fma_f32 v[12:13], v[88:89], s[34:35], v[12:13] op_sel_hi:[1,0,1]
	global_store_dwordx4 v[150:151], v[10:13], off sc1 nt
	ds_write2_b32 v165, v138, v142 offset1:16
	ds_write2_b32 v165, v139, v143 offset0:68 offset1:84
	ds_write2_b32 v165, v140, v144 offset0:136 offset1:152
	ds_write2_b32 v165, v141, v145 offset0:204 offset1:220
	ds_write2_b32 v165, v130, v134 offset0:32 offset1:48
	ds_write2_b32 v165, v131, v135 offset0:100 offset1:116
	ds_write2_b32 v165, v132, v136 offset0:168 offset1:184
	ds_write2_b32 v165, v133, v137 offset0:236 offset1:252
	v_add_co_u32_e32 v10, vcc, s33, v162
	s_nop 1
	v_addc_co_u32_e32 v11, vcc, 0, v163, vcc
	global_load_dwordx4 v[110:113], v[10:11], off
	v_add_co_u32_e32 v10, vcc, s2, v162
	s_mov_b32 s2, 0x28000
	s_nop 0
	v_addc_co_u32_e32 v11, vcc, 0, v163, vcc
	global_load_dwordx4 v[102:105], v[10:11], off
	v_add_co_u32_e32 v10, vcc, s2, v162
	s_mov_b32 s2, 0x2c000
	s_nop 0
	v_addc_co_u32_e32 v11, vcc, 0, v163, vcc
	global_load_dwordx4 v[94:97], v[10:11], off
	v_add_co_u32_e32 v10, vcc, s2, v162
	s_mov_b32 s2, 0x34000
	s_nop 0
	v_addc_co_u32_e32 v11, vcc, 0, v163, vcc
	global_load_dwordx4 v[86:89], v[10:11], off
	ds_read_b128 v[10:13], v164
	v_add_co_u32_e32 v14, vcc, s85, v152
	s_waitcnt lgkmcnt(0)
	v_pk_mul_f32 v[10:11], v[18:19], v[10:11]
	v_pk_mul_f32 v[12:13], v[20:21], v[12:13]
	s_waitcnt vmcnt(11)
	v_pk_fma_f32 v[10:11], v[146:147], s[34:35], v[10:11] op_sel_hi:[1,0,1]
	v_pk_fma_f32 v[12:13], v[148:149], s[34:35], v[12:13] op_sel_hi:[1,0,1]
	v_addc_co_u32_e32 v15, vcc, 0, v153, vcc
	global_store_dwordx4 v[14:15], v[10:13], off sc1 nt
	ds_read_b128 v[10:13], v158
	v_add_co_u32_e32 v14, vcc, s85, v156
	s_waitcnt lgkmcnt(0)
	v_pk_mul_f32 v[10:11], v[18:19], v[10:11]
	v_pk_mul_f32 v[12:13], v[20:21], v[12:13]
	s_waitcnt vmcnt(11)
	v_pk_fma_f32 v[10:11], v[106:107], s[34:35], v[10:11] op_sel_hi:[1,0,1]
	v_pk_fma_f32 v[12:13], v[108:109], s[34:35], v[12:13] op_sel_hi:[1,0,1]
	v_addc_co_u32_e32 v15, vcc, 0, v157, vcc
	global_store_dwordx4 v[14:15], v[10:13], off sc1 nt
	ds_read_b128 v[10:13], v158 offset:1088
	v_add_co_u32_e32 v14, vcc, s85, v154
	s_waitcnt lgkmcnt(0)
	v_pk_mul_f32 v[10:11], v[18:19], v[10:11]
	v_pk_mul_f32 v[12:13], v[20:21], v[12:13]
	s_waitcnt vmcnt(11)
	v_pk_fma_f32 v[10:11], v[98:99], s[34:35], v[10:11] op_sel_hi:[1,0,1]
	v_pk_fma_f32 v[12:13], v[100:101], s[34:35], v[12:13] op_sel_hi:[1,0,1]
	v_addc_co_u32_e32 v15, vcc, 0, v155, vcc
	global_store_dwordx4 v[14:15], v[10:13], off sc1 nt
	ds_read_b128 v[10:13], v158 offset:2176
	v_add_co_u32_e32 v14, vcc, s85, v150
	s_waitcnt lgkmcnt(0)
	v_pk_mul_f32 v[10:11], v[18:19], v[10:11]
	v_pk_mul_f32 v[12:13], v[20:21], v[12:13]
	s_waitcnt vmcnt(11)
	v_pk_fma_f32 v[10:11], v[90:91], s[34:35], v[10:11] op_sel_hi:[1,0,1]
	v_pk_fma_f32 v[12:13], v[92:93], s[34:35], v[12:13] op_sel_hi:[1,0,1]
	v_addc_co_u32_e32 v15, vcc, 0, v151, vcc
	global_store_dwordx4 v[14:15], v[10:13], off sc1 nt
	ds_write2_b32 v165, v122, v126 offset1:16
	ds_write2_b32 v165, v123, v127 offset0:68 offset1:84
	ds_write2_b32 v165, v124, v128 offset0:136 offset1:152
	ds_write2_b32 v165, v125, v129 offset0:204 offset1:220
	ds_write2_b32 v165, v114, v118 offset0:32 offset1:48
	ds_write2_b32 v165, v115, v119 offset0:100 offset1:116
	ds_write2_b32 v165, v116, v120 offset0:168 offset1:184
	ds_write2_b32 v165, v117, v121 offset0:236 offset1:252
	v_add_co_u32_e32 v10, vcc, s46, v162
	s_nop 1
	v_addc_co_u32_e32 v11, vcc, 0, v163, vcc
	global_load_dwordx4 v[114:117], v[10:11], off
	v_add_co_u32_e32 v10, vcc, s2, v162
	s_mov_b32 s2, 0x38000
	s_nop 0
	v_addc_co_u32_e32 v11, vcc, 0, v163, vcc
	global_load_dwordx4 v[106:109], v[10:11], off
	v_add_co_u32_e32 v10, vcc, s2, v162
	s_mov_b32 s2, 0x3c000
	s_nop 0
	v_addc_co_u32_e32 v11, vcc, 0, v163, vcc
	global_load_dwordx4 v[98:101], v[10:11], off
	v_add_co_u32_e32 v10, vcc, s2, v162
	s_mov_b32 s2, 0x44000
	s_nop 0
	v_addc_co_u32_e32 v11, vcc, 0, v163, vcc
	global_load_dwordx4 v[90:93], v[10:11], off
	ds_read_b128 v[10:13], v164
	v_add_co_u32_e32 v14, vcc, s33, v152
	s_waitcnt lgkmcnt(0)
	v_pk_mul_f32 v[10:11], v[18:19], v[10:11]
	v_pk_mul_f32 v[12:13], v[20:21], v[12:13]
	s_waitcnt vmcnt(11)
	v_pk_fma_f32 v[10:11], v[110:111], s[34:35], v[10:11] op_sel_hi:[1,0,1]
	v_pk_fma_f32 v[12:13], v[112:113], s[34:35], v[12:13] op_sel_hi:[1,0,1]
	v_addc_co_u32_e32 v15, vcc, 0, v153, vcc
	global_store_dwordx4 v[14:15], v[10:13], off sc1 nt
	ds_read_b128 v[10:13], v158
	v_add_co_u32_e32 v14, vcc, s33, v156
	s_waitcnt lgkmcnt(0)
	v_pk_mul_f32 v[10:11], v[18:19], v[10:11]
	v_pk_mul_f32 v[12:13], v[20:21], v[12:13]
	s_waitcnt vmcnt(11)
	v_pk_fma_f32 v[10:11], v[102:103], s[34:35], v[10:11] op_sel_hi:[1,0,1]
	v_pk_fma_f32 v[12:13], v[104:105], s[34:35], v[12:13] op_sel_hi:[1,0,1]
	v_addc_co_u32_e32 v15, vcc, 0, v157, vcc
	global_store_dwordx4 v[14:15], v[10:13], off sc1 nt
	ds_read_b128 v[10:13], v158 offset:1088
	v_add_co_u32_e32 v14, vcc, s33, v154
	s_waitcnt lgkmcnt(0)
	v_pk_mul_f32 v[10:11], v[18:19], v[10:11]
	v_pk_mul_f32 v[12:13], v[20:21], v[12:13]
	s_waitcnt vmcnt(11)
; template <int EPI>
; DI void gemm_phase(const P& p, int l, const u16* __restrict__ A, const u16* __restrict__ Bt, int mpx, char* lds) {
;     ...
;     for (int mi = 0; mi < 8; ++mi) {
;       float4 xv[4];
; #pragma unroll
;       for (int i = 0; i < 4; ++i) xv[i] = xn[i];
;       if (mi < 7) {
; #pragma unroll
;         for (int i = 0; i < 4; ++i) xn[i] = *(const float4*)(xr + (size_t)((mi + 1) * 16 + rr0 + 4 * i) * 1024 + c4);
;       }
; #pragma unroll
;       for (int ni = 0; ni < 4; ++ni)
; #pragma unroll
;         for (int j = 0; j < 4; ++j) Cw[(g * 4 + j) * 68 + ni * 16 + r] = acc[mi][ni][j];
;       __builtin_amdgcn_fence(__ATOMIC_RELEASE, "wavefront");
; #pragma unroll
;       for (int i = 0; i < 4; ++i) {
;         const int row = rr0 + 4 * i;
;         const float4 a = *(const float4*)&Cw[row * 68 + c4];
;         float4 z;
;         z.x = alpha * xv[i].x + gt.x * a.x;
;         z.y = alpha * xv[i].y + gt.y * a.y;
;         z.z = alpha * xv[i].z + gt.z * a.z;
;         z.w = alpha * xv[i].w + gt.w * a.w;
;         *(float4*)(Z + (size_t)(mi * 16 + row) * 1024 + c4) = z;
;       }
;       __builtin_amdgcn_fence(__ATOMIC_RELEASE, "wavefront");
	v_pk_fma_f32 v[10:11], v[94:95], s[34:35], v[10:11] op_sel_hi:[1,0,1]
	v_pk_fma_f32 v[12:13], v[96:97], s[34:35], v[12:13] op_sel_hi:[1,0,1]
	v_addc_co_u32_e32 v15, vcc, 0, v155, vcc
	global_store_dwordx4 v[14:15], v[10:13], off sc1 nt
	ds_read_b128 v[10:13], v158 offset:2176
	v_add_co_u32_e32 v14, vcc, s33, v150
	s_waitcnt lgkmcnt(0)
	v_pk_mul_f32 v[10:11], v[18:19], v[10:11]
	v_pk_mul_f32 v[12:13], v[20:21], v[12:13]
	s_waitcnt vmcnt(11)
	v_pk_fma_f32 v[10:11], v[86:87], s[34:35], v[10:11] op_sel_hi:[1,0,1]
	v_pk_fma_f32 v[12:13], v[88:89], s[34:35], v[12:13] op_sel_hi:[1,0,1]
	v_addc_co_u32_e32 v15, vcc, 0, v151, vcc
	global_store_dwordx4 v[14:15], v[10:13], off sc1 nt
	ds_write2_b32 v165, v78, v82 offset1:16
	ds_write2_b32 v165, v79, v83 offset0:68 offset1:84
	ds_write2_b32 v165, v80, v84 offset0:136 offset1:152
	ds_write2_b32 v165, v81, v85 offset0:204 offset1:220
	ds_write2_b32 v165, v70, v74 offset0:32 offset1:48
	ds_write2_b32 v165, v71, v75 offset0:100 offset1:116
	ds_write2_b32 v165, v72, v76 offset0:168 offset1:184
	ds_write2_b32 v165, v73, v77 offset0:236 offset1:252
	v_add_co_u32_e32 v10, vcc, s35, v162
	s_nop 1
	v_addc_co_u32_e32 v11, vcc, 0, v163, vcc
	global_load_dwordx4 v[82:85], v[10:11], off
	v_add_co_u32_e32 v10, vcc, s2, v162
	s_mov_b32 s2, 0x48000
	s_nop 0
	v_addc_co_u32_e32 v11, vcc, 0, v163, vcc
	global_load_dwordx4 v[78:81], v[10:11], off
	v_add_co_u32_e32 v10, vcc, s2, v162
	s_mov_b32 s2, 0x4c000
	s_nop 0
	v_addc_co_u32_e32 v11, vcc, 0, v163, vcc
	global_load_dwordx4 v[74:77], v[10:11], off
	v_add_co_u32_e32 v10, vcc, s2, v162
	s_mov_b32 s2, 0x54000
	s_nop 0
	v_addc_co_u32_e32 v11, vcc, 0, v163, vcc
	global_load_dwordx4 v[70:73], v[10:11], off
	ds_read_b128 v[10:13], v164
	v_add_co_u32_e32 v14, vcc, s46, v152
	s_waitcnt lgkmcnt(0)
	v_pk_mul_f32 v[10:11], v[18:19], v[10:11]
	v_pk_mul_f32 v[12:13], v[20:21], v[12:13]
	s_waitcnt vmcnt(11)
	v_pk_fma_f32 v[10:11], v[114:115], s[34:35], v[10:11] op_sel_hi:[1,0,1]
	v_pk_fma_f32 v[12:13], v[116:117], s[34:35], v[12:13] op_sel_hi:[1,0,1]
	v_addc_co_u32_e32 v15, vcc, 0, v153, vcc
	global_store_dwordx4 v[14:15], v[10:13], off sc1 nt
	ds_read_b128 v[10:13], v158
	v_add_co_u32_e32 v14, vcc, s46, v156
	s_waitcnt lgkmcnt(0)
	v_pk_mul_f32 v[10:11], v[18:19], v[10:11]
	v_pk_mul_f32 v[12:13], v[20:21], v[12:13]
	s_waitcnt vmcnt(11)
	v_pk_fma_f32 v[10:11], v[106:107], s[34:35], v[10:11] op_sel_hi:[1,0,1]
	v_pk_fma_f32 v[12:13], v[108:109], s[34:35], v[12:13] op_sel_hi:[1,0,1]
	v_addc_co_u32_e32 v15, vcc, 0, v157, vcc
	global_store_dwordx4 v[14:15], v[10:13], off sc1 nt
	ds_read_b128 v[10:13], v158 offset:1088
	v_add_co_u32_e32 v14, vcc, s46, v154
	s_waitcnt lgkmcnt(0)
	v_pk_mul_f32 v[10:11], v[18:19], v[10:11]
	v_pk_mul_f32 v[12:13], v[20:21], v[12:13]
	s_waitcnt vmcnt(11)
	v_pk_fma_f32 v[10:11], v[98:99], s[34:35], v[10:11] op_sel_hi:[1,0,1]
	v_pk_fma_f32 v[12:13], v[100:101], s[34:35], v[12:13] op_sel_hi:[1,0,1]
	v_addc_co_u32_e32 v15, vcc, 0, v155, vcc
	global_store_dwordx4 v[14:15], v[10:13], off sc1 nt
	ds_read_b128 v[10:13], v158 offset:2176
	v_add_co_u32_e32 v14, vcc, s46, v150
	s_mov_b32 s46, 0x50000
	s_nop 0
	v_addc_co_u32_e32 v15, vcc, 0, v151, vcc
	s_waitcnt lgkmcnt(0)
	v_pk_mul_f32 v[10:11], v[18:19], v[10:11]
	v_pk_mul_f32 v[12:13], v[20:21], v[12:13]
	s_waitcnt vmcnt(11)
	v_pk_fma_f32 v[10:11], v[90:91], s[34:35], v[10:11] op_sel_hi:[1,0,1]
	v_pk_fma_f32 v[12:13], v[92:93], s[34:35], v[12:13] op_sel_hi:[1,0,1]
	global_store_dwordx4 v[14:15], v[10:13], off sc1 nt
	ds_write2_b32 v165, v62, v66 offset1:16
	ds_write2_b32 v165, v63, v67 offset0:68 offset1:84
	ds_write2_b32 v165, v64, v68 offset0:136 offset1:152
	ds_write2_b32 v165, v65, v69 offset0:204 offset1:220
	ds_write2_b32 v165, v54, v58 offset0:32 offset1:48
	ds_write2_b32 v165, v55, v59 offset0:100 offset1:116
	ds_write2_b32 v165, v56, v60 offset0:168 offset1:184
	ds_write2_b32 v165, v57, v61 offset0:236 offset1:252
	v_add_co_u32_e32 v10, vcc, s46, v162
	s_nop 1
	v_addc_co_u32_e32 v11, vcc, 0, v163, vcc
	global_load_dwordx4 v[66:69], v[10:11], off
	v_add_co_u32_e32 v10, vcc, s2, v162
	s_mov_b32 s2, 0x58000
	s_nop 0
	v_addc_co_u32_e32 v11, vcc, 0, v163, vcc
	global_load_dwordx4 v[62:65], v[10:11], off
	v_add_co_u32_e32 v10, vcc, s2, v162
	s_mov_b32 s2, 0x5c000
	s_nop 0
	v_addc_co_u32_e32 v11, vcc, 0, v163, vcc
	global_load_dwordx4 v[58:61], v[10:11], off
	v_add_co_u32_e32 v10, vcc, s2, v162
	s_mov_b32 s2, 0x64000
	s_nop 0
	v_addc_co_u32_e32 v11, vcc, 0, v163, vcc
	global_load_dwordx4 v[54:57], v[10:11], off
	ds_read_b128 v[10:13], v164
	v_add_co_u32_e32 v14, vcc, s35, v152
	s_waitcnt lgkmcnt(0)
	v_pk_mul_f32 v[10:11], v[18:19], v[10:11]
	v_pk_mul_f32 v[12:13], v[20:21], v[12:13]
	s_waitcnt vmcnt(11)
	v_pk_fma_f32 v[10:11], v[82:83], s[34:35], v[10:11] op_sel_hi:[1,0,1]
	v_pk_fma_f32 v[12:13], v[84:85], s[34:35], v[12:13] op_sel_hi:[1,0,1]
	v_addc_co_u32_e32 v15, vcc, 0, v153, vcc
	global_store_dwordx4 v[14:15], v[10:13], off sc1 nt
	ds_read_b128 v[10:13], v158
	v_add_co_u32_e32 v14, vcc, s35, v156
	s_waitcnt lgkmcnt(0)
	v_pk_mul_f32 v[10:11], v[18:19], v[10:11]
	v_pk_mul_f32 v[12:13], v[20:21], v[12:13]
	s_waitcnt vmcnt(11)
	v_pk_fma_f32 v[10:11], v[78:79], s[34:35], v[10:11] op_sel_hi:[1,0,1]
	v_pk_fma_f32 v[12:13], v[80:81], s[34:35], v[12:13] op_sel_hi:[1,0,1]
	v_addc_co_u32_e32 v15, vcc, 0, v157, vcc
	global_store_dwordx4 v[14:15], v[10:13], off sc1 nt
	ds_read_b128 v[10:13], v158 offset:1088
	v_add_co_u32_e32 v14, vcc, s35, v154
	s_waitcnt lgkmcnt(0)
	v_pk_mul_f32 v[10:11], v[18:19], v[10:11]
	v_pk_mul_f32 v[12:13], v[20:21], v[12:13]
	s_waitcnt vmcnt(11)
; template <int EPI>
; DI void gemm_phase(const P& p, int l, const u16* __restrict__ A, const u16* __restrict__ Bt, int mpx, char* lds) {
;     ...
;     for (int mi = 0; mi < 8; ++mi) {
;       float4 xv[4];
; #pragma unroll
;       for (int i = 0; i < 4; ++i) xv[i] = xn[i];
;       if (mi < 7) {
; #pragma unroll
;         for (int i = 0; i < 4; ++i) xn[i] = *(const float4*)(xr + (size_t)((mi + 1) * 16 + rr0 + 4 * i) * 1024 + c4);
;       }
; #pragma unroll
;       for (int ni = 0; ni < 4; ++ni)
; #pragma unroll
;         for (int j = 0; j < 4; ++j) Cw[(g * 4 + j) * 68 + ni * 16 + r] = acc[mi][ni][j];
;       __builtin_amdgcn_fence(__ATOMIC_RELEASE, "wavefront");
; #pragma unroll
;       for (int i = 0; i < 4; ++i) {
;         const int row = rr0 + 4 * i;
;         const float4 a = *(const float4*)&Cw[row * 68 + c4];
;         float4 z;
;         z.x = alpha * xv[i].x + gt.x * a.x;
;         z.y = alpha * xv[i].y + gt.y * a.y;
;         z.z = alpha * xv[i].z + gt.z * a.z;
;         z.w = alpha * xv[i].w + gt.w * a.w;
;         *(float4*)(Z + (size_t)(mi * 16 + row) * 1024 + c4) = z;
;       }
;       __builtin_amdgcn_fence(__ATOMIC_RELEASE, "wavefront");
	v_pk_fma_f32 v[10:11], v[74:75], s[34:35], v[10:11] op_sel_hi:[1,0,1]
	v_pk_fma_f32 v[12:13], v[76:77], s[34:35], v[12:13] op_sel_hi:[1,0,1]
	v_addc_co_u32_e32 v15, vcc, 0, v155, vcc
	global_store_dwordx4 v[14:15], v[10:13], off sc1 nt
	ds_read_b128 v[10:13], v158 offset:2176
	v_add_co_u32_e32 v14, vcc, s35, v150
	s_waitcnt lgkmcnt(0)
	v_pk_mul_f32 v[10:11], v[18:19], v[10:11]
	v_pk_mul_f32 v[12:13], v[20:21], v[12:13]
	s_waitcnt vmcnt(11)
	v_pk_fma_f32 v[10:11], v[70:71], s[34:35], v[10:11] op_sel_hi:[1,0,1]
	v_pk_fma_f32 v[12:13], v[72:73], s[34:35], v[12:13] op_sel_hi:[1,0,1]
	v_addc_co_u32_e32 v15, vcc, 0, v151, vcc
	global_store_dwordx4 v[14:15], v[10:13], off sc1 nt
	ds_write2_b32 v165, v46, v50 offset1:16
	ds_write2_b32 v165, v47, v51 offset0:68 offset1:84
	ds_write2_b32 v165, v48, v52 offset0:136 offset1:152
	ds_write2_b32 v165, v49, v53 offset0:204 offset1:220
	ds_write2_b32 v165, v38, v42 offset0:32 offset1:48
	ds_write2_b32 v165, v39, v43 offset0:100 offset1:116
	ds_write2_b32 v165, v40, v44 offset0:168 offset1:184
	ds_write2_b32 v165, v41, v45 offset0:236 offset1:252
	v_add_co_u32_e32 v10, vcc, s39, v162
	s_nop 1
	v_addc_co_u32_e32 v11, vcc, 0, v163, vcc
	global_load_dwordx4 v[50:53], v[10:11], off
	v_add_co_u32_e32 v10, vcc, s2, v162
	s_mov_b32 s2, 0x68000
	s_nop 0
	v_addc_co_u32_e32 v11, vcc, 0, v163, vcc
	global_load_dwordx4 v[46:49], v[10:11], off
	v_add_co_u32_e32 v10, vcc, s2, v162
	s_mov_b32 s2, 0x6c000
	s_nop 0
	v_addc_co_u32_e32 v11, vcc, 0, v163, vcc
	global_load_dwordx4 v[42:45], v[10:11], off
	v_add_co_u32_e32 v10, vcc, s2, v162
	s_mov_b32 s2, 0x74000
	s_nop 0
	v_addc_co_u32_e32 v11, vcc, 0, v163, vcc
	global_load_dwordx4 v[38:41], v[10:11], off
	ds_read_b128 v[10:13], v164
	v_add_co_u32_e32 v14, vcc, s46, v152
	s_waitcnt lgkmcnt(0)
	v_pk_mul_f32 v[10:11], v[18:19], v[10:11]
	v_pk_mul_f32 v[12:13], v[20:21], v[12:13]
	s_waitcnt vmcnt(11)
	v_pk_fma_f32 v[10:11], v[66:67], s[34:35], v[10:11] op_sel_hi:[1,0,1]
	v_pk_fma_f32 v[12:13], v[68:69], s[34:35], v[12:13] op_sel_hi:[1,0,1]
	v_addc_co_u32_e32 v15, vcc, 0, v153, vcc
	global_store_dwordx4 v[14:15], v[10:13], off sc1 nt
	ds_read_b128 v[10:13], v158
	v_add_co_u32_e32 v14, vcc, s46, v156
	s_waitcnt lgkmcnt(0)
	v_pk_mul_f32 v[10:11], v[18:19], v[10:11]
	v_pk_mul_f32 v[12:13], v[20:21], v[12:13]
	s_waitcnt vmcnt(11)
	v_pk_fma_f32 v[10:11], v[62:63], s[34:35], v[10:11] op_sel_hi:[1,0,1]
	v_pk_fma_f32 v[12:13], v[64:65], s[34:35], v[12:13] op_sel_hi:[1,0,1]
	v_addc_co_u32_e32 v15, vcc, 0, v157, vcc
	global_store_dwordx4 v[14:15], v[10:13], off sc1 nt
	ds_read_b128 v[10:13], v158 offset:1088
	v_add_co_u32_e32 v14, vcc, s46, v154
	s_waitcnt lgkmcnt(0)
	v_pk_mul_f32 v[10:11], v[18:19], v[10:11]
	v_pk_mul_f32 v[12:13], v[20:21], v[12:13]
	s_waitcnt vmcnt(11)
	v_pk_fma_f32 v[10:11], v[58:59], s[34:35], v[10:11] op_sel_hi:[1,0,1]
	v_pk_fma_f32 v[12:13], v[60:61], s[34:35], v[12:13] op_sel_hi:[1,0,1]
	v_addc_co_u32_e32 v15, vcc, 0, v155, vcc
	global_store_dwordx4 v[14:15], v[10:13], off sc1 nt
	ds_read_b128 v[10:13], v158 offset:2176
	v_add_co_u32_e32 v14, vcc, s46, v150
	s_mov_b32 s46, 0x70000
	s_nop 0
	v_addc_co_u32_e32 v15, vcc, 0, v151, vcc
	s_waitcnt lgkmcnt(0)
	v_pk_mul_f32 v[10:11], v[18:19], v[10:11]
	v_pk_mul_f32 v[12:13], v[20:21], v[12:13]
	s_waitcnt vmcnt(11)
	v_pk_fma_f32 v[10:11], v[54:55], s[34:35], v[10:11] op_sel_hi:[1,0,1]
	v_pk_fma_f32 v[12:13], v[56:57], s[34:35], v[12:13] op_sel_hi:[1,0,1]
	global_store_dwordx4 v[14:15], v[10:13], off sc1 nt
	ds_write2_b32 v165, v30, v34 offset1:16
	ds_write2_b32 v165, v31, v35 offset0:68 offset1:84
	ds_write2_b32 v165, v32, v36 offset0:136 offset1:152
	ds_write2_b32 v165, v33, v37 offset0:204 offset1:220
	ds_write2_b32 v165, v22, v26 offset0:32 offset1:48
	ds_write2_b32 v165, v23, v27 offset0:100 offset1:116
	ds_write2_b32 v165, v24, v28 offset0:168 offset1:184
	ds_write2_b32 v165, v25, v29 offset0:236 offset1:252
	v_add_co_u32_e32 v10, vcc, s46, v162
	s_nop 1
	v_addc_co_u32_e32 v11, vcc, 0, v163, vcc
	global_load_dwordx4 v[10:13], v[10:11], off
	v_add_co_u32_e32 v14, vcc, s2, v162
	s_mov_b32 s2, 0x78000
	s_nop 0
	v_addc_co_u32_e32 v15, vcc, 0, v163, vcc
	global_load_dwordx4 v[30:33], v[14:15], off
	v_add_co_u32_e32 v14, vcc, s2, v162
	s_mov_b32 s2, 0x7c000
	s_nop 0
	v_addc_co_u32_e32 v15, vcc, 0, v163, vcc
	global_load_dwordx4 v[26:29], v[14:15], off
	v_add_co_u32_e32 v14, vcc, s2, v162
	s_nop 1
	v_addc_co_u32_e32 v15, vcc, 0, v163, vcc
	global_load_dwordx4 v[22:25], v[14:15], off
	ds_read_b128 v[14:17], v164
	v_add_co_u32_e32 v34, vcc, s39, v152
	s_waitcnt lgkmcnt(0)
; template <int EPI>
; DI void gemm_phase(const P& p, int l, const u16* __restrict__ A, const u16* __restrict__ Bt, int mpx, char* lds) {
;     ...
;     for (int mi = 0; mi < 8; ++mi) {
;       float4 xv[4];
; #pragma unroll
;       for (int i = 0; i < 4; ++i) xv[i] = xn[i];
;       if (mi < 7) {
; #pragma unroll
;         for (int i = 0; i < 4; ++i) xn[i] = *(const float4*)(xr + (size_t)((mi + 1) * 16 + rr0 + 4 * i) * 1024 + c4);
;       }
; #pragma unroll
;       for (int ni = 0; ni < 4; ++ni)
; #pragma unroll
;         for (int j = 0; j < 4; ++j) Cw[(g * 4 + j) * 68 + ni * 16 + r] = acc[mi][ni][j];
;       __builtin_amdgcn_fence(__ATOMIC_RELEASE, "wavefront");
; #pragma unroll
;       for (int i = 0; i < 4; ++i) {
;         const int row = rr0 + 4 * i;
;         const float4 a = *(const float4*)&Cw[row * 68 + c4];
;         float4 z;
;         z.x = alpha * xv[i].x + gt.x * a.x;
;         z.y = alpha * xv[i].y + gt.y * a.y;
;         z.z = alpha * xv[i].z + gt.z * a.z;
;         z.w = alpha * xv[i].w + gt.w * a.w;
;         *(float4*)(Z + (size_t)(mi * 16 + row) * 1024 + c4) = z;
;       }
;       __builtin_amdgcn_fence(__ATOMIC_RELEASE, "wavefront");
;     ...
;   if (!has_next) break;
;   t = tn; m0 = m1; n0 = n1; Ag = Agn; Bg = Bgn;
	v_pk_mul_f32 v[14:15], v[18:19], v[14:15]
	v_pk_mul_f32 v[16:17], v[20:21], v[16:17]
	s_waitcnt vmcnt(11)
	v_pk_fma_f32 v[14:15], v[50:51], s[34:35], v[14:15] op_sel_hi:[1,0,1]
	v_pk_fma_f32 v[16:17], v[52:53], s[34:35], v[16:17] op_sel_hi:[1,0,1]
	v_addc_co_u32_e32 v35, vcc, 0, v153, vcc
	global_store_dwordx4 v[34:35], v[14:17], off sc1 nt
	ds_read_b128 v[14:17], v158
	v_add_co_u32_e32 v34, vcc, s39, v156
	s_waitcnt lgkmcnt(0)
	v_pk_mul_f32 v[14:15], v[18:19], v[14:15]
	v_pk_mul_f32 v[16:17], v[20:21], v[16:17]
	s_waitcnt vmcnt(11)
	v_pk_fma_f32 v[14:15], v[46:47], s[34:35], v[14:15] op_sel_hi:[1,0,1]
	v_pk_fma_f32 v[16:17], v[48:49], s[34:35], v[16:17] op_sel_hi:[1,0,1]
	v_addc_co_u32_e32 v35, vcc, 0, v157, vcc
	global_store_dwordx4 v[34:35], v[14:17], off sc1 nt
	ds_read_b128 v[14:17], v158 offset:1088
	v_add_co_u32_e32 v34, vcc, s39, v154
	s_waitcnt lgkmcnt(0)
	v_pk_mul_f32 v[14:15], v[18:19], v[14:15]
	v_pk_mul_f32 v[16:17], v[20:21], v[16:17]
	s_waitcnt vmcnt(11)
	v_pk_fma_f32 v[14:15], v[42:43], s[34:35], v[14:15] op_sel_hi:[1,0,1]
	v_pk_fma_f32 v[16:17], v[44:45], s[34:35], v[16:17] op_sel_hi:[1,0,1]
	v_addc_co_u32_e32 v35, vcc, 0, v155, vcc
	global_store_dwordx4 v[34:35], v[14:17], off sc1 nt
	ds_read_b128 v[14:17], v158 offset:2176
	v_add_co_u32_e32 v34, vcc, s39, v150
	s_waitcnt lgkmcnt(0)
	v_pk_mul_f32 v[14:15], v[18:19], v[14:15]
	v_pk_mul_f32 v[16:17], v[20:21], v[16:17]
	s_waitcnt vmcnt(11)
	v_pk_fma_f32 v[14:15], v[38:39], s[34:35], v[14:15] op_sel_hi:[1,0,1]
	v_pk_fma_f32 v[16:17], v[40:41], s[34:35], v[16:17] op_sel_hi:[1,0,1]
	v_addc_co_u32_e32 v35, vcc, 0, v151, vcc
	global_store_dwordx4 v[34:35], v[14:17], off sc1 nt
	ds_write2_b32 v165, v166, v170 offset1:16
	ds_write2_b32 v165, v167, v171 offset0:68 offset1:84
	ds_write2_b32 v165, v168, v172 offset0:136 offset1:152
	ds_write2_b32 v165, v169, v173 offset0:204 offset1:220
	ds_write2_b32 v165, v2, v6 offset0:32 offset1:48
	ds_write2_b32 v165, v3, v7 offset0:100 offset1:116
	ds_write2_b32 v165, v4, v8 offset0:168 offset1:184
	ds_write2_b32 v165, v5, v9 offset0:236 offset1:252
	ds_read_b128 v[2:5], v164
	v_add_co_u32_e32 v6, vcc, s46, v152
	s_waitcnt lgkmcnt(0)
	v_pk_mul_f32 v[2:3], v[18:19], v[2:3]
	v_pk_mul_f32 v[4:5], v[20:21], v[4:5]
	v_addc_co_u32_e32 v7, vcc, 0, v153, vcc
	s_waitcnt vmcnt(7)
	v_pk_fma_f32 v[2:3], v[10:11], s[34:35], v[2:3] op_sel_hi:[1,0,1]
	v_pk_fma_f32 v[4:5], v[12:13], s[34:35], v[4:5] op_sel_hi:[1,0,1]
	global_store_dwordx4 v[6:7], v[2:5], off sc1 nt
	ds_read_b128 v[2:5], v158
	v_add_co_u32_e32 v6, vcc, s46, v156
	s_waitcnt lgkmcnt(0)
	v_pk_mul_f32 v[2:3], v[18:19], v[2:3]
	v_pk_mul_f32 v[4:5], v[20:21], v[4:5]
	s_waitcnt vmcnt(7)
	v_pk_fma_f32 v[2:3], v[30:31], s[34:35], v[2:3] op_sel_hi:[1,0,1]
	v_pk_fma_f32 v[4:5], v[32:33], s[34:35], v[4:5] op_sel_hi:[1,0,1]
	v_addc_co_u32_e32 v7, vcc, 0, v157, vcc
	global_store_dwordx4 v[6:7], v[2:5], off sc1 nt
	ds_read_b128 v[2:5], v158 offset:1088
	v_add_co_u32_e32 v6, vcc, s46, v154
	s_mov_b64 s[46:47], s[44:45]
	s_nop 0
	v_addc_co_u32_e32 v7, vcc, 0, v155, vcc
	s_waitcnt lgkmcnt(0)
	v_pk_mul_f32 v[2:3], v[18:19], v[2:3]
	v_pk_mul_f32 v[4:5], v[20:21], v[4:5]
	s_waitcnt vmcnt(7)
	v_pk_fma_f32 v[2:3], v[26:27], s[34:35], v[2:3] op_sel_hi:[1,0,1]
	v_pk_fma_f32 v[4:5], v[28:29], s[34:35], v[4:5] op_sel_hi:[1,0,1]
	global_store_dwordx4 v[6:7], v[2:5], off sc1 nt
	ds_read_b128 v[2:5], v158 offset:2176
	v_add_co_u32_e32 v6, vcc, 0x70000, v150
	s_waitcnt lgkmcnt(0)
	v_pk_mul_f32 v[2:3], v[18:19], v[2:3]
	v_pk_mul_f32 v[4:5], v[20:21], v[4:5]
	v_addc_co_u32_e32 v7, vcc, 0, v151, vcc
	s_waitcnt vmcnt(7)
	v_pk_fma_f32 v[2:3], v[22:23], s[34:35], v[2:3] op_sel_hi:[1,0,1]
	v_pk_fma_f32 v[4:5], v[24:25], s[34:35], v[4:5] op_sel_hi:[1,0,1]
	s_and_b64 vcc, exec, s[40:41]
	global_store_dwordx4 v[6:7], v[2:5], off sc1 nt
	s_cbranch_vccz .LBB0_69
	v_mov_b32_e32 v236, 0x358637bd

; template <int EPI>
; DI void gemm_phase(const P& p, int l, const u16* __restrict__ A, const u16* __restrict__ Bt, int mpx, char* lds) {
;     ...
;           float v0 = acc[hf * 4 + mi][0][j], v1 = acc[hf * 4 + mi][1][j], v2 = acc[hf * 4 + mi][2][j], v3 = acc[hf * 4 + mi][3][j];
;           const int rowl = mi * 16 + g * 4 + j;
;           const int s = tokw + hf * 64 + rowl;
;           if (tr == 1) {
;             v0 = silu(v0); v1 = silu(v1); v2 = silu(v2); v3 = silu(v3);
;           } else if (tr == 3) {
;             if (donorm) {
;               float ss = v0 * v0 + v1 * v1 + v2 * v2 + v3 * v3;
;               ss += __shfl_xor(ss, 1);
;               ss += __shfl_xor(ss, 2);
;               ss += __shfl_xor(ss, 4);
;               ss += __shfl_xor(ss, 8);
;               const float inv = rsqrtf(ss * (1.f / 64.f) + 1e-6f);
;               v0 *= inv * gv0; v1 *= inv * gv1; v2 *= inv * gv2; v3 *= inv * gv3;
;             }
;             if (dorope) {
;               float sr, cr, sc, cc;
;               sincos_rev((float)(s >> 6) * invf64, sr, cr);
;               sincos_rev((float)(s & 63) * invf64, sc, cc);
;               const float a1 = v0, a2 = v1, b1 = v2, b2 = v3;
;               v0 = a1 * cr - a2 * sr;
;               v1 = a2 * cr + a1 * sr;
;               v2 = b1 * cc - b2 * sc;
;               v3 = b2 * cc + b1 * sc;
;             }
;           } else if (tr == 4) {
;             float sr, cr, sc, cc;
;             sincos_rev((float)(s >> 6) * invf32, sr, cr);
;             sincos_rev((float)(s & 63) * invf32, sc, cc);
;             const float p0 = __shfl_xor(v0, 8), p1 = __shfl_xor(v1, 8), p2 = __shfl_xor(v2, 8), p3 = __shfl_xor(v3, 8);
;             v0 = lo8 ? (v0 * cr - p0 * sr) : (v0 * cr + p0 * sr);
;             v1 = lo8 ? (v1 * cc - p1 * sc) : (v1 * cc + p1 * sc);
;             v2 = lo8 ? (v2 * cr - p2 * sr) : (v2 * cr + p2 * sr);
;             v3 = lo8 ? (v3 * cc - p3 * sc) : (v3 * cc + p3 * sc);
;           }
;           const unsigned u01 = pack2(v0, v1), u23 = pack2(v2, v3);
;           if (kind == 1) {
;             Tl[(0 * 16 + r) * 72 + rowl] = (u16)u01;
;             Tl[(1 * 16 + r) * 72 + rowl] = (u16)(u01 >> 16);
;             Tl[(2 * 16 + r) * 72 + rowl] = (u16)u23;
;             Tl[(3 * 16 + r) * 72 + rowl] = (u16)(u23 >> 16);
;           } else if (tr == 2) {
;             Tl[rowl * 72 + 0 * 16 + r] = f2h(v0);
.Lfe_k0_silu:
	s_add_u32 s62, s44, 0x1000
	s_addc_u32 s63, s45, 0
	v_mul_f32_e32 v174, 0xbfb8aa3b, v6
	v_mul_f32_e32 v175, 0xbfb8aa3b, v10
	v_mul_f32_e32 v176, 0xbfb8aa3b, v14
	v_mul_f32_e32 v177, 0xbfb8aa3b, v18
	v_exp_f32_e32 v174, v174
	v_exp_f32_e32 v175, v175
	v_exp_f32_e32 v176, v176
	v_exp_f32_e32 v177, v177
	v_add_f32_e32 v174, 1.0, v174
	v_add_f32_e32 v175, 1.0, v175
	v_add_f32_e32 v176, 1.0, v176
	v_add_f32_e32 v177, 1.0, v177
	v_rcp_f32_e32 v174, v174
	v_rcp_f32_e32 v175, v175
	v_rcp_f32_e32 v176, v176
	v_rcp_f32_e32 v177, v177
	v_mul_f32_e32 v174, v6, v174
	v_mul_f32_e32 v175, v10, v175
	v_mul_f32_e32 v176, v14, v176
	v_mul_f32_e32 v177, v18, v177
	v_cvt_pk_bf16_f32 v178, v174, v175
	v_cvt_pk_bf16_f32 v179, v176, v177
	ds_write_b16 v170, v178 offset:0
	ds_write_b16_d16_hi v170, v178 offset:32
	ds_write_b16 v170, v179 offset:64
	ds_write_b16_d16_hi v170, v179 offset:96
	v_mul_f32_e32 v180, 0xbfb8aa3b, v7
	v_mul_f32_e32 v181, 0xbfb8aa3b, v11
	v_mul_f32_e32 v182, 0xbfb8aa3b, v15
	v_mul_f32_e32 v183, 0xbfb8aa3b, v19
	v_exp_f32_e32 v180, v180
	v_exp_f32_e32 v181, v181
	v_exp_f32_e32 v182, v182
	v_exp_f32_e32 v183, v183
	v_add_f32_e32 v180, 1.0, v180
	v_add_f32_e32 v181, 1.0, v181
	v_add_f32_e32 v182, 1.0, v182
	v_add_f32_e32 v183, 1.0, v183
	v_rcp_f32_e32 v180, v180
	v_rcp_f32_e32 v181, v181
	v_rcp_f32_e32 v182, v182
	v_rcp_f32_e32 v183, v183
	v_mul_f32_e32 v180, v7, v180
	v_mul_f32_e32 v181, v11, v181
	v_mul_f32_e32 v182, v15, v182
	v_mul_f32_e32 v183, v19, v183
	v_cvt_pk_bf16_f32 v184, v180, v181
	v_cvt_pk_bf16_f32 v185, v182, v183
	ds_write_b16 v170, v184 offset:144
	ds_write_b16_d16_hi v170, v184 offset:176
	ds_write_b16 v170, v185 offset:208
	ds_write_b16_d16_hi v170, v185 offset:240
	v_mul_f32_e32 v186, 0xbfb8aa3b, v8
	v_mul_f32_e32 v187, 0xbfb8aa3b, v12
	v_mul_f32_e32 v188, 0xbfb8aa3b, v16
	v_mul_f32_e32 v189, 0xbfb8aa3b, v20
	v_exp_f32_e32 v186, v186
	v_exp_f32_e32 v187, v187
	v_exp_f32_e32 v188, v188
	v_exp_f32_e32 v189, v189
	v_add_f32_e32 v186, 1.0, v186
	v_add_f32_e32 v187, 1.0, v187
	v_add_f32_e32 v188, 1.0, v188
	v_add_f32_e32 v189, 1.0, v189
	v_rcp_f32_e32 v186, v186
	v_rcp_f32_e32 v187, v187
	v_rcp_f32_e32 v188, v188
	v_rcp_f32_e32 v189, v189
	v_mul_f32_e32 v186, v8, v186
	v_mul_f32_e32 v187, v12, v187
	v_mul_f32_e32 v188, v16, v188
	v_mul_f32_e32 v189, v20, v189
	v_cvt_pk_bf16_f32 v190, v186, v187
	v_cvt_pk_bf16_f32 v191, v188, v189
	ds_write_b16 v170, v190 offset:288
	ds_write_b16_d16_hi v170, v190 offset:320
	ds_write_b16 v170, v191 offset:352
	ds_write_b16_d16_hi v170, v191 offset:384
	v_mul_f32_e32 v192, 0xbfb8aa3b, v9
	v_mul_f32_e32 v193, 0xbfb8aa3b, v13
	v_mul_f32_e32 v174, 0xbfb8aa3b, v17
	v_mul_f32_e32 v175, 0xbfb8aa3b, v21
	v_exp_f32_e32 v192, v192
	v_exp_f32_e32 v193, v193
	v_exp_f32_e32 v174, v174
	v_exp_f32_e32 v175, v175
	v_add_f32_e32 v192, 1.0, v192
	v_add_f32_e32 v193, 1.0, v193
	v_add_f32_e32 v174, 1.0, v174
	v_add_f32_e32 v175, 1.0, v175
	v_rcp_f32_e32 v192, v192
	v_rcp_f32_e32 v193, v193
	v_rcp_f32_e32 v174, v174
	v_rcp_f32_e32 v175, v175
	v_mul_f32_e32 v192, v9, v192
	v_mul_f32_e32 v193, v13, v193
	v_mul_f32_e32 v174, v17, v174
	v_mul_f32_e32 v175, v21, v175
	v_cvt_pk_bf16_f32 v176, v192, v193
	v_cvt_pk_bf16_f32 v177, v174, v175
	ds_write_b16 v170, v176 offset:432
	ds_write_b16_d16_hi v170, v176 offset:464
	ds_write_b16 v170, v177 offset:496
	ds_write_b16_d16_hi v170, v177 offset:528
	v_mul_f32_e32 v178, 0xbfb8aa3b, v22
	v_mul_f32_e32 v179, 0xbfb8aa3b, v26
	v_mul_f32_e32 v180, 0xbfb8aa3b, v30
	v_mul_f32_e32 v181, 0xbfb8aa3b, v34
	v_exp_f32_e32 v178, v178
	v_exp_f32_e32 v179, v179
	v_exp_f32_e32 v180, v180
	v_exp_f32_e32 v181, v181
	v_add_f32_e32 v178, 1.0, v178
	v_add_f32_e32 v179, 1.0, v179
	v_add_f32_e32 v180, 1.0, v180
	v_add_f32_e32 v181, 1.0, v181
	v_rcp_f32_e32 v178, v178
	v_rcp_f32_e32 v179, v179
	v_rcp_f32_e32 v180, v180
	v_rcp_f32_e32 v181, v181
	v_mul_f32_e32 v178, v22, v178
	v_mul_f32_e32 v179, v26, v179
	v_mul_f32_e32 v180, v30, v180
	v_mul_f32_e32 v181, v34, v181
	v_cvt_pk_bf16_f32 v182, v178, v179
	v_cvt_pk_bf16_f32 v183, v180, v181
	ds_write_b16 v170, v182 offset:2304
	ds_write_b16_d16_hi v170, v182 offset:2336
	ds_write_b16 v170, v183 offset:2368
	ds_write_b16_d16_hi v170, v183 offset:2400
	v_mul_f32_e32 v184, 0xbfb8aa3b, v23
	v_mul_f32_e32 v185, 0xbfb8aa3b, v27
	v_mul_f32_e32 v186, 0xbfb8aa3b, v31
	v_mul_f32_e32 v187, 0xbfb8aa3b, v35
	v_exp_f32_e32 v184, v184
	v_exp_f32_e32 v185, v185
	v_exp_f32_e32 v186, v186
	v_exp_f32_e32 v187, v187
	v_add_f32_e32 v184, 1.0, v184
	v_add_f32_e32 v185, 1.0, v185
	v_add_f32_e32 v186, 1.0, v186
	v_add_f32_e32 v187, 1.0, v187
	v_rcp_f32_e32 v184, v184
	v_rcp_f32_e32 v185, v185
	v_rcp_f32_e32 v186, v186
	v_rcp_f32_e32 v187, v187
	v_mul_f32_e32 v184, v23, v184
	v_mul_f32_e32 v185, v27, v185
	v_mul_f32_e32 v186, v31, v186
	v_mul_f32_e32 v187, v35, v187
	v_cvt_pk_bf16_f32 v188, v184, v185
	v_cvt_pk_bf16_f32 v189, v186, v187
	ds_write_b16 v170, v188 offset:2448
	ds_write_b16_d16_hi v170, v188 offset:2480
	ds_write_b16 v170, v189 offset:2512
	ds_write_b16_d16_hi v170, v189 offset:2544
	v_mul_f32_e32 v190, 0xbfb8aa3b, v24
	v_mul_f32_e32 v191, 0xbfb8aa3b, v28
	v_mul_f32_e32 v192, 0xbfb8aa3b, v32
	v_mul_f32_e32 v193, 0xbfb8aa3b, v36
	v_exp_f32_e32 v190, v190
	v_exp_f32_e32 v191, v191
	v_exp_f32_e32 v192, v192
	v_exp_f32_e32 v193, v193
	v_add_f32_e32 v190, 1.0, v190
	v_add_f32_e32 v191, 1.0, v191
	v_add_f32_e32 v192, 1.0, v192
	v_add_f32_e32 v193, 1.0, v193
	v_rcp_f32_e32 v190, v190
	v_rcp_f32_e32 v191, v191
	v_rcp_f32_e32 v192, v192
	v_rcp_f32_e32 v193, v193
	v_mul_f32_e32 v190, v24, v190
	v_mul_f32_e32 v191, v28, v191
	v_mul_f32_e32 v192, v32, v192
; template <int EPI>
; DI void gemm_phase(const P& p, int l, const u16* __restrict__ A, const u16* __restrict__ Bt, int mpx, char* lds) {
;     ...
;           float v0 = acc[hf * 4 + mi][0][j], v1 = acc[hf * 4 + mi][1][j], v2 = acc[hf * 4 + mi][2][j], v3 = acc[hf * 4 + mi][3][j];
;           const int rowl = mi * 16 + g * 4 + j;
;           const int s = tokw + hf * 64 + rowl;
;           if (tr == 1) {
;             v0 = silu(v0); v1 = silu(v1); v2 = silu(v2); v3 = silu(v3);
;           } else if (tr == 3) {
;             if (donorm) {
;               float ss = v0 * v0 + v1 * v1 + v2 * v2 + v3 * v3;
;               ss += __shfl_xor(ss, 1);
;               ss += __shfl_xor(ss, 2);
;               ss += __shfl_xor(ss, 4);
;               ss += __shfl_xor(ss, 8);
;               const float inv = rsqrtf(ss * (1.f / 64.f) + 1e-6f);
;               v0 *= inv * gv0; v1 *= inv * gv1; v2 *= inv * gv2; v3 *= inv * gv3;
;             }
;             if (dorope) {
;               float sr, cr, sc, cc;
;               sincos_rev((float)(s >> 6) * invf64, sr, cr);
;               sincos_rev((float)(s & 63) * invf64, sc, cc);
;               const float a1 = v0, a2 = v1, b1 = v2, b2 = v3;
;               v0 = a1 * cr - a2 * sr;
;               v1 = a2 * cr + a1 * sr;
;               v2 = b1 * cc - b2 * sc;
;               v3 = b2 * cc + b1 * sc;
;             }
;           } else if (tr == 4) {
;             float sr, cr, sc, cc;
;             sincos_rev((float)(s >> 6) * invf32, sr, cr);
;             sincos_rev((float)(s & 63) * invf32, sc, cc);
;             const float p0 = __shfl_xor(v0, 8), p1 = __shfl_xor(v1, 8), p2 = __shfl_xor(v2, 8), p3 = __shfl_xor(v3, 8);
;             v0 = lo8 ? (v0 * cr - p0 * sr) : (v0 * cr + p0 * sr);
;             v1 = lo8 ? (v1 * cc - p1 * sc) : (v1 * cc + p1 * sc);
;             v2 = lo8 ? (v2 * cr - p2 * sr) : (v2 * cr + p2 * sr);
;             v3 = lo8 ? (v3 * cc - p3 * sc) : (v3 * cc + p3 * sc);
;           }
;           const unsigned u01 = pack2(v0, v1), u23 = pack2(v2, v3);
;           if (kind == 1) {
;             Tl[(0 * 16 + r) * 72 + rowl] = (u16)u01;
;             Tl[(1 * 16 + r) * 72 + rowl] = (u16)(u01 >> 16);
;             Tl[(2 * 16 + r) * 72 + rowl] = (u16)u23;
;             Tl[(3 * 16 + r) * 72 + rowl] = (u16)(u23 >> 16);
;           } else if (tr == 2) {
;             Tl[rowl * 72 + 0 * 16 + r] = f2h(v0);
	v_mul_f32_e32 v193, v36, v193
	v_cvt_pk_bf16_f32 v174, v190, v191
	v_cvt_pk_bf16_f32 v175, v192, v193
	ds_write_b16 v170, v174 offset:2592
	ds_write_b16_d16_hi v170, v174 offset:2624
	ds_write_b16 v170, v175 offset:2656
	ds_write_b16_d16_hi v170, v175 offset:2688
	v_mul_f32_e32 v176, 0xbfb8aa3b, v25
	v_mul_f32_e32 v177, 0xbfb8aa3b, v29
	v_mul_f32_e32 v178, 0xbfb8aa3b, v33
	v_mul_f32_e32 v179, 0xbfb8aa3b, v37
	v_exp_f32_e32 v176, v176
	v_exp_f32_e32 v177, v177
	v_exp_f32_e32 v178, v178
	v_exp_f32_e32 v179, v179
	v_add_f32_e32 v176, 1.0, v176
	v_add_f32_e32 v177, 1.0, v177
	v_add_f32_e32 v178, 1.0, v178
	v_add_f32_e32 v179, 1.0, v179
	v_rcp_f32_e32 v176, v176
	v_rcp_f32_e32 v177, v177
	v_rcp_f32_e32 v178, v178
	v_rcp_f32_e32 v179, v179
	v_mul_f32_e32 v176, v25, v176
	v_mul_f32_e32 v177, v29, v177
	v_mul_f32_e32 v178, v33, v178
	v_mul_f32_e32 v179, v37, v179
	v_cvt_pk_bf16_f32 v180, v176, v177
	v_cvt_pk_bf16_f32 v181, v178, v179
	ds_write_b16 v170, v180 offset:2736
	ds_write_b16_d16_hi v170, v180 offset:2768
	ds_write_b16 v170, v181 offset:2800
	ds_write_b16_d16_hi v170, v181 offset:2832
	v_mul_f32_e32 v182, 0xbfb8aa3b, v38
	v_mul_f32_e32 v183, 0xbfb8aa3b, v42
	v_mul_f32_e32 v184, 0xbfb8aa3b, v46
	v_mul_f32_e32 v185, 0xbfb8aa3b, v50
	v_exp_f32_e32 v182, v182
	v_exp_f32_e32 v183, v183
	v_exp_f32_e32 v184, v184
	v_exp_f32_e32 v185, v185
	v_add_f32_e32 v182, 1.0, v182
	v_add_f32_e32 v183, 1.0, v183
	v_add_f32_e32 v184, 1.0, v184
	v_add_f32_e32 v185, 1.0, v185
	v_rcp_f32_e32 v182, v182
	v_rcp_f32_e32 v183, v183
	v_rcp_f32_e32 v184, v184
	v_rcp_f32_e32 v185, v185
	v_mul_f32_e32 v182, v38, v182
	v_mul_f32_e32 v183, v42, v183
	v_mul_f32_e32 v184, v46, v184
	v_mul_f32_e32 v185, v50, v185
	v_cvt_pk_bf16_f32 v186, v182, v183
	v_cvt_pk_bf16_f32 v187, v184, v185
	ds_write_b16 v170, v186 offset:4608
	ds_write_b16_d16_hi v170, v186 offset:4640
	ds_write_b16 v170, v187 offset:4672
	ds_write_b16_d16_hi v170, v187 offset:4704
	v_mul_f32_e32 v188, 0xbfb8aa3b, v39
	v_mul_f32_e32 v189, 0xbfb8aa3b, v43
	v_mul_f32_e32 v190, 0xbfb8aa3b, v47
	v_mul_f32_e32 v191, 0xbfb8aa3b, v51
	v_exp_f32_e32 v188, v188
	v_exp_f32_e32 v189, v189
	v_exp_f32_e32 v190, v190
	v_exp_f32_e32 v191, v191
	v_add_f32_e32 v188, 1.0, v188
	v_add_f32_e32 v189, 1.0, v189
	v_add_f32_e32 v190, 1.0, v190
	v_add_f32_e32 v191, 1.0, v191
	v_rcp_f32_e32 v188, v188
	v_rcp_f32_e32 v189, v189
	v_rcp_f32_e32 v190, v190
	v_rcp_f32_e32 v191, v191
	v_mul_f32_e32 v188, v39, v188
	v_mul_f32_e32 v189, v43, v189
	v_mul_f32_e32 v190, v47, v190
	v_mul_f32_e32 v191, v51, v191
	v_cvt_pk_bf16_f32 v192, v188, v189
	v_cvt_pk_bf16_f32 v193, v190, v191
	ds_write_b16 v170, v192 offset:4752
	ds_write_b16_d16_hi v170, v192 offset:4784
	ds_write_b16 v170, v193 offset:4816
	ds_write_b16_d16_hi v170, v193 offset:4848
	v_mul_f32_e32 v174, 0xbfb8aa3b, v40
	v_mul_f32_e32 v175, 0xbfb8aa3b, v44
	v_mul_f32_e32 v176, 0xbfb8aa3b, v48
	v_mul_f32_e32 v177, 0xbfb8aa3b, v52
	v_exp_f32_e32 v174, v174
	v_exp_f32_e32 v175, v175
	v_exp_f32_e32 v176, v176
	v_exp_f32_e32 v177, v177
	v_add_f32_e32 v174, 1.0, v174
	v_add_f32_e32 v175, 1.0, v175
	v_add_f32_e32 v176, 1.0, v176
	v_add_f32_e32 v177, 1.0, v177
	v_rcp_f32_e32 v174, v174
	v_rcp_f32_e32 v175, v175
	v_rcp_f32_e32 v176, v176
	v_rcp_f32_e32 v177, v177
	v_mul_f32_e32 v174, v40, v174
	v_mul_f32_e32 v175, v44, v175
	v_mul_f32_e32 v176, v48, v176
	v_mul_f32_e32 v177, v52, v177
	v_cvt_pk_bf16_f32 v178, v174, v175
	v_cvt_pk_bf16_f32 v179, v176, v177
	ds_write_b16 v170, v178 offset:4896
	ds_write_b16_d16_hi v170, v178 offset:4928
	ds_write_b16 v170, v179 offset:4960
	ds_write_b16_d16_hi v170, v179 offset:4992
	v_mul_f32_e32 v180, 0xbfb8aa3b, v41
	v_mul_f32_e32 v181, 0xbfb8aa3b, v45
	v_mul_f32_e32 v182, 0xbfb8aa3b, v49
	v_mul_f32_e32 v183, 0xbfb8aa3b, v53
	v_exp_f32_e32 v180, v180
	v_exp_f32_e32 v181, v181
	v_exp_f32_e32 v182, v182
	v_exp_f32_e32 v183, v183
	v_add_f32_e32 v180, 1.0, v180
	v_add_f32_e32 v181, 1.0, v181
	v_add_f32_e32 v182, 1.0, v182
	v_add_f32_e32 v183, 1.0, v183
	v_rcp_f32_e32 v180, v180
	v_rcp_f32_e32 v181, v181
	v_rcp_f32_e32 v182, v182
	v_rcp_f32_e32 v183, v183
	v_mul_f32_e32 v180, v41, v180
	v_mul_f32_e32 v181, v45, v181
	v_mul_f32_e32 v182, v49, v182
	v_mul_f32_e32 v183, v53, v183
	v_cvt_pk_bf16_f32 v184, v180, v181
	v_cvt_pk_bf16_f32 v185, v182, v183
	ds_write_b16 v170, v184 offset:5040
	ds_write_b16_d16_hi v170, v184 offset:5072
	ds_write_b16 v170, v185 offset:5104
	ds_write_b16_d16_hi v170, v185 offset:5136
	v_mul_f32_e32 v186, 0xbfb8aa3b, v54
	v_mul_f32_e32 v187, 0xbfb8aa3b, v58
	v_mul_f32_e32 v188, 0xbfb8aa3b, v62
	v_mul_f32_e32 v189, 0xbfb8aa3b, v66
	v_exp_f32_e32 v186, v186
	v_exp_f32_e32 v187, v187
	v_exp_f32_e32 v188, v188
	v_exp_f32_e32 v189, v189
	v_add_f32_e32 v186, 1.0, v186
	v_add_f32_e32 v187, 1.0, v187
	v_add_f32_e32 v188, 1.0, v188
	v_add_f32_e32 v189, 1.0, v189
	v_rcp_f32_e32 v186, v186
	v_rcp_f32_e32 v187, v187
	v_rcp_f32_e32 v188, v188
	v_rcp_f32_e32 v189, v189
	v_mul_f32_e32 v186, v54, v186
	v_mul_f32_e32 v187, v58, v187
	v_mul_f32_e32 v188, v62, v188
	v_mul_f32_e32 v189, v66, v189
	v_cvt_pk_bf16_f32 v190, v186, v187
	v_cvt_pk_bf16_f32 v191, v188, v189
	ds_write_b16 v170, v190 offset:6912
	ds_write_b16_d16_hi v170, v190 offset:6944
	ds_write_b16 v170, v191 offset:6976
	ds_write_b16_d16_hi v170, v191 offset:7008
	v_mul_f32_e32 v192, 0xbfb8aa3b, v55
	v_mul_f32_e32 v193, 0xbfb8aa3b, v59
	v_mul_f32_e32 v174, 0xbfb8aa3b, v63
	v_mul_f32_e32 v175, 0xbfb8aa3b, v67
	v_exp_f32_e32 v192, v192
	v_exp_f32_e32 v193, v193
	v_exp_f32_e32 v174, v174
	v_exp_f32_e32 v175, v175
	v_add_f32_e32 v192, 1.0, v192
	v_add_f32_e32 v193, 1.0, v193
	v_add_f32_e32 v174, 1.0, v174
; DI float silu(float v) { return v * __builtin_amdgcn_rcpf(1.f + __builtin_amdgcn_exp2f(-1.4426950408889634f * v)); }
; template <int EPI>
; DI void gemm_phase(const P& p, int l, const u16* __restrict__ A, const u16* __restrict__ Bt, int mpx, char* lds) {
;     ...
;           if (tr == 1) {
;             v0 = silu(v0); v1 = silu(v1); v2 = silu(v2); v3 = silu(v3);
;     ...
;           const unsigned u01 = pack2(v0, v1), u23 = pack2(v2, v3);
;           if (kind == 1) {
;             Tl[(0 * 16 + r) * 72 + rowl] = (u16)u01;
;             Tl[(1 * 16 + r) * 72 + rowl] = (u16)(u01 >> 16);
;             Tl[(2 * 16 + r) * 72 + rowl] = (u16)u23;
;             Tl[(3 * 16 + r) * 72 + rowl] = (u16)(u23 >> 16);
;           } else if (tr == 2) {
;             Tl[rowl * 72 + 0 * 16 + r] = f2h(v0);
;             Tl[rowl * 72 + 1 * 16 + r] = f2h(v1);
;             Tl[rowl * 72 + 2 * 16 + r] = f2h(v2);
;             Tl[rowl * 72 + 3 * 16 + r] = f2h(v3);
;           } else {
;             Tl[rowl * 72 + 0 * 16 + r] = (u16)u01;
;             Tl[rowl * 72 + 1 * 16 + r] = (u16)(u01 >> 16);
;             Tl[rowl * 72 + 2 * 16 + r] = (u16)u23;
;             Tl[rowl * 72 + 3 * 16 + r] = (u16)(u23 >> 16);
;           }
;         }
;       }
;       __builtin_amdgcn_fence(__ATOMIC_RELEASE, "wavefront");
;       u16* dh = (kind == 1) ? dst + hf * 64 : dst + (size_t)(hf * 64) * rstride;
; #pragma unroll
;       for (int i = 0; i < 8; ++i) {
;         const int c = lane + i * 64;
;         const int row = c >> 3, cc = c & 7;
;         uint4 v = *(const uint4*)&Tl[row * 72 + cc * 8];
;         *(uint4*)(dh + (size_t)row * rstride + cc * 8) = v;
;       }
	v_add_f32_e32 v175, 1.0, v175
	v_rcp_f32_e32 v192, v192
	v_rcp_f32_e32 v193, v193
	v_rcp_f32_e32 v174, v174
	v_rcp_f32_e32 v175, v175
	v_mul_f32_e32 v192, v55, v192
	v_mul_f32_e32 v193, v59, v193
	v_mul_f32_e32 v174, v63, v174
	v_mul_f32_e32 v175, v67, v175
	v_cvt_pk_bf16_f32 v176, v192, v193
	v_cvt_pk_bf16_f32 v177, v174, v175
	ds_write_b16 v170, v176 offset:7056
	ds_write_b16_d16_hi v170, v176 offset:7088
	ds_write_b16 v170, v177 offset:7120
	ds_write_b16_d16_hi v170, v177 offset:7152
	v_mul_f32_e32 v178, 0xbfb8aa3b, v56
	v_mul_f32_e32 v179, 0xbfb8aa3b, v60
	v_mul_f32_e32 v180, 0xbfb8aa3b, v64
	v_mul_f32_e32 v181, 0xbfb8aa3b, v68
	v_exp_f32_e32 v178, v178
	v_exp_f32_e32 v179, v179
	v_exp_f32_e32 v180, v180
	v_exp_f32_e32 v181, v181
	v_add_f32_e32 v178, 1.0, v178
	v_add_f32_e32 v179, 1.0, v179
	v_add_f32_e32 v180, 1.0, v180
	v_add_f32_e32 v181, 1.0, v181
	v_rcp_f32_e32 v178, v178
	v_rcp_f32_e32 v179, v179
	v_rcp_f32_e32 v180, v180
	v_rcp_f32_e32 v181, v181
	v_mul_f32_e32 v178, v56, v178
	v_mul_f32_e32 v179, v60, v179
	v_mul_f32_e32 v180, v64, v180
	v_mul_f32_e32 v181, v68, v181
	v_cvt_pk_bf16_f32 v182, v178, v179
	v_cvt_pk_bf16_f32 v183, v180, v181
	ds_write_b16 v170, v182 offset:7200
	ds_write_b16_d16_hi v170, v182 offset:7232
	ds_write_b16 v170, v183 offset:7264
	ds_write_b16_d16_hi v170, v183 offset:7296
	v_mul_f32_e32 v184, 0xbfb8aa3b, v57
	v_mul_f32_e32 v185, 0xbfb8aa3b, v61
	v_mul_f32_e32 v186, 0xbfb8aa3b, v65
	v_mul_f32_e32 v187, 0xbfb8aa3b, v69
	v_exp_f32_e32 v184, v184
	v_exp_f32_e32 v185, v185
	v_exp_f32_e32 v186, v186
	v_exp_f32_e32 v187, v187
	v_add_f32_e32 v184, 1.0, v184
	v_add_f32_e32 v185, 1.0, v185
	v_add_f32_e32 v186, 1.0, v186
	v_add_f32_e32 v187, 1.0, v187
	v_rcp_f32_e32 v184, v184
	v_rcp_f32_e32 v185, v185
	v_rcp_f32_e32 v186, v186
	v_rcp_f32_e32 v187, v187
	v_mul_f32_e32 v184, v57, v184
	v_mul_f32_e32 v185, v61, v185
	v_mul_f32_e32 v186, v65, v186
	v_mul_f32_e32 v187, v69, v187
	v_cvt_pk_bf16_f32 v188, v184, v185
	v_cvt_pk_bf16_f32 v189, v186, v187
	ds_write_b16 v170, v188 offset:7344
	ds_write_b16_d16_hi v170, v188 offset:7376
	ds_write_b16 v170, v189 offset:7408
	ds_write_b16_d16_hi v170, v189 offset:7440
	ds_read_b128 v[130:133], v171 offset:0
	ds_read_b128 v[134:137], v171 offset:1152
	ds_read_b128 v[138:141], v171 offset:2304
	ds_read_b128 v[142:145], v171 offset:3456
	ds_read_b128 v[146:149], v171 offset:4608
	ds_read_b128 v[150:153], v171 offset:5760
	ds_read_b128 v[154:157], v171 offset:6912
	ds_read_b128 v[158:161], v171 offset:8064
	s_waitcnt lgkmcnt(7)
	global_store_dwordx4 v172, v[130:133], s[44:45] offset:0 sc1 nt
	s_waitcnt lgkmcnt(6)
	global_store_dwordx4 v172, v[134:137], s[44:45] offset:1024 sc1 nt
	s_waitcnt lgkmcnt(5)
	global_store_dwordx4 v172, v[138:141], s[44:45] offset:2048 sc1 nt
	s_waitcnt lgkmcnt(4)
	global_store_dwordx4 v172, v[142:145], s[44:45] offset:3072 sc1 nt
	s_waitcnt lgkmcnt(3)
	global_store_dwordx4 v172, v[146:149], s[62:63] offset:0 sc1 nt
	s_waitcnt lgkmcnt(2)
	global_store_dwordx4 v172, v[150:153], s[62:63] offset:1024 sc1 nt
	s_waitcnt lgkmcnt(1)
	global_store_dwordx4 v172, v[154:157], s[62:63] offset:2048 sc1 nt
	s_waitcnt lgkmcnt(0)
	global_store_dwordx4 v172, v[158:161], s[62:63] offset:3072 sc1 nt
	s_add_u32 s44, s44, 0x2000
	s_addc_u32 s45, s45, 0
	s_add_u32 s62, s62, 0x2000
	s_addc_u32 s63, s63, 0
	v_mul_f32_e32 v174, 0xbfb8aa3b, v70
	v_mul_f32_e32 v175, 0xbfb8aa3b, v74
	v_mul_f32_e32 v176, 0xbfb8aa3b, v78
	v_mul_f32_e32 v177, 0xbfb8aa3b, v82
	v_exp_f32_e32 v174, v174
	v_exp_f32_e32 v175, v175
	v_exp_f32_e32 v176, v176
	v_exp_f32_e32 v177, v177
	v_add_f32_e32 v174, 1.0, v174
	v_add_f32_e32 v175, 1.0, v175
	v_add_f32_e32 v176, 1.0, v176
	v_add_f32_e32 v177, 1.0, v177
	v_rcp_f32_e32 v174, v174
	v_rcp_f32_e32 v175, v175
	v_rcp_f32_e32 v176, v176
	v_rcp_f32_e32 v177, v177
	v_mul_f32_e32 v174, v70, v174
	v_mul_f32_e32 v175, v74, v175
	v_mul_f32_e32 v176, v78, v176
	v_mul_f32_e32 v177, v82, v177
	v_cvt_pk_bf16_f32 v178, v174, v175
	v_cvt_pk_bf16_f32 v179, v176, v177
	ds_write_b16 v170, v178 offset:0
	ds_write_b16_d16_hi v170, v178 offset:32
	ds_write_b16 v170, v179 offset:64
	ds_write_b16_d16_hi v170, v179 offset:96
	v_mul_f32_e32 v180, 0xbfb8aa3b, v71
	v_mul_f32_e32 v181, 0xbfb8aa3b, v75
	v_mul_f32_e32 v182, 0xbfb8aa3b, v79
	v_mul_f32_e32 v183, 0xbfb8aa3b, v83
	v_exp_f32_e32 v180, v180
	v_exp_f32_e32 v181, v181
	v_exp_f32_e32 v182, v182
	v_exp_f32_e32 v183, v183
	v_add_f32_e32 v180, 1.0, v180
	v_add_f32_e32 v181, 1.0, v181
	v_add_f32_e32 v182, 1.0, v182
	v_add_f32_e32 v183, 1.0, v183
	v_rcp_f32_e32 v180, v180
	v_rcp_f32_e32 v181, v181
	v_rcp_f32_e32 v182, v182
	v_rcp_f32_e32 v183, v183
	v_mul_f32_e32 v180, v71, v180
	v_mul_f32_e32 v181, v75, v181
	v_mul_f32_e32 v182, v79, v182
	v_mul_f32_e32 v183, v83, v183
	v_cvt_pk_bf16_f32 v184, v180, v181
	v_cvt_pk_bf16_f32 v185, v182, v183
	ds_write_b16 v170, v184 offset:144
	ds_write_b16_d16_hi v170, v184 offset:176
	ds_write_b16 v170, v185 offset:208
	ds_write_b16_d16_hi v170, v185 offset:240
	v_mul_f32_e32 v186, 0xbfb8aa3b, v72
	v_mul_f32_e32 v187, 0xbfb8aa3b, v76
	v_mul_f32_e32 v188, 0xbfb8aa3b, v80
	v_mul_f32_e32 v189, 0xbfb8aa3b, v84
	v_exp_f32_e32 v186, v186
	v_exp_f32_e32 v187, v187
	v_exp_f32_e32 v188, v188
	v_exp_f32_e32 v189, v189
	v_add_f32_e32 v186, 1.0, v186
	v_add_f32_e32 v187, 1.0, v187
	v_add_f32_e32 v188, 1.0, v188
	v_add_f32_e32 v189, 1.0, v189
	v_rcp_f32_e32 v186, v186
	v_rcp_f32_e32 v187, v187
	v_rcp_f32_e32 v188, v188
	v_rcp_f32_e32 v189, v189
	v_mul_f32_e32 v186, v72, v186
	v_mul_f32_e32 v187, v76, v187
	v_mul_f32_e32 v188, v80, v188
	v_mul_f32_e32 v189, v84, v189
	v_cvt_pk_bf16_f32 v190, v186, v187
; template <int EPI>
; DI void gemm_phase(const P& p, int l, const u16* __restrict__ A, const u16* __restrict__ Bt, int mpx, char* lds) {
;     ...
;           float v0 = acc[hf * 4 + mi][0][j], v1 = acc[hf * 4 + mi][1][j], v2 = acc[hf * 4 + mi][2][j], v3 = acc[hf * 4 + mi][3][j];
;           const int rowl = mi * 16 + g * 4 + j;
;           const int s = tokw + hf * 64 + rowl;
;           if (tr == 1) {
;             v0 = silu(v0); v1 = silu(v1); v2 = silu(v2); v3 = silu(v3);
;           } else if (tr == 3) {
;             if (donorm) {
;               float ss = v0 * v0 + v1 * v1 + v2 * v2 + v3 * v3;
;               ss += __shfl_xor(ss, 1);
;               ss += __shfl_xor(ss, 2);
;               ss += __shfl_xor(ss, 4);
;               ss += __shfl_xor(ss, 8);
;               const float inv = rsqrtf(ss * (1.f / 64.f) + 1e-6f);
;               v0 *= inv * gv0; v1 *= inv * gv1; v2 *= inv * gv2; v3 *= inv * gv3;
;             }
;             if (dorope) {
;               float sr, cr, sc, cc;
;               sincos_rev((float)(s >> 6) * invf64, sr, cr);
;               sincos_rev((float)(s & 63) * invf64, sc, cc);
;               const float a1 = v0, a2 = v1, b1 = v2, b2 = v3;
;               v0 = a1 * cr - a2 * sr;
;               v1 = a2 * cr + a1 * sr;
;               v2 = b1 * cc - b2 * sc;
;               v3 = b2 * cc + b1 * sc;
;             }
;           } else if (tr == 4) {
;             float sr, cr, sc, cc;
;             sincos_rev((float)(s >> 6) * invf32, sr, cr);
;             sincos_rev((float)(s & 63) * invf32, sc, cc);
;             const float p0 = __shfl_xor(v0, 8), p1 = __shfl_xor(v1, 8), p2 = __shfl_xor(v2, 8), p3 = __shfl_xor(v3, 8);
;             v0 = lo8 ? (v0 * cr - p0 * sr) : (v0 * cr + p0 * sr);
;             v1 = lo8 ? (v1 * cc - p1 * sc) : (v1 * cc + p1 * sc);
;             v2 = lo8 ? (v2 * cr - p2 * sr) : (v2 * cr + p2 * sr);
;             v3 = lo8 ? (v3 * cc - p3 * sc) : (v3 * cc + p3 * sc);
;           }
;           const unsigned u01 = pack2(v0, v1), u23 = pack2(v2, v3);
;           if (kind == 1) {
;             Tl[(0 * 16 + r) * 72 + rowl] = (u16)u01;
;             Tl[(1 * 16 + r) * 72 + rowl] = (u16)(u01 >> 16);
;             Tl[(2 * 16 + r) * 72 + rowl] = (u16)u23;
;             Tl[(3 * 16 + r) * 72 + rowl] = (u16)(u23 >> 16);
;           } else if (tr == 2) {
;             Tl[rowl * 72 + 0 * 16 + r] = f2h(v0);
	v_cvt_pk_bf16_f32 v191, v188, v189
	ds_write_b16 v170, v190 offset:288
	ds_write_b16_d16_hi v170, v190 offset:320
	ds_write_b16 v170, v191 offset:352
	ds_write_b16_d16_hi v170, v191 offset:384
	v_mul_f32_e32 v192, 0xbfb8aa3b, v73
	v_mul_f32_e32 v193, 0xbfb8aa3b, v77
	v_mul_f32_e32 v174, 0xbfb8aa3b, v81
	v_mul_f32_e32 v175, 0xbfb8aa3b, v85
	v_exp_f32_e32 v192, v192
	v_exp_f32_e32 v193, v193
	v_exp_f32_e32 v174, v174
	v_exp_f32_e32 v175, v175
	v_add_f32_e32 v192, 1.0, v192
	v_add_f32_e32 v193, 1.0, v193
	v_add_f32_e32 v174, 1.0, v174
	v_add_f32_e32 v175, 1.0, v175
	v_rcp_f32_e32 v192, v192
	v_rcp_f32_e32 v193, v193
	v_rcp_f32_e32 v174, v174
	v_rcp_f32_e32 v175, v175
	v_mul_f32_e32 v192, v73, v192
	v_mul_f32_e32 v193, v77, v193
	v_mul_f32_e32 v174, v81, v174
	v_mul_f32_e32 v175, v85, v175
	v_cvt_pk_bf16_f32 v176, v192, v193
	v_cvt_pk_bf16_f32 v177, v174, v175
	ds_write_b16 v170, v176 offset:432
	ds_write_b16_d16_hi v170, v176 offset:464
	ds_write_b16 v170, v177 offset:496
	ds_write_b16_d16_hi v170, v177 offset:528
	v_mul_f32_e32 v178, 0xbfb8aa3b, v86
	v_mul_f32_e32 v179, 0xbfb8aa3b, v90
	v_mul_f32_e32 v180, 0xbfb8aa3b, v94
	v_mul_f32_e32 v181, 0xbfb8aa3b, v98
	v_exp_f32_e32 v178, v178
	v_exp_f32_e32 v179, v179
	v_exp_f32_e32 v180, v180
	v_exp_f32_e32 v181, v181
	v_add_f32_e32 v178, 1.0, v178
	v_add_f32_e32 v179, 1.0, v179
	v_add_f32_e32 v180, 1.0, v180
	v_add_f32_e32 v181, 1.0, v181
	v_rcp_f32_e32 v178, v178
	v_rcp_f32_e32 v179, v179
	v_rcp_f32_e32 v180, v180
	v_rcp_f32_e32 v181, v181
	v_mul_f32_e32 v178, v86, v178
	v_mul_f32_e32 v179, v90, v179
	v_mul_f32_e32 v180, v94, v180
	v_mul_f32_e32 v181, v98, v181
	v_cvt_pk_bf16_f32 v182, v178, v179
	v_cvt_pk_bf16_f32 v183, v180, v181
	ds_write_b16 v170, v182 offset:2304
	ds_write_b16_d16_hi v170, v182 offset:2336
	ds_write_b16 v170, v183 offset:2368
	ds_write_b16_d16_hi v170, v183 offset:2400
	v_mul_f32_e32 v184, 0xbfb8aa3b, v87
	v_mul_f32_e32 v185, 0xbfb8aa3b, v91
	v_mul_f32_e32 v186, 0xbfb8aa3b, v95
	v_mul_f32_e32 v187, 0xbfb8aa3b, v99
	v_exp_f32_e32 v184, v184
	v_exp_f32_e32 v185, v185
	v_exp_f32_e32 v186, v186
	v_exp_f32_e32 v187, v187
	v_add_f32_e32 v184, 1.0, v184
	v_add_f32_e32 v185, 1.0, v185
	v_add_f32_e32 v186, 1.0, v186
	v_add_f32_e32 v187, 1.0, v187
	v_rcp_f32_e32 v184, v184
	v_rcp_f32_e32 v185, v185
	v_rcp_f32_e32 v186, v186
	v_rcp_f32_e32 v187, v187
	v_mul_f32_e32 v184, v87, v184
	v_mul_f32_e32 v185, v91, v185
	v_mul_f32_e32 v186, v95, v186
	v_mul_f32_e32 v187, v99, v187
	v_cvt_pk_bf16_f32 v188, v184, v185
	v_cvt_pk_bf16_f32 v189, v186, v187
	ds_write_b16 v170, v188 offset:2448
	ds_write_b16_d16_hi v170, v188 offset:2480
	ds_write_b16 v170, v189 offset:2512
	ds_write_b16_d16_hi v170, v189 offset:2544
	v_mul_f32_e32 v190, 0xbfb8aa3b, v88
	v_mul_f32_e32 v191, 0xbfb8aa3b, v92
	v_mul_f32_e32 v192, 0xbfb8aa3b, v96
	v_mul_f32_e32 v193, 0xbfb8aa3b, v100
	v_exp_f32_e32 v190, v190
	v_exp_f32_e32 v191, v191
	v_exp_f32_e32 v192, v192
	v_exp_f32_e32 v193, v193
	v_add_f32_e32 v190, 1.0, v190
	v_add_f32_e32 v191, 1.0, v191
	v_add_f32_e32 v192, 1.0, v192
	v_add_f32_e32 v193, 1.0, v193
	v_rcp_f32_e32 v190, v190
	v_rcp_f32_e32 v191, v191
	v_rcp_f32_e32 v192, v192
	v_rcp_f32_e32 v193, v193
	v_mul_f32_e32 v190, v88, v190
	v_mul_f32_e32 v191, v92, v191
	v_mul_f32_e32 v192, v96, v192
	v_mul_f32_e32 v193, v100, v193
	v_cvt_pk_bf16_f32 v174, v190, v191
	v_cvt_pk_bf16_f32 v175, v192, v193
	ds_write_b16 v170, v174 offset:2592
	ds_write_b16_d16_hi v170, v174 offset:2624
	ds_write_b16 v170, v175 offset:2656
	ds_write_b16_d16_hi v170, v175 offset:2688
	v_mul_f32_e32 v176, 0xbfb8aa3b, v89
	v_mul_f32_e32 v177, 0xbfb8aa3b, v93
	v_mul_f32_e32 v178, 0xbfb8aa3b, v97
	v_mul_f32_e32 v179, 0xbfb8aa3b, v101
	v_exp_f32_e32 v176, v176
	v_exp_f32_e32 v177, v177
	v_exp_f32_e32 v178, v178
	v_exp_f32_e32 v179, v179
	v_add_f32_e32 v176, 1.0, v176
	v_add_f32_e32 v177, 1.0, v177
	v_add_f32_e32 v178, 1.0, v178
	v_add_f32_e32 v179, 1.0, v179
	v_rcp_f32_e32 v176, v176
	v_rcp_f32_e32 v177, v177
	v_rcp_f32_e32 v178, v178
	v_rcp_f32_e32 v179, v179
	v_mul_f32_e32 v176, v89, v176
	v_mul_f32_e32 v177, v93, v177
	v_mul_f32_e32 v178, v97, v178
	v_mul_f32_e32 v179, v101, v179
	v_cvt_pk_bf16_f32 v180, v176, v177
	v_cvt_pk_bf16_f32 v181, v178, v179
	ds_write_b16 v170, v180 offset:2736
	ds_write_b16_d16_hi v170, v180 offset:2768
	ds_write_b16 v170, v181 offset:2800
	ds_write_b16_d16_hi v170, v181 offset:2832
	v_mul_f32_e32 v182, 0xbfb8aa3b, v102
	v_mul_f32_e32 v183, 0xbfb8aa3b, v106
	v_mul_f32_e32 v184, 0xbfb8aa3b, v110
	v_mul_f32_e32 v185, 0xbfb8aa3b, v114
	v_exp_f32_e32 v182, v182
	v_exp_f32_e32 v183, v183
	v_exp_f32_e32 v184, v184
	v_exp_f32_e32 v185, v185
	v_add_f32_e32 v182, 1.0, v182
	v_add_f32_e32 v183, 1.0, v183
	v_add_f32_e32 v184, 1.0, v184
	v_add_f32_e32 v185, 1.0, v185
	v_rcp_f32_e32 v182, v182
	v_rcp_f32_e32 v183, v183
	v_rcp_f32_e32 v184, v184
	v_rcp_f32_e32 v185, v185
	v_mul_f32_e32 v182, v102, v182
	v_mul_f32_e32 v183, v106, v183
	v_mul_f32_e32 v184, v110, v184
	v_mul_f32_e32 v185, v114, v185
	v_cvt_pk_bf16_f32 v186, v182, v183
	v_cvt_pk_bf16_f32 v187, v184, v185
	ds_write_b16 v170, v186 offset:4608
	ds_write_b16_d16_hi v170, v186 offset:4640
	ds_write_b16 v170, v187 offset:4672
	ds_write_b16_d16_hi v170, v187 offset:4704
	v_mul_f32_e32 v188, 0xbfb8aa3b, v103
	v_mul_f32_e32 v189, 0xbfb8aa3b, v107
	v_mul_f32_e32 v190, 0xbfb8aa3b, v111
	v_mul_f32_e32 v191, 0xbfb8aa3b, v115
	v_exp_f32_e32 v188, v188
	v_exp_f32_e32 v189, v189
	v_exp_f32_e32 v190, v190
	v_exp_f32_e32 v191, v191
	v_add_f32_e32 v188, 1.0, v188
	v_add_f32_e32 v189, 1.0, v189
	v_add_f32_e32 v190, 1.0, v190
	v_add_f32_e32 v191, 1.0, v191
	v_rcp_f32_e32 v188, v188
; DI float silu(float v) { return v * __builtin_amdgcn_rcpf(1.f + __builtin_amdgcn_exp2f(-1.4426950408889634f * v)); }
; template <int EPI>
; DI void gemm_phase(const P& p, int l, const u16* __restrict__ A, const u16* __restrict__ Bt, int mpx, char* lds) {
;     ...
;           if (tr == 1) {
;             v0 = silu(v0); v1 = silu(v1); v2 = silu(v2); v3 = silu(v3);
;     ...
;           const unsigned u01 = pack2(v0, v1), u23 = pack2(v2, v3);
;           if (kind == 1) {
;             Tl[(0 * 16 + r) * 72 + rowl] = (u16)u01;
;             Tl[(1 * 16 + r) * 72 + rowl] = (u16)(u01 >> 16);
;             Tl[(2 * 16 + r) * 72 + rowl] = (u16)u23;
;             Tl[(3 * 16 + r) * 72 + rowl] = (u16)(u23 >> 16);
;           } else if (tr == 2) {
;             Tl[rowl * 72 + 0 * 16 + r] = f2h(v0);
;             Tl[rowl * 72 + 1 * 16 + r] = f2h(v1);
;             Tl[rowl * 72 + 2 * 16 + r] = f2h(v2);
;             Tl[rowl * 72 + 3 * 16 + r] = f2h(v3);
;           } else {
;             Tl[rowl * 72 + 0 * 16 + r] = (u16)u01;
;             Tl[rowl * 72 + 1 * 16 + r] = (u16)(u01 >> 16);
;             Tl[rowl * 72 + 2 * 16 + r] = (u16)u23;
;             Tl[rowl * 72 + 3 * 16 + r] = (u16)(u23 >> 16);
;           }
;         }
;       }
;       __builtin_amdgcn_fence(__ATOMIC_RELEASE, "wavefront");
;       u16* dh = (kind == 1) ? dst + hf * 64 : dst + (size_t)(hf * 64) * rstride;
; #pragma unroll
;       for (int i = 0; i < 8; ++i) {
;         const int c = lane + i * 64;
;         const int row = c >> 3, cc = c & 7;
;         uint4 v = *(const uint4*)&Tl[row * 72 + cc * 8];
;         *(uint4*)(dh + (size_t)row * rstride + cc * 8) = v;
;       }
	v_rcp_f32_e32 v189, v189
	v_rcp_f32_e32 v190, v190
	v_rcp_f32_e32 v191, v191
	v_mul_f32_e32 v188, v103, v188
	v_mul_f32_e32 v189, v107, v189
	v_mul_f32_e32 v190, v111, v190
	v_mul_f32_e32 v191, v115, v191
	v_cvt_pk_bf16_f32 v192, v188, v189
	v_cvt_pk_bf16_f32 v193, v190, v191
	ds_write_b16 v170, v192 offset:4752
	ds_write_b16_d16_hi v170, v192 offset:4784
	ds_write_b16 v170, v193 offset:4816
	ds_write_b16_d16_hi v170, v193 offset:4848
	v_mul_f32_e32 v174, 0xbfb8aa3b, v104
	v_mul_f32_e32 v175, 0xbfb8aa3b, v108
	v_mul_f32_e32 v176, 0xbfb8aa3b, v112
	v_mul_f32_e32 v177, 0xbfb8aa3b, v116
	v_exp_f32_e32 v174, v174
	v_exp_f32_e32 v175, v175
	v_exp_f32_e32 v176, v176
	v_exp_f32_e32 v177, v177
	v_add_f32_e32 v174, 1.0, v174
	v_add_f32_e32 v175, 1.0, v175
	v_add_f32_e32 v176, 1.0, v176
	v_add_f32_e32 v177, 1.0, v177
	v_rcp_f32_e32 v174, v174
	v_rcp_f32_e32 v175, v175
	v_rcp_f32_e32 v176, v176
	v_rcp_f32_e32 v177, v177
	v_mul_f32_e32 v174, v104, v174
	v_mul_f32_e32 v175, v108, v175
	v_mul_f32_e32 v176, v112, v176
	v_mul_f32_e32 v177, v116, v177
	v_cvt_pk_bf16_f32 v178, v174, v175
	v_cvt_pk_bf16_f32 v179, v176, v177
	ds_write_b16 v170, v178 offset:4896
	ds_write_b16_d16_hi v170, v178 offset:4928
	ds_write_b16 v170, v179 offset:4960
	ds_write_b16_d16_hi v170, v179 offset:4992
	v_mul_f32_e32 v180, 0xbfb8aa3b, v105
	v_mul_f32_e32 v181, 0xbfb8aa3b, v109
	v_mul_f32_e32 v182, 0xbfb8aa3b, v113
	v_mul_f32_e32 v183, 0xbfb8aa3b, v117
	v_exp_f32_e32 v180, v180
	v_exp_f32_e32 v181, v181
	v_exp_f32_e32 v182, v182
	v_exp_f32_e32 v183, v183
	v_add_f32_e32 v180, 1.0, v180
	v_add_f32_e32 v181, 1.0, v181
	v_add_f32_e32 v182, 1.0, v182
	v_add_f32_e32 v183, 1.0, v183
	v_rcp_f32_e32 v180, v180
	v_rcp_f32_e32 v181, v181
	v_rcp_f32_e32 v182, v182
	v_rcp_f32_e32 v183, v183
	v_mul_f32_e32 v180, v105, v180
	v_mul_f32_e32 v181, v109, v181
	v_mul_f32_e32 v182, v113, v182
	v_mul_f32_e32 v183, v117, v183
	v_cvt_pk_bf16_f32 v184, v180, v181
	v_cvt_pk_bf16_f32 v185, v182, v183
	ds_write_b16 v170, v184 offset:5040
	ds_write_b16_d16_hi v170, v184 offset:5072
	ds_write_b16 v170, v185 offset:5104
	ds_write_b16_d16_hi v170, v185 offset:5136
	v_mul_f32_e32 v186, 0xbfb8aa3b, v118
	v_mul_f32_e32 v187, 0xbfb8aa3b, v122
	v_mul_f32_e32 v188, 0xbfb8aa3b, v126
	v_mul_f32_e32 v189, 0xbfb8aa3b, v2
	v_exp_f32_e32 v186, v186
	v_exp_f32_e32 v187, v187
	v_exp_f32_e32 v188, v188
	v_exp_f32_e32 v189, v189
	v_add_f32_e32 v186, 1.0, v186
	v_add_f32_e32 v187, 1.0, v187
	v_add_f32_e32 v188, 1.0, v188
	v_add_f32_e32 v189, 1.0, v189
	v_rcp_f32_e32 v186, v186
	v_rcp_f32_e32 v187, v187
	v_rcp_f32_e32 v188, v188
	v_rcp_f32_e32 v189, v189
	v_mul_f32_e32 v186, v118, v186
	v_mul_f32_e32 v187, v122, v187
	v_mul_f32_e32 v188, v126, v188
	v_mul_f32_e32 v189, v2, v189
	v_cvt_pk_bf16_f32 v190, v186, v187
	v_cvt_pk_bf16_f32 v191, v188, v189
	ds_write_b16 v170, v190 offset:6912
	ds_write_b16_d16_hi v170, v190 offset:6944
	ds_write_b16 v170, v191 offset:6976
	ds_write_b16_d16_hi v170, v191 offset:7008
	v_mul_f32_e32 v192, 0xbfb8aa3b, v119
	v_mul_f32_e32 v193, 0xbfb8aa3b, v123
	v_mul_f32_e32 v174, 0xbfb8aa3b, v127
	v_mul_f32_e32 v175, 0xbfb8aa3b, v3
	v_exp_f32_e32 v192, v192
	v_exp_f32_e32 v193, v193
	v_exp_f32_e32 v174, v174
	v_exp_f32_e32 v175, v175
	v_add_f32_e32 v192, 1.0, v192
	v_add_f32_e32 v193, 1.0, v193
	v_add_f32_e32 v174, 1.0, v174
	v_add_f32_e32 v175, 1.0, v175
	v_rcp_f32_e32 v192, v192
	v_rcp_f32_e32 v193, v193
	v_rcp_f32_e32 v174, v174
	v_rcp_f32_e32 v175, v175
	v_mul_f32_e32 v192, v119, v192
	v_mul_f32_e32 v193, v123, v193
	v_mul_f32_e32 v174, v127, v174
	v_mul_f32_e32 v175, v3, v175
	v_cvt_pk_bf16_f32 v176, v192, v193
	v_cvt_pk_bf16_f32 v177, v174, v175
	ds_write_b16 v170, v176 offset:7056
	ds_write_b16_d16_hi v170, v176 offset:7088
	ds_write_b16 v170, v177 offset:7120
	ds_write_b16_d16_hi v170, v177 offset:7152
	v_mul_f32_e32 v178, 0xbfb8aa3b, v120
	v_mul_f32_e32 v179, 0xbfb8aa3b, v124
	v_mul_f32_e32 v180, 0xbfb8aa3b, v128
	v_mul_f32_e32 v181, 0xbfb8aa3b, v4
	v_exp_f32_e32 v178, v178
	v_exp_f32_e32 v179, v179
	v_exp_f32_e32 v180, v180
	v_exp_f32_e32 v181, v181
	v_add_f32_e32 v178, 1.0, v178
	v_add_f32_e32 v179, 1.0, v179
	v_add_f32_e32 v180, 1.0, v180
	v_add_f32_e32 v181, 1.0, v181
	v_rcp_f32_e32 v178, v178
	v_rcp_f32_e32 v179, v179
	v_rcp_f32_e32 v180, v180
	v_rcp_f32_e32 v181, v181
	v_mul_f32_e32 v178, v120, v178
	v_mul_f32_e32 v179, v124, v179
	v_mul_f32_e32 v180, v128, v180
	v_mul_f32_e32 v181, v4, v181
	v_cvt_pk_bf16_f32 v182, v178, v179
	v_cvt_pk_bf16_f32 v183, v180, v181
	ds_write_b16 v170, v182 offset:7200
	ds_write_b16_d16_hi v170, v182 offset:7232
	ds_write_b16 v170, v183 offset:7264
	ds_write_b16_d16_hi v170, v183 offset:7296
	v_mul_f32_e32 v184, 0xbfb8aa3b, v121
	v_mul_f32_e32 v185, 0xbfb8aa3b, v125
	v_mul_f32_e32 v186, 0xbfb8aa3b, v129
	v_mul_f32_e32 v187, 0xbfb8aa3b, v5
	v_exp_f32_e32 v184, v184
	v_exp_f32_e32 v185, v185
	v_exp_f32_e32 v186, v186
	v_exp_f32_e32 v187, v187
	v_add_f32_e32 v184, 1.0, v184
	v_add_f32_e32 v185, 1.0, v185
	v_add_f32_e32 v186, 1.0, v186
	v_add_f32_e32 v187, 1.0, v187
	v_rcp_f32_e32 v184, v184
	v_rcp_f32_e32 v185, v185
	v_rcp_f32_e32 v186, v186
	v_rcp_f32_e32 v187, v187
	v_mul_f32_e32 v184, v121, v184
	v_mul_f32_e32 v185, v125, v185
	v_mul_f32_e32 v186, v129, v186
	v_mul_f32_e32 v187, v5, v187
	v_cvt_pk_bf16_f32 v188, v184, v185
	v_cvt_pk_bf16_f32 v189, v186, v187
	ds_write_b16 v170, v188 offset:7344
	ds_write_b16_d16_hi v170, v188 offset:7376
	ds_write_b16 v170, v189 offset:7408
	ds_write_b16_d16_hi v170, v189 offset:7440
	ds_read_b128 v[130:133], v171 offset:0
	ds_read_b128 v[134:137], v171 offset:1152
	ds_read_b128 v[138:141], v171 offset:2304
	ds_read_b128 v[142:145], v171 offset:3456
	ds_read_b128 v[146:149], v171 offset:4608
	ds_read_b128 v[150:153], v171 offset:5760
	ds_read_b128 v[154:157], v171 offset:6912
	ds_read_b128 v[158:161], v171 offset:8064
	s_waitcnt lgkmcnt(7)
	global_store_dwordx4 v172, v[130:133], s[44:45] offset:0 sc1 nt
	s_waitcnt lgkmcnt(6)
	global_store_dwordx4 v172, v[134:137], s[44:45] offset:1024 sc1 nt
	s_waitcnt lgkmcnt(5)
	global_store_dwordx4 v172, v[138:141], s[44:45] offset:2048 sc1 nt
	s_waitcnt lgkmcnt(4)
	global_store_dwordx4 v172, v[142:145], s[44:45] offset:3072 sc1 nt
	s_waitcnt lgkmcnt(3)
	global_store_dwordx4 v172, v[146:149], s[62:63] offset:0 sc1 nt
	s_waitcnt lgkmcnt(2)
	global_store_dwordx4 v172, v[150:153], s[62:63] offset:1024 sc1 nt
	s_waitcnt lgkmcnt(1)
	global_store_dwordx4 v172, v[154:157], s[62:63] offset:2048 sc1 nt
	s_waitcnt lgkmcnt(0)
	global_store_dwordx4 v172, v[158:161], s[62:63] offset:3072 sc1 nt
	s_branch .Lfe_done
; template <int EPI>
; DI void gemm_phase(const P& p, int l, const u16* __restrict__ A, const u16* __restrict__ Bt, int mpx, char* lds) {
;     ...
;           const unsigned u01 = pack2(v0, v1), u23 = pack2(v2, v3);
;           if (kind == 1) {
;             Tl[(0 * 16 + r) * 72 + rowl] = (u16)u01;
;             Tl[(1 * 16 + r) * 72 + rowl] = (u16)(u01 >> 16);
;             Tl[(2 * 16 + r) * 72 + rowl] = (u16)u23;
;             Tl[(3 * 16 + r) * 72 + rowl] = (u16)(u23 >> 16);
;           } else if (tr == 2) {
;             Tl[rowl * 72 + 0 * 16 + r] = f2h(v0);
;             Tl[rowl * 72 + 1 * 16 + r] = f2h(v1);
;             Tl[rowl * 72 + 2 * 16 + r] = f2h(v2);
;             Tl[rowl * 72 + 3 * 16 + r] = f2h(v3);
;           } else {
;             Tl[rowl * 72 + 0 * 16 + r] = (u16)u01;
;             Tl[rowl * 72 + 1 * 16 + r] = (u16)(u01 >> 16);
;             Tl[rowl * 72 + 2 * 16 + r] = (u16)u23;
;             Tl[rowl * 72 + 3 * 16 + r] = (u16)(u23 >> 16);
;           }
;         }
;       }
;       __builtin_amdgcn_fence(__ATOMIC_RELEASE, "wavefront");
;       u16* dh = (kind == 1) ? dst + hf * 64 : dst + (size_t)(hf * 64) * rstride;
; #pragma unroll
;       for (int i = 0; i < 8; ++i) {
;         const int c = lane + i * 64;
;         const int row = c >> 3, cc = c & 7;
;         uint4 v = *(const uint4*)&Tl[row * 72 + cc * 8];
;         *(uint4*)(dh + (size_t)row * rstride + cc * 8) = v;
;       }
.Lfe_k0_plain:
	s_add_u32 s62, s44, 0x1000
	s_addc_u32 s63, s45, 0
	v_cvt_pk_bf16_f32 v178, v6, v10
	v_cvt_pk_bf16_f32 v179, v14, v18
	ds_write_b16 v170, v178 offset:0
	ds_write_b16_d16_hi v170, v178 offset:32
	ds_write_b16 v170, v179 offset:64
	ds_write_b16_d16_hi v170, v179 offset:96
	v_cvt_pk_bf16_f32 v184, v7, v11
	v_cvt_pk_bf16_f32 v185, v15, v19
	ds_write_b16 v170, v184 offset:144
	ds_write_b16_d16_hi v170, v184 offset:176
	ds_write_b16 v170, v185 offset:208
	ds_write_b16_d16_hi v170, v185 offset:240
	v_cvt_pk_bf16_f32 v190, v8, v12
	v_cvt_pk_bf16_f32 v191, v16, v20
	ds_write_b16 v170, v190 offset:288
	ds_write_b16_d16_hi v170, v190 offset:320
	ds_write_b16 v170, v191 offset:352
	ds_write_b16_d16_hi v170, v191 offset:384
	v_cvt_pk_bf16_f32 v176, v9, v13
	v_cvt_pk_bf16_f32 v177, v17, v21
	ds_write_b16 v170, v176 offset:432
	ds_write_b16_d16_hi v170, v176 offset:464
	ds_write_b16 v170, v177 offset:496
	ds_write_b16_d16_hi v170, v177 offset:528
	v_cvt_pk_bf16_f32 v182, v22, v26
	v_cvt_pk_bf16_f32 v183, v30, v34
	ds_write_b16 v170, v182 offset:2304
	ds_write_b16_d16_hi v170, v182 offset:2336
	ds_write_b16 v170, v183 offset:2368
	ds_write_b16_d16_hi v170, v183 offset:2400
	v_cvt_pk_bf16_f32 v188, v23, v27
	v_cvt_pk_bf16_f32 v189, v31, v35
	ds_write_b16 v170, v188 offset:2448
	ds_write_b16_d16_hi v170, v188 offset:2480
	ds_write_b16 v170, v189 offset:2512
	ds_write_b16_d16_hi v170, v189 offset:2544
	v_cvt_pk_bf16_f32 v174, v24, v28
	v_cvt_pk_bf16_f32 v175, v32, v36
	ds_write_b16 v170, v174 offset:2592
	ds_write_b16_d16_hi v170, v174 offset:2624
	ds_write_b16 v170, v175 offset:2656
	ds_write_b16_d16_hi v170, v175 offset:2688
	v_cvt_pk_bf16_f32 v180, v25, v29
	v_cvt_pk_bf16_f32 v181, v33, v37
	ds_write_b16 v170, v180 offset:2736
	ds_write_b16_d16_hi v170, v180 offset:2768
	ds_write_b16 v170, v181 offset:2800
	ds_write_b16_d16_hi v170, v181 offset:2832
	v_cvt_pk_bf16_f32 v186, v38, v42
	v_cvt_pk_bf16_f32 v187, v46, v50
	ds_write_b16 v170, v186 offset:4608
	ds_write_b16_d16_hi v170, v186 offset:4640
	ds_write_b16 v170, v187 offset:4672
	ds_write_b16_d16_hi v170, v187 offset:4704
	v_cvt_pk_bf16_f32 v192, v39, v43
	v_cvt_pk_bf16_f32 v193, v47, v51
	ds_write_b16 v170, v192 offset:4752
	ds_write_b16_d16_hi v170, v192 offset:4784
	ds_write_b16 v170, v193 offset:4816
	ds_write_b16_d16_hi v170, v193 offset:4848
	v_cvt_pk_bf16_f32 v178, v40, v44
	v_cvt_pk_bf16_f32 v179, v48, v52
	ds_write_b16 v170, v178 offset:4896
	ds_write_b16_d16_hi v170, v178 offset:4928
	ds_write_b16 v170, v179 offset:4960
	ds_write_b16_d16_hi v170, v179 offset:4992
	v_cvt_pk_bf16_f32 v184, v41, v45
	v_cvt_pk_bf16_f32 v185, v49, v53
	ds_write_b16 v170, v184 offset:5040
	ds_write_b16_d16_hi v170, v184 offset:5072
	ds_write_b16 v170, v185 offset:5104
	ds_write_b16_d16_hi v170, v185 offset:5136
	v_cvt_pk_bf16_f32 v190, v54, v58
	v_cvt_pk_bf16_f32 v191, v62, v66
	ds_write_b16 v170, v190 offset:6912
	ds_write_b16_d16_hi v170, v190 offset:6944
	ds_write_b16 v170, v191 offset:6976
	ds_write_b16_d16_hi v170, v191 offset:7008
	v_cvt_pk_bf16_f32 v176, v55, v59
	v_cvt_pk_bf16_f32 v177, v63, v67
	ds_write_b16 v170, v176 offset:7056
	ds_write_b16_d16_hi v170, v176 offset:7088
	ds_write_b16 v170, v177 offset:7120
	ds_write_b16_d16_hi v170, v177 offset:7152
	v_cvt_pk_bf16_f32 v182, v56, v60
	v_cvt_pk_bf16_f32 v183, v64, v68
	ds_write_b16 v170, v182 offset:7200
	ds_write_b16_d16_hi v170, v182 offset:7232
	ds_write_b16 v170, v183 offset:7264
	ds_write_b16_d16_hi v170, v183 offset:7296
	v_cvt_pk_bf16_f32 v188, v57, v61
	v_cvt_pk_bf16_f32 v189, v65, v69
	ds_write_b16 v170, v188 offset:7344
	ds_write_b16_d16_hi v170, v188 offset:7376
	ds_write_b16 v170, v189 offset:7408
	ds_write_b16_d16_hi v170, v189 offset:7440
	ds_read_b128 v[130:133], v171 offset:0
	ds_read_b128 v[134:137], v171 offset:1152
	ds_read_b128 v[138:141], v171 offset:2304
	ds_read_b128 v[142:145], v171 offset:3456
	ds_read_b128 v[146:149], v171 offset:4608
	ds_read_b128 v[150:153], v171 offset:5760
	ds_read_b128 v[154:157], v171 offset:6912
	ds_read_b128 v[158:161], v171 offset:8064
	s_waitcnt lgkmcnt(7)
	global_store_dwordx4 v172, v[130:133], s[44:45] offset:0 sc1 nt
	s_waitcnt lgkmcnt(6)
	global_store_dwordx4 v172, v[134:137], s[44:45] offset:1024 sc1 nt
	s_waitcnt lgkmcnt(5)
	global_store_dwordx4 v172, v[138:141], s[44:45] offset:2048 sc1 nt
	s_waitcnt lgkmcnt(4)
	global_store_dwordx4 v172, v[142:145], s[44:45] offset:3072 sc1 nt
	s_waitcnt lgkmcnt(3)
	global_store_dwordx4 v172, v[146:149], s[62:63] offset:0 sc1 nt
	s_waitcnt lgkmcnt(2)
	global_store_dwordx4 v172, v[150:153], s[62:63] offset:1024 sc1 nt
	s_waitcnt lgkmcnt(1)
	global_store_dwordx4 v172, v[154:157], s[62:63] offset:2048 sc1 nt
	s_waitcnt lgkmcnt(0)
; template <int EPI>
; DI void gemm_phase(const P& p, int l, const u16* __restrict__ A, const u16* __restrict__ Bt, int mpx, char* lds) {
;     ...
;           const unsigned u01 = pack2(v0, v1), u23 = pack2(v2, v3);
;           if (kind == 1) {
;             Tl[(0 * 16 + r) * 72 + rowl] = (u16)u01;
;             Tl[(1 * 16 + r) * 72 + rowl] = (u16)(u01 >> 16);
;             Tl[(2 * 16 + r) * 72 + rowl] = (u16)u23;
;             Tl[(3 * 16 + r) * 72 + rowl] = (u16)(u23 >> 16);
;           } else if (tr == 2) {
;             Tl[rowl * 72 + 0 * 16 + r] = f2h(v0);
;             Tl[rowl * 72 + 1 * 16 + r] = f2h(v1);
;             Tl[rowl * 72 + 2 * 16 + r] = f2h(v2);
;             Tl[rowl * 72 + 3 * 16 + r] = f2h(v3);
;           } else {
;             Tl[rowl * 72 + 0 * 16 + r] = (u16)u01;
;             Tl[rowl * 72 + 1 * 16 + r] = (u16)(u01 >> 16);
;             Tl[rowl * 72 + 2 * 16 + r] = (u16)u23;
;             Tl[rowl * 72 + 3 * 16 + r] = (u16)(u23 >> 16);
;           }
;         }
;       }
;       __builtin_amdgcn_fence(__ATOMIC_RELEASE, "wavefront");
;       u16* dh = (kind == 1) ? dst + hf * 64 : dst + (size_t)(hf * 64) * rstride;
; #pragma unroll
;       for (int i = 0; i < 8; ++i) {
;         const int c = lane + i * 64;
;         const int row = c >> 3, cc = c & 7;
;         uint4 v = *(const uint4*)&Tl[row * 72 + cc * 8];
;         *(uint4*)(dh + (size_t)row * rstride + cc * 8) = v;
;       }
	global_store_dwordx4 v172, v[158:161], s[62:63] offset:3072 sc1 nt
	s_add_u32 s44, s44, 0x2000
	s_addc_u32 s45, s45, 0
	s_add_u32 s62, s62, 0x2000
	s_addc_u32 s63, s63, 0
	v_cvt_pk_bf16_f32 v178, v70, v74
	v_cvt_pk_bf16_f32 v179, v78, v82
	ds_write_b16 v170, v178 offset:0
	ds_write_b16_d16_hi v170, v178 offset:32
	ds_write_b16 v170, v179 offset:64
	ds_write_b16_d16_hi v170, v179 offset:96
	v_cvt_pk_bf16_f32 v184, v71, v75
	v_cvt_pk_bf16_f32 v185, v79, v83
	ds_write_b16 v170, v184 offset:144
	ds_write_b16_d16_hi v170, v184 offset:176
	ds_write_b16 v170, v185 offset:208
	ds_write_b16_d16_hi v170, v185 offset:240
	v_cvt_pk_bf16_f32 v190, v72, v76
	v_cvt_pk_bf16_f32 v191, v80, v84
	ds_write_b16 v170, v190 offset:288
	ds_write_b16_d16_hi v170, v190 offset:320
	ds_write_b16 v170, v191 offset:352
	ds_write_b16_d16_hi v170, v191 offset:384
	v_cvt_pk_bf16_f32 v176, v73, v77
	v_cvt_pk_bf16_f32 v177, v81, v85
	ds_write_b16 v170, v176 offset:432
	ds_write_b16_d16_hi v170, v176 offset:464
	ds_write_b16 v170, v177 offset:496
	ds_write_b16_d16_hi v170, v177 offset:528
	v_cvt_pk_bf16_f32 v182, v86, v90
	v_cvt_pk_bf16_f32 v183, v94, v98
	ds_write_b16 v170, v182 offset:2304
	ds_write_b16_d16_hi v170, v182 offset:2336
	ds_write_b16 v170, v183 offset:2368
	ds_write_b16_d16_hi v170, v183 offset:2400
	v_cvt_pk_bf16_f32 v188, v87, v91
	v_cvt_pk_bf16_f32 v189, v95, v99
	ds_write_b16 v170, v188 offset:2448
	ds_write_b16_d16_hi v170, v188 offset:2480
	ds_write_b16 v170, v189 offset:2512
	ds_write_b16_d16_hi v170, v189 offset:2544
	v_cvt_pk_bf16_f32 v174, v88, v92
	v_cvt_pk_bf16_f32 v175, v96, v100
	ds_write_b16 v170, v174 offset:2592
	ds_write_b16_d16_hi v170, v174 offset:2624
	ds_write_b16 v170, v175 offset:2656
	ds_write_b16_d16_hi v170, v175 offset:2688
	v_cvt_pk_bf16_f32 v180, v89, v93
	v_cvt_pk_bf16_f32 v181, v97, v101
	ds_write_b16 v170, v180 offset:2736
	ds_write_b16_d16_hi v170, v180 offset:2768
	ds_write_b16 v170, v181 offset:2800
	ds_write_b16_d16_hi v170, v181 offset:2832
	v_cvt_pk_bf16_f32 v186, v102, v106
	v_cvt_pk_bf16_f32 v187, v110, v114
	ds_write_b16 v170, v186 offset:4608
	ds_write_b16_d16_hi v170, v186 offset:4640
	ds_write_b16 v170, v187 offset:4672
	ds_write_b16_d16_hi v170, v187 offset:4704
	v_cvt_pk_bf16_f32 v192, v103, v107
	v_cvt_pk_bf16_f32 v193, v111, v115
	ds_write_b16 v170, v192 offset:4752
	ds_write_b16_d16_hi v170, v192 offset:4784
	ds_write_b16 v170, v193 offset:4816
	ds_write_b16_d16_hi v170, v193 offset:4848
	v_cvt_pk_bf16_f32 v178, v104, v108
	v_cvt_pk_bf16_f32 v179, v112, v116
	ds_write_b16 v170, v178 offset:4896
	ds_write_b16_d16_hi v170, v178 offset:4928
	ds_write_b16 v170, v179 offset:4960
	ds_write_b16_d16_hi v170, v179 offset:4992
	v_cvt_pk_bf16_f32 v184, v105, v109
	v_cvt_pk_bf16_f32 v185, v113, v117
	ds_write_b16 v170, v184 offset:5040
	ds_write_b16_d16_hi v170, v184 offset:5072
	ds_write_b16 v170, v185 offset:5104
	ds_write_b16_d16_hi v170, v185 offset:5136
	v_cvt_pk_bf16_f32 v190, v118, v122
	v_cvt_pk_bf16_f32 v191, v126, v2
	ds_write_b16 v170, v190 offset:6912
	ds_write_b16_d16_hi v170, v190 offset:6944
	ds_write_b16 v170, v191 offset:6976
	ds_write_b16_d16_hi v170, v191 offset:7008
	v_cvt_pk_bf16_f32 v176, v119, v123
	v_cvt_pk_bf16_f32 v177, v127, v3
	ds_write_b16 v170, v176 offset:7056
	ds_write_b16_d16_hi v170, v176 offset:7088
	ds_write_b16 v170, v177 offset:7120
	ds_write_b16_d16_hi v170, v177 offset:7152
	v_cvt_pk_bf16_f32 v182, v120, v124
	v_cvt_pk_bf16_f32 v183, v128, v4
	ds_write_b16 v170, v182 offset:7200
	ds_write_b16_d16_hi v170, v182 offset:7232
	ds_write_b16 v170, v183 offset:7264
	ds_write_b16_d16_hi v170, v183 offset:7296
	v_cvt_pk_bf16_f32 v188, v121, v125
	v_cvt_pk_bf16_f32 v189, v129, v5
	ds_write_b16 v170, v188 offset:7344
	ds_write_b16_d16_hi v170, v188 offset:7376
	ds_write_b16 v170, v189 offset:7408
	ds_write_b16_d16_hi v170, v189 offset:7440
	ds_read_b128 v[130:133], v171 offset:0
	ds_read_b128 v[134:137], v171 offset:1152
	ds_read_b128 v[138:141], v171 offset:2304
	ds_read_b128 v[142:145], v171 offset:3456
	ds_read_b128 v[146:149], v171 offset:4608
	ds_read_b128 v[150:153], v171 offset:5760
	ds_read_b128 v[154:157], v171 offset:6912
	ds_read_b128 v[158:161], v171 offset:8064
	s_waitcnt lgkmcnt(7)
	global_store_dwordx4 v172, v[130:133], s[44:45] offset:0 sc1 nt
	s_waitcnt lgkmcnt(6)
	global_store_dwordx4 v172, v[134:137], s[44:45] offset:1024 sc1 nt
	s_waitcnt lgkmcnt(5)
	global_store_dwordx4 v172, v[138:141], s[44:45] offset:2048 sc1 nt
	s_waitcnt lgkmcnt(4)
	global_store_dwordx4 v172, v[142:145], s[44:45] offset:3072 sc1 nt
	s_waitcnt lgkmcnt(3)
	global_store_dwordx4 v172, v[146:149], s[62:63] offset:0 sc1 nt
	s_waitcnt lgkmcnt(2)
	global_store_dwordx4 v172, v[150:153], s[62:63] offset:1024 sc1 nt
	s_waitcnt lgkmcnt(1)
	global_store_dwordx4 v172, v[154:157], s[62:63] offset:2048 sc1 nt
	s_waitcnt lgkmcnt(0)
	global_store_dwordx4 v172, v[158:161], s[62:63] offset:3072 sc1 nt
	s_branch .Lfe_done
; template <int EPI>
; DI void gemm_phase(const P& p, int l, const u16* __restrict__ A, const u16* __restrict__ Bt, int mpx, char* lds) {
;     ...
;           } else if (tr == 2) {
;             Tl[rowl * 72 + 0 * 16 + r] = f2h(v0);
;             Tl[rowl * 72 + 1 * 16 + r] = f2h(v1);
;             Tl[rowl * 72 + 2 * 16 + r] = f2h(v2);
;             Tl[rowl * 72 + 3 * 16 + r] = f2h(v3);
;           } else {
;             Tl[rowl * 72 + 0 * 16 + r] = (u16)u01;
;             Tl[rowl * 72 + 1 * 16 + r] = (u16)(u01 >> 16);
;             Tl[rowl * 72 + 2 * 16 + r] = (u16)u23;
;             Tl[rowl * 72 + 3 * 16 + r] = (u16)(u23 >> 16);
;           }
;         }
;       }
;       __builtin_amdgcn_fence(__ATOMIC_RELEASE, "wavefront");
;       u16* dh = (kind == 1) ? dst + hf * 64 : dst + (size_t)(hf * 64) * rstride;
; #pragma unroll
;       for (int i = 0; i < 8; ++i) {
;         const int c = lane + i * 64;
;         const int row = c >> 3, cc = c & 7;
;         uint4 v = *(const uint4*)&Tl[row * 72 + cc * 8];
;         *(uint4*)(dh + (size_t)row * rstride + cc * 8) = v;
;       }
.Lfe_k0_fp16:
	s_add_u32 s62, s44, 0x1000
	s_addc_u32 s63, s45, 0
	v_cvt_f16_f32_e32 v174, v6
	v_cvt_f16_f32_e32 v175, v10
	v_cvt_f16_f32_e32 v176, v14
	v_cvt_f16_f32_e32 v177, v18
	ds_write_b16 v170, v174 offset:0
	ds_write_b16 v170, v175 offset:32
	ds_write_b16 v170, v176 offset:64
	ds_write_b16 v170, v177 offset:96
	v_cvt_f16_f32_e32 v180, v7
	v_cvt_f16_f32_e32 v181, v11
	v_cvt_f16_f32_e32 v182, v15
	v_cvt_f16_f32_e32 v183, v19
	ds_write_b16 v170, v180 offset:144
	ds_write_b16 v170, v181 offset:176
	ds_write_b16 v170, v182 offset:208
	ds_write_b16 v170, v183 offset:240
	v_cvt_f16_f32_e32 v186, v8
	v_cvt_f16_f32_e32 v187, v12
	v_cvt_f16_f32_e32 v188, v16
	v_cvt_f16_f32_e32 v189, v20
	ds_write_b16 v170, v186 offset:288
	ds_write_b16 v170, v187 offset:320
	ds_write_b16 v170, v188 offset:352
	ds_write_b16 v170, v189 offset:384
	v_cvt_f16_f32_e32 v192, v9
	v_cvt_f16_f32_e32 v193, v13
	v_cvt_f16_f32_e32 v174, v17
	v_cvt_f16_f32_e32 v175, v21
	ds_write_b16 v170, v192 offset:432
	ds_write_b16 v170, v193 offset:464
	ds_write_b16 v170, v174 offset:496
	ds_write_b16 v170, v175 offset:528
	v_cvt_f16_f32_e32 v178, v22
	v_cvt_f16_f32_e32 v179, v26
	v_cvt_f16_f32_e32 v180, v30
	v_cvt_f16_f32_e32 v181, v34
	ds_write_b16 v170, v178 offset:2304
	ds_write_b16 v170, v179 offset:2336
	ds_write_b16 v170, v180 offset:2368
	ds_write_b16 v170, v181 offset:2400
	v_cvt_f16_f32_e32 v184, v23
	v_cvt_f16_f32_e32 v185, v27
	v_cvt_f16_f32_e32 v186, v31
	v_cvt_f16_f32_e32 v187, v35
	ds_write_b16 v170, v184 offset:2448
	ds_write_b16 v170, v185 offset:2480
	ds_write_b16 v170, v186 offset:2512
	ds_write_b16 v170, v187 offset:2544
	v_cvt_f16_f32_e32 v190, v24
	v_cvt_f16_f32_e32 v191, v28
	v_cvt_f16_f32_e32 v192, v32
	v_cvt_f16_f32_e32 v193, v36
	ds_write_b16 v170, v190 offset:2592
	ds_write_b16 v170, v191 offset:2624
	ds_write_b16 v170, v192 offset:2656
	ds_write_b16 v170, v193 offset:2688
	v_cvt_f16_f32_e32 v176, v25
	v_cvt_f16_f32_e32 v177, v29
	v_cvt_f16_f32_e32 v178, v33
	v_cvt_f16_f32_e32 v179, v37
	ds_write_b16 v170, v176 offset:2736
	ds_write_b16 v170, v177 offset:2768
	ds_write_b16 v170, v178 offset:2800
	ds_write_b16 v170, v179 offset:2832
	v_cvt_f16_f32_e32 v182, v38
	v_cvt_f16_f32_e32 v183, v42
	v_cvt_f16_f32_e32 v184, v46
	v_cvt_f16_f32_e32 v185, v50
	ds_write_b16 v170, v182 offset:4608
	ds_write_b16 v170, v183 offset:4640
	ds_write_b16 v170, v184 offset:4672
	ds_write_b16 v170, v185 offset:4704
	v_cvt_f16_f32_e32 v188, v39
	v_cvt_f16_f32_e32 v189, v43
	v_cvt_f16_f32_e32 v190, v47
	v_cvt_f16_f32_e32 v191, v51
	ds_write_b16 v170, v188 offset:4752
	ds_write_b16 v170, v189 offset:4784
	ds_write_b16 v170, v190 offset:4816
	ds_write_b16 v170, v191 offset:4848
	v_cvt_f16_f32_e32 v174, v40
	v_cvt_f16_f32_e32 v175, v44
	v_cvt_f16_f32_e32 v176, v48
	v_cvt_f16_f32_e32 v177, v52
	ds_write_b16 v170, v174 offset:4896
	ds_write_b16 v170, v175 offset:4928
	ds_write_b16 v170, v176 offset:4960
	ds_write_b16 v170, v177 offset:4992
	v_cvt_f16_f32_e32 v180, v41
	v_cvt_f16_f32_e32 v181, v45
	v_cvt_f16_f32_e32 v182, v49
	v_cvt_f16_f32_e32 v183, v53
	ds_write_b16 v170, v180 offset:5040
	ds_write_b16 v170, v181 offset:5072
	ds_write_b16 v170, v182 offset:5104
	ds_write_b16 v170, v183 offset:5136
	v_cvt_f16_f32_e32 v186, v54
	v_cvt_f16_f32_e32 v187, v58
	v_cvt_f16_f32_e32 v188, v62
	v_cvt_f16_f32_e32 v189, v66
	ds_write_b16 v170, v186 offset:6912
	ds_write_b16 v170, v187 offset:6944
	ds_write_b16 v170, v188 offset:6976
	ds_write_b16 v170, v189 offset:7008
	v_cvt_f16_f32_e32 v192, v55
	v_cvt_f16_f32_e32 v193, v59
	v_cvt_f16_f32_e32 v174, v63
	v_cvt_f16_f32_e32 v175, v67
	ds_write_b16 v170, v192 offset:7056
	ds_write_b16 v170, v193 offset:7088
	ds_write_b16 v170, v174 offset:7120
	ds_write_b16 v170, v175 offset:7152
	v_cvt_f16_f32_e32 v178, v56
	v_cvt_f16_f32_e32 v179, v60
	v_cvt_f16_f32_e32 v180, v64
	v_cvt_f16_f32_e32 v181, v68
	ds_write_b16 v170, v178 offset:7200
	ds_write_b16 v170, v179 offset:7232
	ds_write_b16 v170, v180 offset:7264
	ds_write_b16 v170, v181 offset:7296
	v_cvt_f16_f32_e32 v184, v57
	v_cvt_f16_f32_e32 v185, v61
	v_cvt_f16_f32_e32 v186, v65
	v_cvt_f16_f32_e32 v187, v69
	ds_write_b16 v170, v184 offset:7344
	ds_write_b16 v170, v185 offset:7376
	ds_write_b16 v170, v186 offset:7408
	ds_write_b16 v170, v187 offset:7440
	ds_read_b128 v[130:133], v171 offset:0
	ds_read_b128 v[134:137], v171 offset:1152
	ds_read_b128 v[138:141], v171 offset:2304
	ds_read_b128 v[142:145], v171 offset:3456
	ds_read_b128 v[146:149], v171 offset:4608
	ds_read_b128 v[150:153], v171 offset:5760
	ds_read_b128 v[154:157], v171 offset:6912
	ds_read_b128 v[158:161], v171 offset:8064
	s_waitcnt lgkmcnt(7)
	global_store_dwordx4 v172, v[130:133], s[44:45] offset:0 sc1 nt
	s_waitcnt lgkmcnt(6)
	global_store_dwordx4 v172, v[134:137], s[44:45] offset:1024 sc1 nt
	s_waitcnt lgkmcnt(5)
	global_store_dwordx4 v172, v[138:141], s[44:45] offset:2048 sc1 nt
	s_waitcnt lgkmcnt(4)
	global_store_dwordx4 v172, v[142:145], s[44:45] offset:3072 sc1 nt
	s_waitcnt lgkmcnt(3)
	global_store_dwordx4 v172, v[146:149], s[62:63] offset:0 sc1 nt
	s_waitcnt lgkmcnt(2)
	global_store_dwordx4 v172, v[150:153], s[62:63] offset:1024 sc1 nt
	s_waitcnt lgkmcnt(1)
	global_store_dwordx4 v172, v[154:157], s[62:63] offset:2048 sc1 nt
	s_waitcnt lgkmcnt(0)
; template <int EPI>
; DI void gemm_phase(const P& p, int l, const u16* __restrict__ A, const u16* __restrict__ Bt, int mpx, char* lds) {
;     ...
;           } else if (tr == 2) {
;             Tl[rowl * 72 + 0 * 16 + r] = f2h(v0);
;             Tl[rowl * 72 + 1 * 16 + r] = f2h(v1);
;             Tl[rowl * 72 + 2 * 16 + r] = f2h(v2);
;             Tl[rowl * 72 + 3 * 16 + r] = f2h(v3);
;           } else {
;             Tl[rowl * 72 + 0 * 16 + r] = (u16)u01;
;             Tl[rowl * 72 + 1 * 16 + r] = (u16)(u01 >> 16);
;             Tl[rowl * 72 + 2 * 16 + r] = (u16)u23;
;             Tl[rowl * 72 + 3 * 16 + r] = (u16)(u23 >> 16);
;           }
;         }
;       }
;       __builtin_amdgcn_fence(__ATOMIC_RELEASE, "wavefront");
;       u16* dh = (kind == 1) ? dst + hf * 64 : dst + (size_t)(hf * 64) * rstride;
; #pragma unroll
;       for (int i = 0; i < 8; ++i) {
;         const int c = lane + i * 64;
;         const int row = c >> 3, cc = c & 7;
;         uint4 v = *(const uint4*)&Tl[row * 72 + cc * 8];
;         *(uint4*)(dh + (size_t)row * rstride + cc * 8) = v;
;       }
	global_store_dwordx4 v172, v[158:161], s[62:63] offset:3072 sc1 nt
	s_add_u32 s44, s44, 0x2000
	s_addc_u32 s45, s45, 0
	s_add_u32 s62, s62, 0x2000
	s_addc_u32 s63, s63, 0
	v_cvt_f16_f32_e32 v174, v70
	v_cvt_f16_f32_e32 v175, v74
	v_cvt_f16_f32_e32 v176, v78
	v_cvt_f16_f32_e32 v177, v82
	ds_write_b16 v170, v174 offset:0
	ds_write_b16 v170, v175 offset:32
	ds_write_b16 v170, v176 offset:64
	ds_write_b16 v170, v177 offset:96
	v_cvt_f16_f32_e32 v180, v71
	v_cvt_f16_f32_e32 v181, v75
	v_cvt_f16_f32_e32 v182, v79
	v_cvt_f16_f32_e32 v183, v83
	ds_write_b16 v170, v180 offset:144
	ds_write_b16 v170, v181 offset:176
	ds_write_b16 v170, v182 offset:208
	ds_write_b16 v170, v183 offset:240
	v_cvt_f16_f32_e32 v186, v72
	v_cvt_f16_f32_e32 v187, v76
	v_cvt_f16_f32_e32 v188, v80
	v_cvt_f16_f32_e32 v189, v84
	ds_write_b16 v170, v186 offset:288
	ds_write_b16 v170, v187 offset:320
	ds_write_b16 v170, v188 offset:352
	ds_write_b16 v170, v189 offset:384
	v_cvt_f16_f32_e32 v192, v73
	v_cvt_f16_f32_e32 v193, v77
	v_cvt_f16_f32_e32 v174, v81
	v_cvt_f16_f32_e32 v175, v85
	ds_write_b16 v170, v192 offset:432
	ds_write_b16 v170, v193 offset:464
	ds_write_b16 v170, v174 offset:496
	ds_write_b16 v170, v175 offset:528
	v_cvt_f16_f32_e32 v178, v86
	v_cvt_f16_f32_e32 v179, v90
	v_cvt_f16_f32_e32 v180, v94
	v_cvt_f16_f32_e32 v181, v98
	ds_write_b16 v170, v178 offset:2304
	ds_write_b16 v170, v179 offset:2336
	ds_write_b16 v170, v180 offset:2368
	ds_write_b16 v170, v181 offset:2400
	v_cvt_f16_f32_e32 v184, v87
	v_cvt_f16_f32_e32 v185, v91
	v_cvt_f16_f32_e32 v186, v95
	v_cvt_f16_f32_e32 v187, v99
	ds_write_b16 v170, v184 offset:2448
	ds_write_b16 v170, v185 offset:2480
	ds_write_b16 v170, v186 offset:2512
	ds_write_b16 v170, v187 offset:2544
	v_cvt_f16_f32_e32 v190, v88
	v_cvt_f16_f32_e32 v191, v92
	v_cvt_f16_f32_e32 v192, v96
	v_cvt_f16_f32_e32 v193, v100
	ds_write_b16 v170, v190 offset:2592
	ds_write_b16 v170, v191 offset:2624
	ds_write_b16 v170, v192 offset:2656
	ds_write_b16 v170, v193 offset:2688
	v_cvt_f16_f32_e32 v176, v89
	v_cvt_f16_f32_e32 v177, v93
	v_cvt_f16_f32_e32 v178, v97
	v_cvt_f16_f32_e32 v179, v101
	ds_write_b16 v170, v176 offset:2736
	ds_write_b16 v170, v177 offset:2768
	ds_write_b16 v170, v178 offset:2800
	ds_write_b16 v170, v179 offset:2832
	v_cvt_f16_f32_e32 v182, v102
	v_cvt_f16_f32_e32 v183, v106
	v_cvt_f16_f32_e32 v184, v110
	v_cvt_f16_f32_e32 v185, v114
	ds_write_b16 v170, v182 offset:4608
	ds_write_b16 v170, v183 offset:4640
	ds_write_b16 v170, v184 offset:4672
	ds_write_b16 v170, v185 offset:4704
	v_cvt_f16_f32_e32 v188, v103
	v_cvt_f16_f32_e32 v189, v107
	v_cvt_f16_f32_e32 v190, v111
	v_cvt_f16_f32_e32 v191, v115
	ds_write_b16 v170, v188 offset:4752
	ds_write_b16 v170, v189 offset:4784
	ds_write_b16 v170, v190 offset:4816
	ds_write_b16 v170, v191 offset:4848
	v_cvt_f16_f32_e32 v174, v104
	v_cvt_f16_f32_e32 v175, v108
	v_cvt_f16_f32_e32 v176, v112
	v_cvt_f16_f32_e32 v177, v116
	ds_write_b16 v170, v174 offset:4896
	ds_write_b16 v170, v175 offset:4928
	ds_write_b16 v170, v176 offset:4960
	ds_write_b16 v170, v177 offset:4992
	v_cvt_f16_f32_e32 v180, v105
	v_cvt_f16_f32_e32 v181, v109
	v_cvt_f16_f32_e32 v182, v113
	v_cvt_f16_f32_e32 v183, v117
	ds_write_b16 v170, v180 offset:5040
	ds_write_b16 v170, v181 offset:5072
	ds_write_b16 v170, v182 offset:5104
	ds_write_b16 v170, v183 offset:5136
	v_cvt_f16_f32_e32 v186, v118
	v_cvt_f16_f32_e32 v187, v122
	v_cvt_f16_f32_e32 v188, v126
	v_cvt_f16_f32_e32 v189, v2
	ds_write_b16 v170, v186 offset:6912
	ds_write_b16 v170, v187 offset:6944
	ds_write_b16 v170, v188 offset:6976
	ds_write_b16 v170, v189 offset:7008
	v_cvt_f16_f32_e32 v192, v119
	v_cvt_f16_f32_e32 v193, v123
	v_cvt_f16_f32_e32 v174, v127
	v_cvt_f16_f32_e32 v175, v3
	ds_write_b16 v170, v192 offset:7056
	ds_write_b16 v170, v193 offset:7088
	ds_write_b16 v170, v174 offset:7120
	ds_write_b16 v170, v175 offset:7152
	v_cvt_f16_f32_e32 v178, v120
	v_cvt_f16_f32_e32 v179, v124
	v_cvt_f16_f32_e32 v180, v128
	v_cvt_f16_f32_e32 v181, v4
	ds_write_b16 v170, v178 offset:7200
	ds_write_b16 v170, v179 offset:7232
	ds_write_b16 v170, v180 offset:7264
	ds_write_b16 v170, v181 offset:7296
	v_cvt_f16_f32_e32 v184, v121
	v_cvt_f16_f32_e32 v185, v125
	v_cvt_f16_f32_e32 v186, v129
	v_cvt_f16_f32_e32 v187, v5
	ds_write_b16 v170, v184 offset:7344
	ds_write_b16 v170, v185 offset:7376
	ds_write_b16 v170, v186 offset:7408
	ds_write_b16 v170, v187 offset:7440
	ds_read_b128 v[130:133], v171 offset:0
	ds_read_b128 v[134:137], v171 offset:1152
	ds_read_b128 v[138:141], v171 offset:2304
	ds_read_b128 v[142:145], v171 offset:3456
	ds_read_b128 v[146:149], v171 offset:4608
	ds_read_b128 v[150:153], v171 offset:5760
	ds_read_b128 v[154:157], v171 offset:6912
	ds_read_b128 v[158:161], v171 offset:8064
	s_waitcnt lgkmcnt(7)
	global_store_dwordx4 v172, v[130:133], s[44:45] offset:0 sc1 nt
	s_waitcnt lgkmcnt(6)
	global_store_dwordx4 v172, v[134:137], s[44:45] offset:1024 sc1 nt
	s_waitcnt lgkmcnt(5)
	global_store_dwordx4 v172, v[138:141], s[44:45] offset:2048 sc1 nt
	s_waitcnt lgkmcnt(4)
	global_store_dwordx4 v172, v[142:145], s[44:45] offset:3072 sc1 nt
	s_waitcnt lgkmcnt(3)
	global_store_dwordx4 v172, v[146:149], s[62:63] offset:0 sc1 nt
	s_waitcnt lgkmcnt(2)
	global_store_dwordx4 v172, v[150:153], s[62:63] offset:1024 sc1 nt
	s_waitcnt lgkmcnt(1)
	global_store_dwordx4 v172, v[154:157], s[62:63] offset:2048 sc1 nt
	s_waitcnt lgkmcnt(0)
	global_store_dwordx4 v172, v[158:161], s[62:63] offset:3072 sc1 nt
	s_branch .Lfe_done
; DI void sincos_rev(float ang, float& s, float& c) {
;   float rev = ang * 0.15915494309189535f;
;   rev -= rintf(rev);
;   s = __builtin_amdgcn_sinf(rev);
;   c = __builtin_amdgcn_cosf(rev);
; }
; template <int EPI>
; DI void gemm_phase(const P& p, int l, const u16* __restrict__ A, const u16* __restrict__ Bt, int mpx, char* lds) {
;     ...
;             if (dorope) {
;               float sr, cr, sc, cc;
;               sincos_rev((float)(s >> 6) * invf64, sr, cr);
;               sincos_rev((float)(s & 63) * invf64, sc, cc);
;               const float a1 = v0, a2 = v1, b1 = v2, b2 = v3;
;               v0 = a1 * cr - a2 * sr;
;               v1 = a2 * cr + a1 * sr;
;               v2 = b1 * cc - b2 * sc;
;               v3 = b2 * cc + b1 * sc;
;             }
;           } else if (tr == 4) {
;             float sr, cr, sc, cc;
;             sincos_rev((float)(s >> 6) * invf32, sr, cr);
;             sincos_rev((float)(s & 63) * invf32, sc, cc);
;             const float p0 = __shfl_xor(v0, 8), p1 = __shfl_xor(v1, 8), p2 = __shfl_xor(v2, 8), p3 = __shfl_xor(v3, 8);
;             v0 = lo8 ? (v0 * cr - p0 * sr) : (v0 * cr + p0 * sr);
;             v1 = lo8 ? (v1 * cc - p1 * sc) : (v1 * cc + p1 * sc);
;             v2 = lo8 ? (v2 * cr - p2 * sr) : (v2 * cr + p2 * sr);
;             v3 = lo8 ? (v3 * cc - p3 * sc) : (v3 * cc + p3 * sc);
;           }
;           const unsigned u01 = pack2(v0, v1), u23 = pack2(v2, v3);
;           if (kind == 1) {
;             Tl[(0 * 16 + r) * 72 + rowl] = (u16)u01;
;             Tl[(1 * 16 + r) * 72 + rowl] = (u16)(u01 >> 16);
;             Tl[(2 * 16 + r) * 72 + rowl] = (u16)u23;
;             Tl[(3 * 16 + r) * 72 + rowl] = (u16)(u23 >> 16);
;           } else if (tr == 2) {
;             Tl[rowl * 72 + 0 * 16 + r] = f2h(v0);
;             Tl[rowl * 72 + 1 * 16 + r] = f2h(v1);
;             Tl[rowl * 72 + 2 * 16 + r] = f2h(v2);
;             Tl[rowl * 72 + 3 * 16 + r] = f2h(v3);
;           } else {
;             Tl[rowl * 72 + 0 * 16 + r] = (u16)u01;
;             Tl[rowl * 72 + 1 * 16 + r] = (u16)(u01 >> 16);
;             Tl[rowl * 72 + 2 * 16 + r] = (u16)u23;
;             Tl[rowl * 72 + 3 * 16 + r] = (u16)(u23 >> 16);
.Lfe_k0_rope64:
	v_and_b32_e32 v0, 15, v226
	v_cvt_f32_ubyte0_e32 v0, v0
	v_mul_f32_e32 v0, 0xc1549a78, v0
	v_mul_f32_e32 v0, 0x3d800000, v0
	v_exp_f32_e32 v174, v0
	v_lshrrev_b32_e32 v0, 4, v226
	v_lshlrev_b32_e32 v0, 2, v0
	v_add_u32_e32 v182, 0, v0
	v_cvt_f32_i32_e32 v182, v182
	v_mul_f32_e32 v182, v174, v182
	v_mul_f32_e32 v183, 0.15915494, v182
	v_rndne_f32_e32 v183, v183
	v_fma_f32 v183, v182, 0.15915494, -v183
	v_sin_f32_e32 v212, v183
	v_cos_f32_e32 v238, v183
	v_add_u32_e32 v182, 1, v0
	v_cvt_f32_i32_e32 v182, v182
	v_mul_f32_e32 v182, v174, v182
	v_mul_f32_e32 v183, 0.15915494, v182
	v_rndne_f32_e32 v183, v183
	v_fma_f32 v183, v182, 0.15915494, -v183
	v_sin_f32_e32 v213, v183
	v_cos_f32_e32 v239, v183
	v_add_u32_e32 v182, 2, v0
	v_cvt_f32_i32_e32 v182, v182
	v_mul_f32_e32 v182, v174, v182
	v_mul_f32_e32 v183, 0.15915494, v182
	v_rndne_f32_e32 v183, v183
	v_fma_f32 v183, v182, 0.15915494, -v183
	v_sin_f32_e32 v214, v183
	v_cos_f32_e32 v240, v183
	v_add_u32_e32 v182, 3, v0
	v_cvt_f32_i32_e32 v182, v182
	v_mul_f32_e32 v182, v174, v182
	v_mul_f32_e32 v183, 0.15915494, v182
	v_rndne_f32_e32 v183, v183
	v_fma_f32 v183, v182, 0.15915494, -v183
	v_sin_f32_e32 v215, v183
	v_cos_f32_e32 v241, v183
	v_add_u32_e32 v182, 16, v0
	v_cvt_f32_i32_e32 v182, v182
	v_mul_f32_e32 v182, v174, v182
	v_mul_f32_e32 v183, 0.15915494, v182
	v_rndne_f32_e32 v183, v183
	v_fma_f32 v183, v182, 0.15915494, -v183
	v_sin_f32_e32 v216, v183
	v_cos_f32_e32 v242, v183
	v_add_u32_e32 v182, 17, v0
	v_cvt_f32_i32_e32 v182, v182
	v_mul_f32_e32 v182, v174, v182
	v_mul_f32_e32 v183, 0.15915494, v182
	v_rndne_f32_e32 v183, v183
	v_fma_f32 v183, v182, 0.15915494, -v183
	v_sin_f32_e32 v217, v183
	v_cos_f32_e32 v243, v183
	v_add_u32_e32 v182, 18, v0
	v_cvt_f32_i32_e32 v182, v182
	v_mul_f32_e32 v182, v174, v182
	v_mul_f32_e32 v183, 0.15915494, v182
	v_rndne_f32_e32 v183, v183
	v_fma_f32 v183, v182, 0.15915494, -v183
	v_sin_f32_e32 v218, v183
	v_cos_f32_e32 v244, v183
	v_add_u32_e32 v182, 19, v0
	v_cvt_f32_i32_e32 v182, v182
	v_mul_f32_e32 v182, v174, v182
	v_mul_f32_e32 v183, 0.15915494, v182
	v_rndne_f32_e32 v183, v183
	v_fma_f32 v183, v182, 0.15915494, -v183
	v_sin_f32_e32 v219, v183
	v_cos_f32_e32 v245, v183
	v_add_u32_e32 v182, 32, v0
	v_cvt_f32_i32_e32 v182, v182
	v_mul_f32_e32 v182, v174, v182
	v_mul_f32_e32 v183, 0.15915494, v182
	v_rndne_f32_e32 v183, v183
	v_fma_f32 v183, v182, 0.15915494, -v183
	v_sin_f32_e32 v220, v183
	v_cos_f32_e32 v246, v183
	v_add_u32_e32 v182, 33, v0
	v_cvt_f32_i32_e32 v182, v182
	v_mul_f32_e32 v182, v174, v182
	v_mul_f32_e32 v183, 0.15915494, v182
	v_rndne_f32_e32 v183, v183
	v_fma_f32 v183, v182, 0.15915494, -v183
	v_sin_f32_e32 v221, v183
	v_cos_f32_e32 v247, v183
	v_add_u32_e32 v182, 34, v0
	v_cvt_f32_i32_e32 v182, v182
	v_mul_f32_e32 v182, v174, v182
	v_mul_f32_e32 v183, 0.15915494, v182
	v_rndne_f32_e32 v183, v183
	v_fma_f32 v183, v182, 0.15915494, -v183
	v_sin_f32_e32 v222, v183
	v_cos_f32_e32 v248, v183
	v_add_u32_e32 v182, 35, v0
	v_cvt_f32_i32_e32 v182, v182
	v_mul_f32_e32 v182, v174, v182
	v_mul_f32_e32 v183, 0.15915494, v182
	v_rndne_f32_e32 v183, v183
	v_fma_f32 v183, v182, 0.15915494, -v183
	v_sin_f32_e32 v223, v183
	v_cos_f32_e32 v249, v183
	v_add_u32_e32 v182, 48, v0
	v_cvt_f32_i32_e32 v182, v182
	v_mul_f32_e32 v182, v174, v182
	v_mul_f32_e32 v183, 0.15915494, v182
	v_rndne_f32_e32 v183, v183
	v_fma_f32 v183, v182, 0.15915494, -v183
	v_sin_f32_e32 v234, v183
	v_cos_f32_e32 v250, v183
	v_add_u32_e32 v182, 49, v0
	v_cvt_f32_i32_e32 v182, v182
	v_mul_f32_e32 v182, v174, v182
	v_mul_f32_e32 v183, 0.15915494, v182
	v_rndne_f32_e32 v183, v183
	v_fma_f32 v183, v182, 0.15915494, -v183
	v_sin_f32_e32 v235, v183
	v_cos_f32_e32 v251, v183
	v_add_u32_e32 v182, 50, v0
	v_cvt_f32_i32_e32 v182, v182
	v_mul_f32_e32 v182, v174, v182
	v_mul_f32_e32 v183, 0.15915494, v182
	v_rndne_f32_e32 v183, v183
	v_fma_f32 v183, v182, 0.15915494, -v183
	v_sin_f32_e32 v236, v183
	v_cos_f32_e32 v252, v183
	v_add_u32_e32 v182, 51, v0
	v_cvt_f32_i32_e32 v182, v182
	v_mul_f32_e32 v182, v174, v182
	v_mul_f32_e32 v183, 0.15915494, v182
	v_rndne_f32_e32 v183, v183
	v_fma_f32 v183, v182, 0.15915494, -v183
	v_sin_f32_e32 v237, v183
	v_cos_f32_e32 v253, v183
	s_add_u32 s62, s44, 0x1000
	s_addc_u32 s63, s45, 0
	s_lshr_b32 s70, s69, 6
	v_cvt_f32_i32_e32 v182, s70
	v_mul_f32_e32 v182, v174, v182
	v_mul_f32_e32 v183, 0.15915494, v182
	v_rndne_f32_e32 v183, v183
	v_fma_f32 v183, v182, 0.15915494, -v183
	v_sin_f32_e32 v175, v183
	v_cos_f32_e32 v176, v183
	v_mul_f32_e32 v186, v175, v10
	v_mul_f32_e32 v187, v176, v10
	v_fma_f32 v188, v176, v6, -v186
	v_fma_f32 v189, v175, v6, v187
	v_mul_f32_e32 v186, v212, v18
	v_mul_f32_e32 v187, v238, v18
	v_fma_f32 v190, v238, v14, -v186
	v_fma_f32 v191, v212, v14, v187
	v_cvt_pk_bf16_f32 v192, v188, v189
	v_cvt_pk_bf16_f32 v193, v190, v191
	ds_write_b16 v170, v192 offset:0
	ds_write_b16_d16_hi v170, v192 offset:32
	ds_write_b16 v170, v193 offset:64
	ds_write_b16_d16_hi v170, v193 offset:96
	v_mul_f32_e32 v186, v175, v11
	v_mul_f32_e32 v187, v176, v11
	v_fma_f32 v188, v176, v7, -v186
	v_fma_f32 v189, v175, v7, v187
	v_mul_f32_e32 v186, v213, v19
	v_mul_f32_e32 v187, v239, v19
	v_fma_f32 v190, v239, v15, -v186
	v_fma_f32 v191, v213, v15, v187
	v_cvt_pk_bf16_f32 v192, v188, v189
	v_cvt_pk_bf16_f32 v193, v190, v191
	ds_write_b16 v170, v192 offset:144
	ds_write_b16_d16_hi v170, v192 offset:176
	ds_write_b16 v170, v193 offset:208
	ds_write_b16_d16_hi v170, v193 offset:240
	v_mul_f32_e32 v186, v175, v12
	v_mul_f32_e32 v187, v176, v12
	v_fma_f32 v188, v176, v8, -v186
	v_fma_f32 v189, v175, v8, v187
	v_mul_f32_e32 v186, v214, v20
; template <int EPI>
; DI void gemm_phase(const P& p, int l, const u16* __restrict__ A, const u16* __restrict__ Bt, int mpx, char* lds) {
;     ...
;             if (dorope) {
;               float sr, cr, sc, cc;
;               sincos_rev((float)(s >> 6) * invf64, sr, cr);
;               sincos_rev((float)(s & 63) * invf64, sc, cc);
;               const float a1 = v0, a2 = v1, b1 = v2, b2 = v3;
;               v0 = a1 * cr - a2 * sr;
;               v1 = a2 * cr + a1 * sr;
;               v2 = b1 * cc - b2 * sc;
;               v3 = b2 * cc + b1 * sc;
;             }
;           } else if (tr == 4) {
;             float sr, cr, sc, cc;
;             sincos_rev((float)(s >> 6) * invf32, sr, cr);
;             sincos_rev((float)(s & 63) * invf32, sc, cc);
;             const float p0 = __shfl_xor(v0, 8), p1 = __shfl_xor(v1, 8), p2 = __shfl_xor(v2, 8), p3 = __shfl_xor(v3, 8);
;             v0 = lo8 ? (v0 * cr - p0 * sr) : (v0 * cr + p0 * sr);
;             v1 = lo8 ? (v1 * cc - p1 * sc) : (v1 * cc + p1 * sc);
;             v2 = lo8 ? (v2 * cr - p2 * sr) : (v2 * cr + p2 * sr);
;             v3 = lo8 ? (v3 * cc - p3 * sc) : (v3 * cc + p3 * sc);
;           }
;           const unsigned u01 = pack2(v0, v1), u23 = pack2(v2, v3);
;           if (kind == 1) {
;             Tl[(0 * 16 + r) * 72 + rowl] = (u16)u01;
;             Tl[(1 * 16 + r) * 72 + rowl] = (u16)(u01 >> 16);
;             Tl[(2 * 16 + r) * 72 + rowl] = (u16)u23;
;             Tl[(3 * 16 + r) * 72 + rowl] = (u16)(u23 >> 16);
;           } else if (tr == 2) {
;             Tl[rowl * 72 + 0 * 16 + r] = f2h(v0);
;             Tl[rowl * 72 + 1 * 16 + r] = f2h(v1);
;             Tl[rowl * 72 + 2 * 16 + r] = f2h(v2);
;             Tl[rowl * 72 + 3 * 16 + r] = f2h(v3);
;           } else {
;             Tl[rowl * 72 + 0 * 16 + r] = (u16)u01;
;             Tl[rowl * 72 + 1 * 16 + r] = (u16)(u01 >> 16);
;             Tl[rowl * 72 + 2 * 16 + r] = (u16)u23;
;             Tl[rowl * 72 + 3 * 16 + r] = (u16)(u23 >> 16);
	v_mul_f32_e32 v187, v240, v20
	v_fma_f32 v190, v240, v16, -v186
	v_fma_f32 v191, v214, v16, v187
	v_cvt_pk_bf16_f32 v192, v188, v189
	v_cvt_pk_bf16_f32 v193, v190, v191
	ds_write_b16 v170, v192 offset:288
	ds_write_b16_d16_hi v170, v192 offset:320
	ds_write_b16 v170, v193 offset:352
	ds_write_b16_d16_hi v170, v193 offset:384
	v_mul_f32_e32 v186, v175, v13
	v_mul_f32_e32 v187, v176, v13
	v_fma_f32 v188, v176, v9, -v186
	v_fma_f32 v189, v175, v9, v187
	v_mul_f32_e32 v186, v215, v21
	v_mul_f32_e32 v187, v241, v21
	v_fma_f32 v190, v241, v17, -v186
	v_fma_f32 v191, v215, v17, v187
	v_cvt_pk_bf16_f32 v192, v188, v189
	v_cvt_pk_bf16_f32 v193, v190, v191
	ds_write_b16 v170, v192 offset:432
	ds_write_b16_d16_hi v170, v192 offset:464
	ds_write_b16 v170, v193 offset:496
	ds_write_b16_d16_hi v170, v193 offset:528
	v_mul_f32_e32 v186, v175, v26
	v_mul_f32_e32 v187, v176, v26
	v_fma_f32 v188, v176, v22, -v186
	v_fma_f32 v189, v175, v22, v187
	v_mul_f32_e32 v186, v216, v34
	v_mul_f32_e32 v187, v242, v34
	v_fma_f32 v190, v242, v30, -v186
	v_fma_f32 v191, v216, v30, v187
	v_cvt_pk_bf16_f32 v192, v188, v189
	v_cvt_pk_bf16_f32 v193, v190, v191
	ds_write_b16 v170, v192 offset:2304
	ds_write_b16_d16_hi v170, v192 offset:2336
	ds_write_b16 v170, v193 offset:2368
	ds_write_b16_d16_hi v170, v193 offset:2400
	v_mul_f32_e32 v186, v175, v27
	v_mul_f32_e32 v187, v176, v27
	v_fma_f32 v188, v176, v23, -v186
	v_fma_f32 v189, v175, v23, v187
	v_mul_f32_e32 v186, v217, v35
	v_mul_f32_e32 v187, v243, v35
	v_fma_f32 v190, v243, v31, -v186
	v_fma_f32 v191, v217, v31, v187
	v_cvt_pk_bf16_f32 v192, v188, v189
	v_cvt_pk_bf16_f32 v193, v190, v191
	ds_write_b16 v170, v192 offset:2448
	ds_write_b16_d16_hi v170, v192 offset:2480
	ds_write_b16 v170, v193 offset:2512
	ds_write_b16_d16_hi v170, v193 offset:2544
	v_mul_f32_e32 v186, v175, v28
	v_mul_f32_e32 v187, v176, v28
	v_fma_f32 v188, v176, v24, -v186
	v_fma_f32 v189, v175, v24, v187
	v_mul_f32_e32 v186, v218, v36
	v_mul_f32_e32 v187, v244, v36
	v_fma_f32 v190, v244, v32, -v186
	v_fma_f32 v191, v218, v32, v187
	v_cvt_pk_bf16_f32 v192, v188, v189
	v_cvt_pk_bf16_f32 v193, v190, v191
	ds_write_b16 v170, v192 offset:2592
	ds_write_b16_d16_hi v170, v192 offset:2624
	ds_write_b16 v170, v193 offset:2656
	ds_write_b16_d16_hi v170, v193 offset:2688
	v_mul_f32_e32 v186, v175, v29
	v_mul_f32_e32 v187, v176, v29
	v_fma_f32 v188, v176, v25, -v186
	v_fma_f32 v189, v175, v25, v187
	v_mul_f32_e32 v186, v219, v37
	v_mul_f32_e32 v187, v245, v37
	v_fma_f32 v190, v245, v33, -v186
	v_fma_f32 v191, v219, v33, v187
	v_cvt_pk_bf16_f32 v192, v188, v189
	v_cvt_pk_bf16_f32 v193, v190, v191
	ds_write_b16 v170, v192 offset:2736
	ds_write_b16_d16_hi v170, v192 offset:2768
	ds_write_b16 v170, v193 offset:2800
	ds_write_b16_d16_hi v170, v193 offset:2832
	v_mul_f32_e32 v186, v175, v42
	v_mul_f32_e32 v187, v176, v42
	v_fma_f32 v188, v176, v38, -v186
	v_fma_f32 v189, v175, v38, v187
	v_mul_f32_e32 v186, v220, v50
	v_mul_f32_e32 v187, v246, v50
	v_fma_f32 v190, v246, v46, -v186
	v_fma_f32 v191, v220, v46, v187
	v_cvt_pk_bf16_f32 v192, v188, v189
	v_cvt_pk_bf16_f32 v193, v190, v191
	ds_write_b16 v170, v192 offset:4608
	ds_write_b16_d16_hi v170, v192 offset:4640
	ds_write_b16 v170, v193 offset:4672
	ds_write_b16_d16_hi v170, v193 offset:4704
	v_mul_f32_e32 v186, v175, v43
	v_mul_f32_e32 v187, v176, v43
	v_fma_f32 v188, v176, v39, -v186
	v_fma_f32 v189, v175, v39, v187
	v_mul_f32_e32 v186, v221, v51
	v_mul_f32_e32 v187, v247, v51
	v_fma_f32 v190, v247, v47, -v186
	v_fma_f32 v191, v221, v47, v187
	v_cvt_pk_bf16_f32 v192, v188, v189
	v_cvt_pk_bf16_f32 v193, v190, v191
	ds_write_b16 v170, v192 offset:4752
	ds_write_b16_d16_hi v170, v192 offset:4784
	ds_write_b16 v170, v193 offset:4816
	ds_write_b16_d16_hi v170, v193 offset:4848
	v_mul_f32_e32 v186, v175, v44
	v_mul_f32_e32 v187, v176, v44
	v_fma_f32 v188, v176, v40, -v186
	v_fma_f32 v189, v175, v40, v187
	v_mul_f32_e32 v186, v222, v52
	v_mul_f32_e32 v187, v248, v52
	v_fma_f32 v190, v248, v48, -v186
	v_fma_f32 v191, v222, v48, v187
	v_cvt_pk_bf16_f32 v192, v188, v189
	v_cvt_pk_bf16_f32 v193, v190, v191
	ds_write_b16 v170, v192 offset:4896
	ds_write_b16_d16_hi v170, v192 offset:4928
	ds_write_b16 v170, v193 offset:4960
	ds_write_b16_d16_hi v170, v193 offset:4992
	v_mul_f32_e32 v186, v175, v45
	v_mul_f32_e32 v187, v176, v45
	v_fma_f32 v188, v176, v41, -v186
	v_fma_f32 v189, v175, v41, v187
	v_mul_f32_e32 v186, v223, v53
	v_mul_f32_e32 v187, v249, v53
	v_fma_f32 v190, v249, v49, -v186
	v_fma_f32 v191, v223, v49, v187
	v_cvt_pk_bf16_f32 v192, v188, v189
	v_cvt_pk_bf16_f32 v193, v190, v191
	ds_write_b16 v170, v192 offset:5040
	ds_write_b16_d16_hi v170, v192 offset:5072
	ds_write_b16 v170, v193 offset:5104
	ds_write_b16_d16_hi v170, v193 offset:5136
	v_mul_f32_e32 v186, v175, v58
	v_mul_f32_e32 v187, v176, v58
	v_fma_f32 v188, v176, v54, -v186
	v_fma_f32 v189, v175, v54, v187
	v_mul_f32_e32 v186, v234, v66
	v_mul_f32_e32 v187, v250, v66
	v_fma_f32 v190, v250, v62, -v186
	v_fma_f32 v191, v234, v62, v187
	v_cvt_pk_bf16_f32 v192, v188, v189
	v_cvt_pk_bf16_f32 v193, v190, v191
	ds_write_b16 v170, v192 offset:6912
	ds_write_b16_d16_hi v170, v192 offset:6944
	ds_write_b16 v170, v193 offset:6976
	ds_write_b16_d16_hi v170, v193 offset:7008
	v_mul_f32_e32 v186, v175, v59
	v_mul_f32_e32 v187, v176, v59
	v_fma_f32 v188, v176, v55, -v186
	v_fma_f32 v189, v175, v55, v187
	v_mul_f32_e32 v186, v235, v67
	v_mul_f32_e32 v187, v251, v67
	v_fma_f32 v190, v251, v63, -v186
	v_fma_f32 v191, v235, v63, v187
	v_cvt_pk_bf16_f32 v192, v188, v189
	v_cvt_pk_bf16_f32 v193, v190, v191
	ds_write_b16 v170, v192 offset:7056
	ds_write_b16_d16_hi v170, v192 offset:7088
; template <int EPI>
; DI void gemm_phase(const P& p, int l, const u16* __restrict__ A, const u16* __restrict__ Bt, int mpx, char* lds) {
;     ...
;             if (dorope) {
;               float sr, cr, sc, cc;
;               sincos_rev((float)(s >> 6) * invf64, sr, cr);
;               sincos_rev((float)(s & 63) * invf64, sc, cc);
;               const float a1 = v0, a2 = v1, b1 = v2, b2 = v3;
;               v0 = a1 * cr - a2 * sr;
;               v1 = a2 * cr + a1 * sr;
;               v2 = b1 * cc - b2 * sc;
;               v3 = b2 * cc + b1 * sc;
;             }
;           } else if (tr == 4) {
;             float sr, cr, sc, cc;
;             sincos_rev((float)(s >> 6) * invf32, sr, cr);
;             sincos_rev((float)(s & 63) * invf32, sc, cc);
;             const float p0 = __shfl_xor(v0, 8), p1 = __shfl_xor(v1, 8), p2 = __shfl_xor(v2, 8), p3 = __shfl_xor(v3, 8);
;             v0 = lo8 ? (v0 * cr - p0 * sr) : (v0 * cr + p0 * sr);
;             v1 = lo8 ? (v1 * cc - p1 * sc) : (v1 * cc + p1 * sc);
;             v2 = lo8 ? (v2 * cr - p2 * sr) : (v2 * cr + p2 * sr);
;             v3 = lo8 ? (v3 * cc - p3 * sc) : (v3 * cc + p3 * sc);
;           }
;           const unsigned u01 = pack2(v0, v1), u23 = pack2(v2, v3);
;           if (kind == 1) {
;             Tl[(0 * 16 + r) * 72 + rowl] = (u16)u01;
;             Tl[(1 * 16 + r) * 72 + rowl] = (u16)(u01 >> 16);
;             Tl[(2 * 16 + r) * 72 + rowl] = (u16)u23;
;             Tl[(3 * 16 + r) * 72 + rowl] = (u16)(u23 >> 16);
;           } else if (tr == 2) {
;             Tl[rowl * 72 + 0 * 16 + r] = f2h(v0);
;             Tl[rowl * 72 + 1 * 16 + r] = f2h(v1);
;             Tl[rowl * 72 + 2 * 16 + r] = f2h(v2);
;             Tl[rowl * 72 + 3 * 16 + r] = f2h(v3);
;           } else {
;             Tl[rowl * 72 + 0 * 16 + r] = (u16)u01;
;             Tl[rowl * 72 + 1 * 16 + r] = (u16)(u01 >> 16);
;             Tl[rowl * 72 + 2 * 16 + r] = (u16)u23;
;             Tl[rowl * 72 + 3 * 16 + r] = (u16)(u23 >> 16);
;           }
;         }
;       }
;       __builtin_amdgcn_fence(__ATOMIC_RELEASE, "wavefront");
;       u16* dh = (kind == 1) ? dst + hf * 64 : dst + (size_t)(hf * 64) * rstride;
; #pragma unroll
;       for (int i = 0; i < 8; ++i) {
;         const int c = lane + i * 64;
;         const int row = c >> 3, cc = c & 7;
;         uint4 v = *(const uint4*)&Tl[row * 72 + cc * 8];
	ds_write_b16 v170, v193 offset:7120
	ds_write_b16_d16_hi v170, v193 offset:7152
	v_mul_f32_e32 v186, v175, v60
	v_mul_f32_e32 v187, v176, v60
	v_fma_f32 v188, v176, v56, -v186
	v_fma_f32 v189, v175, v56, v187
	v_mul_f32_e32 v186, v236, v68
	v_mul_f32_e32 v187, v252, v68
	v_fma_f32 v190, v252, v64, -v186
	v_fma_f32 v191, v236, v64, v187
	v_cvt_pk_bf16_f32 v192, v188, v189
	v_cvt_pk_bf16_f32 v193, v190, v191
	ds_write_b16 v170, v192 offset:7200
	ds_write_b16_d16_hi v170, v192 offset:7232
	ds_write_b16 v170, v193 offset:7264
	ds_write_b16_d16_hi v170, v193 offset:7296
	v_mul_f32_e32 v186, v175, v61
	v_mul_f32_e32 v187, v176, v61
	v_fma_f32 v188, v176, v57, -v186
	v_fma_f32 v189, v175, v57, v187
	v_mul_f32_e32 v186, v237, v69
	v_mul_f32_e32 v187, v253, v69
	v_fma_f32 v190, v253, v65, -v186
	v_fma_f32 v191, v237, v65, v187
	v_cvt_pk_bf16_f32 v192, v188, v189
	v_cvt_pk_bf16_f32 v193, v190, v191
	ds_write_b16 v170, v192 offset:7344
	ds_write_b16_d16_hi v170, v192 offset:7376
	ds_write_b16 v170, v193 offset:7408
	ds_write_b16_d16_hi v170, v193 offset:7440
	ds_read_b128 v[130:133], v171 offset:0
	ds_read_b128 v[134:137], v171 offset:1152
	ds_read_b128 v[138:141], v171 offset:2304
	ds_read_b128 v[142:145], v171 offset:3456
	ds_read_b128 v[146:149], v171 offset:4608
	ds_read_b128 v[150:153], v171 offset:5760
	ds_read_b128 v[154:157], v171 offset:6912
	ds_read_b128 v[158:161], v171 offset:8064
	s_waitcnt lgkmcnt(7)
	global_store_dwordx4 v172, v[130:133], s[44:45] offset:0 sc1 nt
	s_waitcnt lgkmcnt(6)
	global_store_dwordx4 v172, v[134:137], s[44:45] offset:1024 sc1 nt
	s_waitcnt lgkmcnt(5)
	global_store_dwordx4 v172, v[138:141], s[44:45] offset:2048 sc1 nt
	s_waitcnt lgkmcnt(4)
	global_store_dwordx4 v172, v[142:145], s[44:45] offset:3072 sc1 nt
	s_waitcnt lgkmcnt(3)
	global_store_dwordx4 v172, v[146:149], s[62:63] offset:0 sc1 nt
	s_waitcnt lgkmcnt(2)
	global_store_dwordx4 v172, v[150:153], s[62:63] offset:1024 sc1 nt
	s_waitcnt lgkmcnt(1)
	global_store_dwordx4 v172, v[154:157], s[62:63] offset:2048 sc1 nt
	s_waitcnt lgkmcnt(0)
	global_store_dwordx4 v172, v[158:161], s[62:63] offset:3072 sc1 nt
	s_add_u32 s44, s44, 0x2000
	s_addc_u32 s45, s45, 0
	s_add_u32 s62, s62, 0x2000
	s_addc_u32 s63, s63, 0
	s_lshr_b32 s70, s69, 6
	s_add_i32 s70, s70, 1
	v_cvt_f32_i32_e32 v182, s70
	v_mul_f32_e32 v182, v174, v182
	v_mul_f32_e32 v183, 0.15915494, v182
	v_rndne_f32_e32 v183, v183
	v_fma_f32 v183, v182, 0.15915494, -v183
	v_sin_f32_e32 v175, v183
	v_cos_f32_e32 v176, v183
	v_mul_f32_e32 v186, v175, v74
	v_mul_f32_e32 v187, v176, v74
	v_fma_f32 v188, v176, v70, -v186
	v_fma_f32 v189, v175, v70, v187
	v_mul_f32_e32 v186, v212, v82
	v_mul_f32_e32 v187, v238, v82
	v_fma_f32 v190, v238, v78, -v186
	v_fma_f32 v191, v212, v78, v187
	v_cvt_pk_bf16_f32 v192, v188, v189
	v_cvt_pk_bf16_f32 v193, v190, v191
	ds_write_b16 v170, v192 offset:0
	ds_write_b16_d16_hi v170, v192 offset:32
	ds_write_b16 v170, v193 offset:64
	ds_write_b16_d16_hi v170, v193 offset:96
	v_mul_f32_e32 v186, v175, v75
	v_mul_f32_e32 v187, v176, v75
	v_fma_f32 v188, v176, v71, -v186
	v_fma_f32 v189, v175, v71, v187
	v_mul_f32_e32 v186, v213, v83
	v_mul_f32_e32 v187, v239, v83
	v_fma_f32 v190, v239, v79, -v186
	v_fma_f32 v191, v213, v79, v187
	v_cvt_pk_bf16_f32 v192, v188, v189
	v_cvt_pk_bf16_f32 v193, v190, v191
	ds_write_b16 v170, v192 offset:144
	ds_write_b16_d16_hi v170, v192 offset:176
	ds_write_b16 v170, v193 offset:208
	ds_write_b16_d16_hi v170, v193 offset:240
	v_mul_f32_e32 v186, v175, v76
	v_mul_f32_e32 v187, v176, v76
	v_fma_f32 v188, v176, v72, -v186
	v_fma_f32 v189, v175, v72, v187
	v_mul_f32_e32 v186, v214, v84
	v_mul_f32_e32 v187, v240, v84
	v_fma_f32 v190, v240, v80, -v186
	v_fma_f32 v191, v214, v80, v187
	v_cvt_pk_bf16_f32 v192, v188, v189
	v_cvt_pk_bf16_f32 v193, v190, v191
	ds_write_b16 v170, v192 offset:288
	ds_write_b16_d16_hi v170, v192 offset:320
	ds_write_b16 v170, v193 offset:352
	ds_write_b16_d16_hi v170, v193 offset:384
	v_mul_f32_e32 v186, v175, v77
	v_mul_f32_e32 v187, v176, v77
	v_fma_f32 v188, v176, v73, -v186
	v_fma_f32 v189, v175, v73, v187
	v_mul_f32_e32 v186, v215, v85
	v_mul_f32_e32 v187, v241, v85
	v_fma_f32 v190, v241, v81, -v186
	v_fma_f32 v191, v215, v81, v187
	v_cvt_pk_bf16_f32 v192, v188, v189
	v_cvt_pk_bf16_f32 v193, v190, v191
	ds_write_b16 v170, v192 offset:432
	ds_write_b16_d16_hi v170, v192 offset:464
	ds_write_b16 v170, v193 offset:496
	ds_write_b16_d16_hi v170, v193 offset:528
	v_mul_f32_e32 v186, v175, v90
	v_mul_f32_e32 v187, v176, v90
	v_fma_f32 v188, v176, v86, -v186
	v_fma_f32 v189, v175, v86, v187
	v_mul_f32_e32 v186, v216, v98
	v_mul_f32_e32 v187, v242, v98
	v_fma_f32 v190, v242, v94, -v186
	v_fma_f32 v191, v216, v94, v187
	v_cvt_pk_bf16_f32 v192, v188, v189
	v_cvt_pk_bf16_f32 v193, v190, v191
	ds_write_b16 v170, v192 offset:2304
	ds_write_b16_d16_hi v170, v192 offset:2336
	ds_write_b16 v170, v193 offset:2368
	ds_write_b16_d16_hi v170, v193 offset:2400
	v_mul_f32_e32 v186, v175, v91
	v_mul_f32_e32 v187, v176, v91
	v_fma_f32 v188, v176, v87, -v186
	v_fma_f32 v189, v175, v87, v187
	v_mul_f32_e32 v186, v217, v99
	v_mul_f32_e32 v187, v243, v99
	v_fma_f32 v190, v243, v95, -v186
	v_fma_f32 v191, v217, v95, v187
	v_cvt_pk_bf16_f32 v192, v188, v189
	v_cvt_pk_bf16_f32 v193, v190, v191
	ds_write_b16 v170, v192 offset:2448
	ds_write_b16_d16_hi v170, v192 offset:2480
	ds_write_b16 v170, v193 offset:2512
	ds_write_b16_d16_hi v170, v193 offset:2544
	v_mul_f32_e32 v186, v175, v92
	v_mul_f32_e32 v187, v176, v92
	v_fma_f32 v188, v176, v88, -v186
	v_fma_f32 v189, v175, v88, v187
	v_mul_f32_e32 v186, v218, v100
	v_mul_f32_e32 v187, v244, v100
	v_fma_f32 v190, v244, v96, -v186
; template <int EPI>
; DI void gemm_phase(const P& p, int l, const u16* __restrict__ A, const u16* __restrict__ Bt, int mpx, char* lds) {
;     ...
;             if (dorope) {
;               float sr, cr, sc, cc;
;               sincos_rev((float)(s >> 6) * invf64, sr, cr);
;               sincos_rev((float)(s & 63) * invf64, sc, cc);
;               const float a1 = v0, a2 = v1, b1 = v2, b2 = v3;
;               v0 = a1 * cr - a2 * sr;
;               v1 = a2 * cr + a1 * sr;
;               v2 = b1 * cc - b2 * sc;
;               v3 = b2 * cc + b1 * sc;
;             }
;           } else if (tr == 4) {
;             float sr, cr, sc, cc;
;             sincos_rev((float)(s >> 6) * invf32, sr, cr);
;             sincos_rev((float)(s & 63) * invf32, sc, cc);
;             const float p0 = __shfl_xor(v0, 8), p1 = __shfl_xor(v1, 8), p2 = __shfl_xor(v2, 8), p3 = __shfl_xor(v3, 8);
;             v0 = lo8 ? (v0 * cr - p0 * sr) : (v0 * cr + p0 * sr);
;             v1 = lo8 ? (v1 * cc - p1 * sc) : (v1 * cc + p1 * sc);
;             v2 = lo8 ? (v2 * cr - p2 * sr) : (v2 * cr + p2 * sr);
;             v3 = lo8 ? (v3 * cc - p3 * sc) : (v3 * cc + p3 * sc);
;           }
;           const unsigned u01 = pack2(v0, v1), u23 = pack2(v2, v3);
;           if (kind == 1) {
;             Tl[(0 * 16 + r) * 72 + rowl] = (u16)u01;
;             Tl[(1 * 16 + r) * 72 + rowl] = (u16)(u01 >> 16);
;             Tl[(2 * 16 + r) * 72 + rowl] = (u16)u23;
;             Tl[(3 * 16 + r) * 72 + rowl] = (u16)(u23 >> 16);
;           } else if (tr == 2) {
;             Tl[rowl * 72 + 0 * 16 + r] = f2h(v0);
;             Tl[rowl * 72 + 1 * 16 + r] = f2h(v1);
;             Tl[rowl * 72 + 2 * 16 + r] = f2h(v2);
;             Tl[rowl * 72 + 3 * 16 + r] = f2h(v3);
;           } else {
;             Tl[rowl * 72 + 0 * 16 + r] = (u16)u01;
;             Tl[rowl * 72 + 1 * 16 + r] = (u16)(u01 >> 16);
;             Tl[rowl * 72 + 2 * 16 + r] = (u16)u23;
;             Tl[rowl * 72 + 3 * 16 + r] = (u16)(u23 >> 16);
;           }
;         }
;       }
;       __builtin_amdgcn_fence(__ATOMIC_RELEASE, "wavefront");
;       u16* dh = (kind == 1) ? dst + hf * 64 : dst + (size_t)(hf * 64) * rstride;
; #pragma unroll
;       for (int i = 0; i < 8; ++i) {
;         const int c = lane + i * 64;
;         const int row = c >> 3, cc = c & 7;
;         uint4 v = *(const uint4*)&Tl[row * 72 + cc * 8];
	v_fma_f32 v191, v218, v96, v187
	v_cvt_pk_bf16_f32 v192, v188, v189
	v_cvt_pk_bf16_f32 v193, v190, v191
	ds_write_b16 v170, v192 offset:2592
	ds_write_b16_d16_hi v170, v192 offset:2624
	ds_write_b16 v170, v193 offset:2656
	ds_write_b16_d16_hi v170, v193 offset:2688
	v_mul_f32_e32 v186, v175, v93
	v_mul_f32_e32 v187, v176, v93
	v_fma_f32 v188, v176, v89, -v186
	v_fma_f32 v189, v175, v89, v187
	v_mul_f32_e32 v186, v219, v101
	v_mul_f32_e32 v187, v245, v101
	v_fma_f32 v190, v245, v97, -v186
	v_fma_f32 v191, v219, v97, v187
	v_cvt_pk_bf16_f32 v192, v188, v189
	v_cvt_pk_bf16_f32 v193, v190, v191
	ds_write_b16 v170, v192 offset:2736
	ds_write_b16_d16_hi v170, v192 offset:2768
	ds_write_b16 v170, v193 offset:2800
	ds_write_b16_d16_hi v170, v193 offset:2832
	v_mul_f32_e32 v186, v175, v106
	v_mul_f32_e32 v187, v176, v106
	v_fma_f32 v188, v176, v102, -v186
	v_fma_f32 v189, v175, v102, v187
	v_mul_f32_e32 v186, v220, v114
	v_mul_f32_e32 v187, v246, v114
	v_fma_f32 v190, v246, v110, -v186
	v_fma_f32 v191, v220, v110, v187
	v_cvt_pk_bf16_f32 v192, v188, v189
	v_cvt_pk_bf16_f32 v193, v190, v191
	ds_write_b16 v170, v192 offset:4608
	ds_write_b16_d16_hi v170, v192 offset:4640
	ds_write_b16 v170, v193 offset:4672
	ds_write_b16_d16_hi v170, v193 offset:4704
	v_mul_f32_e32 v186, v175, v107
	v_mul_f32_e32 v187, v176, v107
	v_fma_f32 v188, v176, v103, -v186
	v_fma_f32 v189, v175, v103, v187
	v_mul_f32_e32 v186, v221, v115
	v_mul_f32_e32 v187, v247, v115
	v_fma_f32 v190, v247, v111, -v186
	v_fma_f32 v191, v221, v111, v187
	v_cvt_pk_bf16_f32 v192, v188, v189
	v_cvt_pk_bf16_f32 v193, v190, v191
	ds_write_b16 v170, v192 offset:4752
	ds_write_b16_d16_hi v170, v192 offset:4784
	ds_write_b16 v170, v193 offset:4816
	ds_write_b16_d16_hi v170, v193 offset:4848
	v_mul_f32_e32 v186, v175, v108
	v_mul_f32_e32 v187, v176, v108
	v_fma_f32 v188, v176, v104, -v186
	v_fma_f32 v189, v175, v104, v187
	v_mul_f32_e32 v186, v222, v116
	v_mul_f32_e32 v187, v248, v116
	v_fma_f32 v190, v248, v112, -v186
	v_fma_f32 v191, v222, v112, v187
	v_cvt_pk_bf16_f32 v192, v188, v189
	v_cvt_pk_bf16_f32 v193, v190, v191
	ds_write_b16 v170, v192 offset:4896
	ds_write_b16_d16_hi v170, v192 offset:4928
	ds_write_b16 v170, v193 offset:4960
	ds_write_b16_d16_hi v170, v193 offset:4992
	v_mul_f32_e32 v186, v175, v109
	v_mul_f32_e32 v187, v176, v109
	v_fma_f32 v188, v176, v105, -v186
	v_fma_f32 v189, v175, v105, v187
	v_mul_f32_e32 v186, v223, v117
	v_mul_f32_e32 v187, v249, v117
	v_fma_f32 v190, v249, v113, -v186
	v_fma_f32 v191, v223, v113, v187
	v_cvt_pk_bf16_f32 v192, v188, v189
	v_cvt_pk_bf16_f32 v193, v190, v191
	ds_write_b16 v170, v192 offset:5040
	ds_write_b16_d16_hi v170, v192 offset:5072
	ds_write_b16 v170, v193 offset:5104
	ds_write_b16_d16_hi v170, v193 offset:5136
	v_mul_f32_e32 v186, v175, v122
	v_mul_f32_e32 v187, v176, v122
	v_fma_f32 v188, v176, v118, -v186
	v_fma_f32 v189, v175, v118, v187
	v_mul_f32_e32 v186, v234, v2
	v_mul_f32_e32 v187, v250, v2
	v_fma_f32 v190, v250, v126, -v186
	v_fma_f32 v191, v234, v126, v187
	v_cvt_pk_bf16_f32 v192, v188, v189
	v_cvt_pk_bf16_f32 v193, v190, v191
	ds_write_b16 v170, v192 offset:6912
	ds_write_b16_d16_hi v170, v192 offset:6944
	ds_write_b16 v170, v193 offset:6976
	ds_write_b16_d16_hi v170, v193 offset:7008
	v_mul_f32_e32 v186, v175, v123
	v_mul_f32_e32 v187, v176, v123
	v_fma_f32 v188, v176, v119, -v186
	v_fma_f32 v189, v175, v119, v187
	v_mul_f32_e32 v186, v235, v3
	v_mul_f32_e32 v187, v251, v3
	v_fma_f32 v190, v251, v127, -v186
	v_fma_f32 v191, v235, v127, v187
	v_cvt_pk_bf16_f32 v192, v188, v189
	v_cvt_pk_bf16_f32 v193, v190, v191
	ds_write_b16 v170, v192 offset:7056
	ds_write_b16_d16_hi v170, v192 offset:7088
	ds_write_b16 v170, v193 offset:7120
	ds_write_b16_d16_hi v170, v193 offset:7152
	v_mul_f32_e32 v186, v175, v124
	v_mul_f32_e32 v187, v176, v124
	v_fma_f32 v188, v176, v120, -v186
	v_fma_f32 v189, v175, v120, v187
	v_mul_f32_e32 v186, v236, v4
	v_mul_f32_e32 v187, v252, v4
	v_fma_f32 v190, v252, v128, -v186
	v_fma_f32 v191, v236, v128, v187
	v_cvt_pk_bf16_f32 v192, v188, v189
	v_cvt_pk_bf16_f32 v193, v190, v191
	ds_write_b16 v170, v192 offset:7200
	ds_write_b16_d16_hi v170, v192 offset:7232
	ds_write_b16 v170, v193 offset:7264
	ds_write_b16_d16_hi v170, v193 offset:7296
	v_mul_f32_e32 v186, v175, v125
	v_mul_f32_e32 v187, v176, v125
	v_fma_f32 v188, v176, v121, -v186
	v_fma_f32 v189, v175, v121, v187
	v_mul_f32_e32 v186, v237, v5
	v_mul_f32_e32 v187, v253, v5
	v_fma_f32 v190, v253, v129, -v186
	v_fma_f32 v191, v237, v129, v187
	v_cvt_pk_bf16_f32 v192, v188, v189
	v_cvt_pk_bf16_f32 v193, v190, v191
	ds_write_b16 v170, v192 offset:7344
	ds_write_b16_d16_hi v170, v192 offset:7376
	ds_write_b16 v170, v193 offset:7408
	ds_write_b16_d16_hi v170, v193 offset:7440
	ds_read_b128 v[130:133], v171 offset:0
	ds_read_b128 v[134:137], v171 offset:1152
	ds_read_b128 v[138:141], v171 offset:2304
	ds_read_b128 v[142:145], v171 offset:3456
	ds_read_b128 v[146:149], v171 offset:4608
	ds_read_b128 v[150:153], v171 offset:5760
	ds_read_b128 v[154:157], v171 offset:6912
	ds_read_b128 v[158:161], v171 offset:8064
	s_waitcnt lgkmcnt(7)
	global_store_dwordx4 v172, v[130:133], s[44:45] offset:0 sc1 nt
	s_waitcnt lgkmcnt(6)
	global_store_dwordx4 v172, v[134:137], s[44:45] offset:1024 sc1 nt
	s_waitcnt lgkmcnt(5)
	global_store_dwordx4 v172, v[138:141], s[44:45] offset:2048 sc1 nt
	s_waitcnt lgkmcnt(4)
	global_store_dwordx4 v172, v[142:145], s[44:45] offset:3072 sc1 nt
	s_waitcnt lgkmcnt(3)
	global_store_dwordx4 v172, v[146:149], s[62:63] offset:0 sc1 nt
	s_waitcnt lgkmcnt(2)
	global_store_dwordx4 v172, v[150:153], s[62:63] offset:1024 sc1 nt
	s_waitcnt lgkmcnt(1)
	global_store_dwordx4 v172, v[154:157], s[62:63] offset:2048 sc1 nt
	s_waitcnt lgkmcnt(0)
	global_store_dwordx4 v172, v[158:161], s[62:63] offset:3072 sc1 nt
	s_branch .Lfe_done
; DI void sincos_rev(float ang, float& s, float& c) {
;   float rev = ang * 0.15915494309189535f;
;   rev -= rintf(rev);
;   s = __builtin_amdgcn_sinf(rev);
;   c = __builtin_amdgcn_cosf(rev);
; }
; template <int EPI>
; DI void gemm_phase(const P& p, int l, const u16* __restrict__ A, const u16* __restrict__ Bt, int mpx, char* lds) {
;     ...
;           } else if (tr == 4) {
;             float sr, cr, sc, cc;
;             sincos_rev((float)(s >> 6) * invf32, sr, cr);
;             sincos_rev((float)(s & 63) * invf32, sc, cc);
;             const float p0 = __shfl_xor(v0, 8), p1 = __shfl_xor(v1, 8), p2 = __shfl_xor(v2, 8), p3 = __shfl_xor(v3, 8);
;             v0 = lo8 ? (v0 * cr - p0 * sr) : (v0 * cr + p0 * sr);
;             v1 = lo8 ? (v1 * cc - p1 * sc) : (v1 * cc + p1 * sc);
;             v2 = lo8 ? (v2 * cr - p2 * sr) : (v2 * cr + p2 * sr);
;             v3 = lo8 ? (v3 * cc - p3 * sc) : (v3 * cc + p3 * sc);
;           }
.Lfe_k0_rope32:
	v_and_b32_e32 v0, 7, v226
	v_cvt_f32_ubyte0_e32 v0, v0
	v_mul_f32_e32 v0, 0xc1549a78, v0
	v_mul_f32_e32 v0, 0x3e000000, v0
	v_exp_f32_e32 v174, v0
	v_lshrrev_b32_e32 v0, 4, v226
	v_lshlrev_b32_e32 v0, 2, v0
	v_add_u32_e32 v182, 0, v0
	v_cvt_f32_i32_e32 v182, v182
	v_mul_f32_e32 v182, v174, v182
	v_mul_f32_e32 v183, 0.15915494, v182
	v_rndne_f32_e32 v183, v183
	v_fma_f32 v183, v182, 0.15915494, -v183
	v_sin_f32_e32 v212, v183
	v_cos_f32_e32 v238, v183
	v_add_u32_e32 v182, 1, v0
	v_cvt_f32_i32_e32 v182, v182
	v_mul_f32_e32 v182, v174, v182
	v_mul_f32_e32 v183, 0.15915494, v182
	v_rndne_f32_e32 v183, v183
	v_fma_f32 v183, v182, 0.15915494, -v183
	v_sin_f32_e32 v213, v183
	v_cos_f32_e32 v239, v183
	v_add_u32_e32 v182, 2, v0
	v_cvt_f32_i32_e32 v182, v182
	v_mul_f32_e32 v182, v174, v182
	v_mul_f32_e32 v183, 0.15915494, v182
	v_rndne_f32_e32 v183, v183
	v_fma_f32 v183, v182, 0.15915494, -v183
	v_sin_f32_e32 v214, v183
	v_cos_f32_e32 v240, v183
	v_add_u32_e32 v182, 3, v0
	v_cvt_f32_i32_e32 v182, v182
	v_mul_f32_e32 v182, v174, v182
	v_mul_f32_e32 v183, 0.15915494, v182
	v_rndne_f32_e32 v183, v183
	v_fma_f32 v183, v182, 0.15915494, -v183
	v_sin_f32_e32 v215, v183
	v_cos_f32_e32 v241, v183
	v_add_u32_e32 v182, 16, v0
	v_cvt_f32_i32_e32 v182, v182
	v_mul_f32_e32 v182, v174, v182
	v_mul_f32_e32 v183, 0.15915494, v182
	v_rndne_f32_e32 v183, v183
	v_fma_f32 v183, v182, 0.15915494, -v183
	v_sin_f32_e32 v216, v183
	v_cos_f32_e32 v242, v183
	v_add_u32_e32 v182, 17, v0
	v_cvt_f32_i32_e32 v182, v182
	v_mul_f32_e32 v182, v174, v182
	v_mul_f32_e32 v183, 0.15915494, v182
	v_rndne_f32_e32 v183, v183
	v_fma_f32 v183, v182, 0.15915494, -v183
	v_sin_f32_e32 v217, v183
	v_cos_f32_e32 v243, v183
	v_add_u32_e32 v182, 18, v0
	v_cvt_f32_i32_e32 v182, v182
	v_mul_f32_e32 v182, v174, v182
	v_mul_f32_e32 v183, 0.15915494, v182
	v_rndne_f32_e32 v183, v183
	v_fma_f32 v183, v182, 0.15915494, -v183
	v_sin_f32_e32 v218, v183
	v_cos_f32_e32 v244, v183
	v_add_u32_e32 v182, 19, v0
	v_cvt_f32_i32_e32 v182, v182
	v_mul_f32_e32 v182, v174, v182
	v_mul_f32_e32 v183, 0.15915494, v182
	v_rndne_f32_e32 v183, v183
	v_fma_f32 v183, v182, 0.15915494, -v183
	v_sin_f32_e32 v219, v183
	v_cos_f32_e32 v245, v183
	v_add_u32_e32 v182, 32, v0
	v_cvt_f32_i32_e32 v182, v182
	v_mul_f32_e32 v182, v174, v182
	v_mul_f32_e32 v183, 0.15915494, v182
	v_rndne_f32_e32 v183, v183
	v_fma_f32 v183, v182, 0.15915494, -v183
	v_sin_f32_e32 v220, v183
	v_cos_f32_e32 v246, v183
	v_add_u32_e32 v182, 33, v0
	v_cvt_f32_i32_e32 v182, v182
	v_mul_f32_e32 v182, v174, v182
	v_mul_f32_e32 v183, 0.15915494, v182
	v_rndne_f32_e32 v183, v183
	v_fma_f32 v183, v182, 0.15915494, -v183
	v_sin_f32_e32 v221, v183
	v_cos_f32_e32 v247, v183
	v_add_u32_e32 v182, 34, v0
	v_cvt_f32_i32_e32 v182, v182
	v_mul_f32_e32 v182, v174, v182
	v_mul_f32_e32 v183, 0.15915494, v182
	v_rndne_f32_e32 v183, v183
	v_fma_f32 v183, v182, 0.15915494, -v183
	v_sin_f32_e32 v222, v183
	v_cos_f32_e32 v248, v183
	v_add_u32_e32 v182, 35, v0
	v_cvt_f32_i32_e32 v182, v182
	v_mul_f32_e32 v182, v174, v182
	v_mul_f32_e32 v183, 0.15915494, v182
	v_rndne_f32_e32 v183, v183
	v_fma_f32 v183, v182, 0.15915494, -v183
	v_sin_f32_e32 v223, v183
	v_cos_f32_e32 v249, v183
	v_add_u32_e32 v182, 48, v0
	v_cvt_f32_i32_e32 v182, v182
	v_mul_f32_e32 v182, v174, v182
	v_mul_f32_e32 v183, 0.15915494, v182
	v_rndne_f32_e32 v183, v183
	v_fma_f32 v183, v182, 0.15915494, -v183
	v_sin_f32_e32 v234, v183
	v_cos_f32_e32 v250, v183
	v_add_u32_e32 v182, 49, v0
	v_cvt_f32_i32_e32 v182, v182
	v_mul_f32_e32 v182, v174, v182
	v_mul_f32_e32 v183, 0.15915494, v182
	v_rndne_f32_e32 v183, v183
	v_fma_f32 v183, v182, 0.15915494, -v183
	v_sin_f32_e32 v235, v183
	v_cos_f32_e32 v251, v183
	v_add_u32_e32 v182, 50, v0
	v_cvt_f32_i32_e32 v182, v182
	v_mul_f32_e32 v182, v174, v182
	v_mul_f32_e32 v183, 0.15915494, v182
	v_rndne_f32_e32 v183, v183
	v_fma_f32 v183, v182, 0.15915494, -v183
	v_sin_f32_e32 v236, v183
	v_cos_f32_e32 v252, v183
	v_add_u32_e32 v182, 51, v0
	v_cvt_f32_i32_e32 v182, v182
	v_mul_f32_e32 v182, v174, v182
	v_mul_f32_e32 v183, 0.15915494, v182
	v_rndne_f32_e32 v183, v183
	v_fma_f32 v183, v182, 0.15915494, -v183
	v_sin_f32_e32 v237, v183
	v_cos_f32_e32 v253, v183
	v_and_b32_e32 v0, 8, v226
	v_cmp_eq_u32_e32 vcc, 0, v0
	s_nop 1
	v_cndmask_b32_e64 v212, v212, -v212, vcc
	v_cndmask_b32_e64 v213, v213, -v213, vcc
	v_cndmask_b32_e64 v214, v214, -v214, vcc
	v_cndmask_b32_e64 v215, v215, -v215, vcc
	v_cndmask_b32_e64 v216, v216, -v216, vcc
	v_cndmask_b32_e64 v217, v217, -v217, vcc
	v_cndmask_b32_e64 v218, v218, -v218, vcc
	v_cndmask_b32_e64 v219, v219, -v219, vcc
	v_cndmask_b32_e64 v220, v220, -v220, vcc
	v_cndmask_b32_e64 v221, v221, -v221, vcc
	v_cndmask_b32_e64 v222, v222, -v222, vcc
	v_cndmask_b32_e64 v223, v223, -v223, vcc
	v_cndmask_b32_e64 v234, v234, -v234, vcc
	v_cndmask_b32_e64 v235, v235, -v235, vcc
	v_cndmask_b32_e64 v236, v236, -v236, vcc
	v_cndmask_b32_e64 v237, v237, -v237, vcc
	s_add_u32 s62, s44, 0x1000
	s_addc_u32 s63, s45, 0
	s_lshr_b32 s70, s69, 6
	v_cvt_f32_i32_e32 v182, s70
	v_mul_f32_e32 v182, v174, v182
	v_mul_f32_e32 v183, 0.15915494, v182
	v_rndne_f32_e32 v183, v183
	v_fma_f32 v183, v182, 0.15915494, -v183
	v_sin_f32_e32 v175, v183
	v_cos_f32_e32 v176, v183
	s_nop 0
	v_cndmask_b32_e64 v177, v175, -v175, vcc
	v_mul_f32_dpp v182, v6, v177 row_ror:8 row_mask:0xf bank_mask:0xf
	v_mul_f32_dpp v183, v10, v212 row_ror:8 row_mask:0xf bank_mask:0xf
	v_mul_f32_dpp v184, v14, v177 row_ror:8 row_mask:0xf bank_mask:0xf
	v_mul_f32_dpp v185, v18, v212 row_ror:8 row_mask:0xf bank_mask:0xf
	v_fma_f32 v186, v6, v176, v182
	v_fma_f32 v187, v10, v238, v183
; template <int EPI>
; DI void gemm_phase(const P& p, int l, const u16* __restrict__ A, const u16* __restrict__ Bt, int mpx, char* lds) {
;     ...
;           } else if (tr == 4) {
;             float sr, cr, sc, cc;
;             sincos_rev((float)(s >> 6) * invf32, sr, cr);
;             sincos_rev((float)(s & 63) * invf32, sc, cc);
;             const float p0 = __shfl_xor(v0, 8), p1 = __shfl_xor(v1, 8), p2 = __shfl_xor(v2, 8), p3 = __shfl_xor(v3, 8);
;             v0 = lo8 ? (v0 * cr - p0 * sr) : (v0 * cr + p0 * sr);
;             v1 = lo8 ? (v1 * cc - p1 * sc) : (v1 * cc + p1 * sc);
;             v2 = lo8 ? (v2 * cr - p2 * sr) : (v2 * cr + p2 * sr);
;             v3 = lo8 ? (v3 * cc - p3 * sc) : (v3 * cc + p3 * sc);
;           }
;           const unsigned u01 = pack2(v0, v1), u23 = pack2(v2, v3);
;           if (kind == 1) {
;             Tl[(0 * 16 + r) * 72 + rowl] = (u16)u01;
;             Tl[(1 * 16 + r) * 72 + rowl] = (u16)(u01 >> 16);
;             Tl[(2 * 16 + r) * 72 + rowl] = (u16)u23;
;             Tl[(3 * 16 + r) * 72 + rowl] = (u16)(u23 >> 16);
;           } else if (tr == 2) {
;             Tl[rowl * 72 + 0 * 16 + r] = f2h(v0);
;             Tl[rowl * 72 + 1 * 16 + r] = f2h(v1);
;             Tl[rowl * 72 + 2 * 16 + r] = f2h(v2);
;             Tl[rowl * 72 + 3 * 16 + r] = f2h(v3);
;           } else {
;             Tl[rowl * 72 + 0 * 16 + r] = (u16)u01;
;             Tl[rowl * 72 + 1 * 16 + r] = (u16)(u01 >> 16);
;             Tl[rowl * 72 + 2 * 16 + r] = (u16)u23;
;             Tl[rowl * 72 + 3 * 16 + r] = (u16)(u23 >> 16);
	v_fma_f32 v188, v14, v176, v184
	v_fma_f32 v189, v18, v238, v185
	v_cvt_pk_bf16_f32 v192, v186, v187
	v_cvt_pk_bf16_f32 v193, v188, v189
	ds_write_b16 v170, v192 offset:0
	ds_write_b16_d16_hi v170, v192 offset:32
	ds_write_b16 v170, v193 offset:64
	ds_write_b16_d16_hi v170, v193 offset:96
	v_mul_f32_dpp v182, v7, v177 row_ror:8 row_mask:0xf bank_mask:0xf
	v_mul_f32_dpp v183, v11, v213 row_ror:8 row_mask:0xf bank_mask:0xf
	v_mul_f32_dpp v184, v15, v177 row_ror:8 row_mask:0xf bank_mask:0xf
	v_mul_f32_dpp v185, v19, v213 row_ror:8 row_mask:0xf bank_mask:0xf
	v_fma_f32 v186, v7, v176, v182
	v_fma_f32 v187, v11, v239, v183
	v_fma_f32 v188, v15, v176, v184
	v_fma_f32 v189, v19, v239, v185
	v_cvt_pk_bf16_f32 v192, v186, v187
	v_cvt_pk_bf16_f32 v193, v188, v189
	ds_write_b16 v170, v192 offset:144
	ds_write_b16_d16_hi v170, v192 offset:176
	ds_write_b16 v170, v193 offset:208
	ds_write_b16_d16_hi v170, v193 offset:240
	v_mul_f32_dpp v182, v8, v177 row_ror:8 row_mask:0xf bank_mask:0xf
	v_mul_f32_dpp v183, v12, v214 row_ror:8 row_mask:0xf bank_mask:0xf
	v_mul_f32_dpp v184, v16, v177 row_ror:8 row_mask:0xf bank_mask:0xf
	v_mul_f32_dpp v185, v20, v214 row_ror:8 row_mask:0xf bank_mask:0xf
	v_fma_f32 v186, v8, v176, v182
	v_fma_f32 v187, v12, v240, v183
	v_fma_f32 v188, v16, v176, v184
	v_fma_f32 v189, v20, v240, v185
	v_cvt_pk_bf16_f32 v192, v186, v187
	v_cvt_pk_bf16_f32 v193, v188, v189
	ds_write_b16 v170, v192 offset:288
	ds_write_b16_d16_hi v170, v192 offset:320
	ds_write_b16 v170, v193 offset:352
	ds_write_b16_d16_hi v170, v193 offset:384
	v_mul_f32_dpp v182, v9, v177 row_ror:8 row_mask:0xf bank_mask:0xf
	v_mul_f32_dpp v183, v13, v215 row_ror:8 row_mask:0xf bank_mask:0xf
	v_mul_f32_dpp v184, v17, v177 row_ror:8 row_mask:0xf bank_mask:0xf
	v_mul_f32_dpp v185, v21, v215 row_ror:8 row_mask:0xf bank_mask:0xf
	v_fma_f32 v186, v9, v176, v182
	v_fma_f32 v187, v13, v241, v183
	v_fma_f32 v188, v17, v176, v184
	v_fma_f32 v189, v21, v241, v185
	v_cvt_pk_bf16_f32 v192, v186, v187
	v_cvt_pk_bf16_f32 v193, v188, v189
	ds_write_b16 v170, v192 offset:432
	ds_write_b16_d16_hi v170, v192 offset:464
	ds_write_b16 v170, v193 offset:496
	ds_write_b16_d16_hi v170, v193 offset:528
	v_mul_f32_dpp v182, v22, v177 row_ror:8 row_mask:0xf bank_mask:0xf
	v_mul_f32_dpp v183, v26, v216 row_ror:8 row_mask:0xf bank_mask:0xf
	v_mul_f32_dpp v184, v30, v177 row_ror:8 row_mask:0xf bank_mask:0xf
	v_mul_f32_dpp v185, v34, v216 row_ror:8 row_mask:0xf bank_mask:0xf
	v_fma_f32 v186, v22, v176, v182
	v_fma_f32 v187, v26, v242, v183
	v_fma_f32 v188, v30, v176, v184
	v_fma_f32 v189, v34, v242, v185
	v_cvt_pk_bf16_f32 v192, v186, v187
	v_cvt_pk_bf16_f32 v193, v188, v189
	ds_write_b16 v170, v192 offset:2304
	ds_write_b16_d16_hi v170, v192 offset:2336
	ds_write_b16 v170, v193 offset:2368
	ds_write_b16_d16_hi v170, v193 offset:2400
	v_mul_f32_dpp v182, v23, v177 row_ror:8 row_mask:0xf bank_mask:0xf
	v_mul_f32_dpp v183, v27, v217 row_ror:8 row_mask:0xf bank_mask:0xf
	v_mul_f32_dpp v184, v31, v177 row_ror:8 row_mask:0xf bank_mask:0xf
	v_mul_f32_dpp v185, v35, v217 row_ror:8 row_mask:0xf bank_mask:0xf
	v_fma_f32 v186, v23, v176, v182
	v_fma_f32 v187, v27, v243, v183
	v_fma_f32 v188, v31, v176, v184
	v_fma_f32 v189, v35, v243, v185
	v_cvt_pk_bf16_f32 v192, v186, v187
	v_cvt_pk_bf16_f32 v193, v188, v189
	ds_write_b16 v170, v192 offset:2448
	ds_write_b16_d16_hi v170, v192 offset:2480
	ds_write_b16 v170, v193 offset:2512
	ds_write_b16_d16_hi v170, v193 offset:2544
	v_mul_f32_dpp v182, v24, v177 row_ror:8 row_mask:0xf bank_mask:0xf
	v_mul_f32_dpp v183, v28, v218 row_ror:8 row_mask:0xf bank_mask:0xf
	v_mul_f32_dpp v184, v32, v177 row_ror:8 row_mask:0xf bank_mask:0xf
	v_mul_f32_dpp v185, v36, v218 row_ror:8 row_mask:0xf bank_mask:0xf
	v_fma_f32 v186, v24, v176, v182
	v_fma_f32 v187, v28, v244, v183
	v_fma_f32 v188, v32, v176, v184
	v_fma_f32 v189, v36, v244, v185
	v_cvt_pk_bf16_f32 v192, v186, v187
	v_cvt_pk_bf16_f32 v193, v188, v189
	ds_write_b16 v170, v192 offset:2592
	ds_write_b16_d16_hi v170, v192 offset:2624
	ds_write_b16 v170, v193 offset:2656
	ds_write_b16_d16_hi v170, v193 offset:2688
	v_mul_f32_dpp v182, v25, v177 row_ror:8 row_mask:0xf bank_mask:0xf
	v_mul_f32_dpp v183, v29, v219 row_ror:8 row_mask:0xf bank_mask:0xf
	v_mul_f32_dpp v184, v33, v177 row_ror:8 row_mask:0xf bank_mask:0xf
	v_mul_f32_dpp v185, v37, v219 row_ror:8 row_mask:0xf bank_mask:0xf
	v_fma_f32 v186, v25, v176, v182
	v_fma_f32 v187, v29, v245, v183
	v_fma_f32 v188, v33, v176, v184
	v_fma_f32 v189, v37, v245, v185
	v_cvt_pk_bf16_f32 v192, v186, v187
	v_cvt_pk_bf16_f32 v193, v188, v189
	ds_write_b16 v170, v192 offset:2736
	ds_write_b16_d16_hi v170, v192 offset:2768
	ds_write_b16 v170, v193 offset:2800
	ds_write_b16_d16_hi v170, v193 offset:2832
	v_mul_f32_dpp v182, v38, v177 row_ror:8 row_mask:0xf bank_mask:0xf
	v_mul_f32_dpp v183, v42, v220 row_ror:8 row_mask:0xf bank_mask:0xf
	v_mul_f32_dpp v184, v46, v177 row_ror:8 row_mask:0xf bank_mask:0xf
	v_mul_f32_dpp v185, v50, v220 row_ror:8 row_mask:0xf bank_mask:0xf
	v_fma_f32 v186, v38, v176, v182
	v_fma_f32 v187, v42, v246, v183
	v_fma_f32 v188, v46, v176, v184
	v_fma_f32 v189, v50, v246, v185
	v_cvt_pk_bf16_f32 v192, v186, v187
	v_cvt_pk_bf16_f32 v193, v188, v189
	ds_write_b16 v170, v192 offset:4608
	ds_write_b16_d16_hi v170, v192 offset:4640
	ds_write_b16 v170, v193 offset:4672
	ds_write_b16_d16_hi v170, v193 offset:4704
	v_mul_f32_dpp v182, v39, v177 row_ror:8 row_mask:0xf bank_mask:0xf
	v_mul_f32_dpp v183, v43, v221 row_ror:8 row_mask:0xf bank_mask:0xf
	v_mul_f32_dpp v184, v47, v177 row_ror:8 row_mask:0xf bank_mask:0xf
	v_mul_f32_dpp v185, v51, v221 row_ror:8 row_mask:0xf bank_mask:0xf
; template <int EPI>
; DI void gemm_phase(const P& p, int l, const u16* __restrict__ A, const u16* __restrict__ Bt, int mpx, char* lds) {
;     ...
;           } else if (tr == 4) {
;             float sr, cr, sc, cc;
;             sincos_rev((float)(s >> 6) * invf32, sr, cr);
;             sincos_rev((float)(s & 63) * invf32, sc, cc);
;             const float p0 = __shfl_xor(v0, 8), p1 = __shfl_xor(v1, 8), p2 = __shfl_xor(v2, 8), p3 = __shfl_xor(v3, 8);
;             v0 = lo8 ? (v0 * cr - p0 * sr) : (v0 * cr + p0 * sr);
;             v1 = lo8 ? (v1 * cc - p1 * sc) : (v1 * cc + p1 * sc);
;             v2 = lo8 ? (v2 * cr - p2 * sr) : (v2 * cr + p2 * sr);
;             v3 = lo8 ? (v3 * cc - p3 * sc) : (v3 * cc + p3 * sc);
;           }
;           const unsigned u01 = pack2(v0, v1), u23 = pack2(v2, v3);
;           if (kind == 1) {
;             Tl[(0 * 16 + r) * 72 + rowl] = (u16)u01;
;             Tl[(1 * 16 + r) * 72 + rowl] = (u16)(u01 >> 16);
;             Tl[(2 * 16 + r) * 72 + rowl] = (u16)u23;
;             Tl[(3 * 16 + r) * 72 + rowl] = (u16)(u23 >> 16);
;           } else if (tr == 2) {
;             Tl[rowl * 72 + 0 * 16 + r] = f2h(v0);
;             Tl[rowl * 72 + 1 * 16 + r] = f2h(v1);
;             Tl[rowl * 72 + 2 * 16 + r] = f2h(v2);
;             Tl[rowl * 72 + 3 * 16 + r] = f2h(v3);
;           } else {
;             Tl[rowl * 72 + 0 * 16 + r] = (u16)u01;
;             Tl[rowl * 72 + 1 * 16 + r] = (u16)(u01 >> 16);
;             Tl[rowl * 72 + 2 * 16 + r] = (u16)u23;
;             Tl[rowl * 72 + 3 * 16 + r] = (u16)(u23 >> 16);
;           }
;         }
;       }
;       __builtin_amdgcn_fence(__ATOMIC_RELEASE, "wavefront");
;       u16* dh = (kind == 1) ? dst + hf * 64 : dst + (size_t)(hf * 64) * rstride;
; #pragma unroll
;       for (int i = 0; i < 8; ++i) {
;         const int c = lane + i * 64;
;         const int row = c >> 3, cc = c & 7;
;         uint4 v = *(const uint4*)&Tl[row * 72 + cc * 8];
;         *(uint4*)(dh + (size_t)row * rstride + cc * 8) = v;
;       }
	v_fma_f32 v186, v39, v176, v182
	v_fma_f32 v187, v43, v247, v183
	v_fma_f32 v188, v47, v176, v184
	v_fma_f32 v189, v51, v247, v185
	v_cvt_pk_bf16_f32 v192, v186, v187
	v_cvt_pk_bf16_f32 v193, v188, v189
	ds_write_b16 v170, v192 offset:4752
	ds_write_b16_d16_hi v170, v192 offset:4784
	ds_write_b16 v170, v193 offset:4816
	ds_write_b16_d16_hi v170, v193 offset:4848
	v_mul_f32_dpp v182, v40, v177 row_ror:8 row_mask:0xf bank_mask:0xf
	v_mul_f32_dpp v183, v44, v222 row_ror:8 row_mask:0xf bank_mask:0xf
	v_mul_f32_dpp v184, v48, v177 row_ror:8 row_mask:0xf bank_mask:0xf
	v_mul_f32_dpp v185, v52, v222 row_ror:8 row_mask:0xf bank_mask:0xf
	v_fma_f32 v186, v40, v176, v182
	v_fma_f32 v187, v44, v248, v183
	v_fma_f32 v188, v48, v176, v184
	v_fma_f32 v189, v52, v248, v185
	v_cvt_pk_bf16_f32 v192, v186, v187
	v_cvt_pk_bf16_f32 v193, v188, v189
	ds_write_b16 v170, v192 offset:4896
	ds_write_b16_d16_hi v170, v192 offset:4928
	ds_write_b16 v170, v193 offset:4960
	ds_write_b16_d16_hi v170, v193 offset:4992
	v_mul_f32_dpp v182, v41, v177 row_ror:8 row_mask:0xf bank_mask:0xf
	v_mul_f32_dpp v183, v45, v223 row_ror:8 row_mask:0xf bank_mask:0xf
	v_mul_f32_dpp v184, v49, v177 row_ror:8 row_mask:0xf bank_mask:0xf
	v_mul_f32_dpp v185, v53, v223 row_ror:8 row_mask:0xf bank_mask:0xf
	v_fma_f32 v186, v41, v176, v182
	v_fma_f32 v187, v45, v249, v183
	v_fma_f32 v188, v49, v176, v184
	v_fma_f32 v189, v53, v249, v185
	v_cvt_pk_bf16_f32 v192, v186, v187
	v_cvt_pk_bf16_f32 v193, v188, v189
	ds_write_b16 v170, v192 offset:5040
	ds_write_b16_d16_hi v170, v192 offset:5072
	ds_write_b16 v170, v193 offset:5104
	ds_write_b16_d16_hi v170, v193 offset:5136
	v_mul_f32_dpp v182, v54, v177 row_ror:8 row_mask:0xf bank_mask:0xf
	v_mul_f32_dpp v183, v58, v234 row_ror:8 row_mask:0xf bank_mask:0xf
	v_mul_f32_dpp v184, v62, v177 row_ror:8 row_mask:0xf bank_mask:0xf
	v_mul_f32_dpp v185, v66, v234 row_ror:8 row_mask:0xf bank_mask:0xf
	v_fma_f32 v186, v54, v176, v182
	v_fma_f32 v187, v58, v250, v183
	v_fma_f32 v188, v62, v176, v184
	v_fma_f32 v189, v66, v250, v185
	v_cvt_pk_bf16_f32 v192, v186, v187
	v_cvt_pk_bf16_f32 v193, v188, v189
	ds_write_b16 v170, v192 offset:6912
	ds_write_b16_d16_hi v170, v192 offset:6944
	ds_write_b16 v170, v193 offset:6976
	ds_write_b16_d16_hi v170, v193 offset:7008
	v_mul_f32_dpp v182, v55, v177 row_ror:8 row_mask:0xf bank_mask:0xf
	v_mul_f32_dpp v183, v59, v235 row_ror:8 row_mask:0xf bank_mask:0xf
	v_mul_f32_dpp v184, v63, v177 row_ror:8 row_mask:0xf bank_mask:0xf
	v_mul_f32_dpp v185, v67, v235 row_ror:8 row_mask:0xf bank_mask:0xf
	v_fma_f32 v186, v55, v176, v182
	v_fma_f32 v187, v59, v251, v183
	v_fma_f32 v188, v63, v176, v184
	v_fma_f32 v189, v67, v251, v185
	v_cvt_pk_bf16_f32 v192, v186, v187
	v_cvt_pk_bf16_f32 v193, v188, v189
	ds_write_b16 v170, v192 offset:7056
	ds_write_b16_d16_hi v170, v192 offset:7088
	ds_write_b16 v170, v193 offset:7120
	ds_write_b16_d16_hi v170, v193 offset:7152
	v_mul_f32_dpp v182, v56, v177 row_ror:8 row_mask:0xf bank_mask:0xf
	v_mul_f32_dpp v183, v60, v236 row_ror:8 row_mask:0xf bank_mask:0xf
	v_mul_f32_dpp v184, v64, v177 row_ror:8 row_mask:0xf bank_mask:0xf
	v_mul_f32_dpp v185, v68, v236 row_ror:8 row_mask:0xf bank_mask:0xf
	v_fma_f32 v186, v56, v176, v182
	v_fma_f32 v187, v60, v252, v183
	v_fma_f32 v188, v64, v176, v184
	v_fma_f32 v189, v68, v252, v185
	v_cvt_pk_bf16_f32 v192, v186, v187
	v_cvt_pk_bf16_f32 v193, v188, v189
	ds_write_b16 v170, v192 offset:7200
	ds_write_b16_d16_hi v170, v192 offset:7232
	ds_write_b16 v170, v193 offset:7264
	ds_write_b16_d16_hi v170, v193 offset:7296
	v_mul_f32_dpp v182, v57, v177 row_ror:8 row_mask:0xf bank_mask:0xf
	v_mul_f32_dpp v183, v61, v237 row_ror:8 row_mask:0xf bank_mask:0xf
	v_mul_f32_dpp v184, v65, v177 row_ror:8 row_mask:0xf bank_mask:0xf
	v_mul_f32_dpp v185, v69, v237 row_ror:8 row_mask:0xf bank_mask:0xf
	v_fma_f32 v186, v57, v176, v182
	v_fma_f32 v187, v61, v253, v183
	v_fma_f32 v188, v65, v176, v184
	v_fma_f32 v189, v69, v253, v185
	v_cvt_pk_bf16_f32 v192, v186, v187
	v_cvt_pk_bf16_f32 v193, v188, v189
	ds_write_b16 v170, v192 offset:7344
	ds_write_b16_d16_hi v170, v192 offset:7376
	ds_write_b16 v170, v193 offset:7408
	ds_write_b16_d16_hi v170, v193 offset:7440
	ds_read_b128 v[130:133], v171 offset:0
	ds_read_b128 v[134:137], v171 offset:1152
	ds_read_b128 v[138:141], v171 offset:2304
	ds_read_b128 v[142:145], v171 offset:3456
	ds_read_b128 v[146:149], v171 offset:4608
	ds_read_b128 v[150:153], v171 offset:5760
	ds_read_b128 v[154:157], v171 offset:6912
	ds_read_b128 v[158:161], v171 offset:8064
	s_waitcnt lgkmcnt(7)
	global_store_dwordx4 v172, v[130:133], s[44:45] offset:0 sc1 nt
	s_waitcnt lgkmcnt(6)
	global_store_dwordx4 v172, v[134:137], s[44:45] offset:1024 sc1 nt
	s_waitcnt lgkmcnt(5)
	global_store_dwordx4 v172, v[138:141], s[44:45] offset:2048 sc1 nt
	s_waitcnt lgkmcnt(4)
	global_store_dwordx4 v172, v[142:145], s[44:45] offset:3072 sc1 nt
	s_waitcnt lgkmcnt(3)
	global_store_dwordx4 v172, v[146:149], s[62:63] offset:0 sc1 nt
	s_waitcnt lgkmcnt(2)
	global_store_dwordx4 v172, v[150:153], s[62:63] offset:1024 sc1 nt
	s_waitcnt lgkmcnt(1)
	global_store_dwordx4 v172, v[154:157], s[62:63] offset:2048 sc1 nt
	s_waitcnt lgkmcnt(0)
; template <int EPI>
; DI void gemm_phase(const P& p, int l, const u16* __restrict__ A, const u16* __restrict__ Bt, int mpx, char* lds) {
;     ...
;           } else if (tr == 4) {
;             float sr, cr, sc, cc;
;             sincos_rev((float)(s >> 6) * invf32, sr, cr);
;             sincos_rev((float)(s & 63) * invf32, sc, cc);
;             const float p0 = __shfl_xor(v0, 8), p1 = __shfl_xor(v1, 8), p2 = __shfl_xor(v2, 8), p3 = __shfl_xor(v3, 8);
;             v0 = lo8 ? (v0 * cr - p0 * sr) : (v0 * cr + p0 * sr);
;             v1 = lo8 ? (v1 * cc - p1 * sc) : (v1 * cc + p1 * sc);
;             v2 = lo8 ? (v2 * cr - p2 * sr) : (v2 * cr + p2 * sr);
;             v3 = lo8 ? (v3 * cc - p3 * sc) : (v3 * cc + p3 * sc);
;           }
;           const unsigned u01 = pack2(v0, v1), u23 = pack2(v2, v3);
;           if (kind == 1) {
;             Tl[(0 * 16 + r) * 72 + rowl] = (u16)u01;
;             Tl[(1 * 16 + r) * 72 + rowl] = (u16)(u01 >> 16);
;             Tl[(2 * 16 + r) * 72 + rowl] = (u16)u23;
;             Tl[(3 * 16 + r) * 72 + rowl] = (u16)(u23 >> 16);
;           } else if (tr == 2) {
;             Tl[rowl * 72 + 0 * 16 + r] = f2h(v0);
;             Tl[rowl * 72 + 1 * 16 + r] = f2h(v1);
;             Tl[rowl * 72 + 2 * 16 + r] = f2h(v2);
;             Tl[rowl * 72 + 3 * 16 + r] = f2h(v3);
;           } else {
;             Tl[rowl * 72 + 0 * 16 + r] = (u16)u01;
;             Tl[rowl * 72 + 1 * 16 + r] = (u16)(u01 >> 16);
;             Tl[rowl * 72 + 2 * 16 + r] = (u16)u23;
;             Tl[rowl * 72 + 3 * 16 + r] = (u16)(u23 >> 16);
;           }
;         }
;       }
;       __builtin_amdgcn_fence(__ATOMIC_RELEASE, "wavefront");
;       u16* dh = (kind == 1) ? dst + hf * 64 : dst + (size_t)(hf * 64) * rstride;
; #pragma unroll
;       for (int i = 0; i < 8; ++i) {
;         const int c = lane + i * 64;
;         const int row = c >> 3, cc = c & 7;
;         uint4 v = *(const uint4*)&Tl[row * 72 + cc * 8];
;         *(uint4*)(dh + (size_t)row * rstride + cc * 8) = v;
;       }
	global_store_dwordx4 v172, v[158:161], s[62:63] offset:3072 sc1 nt
	s_add_u32 s44, s44, 0x2000
	s_addc_u32 s45, s45, 0
	s_add_u32 s62, s62, 0x2000
	s_addc_u32 s63, s63, 0
	s_lshr_b32 s70, s69, 6
	s_add_i32 s70, s70, 1
	v_cvt_f32_i32_e32 v182, s70
	v_mul_f32_e32 v182, v174, v182
	v_mul_f32_e32 v183, 0.15915494, v182
	v_rndne_f32_e32 v183, v183
	v_fma_f32 v183, v182, 0.15915494, -v183
	v_sin_f32_e32 v175, v183
	v_cos_f32_e32 v176, v183
	s_nop 0
	v_cndmask_b32_e64 v177, v175, -v175, vcc
	v_mul_f32_dpp v182, v70, v177 row_ror:8 row_mask:0xf bank_mask:0xf
	v_mul_f32_dpp v183, v74, v212 row_ror:8 row_mask:0xf bank_mask:0xf
	v_mul_f32_dpp v184, v78, v177 row_ror:8 row_mask:0xf bank_mask:0xf
	v_mul_f32_dpp v185, v82, v212 row_ror:8 row_mask:0xf bank_mask:0xf
	v_fma_f32 v186, v70, v176, v182
	v_fma_f32 v187, v74, v238, v183
	v_fma_f32 v188, v78, v176, v184
	v_fma_f32 v189, v82, v238, v185
	v_cvt_pk_bf16_f32 v192, v186, v187
	v_cvt_pk_bf16_f32 v193, v188, v189
	ds_write_b16 v170, v192 offset:0
	ds_write_b16_d16_hi v170, v192 offset:32
	ds_write_b16 v170, v193 offset:64
	ds_write_b16_d16_hi v170, v193 offset:96
	v_mul_f32_dpp v182, v71, v177 row_ror:8 row_mask:0xf bank_mask:0xf
	v_mul_f32_dpp v183, v75, v213 row_ror:8 row_mask:0xf bank_mask:0xf
	v_mul_f32_dpp v184, v79, v177 row_ror:8 row_mask:0xf bank_mask:0xf
	v_mul_f32_dpp v185, v83, v213 row_ror:8 row_mask:0xf bank_mask:0xf
	v_fma_f32 v186, v71, v176, v182
	v_fma_f32 v187, v75, v239, v183
	v_fma_f32 v188, v79, v176, v184
	v_fma_f32 v189, v83, v239, v185
	v_cvt_pk_bf16_f32 v192, v186, v187
	v_cvt_pk_bf16_f32 v193, v188, v189
	ds_write_b16 v170, v192 offset:144
	ds_write_b16_d16_hi v170, v192 offset:176
	ds_write_b16 v170, v193 offset:208
	ds_write_b16_d16_hi v170, v193 offset:240
	v_mul_f32_dpp v182, v72, v177 row_ror:8 row_mask:0xf bank_mask:0xf
	v_mul_f32_dpp v183, v76, v214 row_ror:8 row_mask:0xf bank_mask:0xf
	v_mul_f32_dpp v184, v80, v177 row_ror:8 row_mask:0xf bank_mask:0xf
	v_mul_f32_dpp v185, v84, v214 row_ror:8 row_mask:0xf bank_mask:0xf
	v_fma_f32 v186, v72, v176, v182
	v_fma_f32 v187, v76, v240, v183
	v_fma_f32 v188, v80, v176, v184
	v_fma_f32 v189, v84, v240, v185
	v_cvt_pk_bf16_f32 v192, v186, v187
	v_cvt_pk_bf16_f32 v193, v188, v189
	ds_write_b16 v170, v192 offset:288
	ds_write_b16_d16_hi v170, v192 offset:320
	ds_write_b16 v170, v193 offset:352
	ds_write_b16_d16_hi v170, v193 offset:384
	v_mul_f32_dpp v182, v73, v177 row_ror:8 row_mask:0xf bank_mask:0xf
	v_mul_f32_dpp v183, v77, v215 row_ror:8 row_mask:0xf bank_mask:0xf
	v_mul_f32_dpp v184, v81, v177 row_ror:8 row_mask:0xf bank_mask:0xf
	v_mul_f32_dpp v185, v85, v215 row_ror:8 row_mask:0xf bank_mask:0xf
	v_fma_f32 v186, v73, v176, v182
	v_fma_f32 v187, v77, v241, v183
	v_fma_f32 v188, v81, v176, v184
	v_fma_f32 v189, v85, v241, v185
	v_cvt_pk_bf16_f32 v192, v186, v187
	v_cvt_pk_bf16_f32 v193, v188, v189
	ds_write_b16 v170, v192 offset:432
	ds_write_b16_d16_hi v170, v192 offset:464
	ds_write_b16 v170, v193 offset:496
	ds_write_b16_d16_hi v170, v193 offset:528
	v_mul_f32_dpp v182, v86, v177 row_ror:8 row_mask:0xf bank_mask:0xf
	v_mul_f32_dpp v183, v90, v216 row_ror:8 row_mask:0xf bank_mask:0xf
	v_mul_f32_dpp v184, v94, v177 row_ror:8 row_mask:0xf bank_mask:0xf
	v_mul_f32_dpp v185, v98, v216 row_ror:8 row_mask:0xf bank_mask:0xf
	v_fma_f32 v186, v86, v176, v182
	v_fma_f32 v187, v90, v242, v183
	v_fma_f32 v188, v94, v176, v184
	v_fma_f32 v189, v98, v242, v185
	v_cvt_pk_bf16_f32 v192, v186, v187
	v_cvt_pk_bf16_f32 v193, v188, v189
	ds_write_b16 v170, v192 offset:2304
	ds_write_b16_d16_hi v170, v192 offset:2336
	ds_write_b16 v170, v193 offset:2368
	ds_write_b16_d16_hi v170, v193 offset:2400
	v_mul_f32_dpp v182, v87, v177 row_ror:8 row_mask:0xf bank_mask:0xf
	v_mul_f32_dpp v183, v91, v217 row_ror:8 row_mask:0xf bank_mask:0xf
	v_mul_f32_dpp v184, v95, v177 row_ror:8 row_mask:0xf bank_mask:0xf
	v_mul_f32_dpp v185, v99, v217 row_ror:8 row_mask:0xf bank_mask:0xf
	v_fma_f32 v186, v87, v176, v182
	v_fma_f32 v187, v91, v243, v183
	v_fma_f32 v188, v95, v176, v184
	v_fma_f32 v189, v99, v243, v185
	v_cvt_pk_bf16_f32 v192, v186, v187
	v_cvt_pk_bf16_f32 v193, v188, v189
	ds_write_b16 v170, v192 offset:2448
	ds_write_b16_d16_hi v170, v192 offset:2480
	ds_write_b16 v170, v193 offset:2512
	ds_write_b16_d16_hi v170, v193 offset:2544
	v_mul_f32_dpp v182, v88, v177 row_ror:8 row_mask:0xf bank_mask:0xf
	v_mul_f32_dpp v183, v92, v218 row_ror:8 row_mask:0xf bank_mask:0xf
	v_mul_f32_dpp v184, v96, v177 row_ror:8 row_mask:0xf bank_mask:0xf
	v_mul_f32_dpp v185, v100, v218 row_ror:8 row_mask:0xf bank_mask:0xf
	v_fma_f32 v186, v88, v176, v182
	v_fma_f32 v187, v92, v244, v183
	v_fma_f32 v188, v96, v176, v184
	v_fma_f32 v189, v100, v244, v185
	v_cvt_pk_bf16_f32 v192, v186, v187
	v_cvt_pk_bf16_f32 v193, v188, v189
	ds_write_b16 v170, v192 offset:2592
	ds_write_b16_d16_hi v170, v192 offset:2624
	ds_write_b16 v170, v193 offset:2656
	ds_write_b16_d16_hi v170, v193 offset:2688
	v_mul_f32_dpp v182, v89, v177 row_ror:8 row_mask:0xf bank_mask:0xf
	v_mul_f32_dpp v183, v93, v219 row_ror:8 row_mask:0xf bank_mask:0xf
	v_mul_f32_dpp v184, v97, v177 row_ror:8 row_mask:0xf bank_mask:0xf
	v_mul_f32_dpp v185, v101, v219 row_ror:8 row_mask:0xf bank_mask:0xf
	v_fma_f32 v186, v89, v176, v182
	v_fma_f32 v187, v93, v245, v183
	v_fma_f32 v188, v97, v176, v184
	v_fma_f32 v189, v101, v245, v185
	v_cvt_pk_bf16_f32 v192, v186, v187
	v_cvt_pk_bf16_f32 v193, v188, v189
	ds_write_b16 v170, v192 offset:2736
	ds_write_b16_d16_hi v170, v192 offset:2768
	ds_write_b16 v170, v193 offset:2800
	ds_write_b16_d16_hi v170, v193 offset:2832
	v_mul_f32_dpp v182, v102, v177 row_ror:8 row_mask:0xf bank_mask:0xf
; template <int EPI>
; DI void gemm_phase(const P& p, int l, const u16* __restrict__ A, const u16* __restrict__ Bt, int mpx, char* lds) {
;     ...
;           } else if (tr == 4) {
;             float sr, cr, sc, cc;
;             sincos_rev((float)(s >> 6) * invf32, sr, cr);
;             sincos_rev((float)(s & 63) * invf32, sc, cc);
;             const float p0 = __shfl_xor(v0, 8), p1 = __shfl_xor(v1, 8), p2 = __shfl_xor(v2, 8), p3 = __shfl_xor(v3, 8);
;             v0 = lo8 ? (v0 * cr - p0 * sr) : (v0 * cr + p0 * sr);
;             v1 = lo8 ? (v1 * cc - p1 * sc) : (v1 * cc + p1 * sc);
;             v2 = lo8 ? (v2 * cr - p2 * sr) : (v2 * cr + p2 * sr);
;             v3 = lo8 ? (v3 * cc - p3 * sc) : (v3 * cc + p3 * sc);
;           }
;           const unsigned u01 = pack2(v0, v1), u23 = pack2(v2, v3);
;           if (kind == 1) {
;             Tl[(0 * 16 + r) * 72 + rowl] = (u16)u01;
;             Tl[(1 * 16 + r) * 72 + rowl] = (u16)(u01 >> 16);
;             Tl[(2 * 16 + r) * 72 + rowl] = (u16)u23;
;             Tl[(3 * 16 + r) * 72 + rowl] = (u16)(u23 >> 16);
;           } else if (tr == 2) {
;             Tl[rowl * 72 + 0 * 16 + r] = f2h(v0);
;             Tl[rowl * 72 + 1 * 16 + r] = f2h(v1);
;             Tl[rowl * 72 + 2 * 16 + r] = f2h(v2);
;             Tl[rowl * 72 + 3 * 16 + r] = f2h(v3);
;           } else {
;             Tl[rowl * 72 + 0 * 16 + r] = (u16)u01;
;             Tl[rowl * 72 + 1 * 16 + r] = (u16)(u01 >> 16);
;             Tl[rowl * 72 + 2 * 16 + r] = (u16)u23;
;             Tl[rowl * 72 + 3 * 16 + r] = (u16)(u23 >> 16);
;           }
;         }
;       }
;       __builtin_amdgcn_fence(__ATOMIC_RELEASE, "wavefront");
;       u16* dh = (kind == 1) ? dst + hf * 64 : dst + (size_t)(hf * 64) * rstride;
; #pragma unroll
;       for (int i = 0; i < 8; ++i) {
;         const int c = lane + i * 64;
;         const int row = c >> 3, cc = c & 7;
;         uint4 v = *(const uint4*)&Tl[row * 72 + cc * 8];
;         *(uint4*)(dh + (size_t)row * rstride + cc * 8) = v;
;       }
	v_mul_f32_dpp v183, v106, v220 row_ror:8 row_mask:0xf bank_mask:0xf
	v_mul_f32_dpp v184, v110, v177 row_ror:8 row_mask:0xf bank_mask:0xf
	v_mul_f32_dpp v185, v114, v220 row_ror:8 row_mask:0xf bank_mask:0xf
	v_fma_f32 v186, v102, v176, v182
	v_fma_f32 v187, v106, v246, v183
	v_fma_f32 v188, v110, v176, v184
	v_fma_f32 v189, v114, v246, v185
	v_cvt_pk_bf16_f32 v192, v186, v187
	v_cvt_pk_bf16_f32 v193, v188, v189
	ds_write_b16 v170, v192 offset:4608
	ds_write_b16_d16_hi v170, v192 offset:4640
	ds_write_b16 v170, v193 offset:4672
	ds_write_b16_d16_hi v170, v193 offset:4704
	v_mul_f32_dpp v182, v103, v177 row_ror:8 row_mask:0xf bank_mask:0xf
	v_mul_f32_dpp v183, v107, v221 row_ror:8 row_mask:0xf bank_mask:0xf
	v_mul_f32_dpp v184, v111, v177 row_ror:8 row_mask:0xf bank_mask:0xf
	v_mul_f32_dpp v185, v115, v221 row_ror:8 row_mask:0xf bank_mask:0xf
	v_fma_f32 v186, v103, v176, v182
	v_fma_f32 v187, v107, v247, v183
	v_fma_f32 v188, v111, v176, v184
	v_fma_f32 v189, v115, v247, v185
	v_cvt_pk_bf16_f32 v192, v186, v187
	v_cvt_pk_bf16_f32 v193, v188, v189
	ds_write_b16 v170, v192 offset:4752
	ds_write_b16_d16_hi v170, v192 offset:4784
	ds_write_b16 v170, v193 offset:4816
	ds_write_b16_d16_hi v170, v193 offset:4848
	v_mul_f32_dpp v182, v104, v177 row_ror:8 row_mask:0xf bank_mask:0xf
	v_mul_f32_dpp v183, v108, v222 row_ror:8 row_mask:0xf bank_mask:0xf
	v_mul_f32_dpp v184, v112, v177 row_ror:8 row_mask:0xf bank_mask:0xf
	v_mul_f32_dpp v185, v116, v222 row_ror:8 row_mask:0xf bank_mask:0xf
	v_fma_f32 v186, v104, v176, v182
	v_fma_f32 v187, v108, v248, v183
	v_fma_f32 v188, v112, v176, v184
	v_fma_f32 v189, v116, v248, v185
	v_cvt_pk_bf16_f32 v192, v186, v187
	v_cvt_pk_bf16_f32 v193, v188, v189
	ds_write_b16 v170, v192 offset:4896
	ds_write_b16_d16_hi v170, v192 offset:4928
	ds_write_b16 v170, v193 offset:4960
	ds_write_b16_d16_hi v170, v193 offset:4992
	v_mul_f32_dpp v182, v105, v177 row_ror:8 row_mask:0xf bank_mask:0xf
	v_mul_f32_dpp v183, v109, v223 row_ror:8 row_mask:0xf bank_mask:0xf
	v_mul_f32_dpp v184, v113, v177 row_ror:8 row_mask:0xf bank_mask:0xf
	v_mul_f32_dpp v185, v117, v223 row_ror:8 row_mask:0xf bank_mask:0xf
	v_fma_f32 v186, v105, v176, v182
	v_fma_f32 v187, v109, v249, v183
	v_fma_f32 v188, v113, v176, v184
	v_fma_f32 v189, v117, v249, v185
	v_cvt_pk_bf16_f32 v192, v186, v187
	v_cvt_pk_bf16_f32 v193, v188, v189
	ds_write_b16 v170, v192 offset:5040
	ds_write_b16_d16_hi v170, v192 offset:5072
	ds_write_b16 v170, v193 offset:5104
	ds_write_b16_d16_hi v170, v193 offset:5136
	v_mul_f32_dpp v182, v118, v177 row_ror:8 row_mask:0xf bank_mask:0xf
	v_mul_f32_dpp v183, v122, v234 row_ror:8 row_mask:0xf bank_mask:0xf
	v_mul_f32_dpp v184, v126, v177 row_ror:8 row_mask:0xf bank_mask:0xf
	v_mul_f32_dpp v185, v2, v234 row_ror:8 row_mask:0xf bank_mask:0xf
	v_fma_f32 v186, v118, v176, v182
	v_fma_f32 v187, v122, v250, v183
	v_fma_f32 v188, v126, v176, v184
	v_fma_f32 v189, v2, v250, v185
	v_cvt_pk_bf16_f32 v192, v186, v187
	v_cvt_pk_bf16_f32 v193, v188, v189
	ds_write_b16 v170, v192 offset:6912
	ds_write_b16_d16_hi v170, v192 offset:6944
	ds_write_b16 v170, v193 offset:6976
	ds_write_b16_d16_hi v170, v193 offset:7008
	v_mul_f32_dpp v182, v119, v177 row_ror:8 row_mask:0xf bank_mask:0xf
	v_mul_f32_dpp v183, v123, v235 row_ror:8 row_mask:0xf bank_mask:0xf
	v_mul_f32_dpp v184, v127, v177 row_ror:8 row_mask:0xf bank_mask:0xf
	v_mul_f32_dpp v185, v3, v235 row_ror:8 row_mask:0xf bank_mask:0xf
	v_fma_f32 v186, v119, v176, v182
	v_fma_f32 v187, v123, v251, v183
	v_fma_f32 v188, v127, v176, v184
	v_fma_f32 v189, v3, v251, v185
	v_cvt_pk_bf16_f32 v192, v186, v187
	v_cvt_pk_bf16_f32 v193, v188, v189
	ds_write_b16 v170, v192 offset:7056
	ds_write_b16_d16_hi v170, v192 offset:7088
	ds_write_b16 v170, v193 offset:7120
	ds_write_b16_d16_hi v170, v193 offset:7152
	v_mul_f32_dpp v182, v120, v177 row_ror:8 row_mask:0xf bank_mask:0xf
	v_mul_f32_dpp v183, v124, v236 row_ror:8 row_mask:0xf bank_mask:0xf
	v_mul_f32_dpp v184, v128, v177 row_ror:8 row_mask:0xf bank_mask:0xf
	v_mul_f32_dpp v185, v4, v236 row_ror:8 row_mask:0xf bank_mask:0xf
	v_fma_f32 v186, v120, v176, v182
	v_fma_f32 v187, v124, v252, v183
	v_fma_f32 v188, v128, v176, v184
	v_fma_f32 v189, v4, v252, v185
	v_cvt_pk_bf16_f32 v192, v186, v187
	v_cvt_pk_bf16_f32 v193, v188, v189
	ds_write_b16 v170, v192 offset:7200
	ds_write_b16_d16_hi v170, v192 offset:7232
	ds_write_b16 v170, v193 offset:7264
	ds_write_b16_d16_hi v170, v193 offset:7296
	v_mul_f32_dpp v182, v121, v177 row_ror:8 row_mask:0xf bank_mask:0xf
	v_mul_f32_dpp v183, v125, v237 row_ror:8 row_mask:0xf bank_mask:0xf
	v_mul_f32_dpp v184, v129, v177 row_ror:8 row_mask:0xf bank_mask:0xf
	v_mul_f32_dpp v185, v5, v237 row_ror:8 row_mask:0xf bank_mask:0xf
	v_fma_f32 v186, v121, v176, v182
	v_fma_f32 v187, v125, v253, v183
	v_fma_f32 v188, v129, v176, v184
	v_fma_f32 v189, v5, v253, v185
	v_cvt_pk_bf16_f32 v192, v186, v187
	v_cvt_pk_bf16_f32 v193, v188, v189
	ds_write_b16 v170, v192 offset:7344
	ds_write_b16_d16_hi v170, v192 offset:7376
	ds_write_b16 v170, v193 offset:7408
	ds_write_b16_d16_hi v170, v193 offset:7440
	ds_read_b128 v[130:133], v171 offset:0
	ds_read_b128 v[134:137], v171 offset:1152
	ds_read_b128 v[138:141], v171 offset:2304
	ds_read_b128 v[142:145], v171 offset:3456
	ds_read_b128 v[146:149], v171 offset:4608
	ds_read_b128 v[150:153], v171 offset:5760
	ds_read_b128 v[154:157], v171 offset:6912
	ds_read_b128 v[158:161], v171 offset:8064
	s_waitcnt lgkmcnt(7)
	global_store_dwordx4 v172, v[130:133], s[44:45] offset:0 sc1 nt
	s_waitcnt lgkmcnt(6)
	global_store_dwordx4 v172, v[134:137], s[44:45] offset:1024 sc1 nt
	s_waitcnt lgkmcnt(5)
	global_store_dwordx4 v172, v[138:141], s[44:45] offset:2048 sc1 nt
	s_waitcnt lgkmcnt(4)
	global_store_dwordx4 v172, v[142:145], s[44:45] offset:3072 sc1 nt
	s_waitcnt lgkmcnt(3)
	global_store_dwordx4 v172, v[146:149], s[62:63] offset:0 sc1 nt
	s_waitcnt lgkmcnt(2)
	global_store_dwordx4 v172, v[150:153], s[62:63] offset:1024 sc1 nt
	s_waitcnt lgkmcnt(1)
	global_store_dwordx4 v172, v[154:157], s[62:63] offset:2048 sc1 nt
	s_waitcnt lgkmcnt(0)
	global_store_dwordx4 v172, v[158:161], s[62:63] offset:3072 sc1 nt
	s_branch .Lfe_done
; template <int EPI>
; DI void gemm_phase(const P& p, int l, const u16* __restrict__ A, const u16* __restrict__ Bt, int mpx, char* lds) {
;     ...
;     const float* gw = (cb < 1280 ? p.ga_qn : p.ga_kn) + l * 64;
;     float gv0 = 1.f, gv1 = 1.f, gv2 = 1.f, gv3 = 1.f;
;     if (donorm) { gv0 = gw[r]; gv1 = gw[16 + r]; gv2 = gw[32 + r]; gv3 = gw[48 + r]; }
;     const bool dorope = (tr == 3) && !isctx;
;     const float invf64 = exp2f(-13.287712379549449f * (float)r * (1.f / 16.f));
;     const float invf32 = exp2f(-13.287712379549449f * (float)(r & 7) * (1.f / 8.f));
;     ...
;             if (dorope) {
;               float sr, cr, sc, cc;
;               sincos_rev((float)(s >> 6) * invf64, sr, cr);
;               sincos_rev((float)(s & 63) * invf64, sc, cc);
.Lfe_k0_normrope:
	s_cmp_lt_u32 s43, 20
	s_movk_i32 s70, 0x68
	s_cselect_b32 s70, 0x60, s70
	s_add_u32 s70, s96, s70
	s_addc_u32 s71, s97, 0
	s_load_dwordx2 s[70:71], s[70:71], 0x0
	v_and_b32_e32 v0, 15, v226
	v_lshlrev_b32_e32 v0, 2, v0
	v_mov_b32_e32 v173, 0x358637bd
	s_waitcnt lgkmcnt(0)
	s_lshl_b32 s63, s52, 2
	s_add_u32 s70, s70, s63
	s_addc_u32 s71, s71, 0
	global_load_dword v178, v0, s[70:71] offset:0
	global_load_dword v179, v0, s[70:71] offset:64
	global_load_dword v180, v0, s[70:71] offset:128
	global_load_dword v181, v0, s[70:71] offset:192
	v_and_b32_e32 v0, 15, v226
	v_cvt_f32_ubyte0_e32 v0, v0
	v_mul_f32_e32 v0, 0xc1549a78, v0
	v_mul_f32_e32 v0, 0x3d800000, v0
	v_exp_f32_e32 v174, v0
	v_lshrrev_b32_e32 v0, 4, v226
	v_lshlrev_b32_e32 v0, 2, v0
	v_add_u32_e32 v182, 0, v0
	v_cvt_f32_i32_e32 v182, v182
	v_mul_f32_e32 v182, v174, v182
	v_mul_f32_e32 v183, 0.15915494, v182
	v_rndne_f32_e32 v183, v183
	v_fma_f32 v183, v182, 0.15915494, -v183
	v_sin_f32_e32 v212, v183
	v_cos_f32_e32 v238, v183
	v_add_u32_e32 v182, 1, v0
	v_cvt_f32_i32_e32 v182, v182
	v_mul_f32_e32 v182, v174, v182
	v_mul_f32_e32 v183, 0.15915494, v182
	v_rndne_f32_e32 v183, v183
	v_fma_f32 v183, v182, 0.15915494, -v183
	v_sin_f32_e32 v213, v183
	v_cos_f32_e32 v239, v183
	v_add_u32_e32 v182, 2, v0
	v_cvt_f32_i32_e32 v182, v182
	v_mul_f32_e32 v182, v174, v182
	v_mul_f32_e32 v183, 0.15915494, v182
	v_rndne_f32_e32 v183, v183
	v_fma_f32 v183, v182, 0.15915494, -v183
	v_sin_f32_e32 v214, v183
	v_cos_f32_e32 v240, v183
	v_add_u32_e32 v182, 3, v0
	v_cvt_f32_i32_e32 v182, v182
	v_mul_f32_e32 v182, v174, v182
	v_mul_f32_e32 v183, 0.15915494, v182
	v_rndne_f32_e32 v183, v183
	v_fma_f32 v183, v182, 0.15915494, -v183
	v_sin_f32_e32 v215, v183
	v_cos_f32_e32 v241, v183
	v_add_u32_e32 v182, 16, v0
	v_cvt_f32_i32_e32 v182, v182
	v_mul_f32_e32 v182, v174, v182
	v_mul_f32_e32 v183, 0.15915494, v182
	v_rndne_f32_e32 v183, v183
	v_fma_f32 v183, v182, 0.15915494, -v183
	v_sin_f32_e32 v216, v183
	v_cos_f32_e32 v242, v183
	v_add_u32_e32 v182, 17, v0
	v_cvt_f32_i32_e32 v182, v182
	v_mul_f32_e32 v182, v174, v182
	v_mul_f32_e32 v183, 0.15915494, v182
	v_rndne_f32_e32 v183, v183
	v_fma_f32 v183, v182, 0.15915494, -v183
	v_sin_f32_e32 v217, v183
	v_cos_f32_e32 v243, v183
	v_add_u32_e32 v182, 18, v0
	v_cvt_f32_i32_e32 v182, v182
	v_mul_f32_e32 v182, v174, v182
	v_mul_f32_e32 v183, 0.15915494, v182
	v_rndne_f32_e32 v183, v183
	v_fma_f32 v183, v182, 0.15915494, -v183
	v_sin_f32_e32 v218, v183
	v_cos_f32_e32 v244, v183
	v_add_u32_e32 v182, 19, v0
	v_cvt_f32_i32_e32 v182, v182
	v_mul_f32_e32 v182, v174, v182
	v_mul_f32_e32 v183, 0.15915494, v182
	v_rndne_f32_e32 v183, v183
	v_fma_f32 v183, v182, 0.15915494, -v183
	v_sin_f32_e32 v219, v183
	v_cos_f32_e32 v245, v183
	v_add_u32_e32 v182, 32, v0
	v_cvt_f32_i32_e32 v182, v182
	v_mul_f32_e32 v182, v174, v182
	v_mul_f32_e32 v183, 0.15915494, v182
	v_rndne_f32_e32 v183, v183
	v_fma_f32 v183, v182, 0.15915494, -v183
	v_sin_f32_e32 v220, v183
	v_cos_f32_e32 v246, v183
	v_add_u32_e32 v182, 33, v0
	v_cvt_f32_i32_e32 v182, v182
	v_mul_f32_e32 v182, v174, v182
	v_mul_f32_e32 v183, 0.15915494, v182
	v_rndne_f32_e32 v183, v183
	v_fma_f32 v183, v182, 0.15915494, -v183
	v_sin_f32_e32 v221, v183
	v_cos_f32_e32 v247, v183
	v_add_u32_e32 v182, 34, v0
	v_cvt_f32_i32_e32 v182, v182
	v_mul_f32_e32 v182, v174, v182
	v_mul_f32_e32 v183, 0.15915494, v182
	v_rndne_f32_e32 v183, v183
	v_fma_f32 v183, v182, 0.15915494, -v183
	v_sin_f32_e32 v222, v183
	v_cos_f32_e32 v248, v183
	v_add_u32_e32 v182, 35, v0
	v_cvt_f32_i32_e32 v182, v182
	v_mul_f32_e32 v182, v174, v182
	v_mul_f32_e32 v183, 0.15915494, v182
	v_rndne_f32_e32 v183, v183
	v_fma_f32 v183, v182, 0.15915494, -v183
	v_sin_f32_e32 v223, v183
	v_cos_f32_e32 v249, v183
	v_add_u32_e32 v182, 48, v0
	v_cvt_f32_i32_e32 v182, v182
	v_mul_f32_e32 v182, v174, v182
	v_mul_f32_e32 v183, 0.15915494, v182
	v_rndne_f32_e32 v183, v183
	v_fma_f32 v183, v182, 0.15915494, -v183
	v_sin_f32_e32 v234, v183
	v_cos_f32_e32 v250, v183
	v_add_u32_e32 v182, 49, v0
	v_cvt_f32_i32_e32 v182, v182
	v_mul_f32_e32 v182, v174, v182
	v_mul_f32_e32 v183, 0.15915494, v182
	v_rndne_f32_e32 v183, v183
	v_fma_f32 v183, v182, 0.15915494, -v183
	v_sin_f32_e32 v235, v183
	v_cos_f32_e32 v251, v183
	v_add_u32_e32 v182, 50, v0
	v_cvt_f32_i32_e32 v182, v182
	v_mul_f32_e32 v182, v174, v182
	v_mul_f32_e32 v183, 0.15915494, v182
	v_rndne_f32_e32 v183, v183
	v_fma_f32 v183, v182, 0.15915494, -v183
	v_sin_f32_e32 v236, v183
	v_cos_f32_e32 v252, v183
	v_add_u32_e32 v182, 51, v0
	v_cvt_f32_i32_e32 v182, v182
	v_mul_f32_e32 v182, v174, v182
	v_mul_f32_e32 v183, 0.15915494, v182
	v_rndne_f32_e32 v183, v183
	v_fma_f32 v183, v182, 0.15915494, -v183
	v_sin_f32_e32 v237, v183
	v_cos_f32_e32 v253, v183
	s_waitcnt vmcnt(0)
; template <int EPI>
; DI void gemm_phase(const P& p, int l, const u16* __restrict__ A, const u16* __restrict__ Bt, int mpx, char* lds) {
;     ...
;           } else if (tr == 3) {
;             if (donorm) {
;               float ss = v0 * v0 + v1 * v1 + v2 * v2 + v3 * v3;
;               ss += __shfl_xor(ss, 1);
;               ss += __shfl_xor(ss, 2);
;               ss += __shfl_xor(ss, 4);
;               ss += __shfl_xor(ss, 8);
;               const float inv = rsqrtf(ss * (1.f / 64.f) + 1e-6f);
;               v0 *= inv * gv0; v1 *= inv * gv1; v2 *= inv * gv2; v3 *= inv * gv3;
;             }
;             if (dorope) {
;               float sr, cr, sc, cc;
;               sincos_rev((float)(s >> 6) * invf64, sr, cr);
;               sincos_rev((float)(s & 63) * invf64, sc, cc);
;               const float a1 = v0, a2 = v1, b1 = v2, b2 = v3;
;               v0 = a1 * cr - a2 * sr;
;               v1 = a2 * cr + a1 * sr;
;               v2 = b1 * cc - b2 * sc;
;               v3 = b2 * cc + b1 * sc;
;             }
;           } else if (tr == 4) {
;             float sr, cr, sc, cc;
;             sincos_rev((float)(s >> 6) * invf32, sr, cr);
;             sincos_rev((float)(s & 63) * invf32, sc, cc);
;             const float p0 = __shfl_xor(v0, 8), p1 = __shfl_xor(v1, 8), p2 = __shfl_xor(v2, 8), p3 = __shfl_xor(v3, 8);
;             v0 = lo8 ? (v0 * cr - p0 * sr) : (v0 * cr + p0 * sr);
;             v1 = lo8 ? (v1 * cc - p1 * sc) : (v1 * cc + p1 * sc);
;             v2 = lo8 ? (v2 * cr - p2 * sr) : (v2 * cr + p2 * sr);
;             v3 = lo8 ? (v3 * cc - p3 * sc) : (v3 * cc + p3 * sc);
;           }
;           const unsigned u01 = pack2(v0, v1), u23 = pack2(v2, v3);
;           if (kind == 1) {
;             Tl[(0 * 16 + r) * 72 + rowl] = (u16)u01;
;             Tl[(1 * 16 + r) * 72 + rowl] = (u16)(u01 >> 16);
;             Tl[(2 * 16 + r) * 72 + rowl] = (u16)u23;
;             Tl[(3 * 16 + r) * 72 + rowl] = (u16)(u23 >> 16);
;           } else if (tr == 2) {
;             Tl[rowl * 72 + 0 * 16 + r] = f2h(v0);
;             Tl[rowl * 72 + 1 * 16 + r] = f2h(v1);
;             Tl[rowl * 72 + 2 * 16 + r] = f2h(v2);
;             Tl[rowl * 72 + 3 * 16 + r] = f2h(v3);
;           } else {
;             Tl[rowl * 72 + 0 * 16 + r] = (u16)u01;
;             Tl[rowl * 72 + 1 * 16 + r] = (u16)(u01 >> 16);
;             Tl[rowl * 72 + 2 * 16 + r] = (u16)u23;
	s_add_u32 s62, s44, 0x1000
	s_addc_u32 s63, s45, 0
	s_lshr_b32 s70, s69, 6
	v_cvt_f32_i32_e32 v182, s70
	v_mul_f32_e32 v182, v174, v182
	v_mul_f32_e32 v183, 0.15915494, v182
	v_rndne_f32_e32 v183, v183
	v_fma_f32 v183, v182, 0.15915494, -v183
	v_sin_f32_e32 v175, v183
	v_cos_f32_e32 v176, v183
	v_mul_f32_e32 v182, v6, v6
	v_mul_f32_e32 v183, v10, v10
	v_mul_f32_e32 v184, v14, v14
	v_mul_f32_e32 v185, v18, v18
	v_add_f32_e32 v186, v182, v183
	v_add_f32_e32 v186, v186, v184
	v_add_f32_e32 v186, v186, v185
	s_nop 1
	v_add_f32_dpp v186, v186, v186 quad_perm:[1,0,3,2] row_mask:0xf bank_mask:0xf
	s_nop 1
	v_add_f32_dpp v186, v186, v186 quad_perm:[2,3,0,1] row_mask:0xf bank_mask:0xf
	s_nop 1
	v_add_f32_dpp v186, v186, v186 row_half_mirror row_mask:0xf bank_mask:0xf
	s_nop 1
	v_add_f32_dpp v186, v186, v186 row_mirror row_mask:0xf bank_mask:0xf
	v_fmamk_f32 v186, v186, 0x3c800000, v173
	v_rsq_f32_e32 v186, v186
	s_nop 0
	v_mul_f32_e32 v187, v178, v186
	v_mul_f32_e32 v188, v179, v186
	v_mul_f32_e32 v189, v180, v186
	v_mul_f32_e32 v190, v181, v186
	v_mul_f32_e32 v182, v6, v187
	v_mul_f32_e32 v183, v10, v188
	v_mul_f32_e32 v184, v14, v189
	v_mul_f32_e32 v185, v18, v190
	v_mul_f32_e32 v186, v175, v183
	v_mul_f32_e32 v187, v176, v183
	v_fma_f32 v188, v176, v182, -v186
	v_fma_f32 v189, v175, v182, v187
	v_mul_f32_e32 v186, v212, v185
	v_mul_f32_e32 v187, v238, v185
	v_fma_f32 v190, v238, v184, -v186
	v_fma_f32 v191, v212, v184, v187
	v_cvt_pk_bf16_f32 v192, v188, v189
	v_cvt_pk_bf16_f32 v193, v190, v191
	ds_write_b16 v170, v192 offset:0
	ds_write_b16_d16_hi v170, v192 offset:32
	ds_write_b16 v170, v193 offset:64
	ds_write_b16_d16_hi v170, v193 offset:96
	v_mul_f32_e32 v182, v7, v7
	v_mul_f32_e32 v183, v11, v11
	v_mul_f32_e32 v184, v15, v15
	v_mul_f32_e32 v185, v19, v19
	v_add_f32_e32 v186, v182, v183
	v_add_f32_e32 v186, v186, v184
	v_add_f32_e32 v186, v186, v185
	s_nop 1
	v_add_f32_dpp v186, v186, v186 quad_perm:[1,0,3,2] row_mask:0xf bank_mask:0xf
	s_nop 1
	v_add_f32_dpp v186, v186, v186 quad_perm:[2,3,0,1] row_mask:0xf bank_mask:0xf
	s_nop 1
	v_add_f32_dpp v186, v186, v186 row_half_mirror row_mask:0xf bank_mask:0xf
	s_nop 1
	v_add_f32_dpp v186, v186, v186 row_mirror row_mask:0xf bank_mask:0xf
	v_fmamk_f32 v186, v186, 0x3c800000, v173
	v_rsq_f32_e32 v186, v186
	s_nop 0
	v_mul_f32_e32 v187, v178, v186
	v_mul_f32_e32 v188, v179, v186
	v_mul_f32_e32 v189, v180, v186
	v_mul_f32_e32 v190, v181, v186
	v_mul_f32_e32 v182, v7, v187
	v_mul_f32_e32 v183, v11, v188
	v_mul_f32_e32 v184, v15, v189
	v_mul_f32_e32 v185, v19, v190
	v_mul_f32_e32 v186, v175, v183
	v_mul_f32_e32 v187, v176, v183
	v_fma_f32 v188, v176, v182, -v186
	v_fma_f32 v189, v175, v182, v187
	v_mul_f32_e32 v186, v213, v185
	v_mul_f32_e32 v187, v239, v185
	v_fma_f32 v190, v239, v184, -v186
	v_fma_f32 v191, v213, v184, v187
	v_cvt_pk_bf16_f32 v192, v188, v189
	v_cvt_pk_bf16_f32 v193, v190, v191
	ds_write_b16 v170, v192 offset:144
	ds_write_b16_d16_hi v170, v192 offset:176
	ds_write_b16 v170, v193 offset:208
	ds_write_b16_d16_hi v170, v193 offset:240
	v_mul_f32_e32 v182, v8, v8
	v_mul_f32_e32 v183, v12, v12
	v_mul_f32_e32 v184, v16, v16
	v_mul_f32_e32 v185, v20, v20
	v_add_f32_e32 v186, v182, v183
	v_add_f32_e32 v186, v186, v184
	v_add_f32_e32 v186, v186, v185
	s_nop 1
	v_add_f32_dpp v186, v186, v186 quad_perm:[1,0,3,2] row_mask:0xf bank_mask:0xf
	s_nop 1
	v_add_f32_dpp v186, v186, v186 quad_perm:[2,3,0,1] row_mask:0xf bank_mask:0xf
	s_nop 1
	v_add_f32_dpp v186, v186, v186 row_half_mirror row_mask:0xf bank_mask:0xf
	s_nop 1
	v_add_f32_dpp v186, v186, v186 row_mirror row_mask:0xf bank_mask:0xf
	v_fmamk_f32 v186, v186, 0x3c800000, v173
	v_rsq_f32_e32 v186, v186
	s_nop 0
	v_mul_f32_e32 v187, v178, v186
	v_mul_f32_e32 v188, v179, v186
	v_mul_f32_e32 v189, v180, v186
	v_mul_f32_e32 v190, v181, v186
	v_mul_f32_e32 v182, v8, v187
	v_mul_f32_e32 v183, v12, v188
	v_mul_f32_e32 v184, v16, v189
	v_mul_f32_e32 v185, v20, v190
	v_mul_f32_e32 v186, v175, v183
	v_mul_f32_e32 v187, v176, v183
	v_fma_f32 v188, v176, v182, -v186
	v_fma_f32 v189, v175, v182, v187
	v_mul_f32_e32 v186, v214, v185
	v_mul_f32_e32 v187, v240, v185
	v_fma_f32 v190, v240, v184, -v186
	v_fma_f32 v191, v214, v184, v187
	v_cvt_pk_bf16_f32 v192, v188, v189
	v_cvt_pk_bf16_f32 v193, v190, v191
	ds_write_b16 v170, v192 offset:288
	ds_write_b16_d16_hi v170, v192 offset:320
	ds_write_b16 v170, v193 offset:352
	ds_write_b16_d16_hi v170, v193 offset:384
	v_mul_f32_e32 v182, v9, v9
	v_mul_f32_e32 v183, v13, v13
	v_mul_f32_e32 v184, v17, v17
	v_mul_f32_e32 v185, v21, v21
	v_add_f32_e32 v186, v182, v183
	v_add_f32_e32 v186, v186, v184
	v_add_f32_e32 v186, v186, v185
	s_nop 1
	v_add_f32_dpp v186, v186, v186 quad_perm:[1,0,3,2] row_mask:0xf bank_mask:0xf
	s_nop 1
	v_add_f32_dpp v186, v186, v186 quad_perm:[2,3,0,1] row_mask:0xf bank_mask:0xf
	s_nop 1
	v_add_f32_dpp v186, v186, v186 row_half_mirror row_mask:0xf bank_mask:0xf
	s_nop 1
	v_add_f32_dpp v186, v186, v186 row_mirror row_mask:0xf bank_mask:0xf
	v_fmamk_f32 v186, v186, 0x3c800000, v173
	v_rsq_f32_e32 v186, v186
	s_nop 0
	v_mul_f32_e32 v187, v178, v186
	v_mul_f32_e32 v188, v179, v186
	v_mul_f32_e32 v189, v180, v186
	v_mul_f32_e32 v190, v181, v186
	v_mul_f32_e32 v182, v9, v187
	v_mul_f32_e32 v183, v13, v188
	v_mul_f32_e32 v184, v17, v189
	v_mul_f32_e32 v185, v21, v190
	v_mul_f32_e32 v186, v175, v183
	v_mul_f32_e32 v187, v176, v183
	v_fma_f32 v188, v176, v182, -v186
	v_fma_f32 v189, v175, v182, v187
	v_mul_f32_e32 v186, v215, v185
	v_mul_f32_e32 v187, v241, v185
	v_fma_f32 v190, v241, v184, -v186
	v_fma_f32 v191, v215, v184, v187
	v_cvt_pk_bf16_f32 v192, v188, v189
	v_cvt_pk_bf16_f32 v193, v190, v191
; template <int EPI>
; DI void gemm_phase(const P& p, int l, const u16* __restrict__ A, const u16* __restrict__ Bt, int mpx, char* lds) {
;     ...
;           } else if (tr == 3) {
;             if (donorm) {
;               float ss = v0 * v0 + v1 * v1 + v2 * v2 + v3 * v3;
;               ss += __shfl_xor(ss, 1);
;               ss += __shfl_xor(ss, 2);
;               ss += __shfl_xor(ss, 4);
;               ss += __shfl_xor(ss, 8);
;               const float inv = rsqrtf(ss * (1.f / 64.f) + 1e-6f);
;               v0 *= inv * gv0; v1 *= inv * gv1; v2 *= inv * gv2; v3 *= inv * gv3;
;             }
;             if (dorope) {
;               float sr, cr, sc, cc;
;               sincos_rev((float)(s >> 6) * invf64, sr, cr);
;               sincos_rev((float)(s & 63) * invf64, sc, cc);
;               const float a1 = v0, a2 = v1, b1 = v2, b2 = v3;
;               v0 = a1 * cr - a2 * sr;
;               v1 = a2 * cr + a1 * sr;
;               v2 = b1 * cc - b2 * sc;
;               v3 = b2 * cc + b1 * sc;
;             }
;           } else if (tr == 4) {
;             float sr, cr, sc, cc;
;             sincos_rev((float)(s >> 6) * invf32, sr, cr);
;             sincos_rev((float)(s & 63) * invf32, sc, cc);
;             const float p0 = __shfl_xor(v0, 8), p1 = __shfl_xor(v1, 8), p2 = __shfl_xor(v2, 8), p3 = __shfl_xor(v3, 8);
;             v0 = lo8 ? (v0 * cr - p0 * sr) : (v0 * cr + p0 * sr);
;             v1 = lo8 ? (v1 * cc - p1 * sc) : (v1 * cc + p1 * sc);
;             v2 = lo8 ? (v2 * cr - p2 * sr) : (v2 * cr + p2 * sr);
;             v3 = lo8 ? (v3 * cc - p3 * sc) : (v3 * cc + p3 * sc);
;           }
;           const unsigned u01 = pack2(v0, v1), u23 = pack2(v2, v3);
;           if (kind == 1) {
;             Tl[(0 * 16 + r) * 72 + rowl] = (u16)u01;
;             Tl[(1 * 16 + r) * 72 + rowl] = (u16)(u01 >> 16);
;             Tl[(2 * 16 + r) * 72 + rowl] = (u16)u23;
;             Tl[(3 * 16 + r) * 72 + rowl] = (u16)(u23 >> 16);
;           } else if (tr == 2) {
;             Tl[rowl * 72 + 0 * 16 + r] = f2h(v0);
;             Tl[rowl * 72 + 1 * 16 + r] = f2h(v1);
;             Tl[rowl * 72 + 2 * 16 + r] = f2h(v2);
;             Tl[rowl * 72 + 3 * 16 + r] = f2h(v3);
;           } else {
;             Tl[rowl * 72 + 0 * 16 + r] = (u16)u01;
;             Tl[rowl * 72 + 1 * 16 + r] = (u16)(u01 >> 16);
;             Tl[rowl * 72 + 2 * 16 + r] = (u16)u23;
	ds_write_b16 v170, v192 offset:432
	ds_write_b16_d16_hi v170, v192 offset:464
	ds_write_b16 v170, v193 offset:496
	ds_write_b16_d16_hi v170, v193 offset:528
	v_mul_f32_e32 v182, v22, v22
	v_mul_f32_e32 v183, v26, v26
	v_mul_f32_e32 v184, v30, v30
	v_mul_f32_e32 v185, v34, v34
	v_add_f32_e32 v186, v182, v183
	v_add_f32_e32 v186, v186, v184
	v_add_f32_e32 v186, v186, v185
	s_nop 1
	v_add_f32_dpp v186, v186, v186 quad_perm:[1,0,3,2] row_mask:0xf bank_mask:0xf
	s_nop 1
	v_add_f32_dpp v186, v186, v186 quad_perm:[2,3,0,1] row_mask:0xf bank_mask:0xf
	s_nop 1
	v_add_f32_dpp v186, v186, v186 row_half_mirror row_mask:0xf bank_mask:0xf
	s_nop 1
	v_add_f32_dpp v186, v186, v186 row_mirror row_mask:0xf bank_mask:0xf
	v_fmamk_f32 v186, v186, 0x3c800000, v173
	v_rsq_f32_e32 v186, v186
	s_nop 0
	v_mul_f32_e32 v187, v178, v186
	v_mul_f32_e32 v188, v179, v186
	v_mul_f32_e32 v189, v180, v186
	v_mul_f32_e32 v190, v181, v186
	v_mul_f32_e32 v182, v22, v187
	v_mul_f32_e32 v183, v26, v188
	v_mul_f32_e32 v184, v30, v189
	v_mul_f32_e32 v185, v34, v190
	v_mul_f32_e32 v186, v175, v183
	v_mul_f32_e32 v187, v176, v183
	v_fma_f32 v188, v176, v182, -v186
	v_fma_f32 v189, v175, v182, v187
	v_mul_f32_e32 v186, v216, v185
	v_mul_f32_e32 v187, v242, v185
	v_fma_f32 v190, v242, v184, -v186
	v_fma_f32 v191, v216, v184, v187
	v_cvt_pk_bf16_f32 v192, v188, v189
	v_cvt_pk_bf16_f32 v193, v190, v191
	ds_write_b16 v170, v192 offset:2304
	ds_write_b16_d16_hi v170, v192 offset:2336
	ds_write_b16 v170, v193 offset:2368
	ds_write_b16_d16_hi v170, v193 offset:2400
	v_mul_f32_e32 v182, v23, v23
	v_mul_f32_e32 v183, v27, v27
	v_mul_f32_e32 v184, v31, v31
	v_mul_f32_e32 v185, v35, v35
	v_add_f32_e32 v186, v182, v183
	v_add_f32_e32 v186, v186, v184
	v_add_f32_e32 v186, v186, v185
	s_nop 1
	v_add_f32_dpp v186, v186, v186 quad_perm:[1,0,3,2] row_mask:0xf bank_mask:0xf
	s_nop 1
	v_add_f32_dpp v186, v186, v186 quad_perm:[2,3,0,1] row_mask:0xf bank_mask:0xf
	s_nop 1
	v_add_f32_dpp v186, v186, v186 row_half_mirror row_mask:0xf bank_mask:0xf
	s_nop 1
	v_add_f32_dpp v186, v186, v186 row_mirror row_mask:0xf bank_mask:0xf
	v_fmamk_f32 v186, v186, 0x3c800000, v173
	v_rsq_f32_e32 v186, v186
	s_nop 0
	v_mul_f32_e32 v187, v178, v186
	v_mul_f32_e32 v188, v179, v186
	v_mul_f32_e32 v189, v180, v186
	v_mul_f32_e32 v190, v181, v186
	v_mul_f32_e32 v182, v23, v187
	v_mul_f32_e32 v183, v27, v188
	v_mul_f32_e32 v184, v31, v189
	v_mul_f32_e32 v185, v35, v190
	v_mul_f32_e32 v186, v175, v183
	v_mul_f32_e32 v187, v176, v183
	v_fma_f32 v188, v176, v182, -v186
	v_fma_f32 v189, v175, v182, v187
	v_mul_f32_e32 v186, v217, v185
	v_mul_f32_e32 v187, v243, v185
	v_fma_f32 v190, v243, v184, -v186
	v_fma_f32 v191, v217, v184, v187
	v_cvt_pk_bf16_f32 v192, v188, v189
	v_cvt_pk_bf16_f32 v193, v190, v191
	ds_write_b16 v170, v192 offset:2448
	ds_write_b16_d16_hi v170, v192 offset:2480
	ds_write_b16 v170, v193 offset:2512
	ds_write_b16_d16_hi v170, v193 offset:2544
	v_mul_f32_e32 v182, v24, v24
	v_mul_f32_e32 v183, v28, v28
	v_mul_f32_e32 v184, v32, v32
	v_mul_f32_e32 v185, v36, v36
	v_add_f32_e32 v186, v182, v183
	v_add_f32_e32 v186, v186, v184
	v_add_f32_e32 v186, v186, v185
	s_nop 1
	v_add_f32_dpp v186, v186, v186 quad_perm:[1,0,3,2] row_mask:0xf bank_mask:0xf
	s_nop 1
	v_add_f32_dpp v186, v186, v186 quad_perm:[2,3,0,1] row_mask:0xf bank_mask:0xf
	s_nop 1
	v_add_f32_dpp v186, v186, v186 row_half_mirror row_mask:0xf bank_mask:0xf
	s_nop 1
	v_add_f32_dpp v186, v186, v186 row_mirror row_mask:0xf bank_mask:0xf
	v_fmamk_f32 v186, v186, 0x3c800000, v173
	v_rsq_f32_e32 v186, v186
	s_nop 0
	v_mul_f32_e32 v187, v178, v186
	v_mul_f32_e32 v188, v179, v186
	v_mul_f32_e32 v189, v180, v186
	v_mul_f32_e32 v190, v181, v186
	v_mul_f32_e32 v182, v24, v187
	v_mul_f32_e32 v183, v28, v188
	v_mul_f32_e32 v184, v32, v189
	v_mul_f32_e32 v185, v36, v190
	v_mul_f32_e32 v186, v175, v183
	v_mul_f32_e32 v187, v176, v183
	v_fma_f32 v188, v176, v182, -v186
	v_fma_f32 v189, v175, v182, v187
	v_mul_f32_e32 v186, v218, v185
	v_mul_f32_e32 v187, v244, v185
	v_fma_f32 v190, v244, v184, -v186
	v_fma_f32 v191, v218, v184, v187
	v_cvt_pk_bf16_f32 v192, v188, v189
	v_cvt_pk_bf16_f32 v193, v190, v191
	ds_write_b16 v170, v192 offset:2592
	ds_write_b16_d16_hi v170, v192 offset:2624
	ds_write_b16 v170, v193 offset:2656
	ds_write_b16_d16_hi v170, v193 offset:2688
	v_mul_f32_e32 v182, v25, v25
	v_mul_f32_e32 v183, v29, v29
	v_mul_f32_e32 v184, v33, v33
	v_mul_f32_e32 v185, v37, v37
	v_add_f32_e32 v186, v182, v183
	v_add_f32_e32 v186, v186, v184
	v_add_f32_e32 v186, v186, v185
	s_nop 1
	v_add_f32_dpp v186, v186, v186 quad_perm:[1,0,3,2] row_mask:0xf bank_mask:0xf
	s_nop 1
	v_add_f32_dpp v186, v186, v186 quad_perm:[2,3,0,1] row_mask:0xf bank_mask:0xf
	s_nop 1
	v_add_f32_dpp v186, v186, v186 row_half_mirror row_mask:0xf bank_mask:0xf
	s_nop 1
	v_add_f32_dpp v186, v186, v186 row_mirror row_mask:0xf bank_mask:0xf
	v_fmamk_f32 v186, v186, 0x3c800000, v173
	v_rsq_f32_e32 v186, v186
	s_nop 0
	v_mul_f32_e32 v187, v178, v186
	v_mul_f32_e32 v188, v179, v186
	v_mul_f32_e32 v189, v180, v186
	v_mul_f32_e32 v190, v181, v186
	v_mul_f32_e32 v182, v25, v187
	v_mul_f32_e32 v183, v29, v188
	v_mul_f32_e32 v184, v33, v189
	v_mul_f32_e32 v185, v37, v190
	v_mul_f32_e32 v186, v175, v183
	v_mul_f32_e32 v187, v176, v183
	v_fma_f32 v188, v176, v182, -v186
	v_fma_f32 v189, v175, v182, v187
	v_mul_f32_e32 v186, v219, v185
	v_mul_f32_e32 v187, v245, v185
	v_fma_f32 v190, v245, v184, -v186
	v_fma_f32 v191, v219, v184, v187
	v_cvt_pk_bf16_f32 v192, v188, v189
	v_cvt_pk_bf16_f32 v193, v190, v191
	ds_write_b16 v170, v192 offset:2736
	ds_write_b16_d16_hi v170, v192 offset:2768
	ds_write_b16 v170, v193 offset:2800
; template <int EPI>
; DI void gemm_phase(const P& p, int l, const u16* __restrict__ A, const u16* __restrict__ Bt, int mpx, char* lds) {
;     ...
;           float v0 = acc[hf * 4 + mi][0][j], v1 = acc[hf * 4 + mi][1][j], v2 = acc[hf * 4 + mi][2][j], v3 = acc[hf * 4 + mi][3][j];
;           const int rowl = mi * 16 + g * 4 + j;
;           const int s = tokw + hf * 64 + rowl;
;           if (tr == 1) {
;             v0 = silu(v0); v1 = silu(v1); v2 = silu(v2); v3 = silu(v3);
;           } else if (tr == 3) {
;             if (donorm) {
;               float ss = v0 * v0 + v1 * v1 + v2 * v2 + v3 * v3;
;               ss += __shfl_xor(ss, 1);
;               ss += __shfl_xor(ss, 2);
;               ss += __shfl_xor(ss, 4);
;               ss += __shfl_xor(ss, 8);
;               const float inv = rsqrtf(ss * (1.f / 64.f) + 1e-6f);
;               v0 *= inv * gv0; v1 *= inv * gv1; v2 *= inv * gv2; v3 *= inv * gv3;
;             }
;             if (dorope) {
;               float sr, cr, sc, cc;
;               sincos_rev((float)(s >> 6) * invf64, sr, cr);
;               sincos_rev((float)(s & 63) * invf64, sc, cc);
;               const float a1 = v0, a2 = v1, b1 = v2, b2 = v3;
;               v0 = a1 * cr - a2 * sr;
;               v1 = a2 * cr + a1 * sr;
;               v2 = b1 * cc - b2 * sc;
;               v3 = b2 * cc + b1 * sc;
;             }
;           } else if (tr == 4) {
;             float sr, cr, sc, cc;
;             sincos_rev((float)(s >> 6) * invf32, sr, cr);
;             sincos_rev((float)(s & 63) * invf32, sc, cc);
;             const float p0 = __shfl_xor(v0, 8), p1 = __shfl_xor(v1, 8), p2 = __shfl_xor(v2, 8), p3 = __shfl_xor(v3, 8);
;             v0 = lo8 ? (v0 * cr - p0 * sr) : (v0 * cr + p0 * sr);
;             v1 = lo8 ? (v1 * cc - p1 * sc) : (v1 * cc + p1 * sc);
;             v2 = lo8 ? (v2 * cr - p2 * sr) : (v2 * cr + p2 * sr);
;             v3 = lo8 ? (v3 * cc - p3 * sc) : (v3 * cc + p3 * sc);
;           }
;           const unsigned u01 = pack2(v0, v1), u23 = pack2(v2, v3);
;           if (kind == 1) {
;             Tl[(0 * 16 + r) * 72 + rowl] = (u16)u01;
;             Tl[(1 * 16 + r) * 72 + rowl] = (u16)(u01 >> 16);
;             Tl[(2 * 16 + r) * 72 + rowl] = (u16)u23;
;             Tl[(3 * 16 + r) * 72 + rowl] = (u16)(u23 >> 16);
;           } else if (tr == 2) {
;             Tl[rowl * 72 + 0 * 16 + r] = f2h(v0);
	ds_write_b16_d16_hi v170, v193 offset:2832
	v_mul_f32_e32 v182, v38, v38
	v_mul_f32_e32 v183, v42, v42
	v_mul_f32_e32 v184, v46, v46
	v_mul_f32_e32 v185, v50, v50
	v_add_f32_e32 v186, v182, v183
	v_add_f32_e32 v186, v186, v184
	v_add_f32_e32 v186, v186, v185
	s_nop 1
	v_add_f32_dpp v186, v186, v186 quad_perm:[1,0,3,2] row_mask:0xf bank_mask:0xf
	s_nop 1
	v_add_f32_dpp v186, v186, v186 quad_perm:[2,3,0,1] row_mask:0xf bank_mask:0xf
	s_nop 1
	v_add_f32_dpp v186, v186, v186 row_half_mirror row_mask:0xf bank_mask:0xf
	s_nop 1
	v_add_f32_dpp v186, v186, v186 row_mirror row_mask:0xf bank_mask:0xf
	v_fmamk_f32 v186, v186, 0x3c800000, v173
	v_rsq_f32_e32 v186, v186
	s_nop 0
	v_mul_f32_e32 v187, v178, v186
	v_mul_f32_e32 v188, v179, v186
	v_mul_f32_e32 v189, v180, v186
	v_mul_f32_e32 v190, v181, v186
	v_mul_f32_e32 v182, v38, v187
	v_mul_f32_e32 v183, v42, v188
	v_mul_f32_e32 v184, v46, v189
	v_mul_f32_e32 v185, v50, v190
	v_mul_f32_e32 v186, v175, v183
	v_mul_f32_e32 v187, v176, v183
	v_fma_f32 v188, v176, v182, -v186
	v_fma_f32 v189, v175, v182, v187
	v_mul_f32_e32 v186, v220, v185
	v_mul_f32_e32 v187, v246, v185
	v_fma_f32 v190, v246, v184, -v186
	v_fma_f32 v191, v220, v184, v187
	v_cvt_pk_bf16_f32 v192, v188, v189
	v_cvt_pk_bf16_f32 v193, v190, v191
	ds_write_b16 v170, v192 offset:4608
	ds_write_b16_d16_hi v170, v192 offset:4640
	ds_write_b16 v170, v193 offset:4672
	ds_write_b16_d16_hi v170, v193 offset:4704
	v_mul_f32_e32 v182, v39, v39
	v_mul_f32_e32 v183, v43, v43
	v_mul_f32_e32 v184, v47, v47
	v_mul_f32_e32 v185, v51, v51
	v_add_f32_e32 v186, v182, v183
	v_add_f32_e32 v186, v186, v184
	v_add_f32_e32 v186, v186, v185
	s_nop 1
	v_add_f32_dpp v186, v186, v186 quad_perm:[1,0,3,2] row_mask:0xf bank_mask:0xf
	s_nop 1
	v_add_f32_dpp v186, v186, v186 quad_perm:[2,3,0,1] row_mask:0xf bank_mask:0xf
	s_nop 1
	v_add_f32_dpp v186, v186, v186 row_half_mirror row_mask:0xf bank_mask:0xf
	s_nop 1
	v_add_f32_dpp v186, v186, v186 row_mirror row_mask:0xf bank_mask:0xf
	v_fmamk_f32 v186, v186, 0x3c800000, v173
	v_rsq_f32_e32 v186, v186
	s_nop 0
	v_mul_f32_e32 v187, v178, v186
	v_mul_f32_e32 v188, v179, v186
	v_mul_f32_e32 v189, v180, v186
	v_mul_f32_e32 v190, v181, v186
	v_mul_f32_e32 v182, v39, v187
	v_mul_f32_e32 v183, v43, v188
	v_mul_f32_e32 v184, v47, v189
	v_mul_f32_e32 v185, v51, v190
	v_mul_f32_e32 v186, v175, v183
	v_mul_f32_e32 v187, v176, v183
	v_fma_f32 v188, v176, v182, -v186
	v_fma_f32 v189, v175, v182, v187
	v_mul_f32_e32 v186, v221, v185
	v_mul_f32_e32 v187, v247, v185
	v_fma_f32 v190, v247, v184, -v186
	v_fma_f32 v191, v221, v184, v187
	v_cvt_pk_bf16_f32 v192, v188, v189
	v_cvt_pk_bf16_f32 v193, v190, v191
	ds_write_b16 v170, v192 offset:4752
	ds_write_b16_d16_hi v170, v192 offset:4784
	ds_write_b16 v170, v193 offset:4816
	ds_write_b16_d16_hi v170, v193 offset:4848
	v_mul_f32_e32 v182, v40, v40
	v_mul_f32_e32 v183, v44, v44
	v_mul_f32_e32 v184, v48, v48
	v_mul_f32_e32 v185, v52, v52
	v_add_f32_e32 v186, v182, v183
	v_add_f32_e32 v186, v186, v184
	v_add_f32_e32 v186, v186, v185
	s_nop 1
	v_add_f32_dpp v186, v186, v186 quad_perm:[1,0,3,2] row_mask:0xf bank_mask:0xf
	s_nop 1
	v_add_f32_dpp v186, v186, v186 quad_perm:[2,3,0,1] row_mask:0xf bank_mask:0xf
	s_nop 1
	v_add_f32_dpp v186, v186, v186 row_half_mirror row_mask:0xf bank_mask:0xf
	s_nop 1
	v_add_f32_dpp v186, v186, v186 row_mirror row_mask:0xf bank_mask:0xf
	v_fmamk_f32 v186, v186, 0x3c800000, v173
	v_rsq_f32_e32 v186, v186
	s_nop 0
	v_mul_f32_e32 v187, v178, v186
	v_mul_f32_e32 v188, v179, v186
	v_mul_f32_e32 v189, v180, v186
	v_mul_f32_e32 v190, v181, v186
	v_mul_f32_e32 v182, v40, v187
	v_mul_f32_e32 v183, v44, v188
	v_mul_f32_e32 v184, v48, v189
	v_mul_f32_e32 v185, v52, v190
	v_mul_f32_e32 v186, v175, v183
	v_mul_f32_e32 v187, v176, v183
	v_fma_f32 v188, v176, v182, -v186
	v_fma_f32 v189, v175, v182, v187
	v_mul_f32_e32 v186, v222, v185
	v_mul_f32_e32 v187, v248, v185
	v_fma_f32 v190, v248, v184, -v186
	v_fma_f32 v191, v222, v184, v187
	v_cvt_pk_bf16_f32 v192, v188, v189
	v_cvt_pk_bf16_f32 v193, v190, v191
	ds_write_b16 v170, v192 offset:4896
	ds_write_b16_d16_hi v170, v192 offset:4928
	ds_write_b16 v170, v193 offset:4960
	ds_write_b16_d16_hi v170, v193 offset:4992
	v_mul_f32_e32 v182, v41, v41
	v_mul_f32_e32 v183, v45, v45
	v_mul_f32_e32 v184, v49, v49
	v_mul_f32_e32 v185, v53, v53
	v_add_f32_e32 v186, v182, v183
	v_add_f32_e32 v186, v186, v184
	v_add_f32_e32 v186, v186, v185
	s_nop 1
	v_add_f32_dpp v186, v186, v186 quad_perm:[1,0,3,2] row_mask:0xf bank_mask:0xf
	s_nop 1
	v_add_f32_dpp v186, v186, v186 quad_perm:[2,3,0,1] row_mask:0xf bank_mask:0xf
	s_nop 1
	v_add_f32_dpp v186, v186, v186 row_half_mirror row_mask:0xf bank_mask:0xf
	s_nop 1
	v_add_f32_dpp v186, v186, v186 row_mirror row_mask:0xf bank_mask:0xf
	v_fmamk_f32 v186, v186, 0x3c800000, v173
	v_rsq_f32_e32 v186, v186
	s_nop 0
	v_mul_f32_e32 v187, v178, v186
	v_mul_f32_e32 v188, v179, v186
	v_mul_f32_e32 v189, v180, v186
	v_mul_f32_e32 v190, v181, v186
	v_mul_f32_e32 v182, v41, v187
	v_mul_f32_e32 v183, v45, v188
	v_mul_f32_e32 v184, v49, v189
	v_mul_f32_e32 v185, v53, v190
	v_mul_f32_e32 v186, v175, v183
	v_mul_f32_e32 v187, v176, v183
	v_fma_f32 v188, v176, v182, -v186
	v_fma_f32 v189, v175, v182, v187
	v_mul_f32_e32 v186, v223, v185
	v_mul_f32_e32 v187, v249, v185
	v_fma_f32 v190, v249, v184, -v186
	v_fma_f32 v191, v223, v184, v187
	v_cvt_pk_bf16_f32 v192, v188, v189
	v_cvt_pk_bf16_f32 v193, v190, v191
	ds_write_b16 v170, v192 offset:5040
	ds_write_b16_d16_hi v170, v192 offset:5072
	ds_write_b16 v170, v193 offset:5104
	ds_write_b16_d16_hi v170, v193 offset:5136
	v_mul_f32_e32 v182, v54, v54
	v_mul_f32_e32 v183, v58, v58
; template <int EPI>
; DI void gemm_phase(const P& p, int l, const u16* __restrict__ A, const u16* __restrict__ Bt, int mpx, char* lds) {
;     ...
;           float v0 = acc[hf * 4 + mi][0][j], v1 = acc[hf * 4 + mi][1][j], v2 = acc[hf * 4 + mi][2][j], v3 = acc[hf * 4 + mi][3][j];
;           const int rowl = mi * 16 + g * 4 + j;
;           const int s = tokw + hf * 64 + rowl;
;           if (tr == 1) {
;             v0 = silu(v0); v1 = silu(v1); v2 = silu(v2); v3 = silu(v3);
;           } else if (tr == 3) {
;             if (donorm) {
;               float ss = v0 * v0 + v1 * v1 + v2 * v2 + v3 * v3;
;               ss += __shfl_xor(ss, 1);
;               ss += __shfl_xor(ss, 2);
;               ss += __shfl_xor(ss, 4);
;               ss += __shfl_xor(ss, 8);
;               const float inv = rsqrtf(ss * (1.f / 64.f) + 1e-6f);
;               v0 *= inv * gv0; v1 *= inv * gv1; v2 *= inv * gv2; v3 *= inv * gv3;
;             }
;             if (dorope) {
;               float sr, cr, sc, cc;
;               sincos_rev((float)(s >> 6) * invf64, sr, cr);
;               sincos_rev((float)(s & 63) * invf64, sc, cc);
;               const float a1 = v0, a2 = v1, b1 = v2, b2 = v3;
;               v0 = a1 * cr - a2 * sr;
;               v1 = a2 * cr + a1 * sr;
;               v2 = b1 * cc - b2 * sc;
;               v3 = b2 * cc + b1 * sc;
;             }
;           } else if (tr == 4) {
;             float sr, cr, sc, cc;
;             sincos_rev((float)(s >> 6) * invf32, sr, cr);
;             sincos_rev((float)(s & 63) * invf32, sc, cc);
;             const float p0 = __shfl_xor(v0, 8), p1 = __shfl_xor(v1, 8), p2 = __shfl_xor(v2, 8), p3 = __shfl_xor(v3, 8);
;             v0 = lo8 ? (v0 * cr - p0 * sr) : (v0 * cr + p0 * sr);
;             v1 = lo8 ? (v1 * cc - p1 * sc) : (v1 * cc + p1 * sc);
;             v2 = lo8 ? (v2 * cr - p2 * sr) : (v2 * cr + p2 * sr);
;             v3 = lo8 ? (v3 * cc - p3 * sc) : (v3 * cc + p3 * sc);
;           }
;           const unsigned u01 = pack2(v0, v1), u23 = pack2(v2, v3);
;           if (kind == 1) {
;             Tl[(0 * 16 + r) * 72 + rowl] = (u16)u01;
;             Tl[(1 * 16 + r) * 72 + rowl] = (u16)(u01 >> 16);
;             Tl[(2 * 16 + r) * 72 + rowl] = (u16)u23;
;             Tl[(3 * 16 + r) * 72 + rowl] = (u16)(u23 >> 16);
;           } else if (tr == 2) {
;             Tl[rowl * 72 + 0 * 16 + r] = f2h(v0);
	v_mul_f32_e32 v184, v62, v62
	v_mul_f32_e32 v185, v66, v66
	v_add_f32_e32 v186, v182, v183
	v_add_f32_e32 v186, v186, v184
	v_add_f32_e32 v186, v186, v185
	s_nop 1
	v_add_f32_dpp v186, v186, v186 quad_perm:[1,0,3,2] row_mask:0xf bank_mask:0xf
	s_nop 1
	v_add_f32_dpp v186, v186, v186 quad_perm:[2,3,0,1] row_mask:0xf bank_mask:0xf
	s_nop 1
	v_add_f32_dpp v186, v186, v186 row_half_mirror row_mask:0xf bank_mask:0xf
	s_nop 1
	v_add_f32_dpp v186, v186, v186 row_mirror row_mask:0xf bank_mask:0xf
	v_fmamk_f32 v186, v186, 0x3c800000, v173
	v_rsq_f32_e32 v186, v186
	s_nop 0
	v_mul_f32_e32 v187, v178, v186
	v_mul_f32_e32 v188, v179, v186
	v_mul_f32_e32 v189, v180, v186
	v_mul_f32_e32 v190, v181, v186
	v_mul_f32_e32 v182, v54, v187
	v_mul_f32_e32 v183, v58, v188
	v_mul_f32_e32 v184, v62, v189
	v_mul_f32_e32 v185, v66, v190
	v_mul_f32_e32 v186, v175, v183
	v_mul_f32_e32 v187, v176, v183
	v_fma_f32 v188, v176, v182, -v186
	v_fma_f32 v189, v175, v182, v187
	v_mul_f32_e32 v186, v234, v185
	v_mul_f32_e32 v187, v250, v185
	v_fma_f32 v190, v250, v184, -v186
	v_fma_f32 v191, v234, v184, v187
	v_cvt_pk_bf16_f32 v192, v188, v189
	v_cvt_pk_bf16_f32 v193, v190, v191
	ds_write_b16 v170, v192 offset:6912
	ds_write_b16_d16_hi v170, v192 offset:6944
	ds_write_b16 v170, v193 offset:6976
	ds_write_b16_d16_hi v170, v193 offset:7008
	v_mul_f32_e32 v182, v55, v55
	v_mul_f32_e32 v183, v59, v59
	v_mul_f32_e32 v184, v63, v63
	v_mul_f32_e32 v185, v67, v67
	v_add_f32_e32 v186, v182, v183
	v_add_f32_e32 v186, v186, v184
	v_add_f32_e32 v186, v186, v185
	s_nop 1
	v_add_f32_dpp v186, v186, v186 quad_perm:[1,0,3,2] row_mask:0xf bank_mask:0xf
	s_nop 1
	v_add_f32_dpp v186, v186, v186 quad_perm:[2,3,0,1] row_mask:0xf bank_mask:0xf
	s_nop 1
	v_add_f32_dpp v186, v186, v186 row_half_mirror row_mask:0xf bank_mask:0xf
	s_nop 1
	v_add_f32_dpp v186, v186, v186 row_mirror row_mask:0xf bank_mask:0xf
	v_fmamk_f32 v186, v186, 0x3c800000, v173
	v_rsq_f32_e32 v186, v186
	s_nop 0
	v_mul_f32_e32 v187, v178, v186
	v_mul_f32_e32 v188, v179, v186
	v_mul_f32_e32 v189, v180, v186
	v_mul_f32_e32 v190, v181, v186
	v_mul_f32_e32 v182, v55, v187
	v_mul_f32_e32 v183, v59, v188
	v_mul_f32_e32 v184, v63, v189
	v_mul_f32_e32 v185, v67, v190
	v_mul_f32_e32 v186, v175, v183
	v_mul_f32_e32 v187, v176, v183
	v_fma_f32 v188, v176, v182, -v186
	v_fma_f32 v189, v175, v182, v187
	v_mul_f32_e32 v186, v235, v185
	v_mul_f32_e32 v187, v251, v185
	v_fma_f32 v190, v251, v184, -v186
	v_fma_f32 v191, v235, v184, v187
	v_cvt_pk_bf16_f32 v192, v188, v189
	v_cvt_pk_bf16_f32 v193, v190, v191
	ds_write_b16 v170, v192 offset:7056
	ds_write_b16_d16_hi v170, v192 offset:7088
	ds_write_b16 v170, v193 offset:7120
	ds_write_b16_d16_hi v170, v193 offset:7152
	v_mul_f32_e32 v182, v56, v56
	v_mul_f32_e32 v183, v60, v60
	v_mul_f32_e32 v184, v64, v64
	v_mul_f32_e32 v185, v68, v68
	v_add_f32_e32 v186, v182, v183
	v_add_f32_e32 v186, v186, v184
	v_add_f32_e32 v186, v186, v185
	s_nop 1
	v_add_f32_dpp v186, v186, v186 quad_perm:[1,0,3,2] row_mask:0xf bank_mask:0xf
	s_nop 1
	v_add_f32_dpp v186, v186, v186 quad_perm:[2,3,0,1] row_mask:0xf bank_mask:0xf
	s_nop 1
	v_add_f32_dpp v186, v186, v186 row_half_mirror row_mask:0xf bank_mask:0xf
	s_nop 1
	v_add_f32_dpp v186, v186, v186 row_mirror row_mask:0xf bank_mask:0xf
	v_fmamk_f32 v186, v186, 0x3c800000, v173
	v_rsq_f32_e32 v186, v186
	s_nop 0
	v_mul_f32_e32 v187, v178, v186
	v_mul_f32_e32 v188, v179, v186
	v_mul_f32_e32 v189, v180, v186
	v_mul_f32_e32 v190, v181, v186
	v_mul_f32_e32 v182, v56, v187
	v_mul_f32_e32 v183, v60, v188
	v_mul_f32_e32 v184, v64, v189
	v_mul_f32_e32 v185, v68, v190
	v_mul_f32_e32 v186, v175, v183
	v_mul_f32_e32 v187, v176, v183
	v_fma_f32 v188, v176, v182, -v186
	v_fma_f32 v189, v175, v182, v187
	v_mul_f32_e32 v186, v236, v185
	v_mul_f32_e32 v187, v252, v185
	v_fma_f32 v190, v252, v184, -v186
	v_fma_f32 v191, v236, v184, v187
	v_cvt_pk_bf16_f32 v192, v188, v189
	v_cvt_pk_bf16_f32 v193, v190, v191
	ds_write_b16 v170, v192 offset:7200
	ds_write_b16_d16_hi v170, v192 offset:7232
	ds_write_b16 v170, v193 offset:7264
	ds_write_b16_d16_hi v170, v193 offset:7296
	v_mul_f32_e32 v182, v57, v57
	v_mul_f32_e32 v183, v61, v61
	v_mul_f32_e32 v184, v65, v65
	v_mul_f32_e32 v185, v69, v69
	v_add_f32_e32 v186, v182, v183
	v_add_f32_e32 v186, v186, v184
	v_add_f32_e32 v186, v186, v185
	s_nop 1
	v_add_f32_dpp v186, v186, v186 quad_perm:[1,0,3,2] row_mask:0xf bank_mask:0xf
	s_nop 1
	v_add_f32_dpp v186, v186, v186 quad_perm:[2,3,0,1] row_mask:0xf bank_mask:0xf
	s_nop 1
	v_add_f32_dpp v186, v186, v186 row_half_mirror row_mask:0xf bank_mask:0xf
	s_nop 1
	v_add_f32_dpp v186, v186, v186 row_mirror row_mask:0xf bank_mask:0xf
	v_fmamk_f32 v186, v186, 0x3c800000, v173
	v_rsq_f32_e32 v186, v186
	s_nop 0
	v_mul_f32_e32 v187, v178, v186
	v_mul_f32_e32 v188, v179, v186
	v_mul_f32_e32 v189, v180, v186
	v_mul_f32_e32 v190, v181, v186
	v_mul_f32_e32 v182, v57, v187
	v_mul_f32_e32 v183, v61, v188
	v_mul_f32_e32 v184, v65, v189
	v_mul_f32_e32 v185, v69, v190
	v_mul_f32_e32 v186, v175, v183
	v_mul_f32_e32 v187, v176, v183
	v_fma_f32 v188, v176, v182, -v186
	v_fma_f32 v189, v175, v182, v187
	v_mul_f32_e32 v186, v237, v185
	v_mul_f32_e32 v187, v253, v185
	v_fma_f32 v190, v253, v184, -v186
	v_fma_f32 v191, v237, v184, v187
	v_cvt_pk_bf16_f32 v192, v188, v189
	v_cvt_pk_bf16_f32 v193, v190, v191
	ds_write_b16 v170, v192 offset:7344
	ds_write_b16_d16_hi v170, v192 offset:7376
	ds_write_b16 v170, v193 offset:7408
	ds_write_b16_d16_hi v170, v193 offset:7440
	ds_read_b128 v[130:133], v171 offset:0
	ds_read_b128 v[134:137], v171 offset:1152
	ds_read_b128 v[138:141], v171 offset:2304
	ds_read_b128 v[142:145], v171 offset:3456
	ds_read_b128 v[146:149], v171 offset:4608
	ds_read_b128 v[150:153], v171 offset:5760
	ds_read_b128 v[154:157], v171 offset:6912
	ds_read_b128 v[158:161], v171 offset:8064
	s_waitcnt lgkmcnt(7)
; template <int EPI>
; DI void gemm_phase(const P& p, int l, const u16* __restrict__ A, const u16* __restrict__ Bt, int mpx, char* lds) {
;     ...
;           float v0 = acc[hf * 4 + mi][0][j], v1 = acc[hf * 4 + mi][1][j], v2 = acc[hf * 4 + mi][2][j], v3 = acc[hf * 4 + mi][3][j];
;           const int rowl = mi * 16 + g * 4 + j;
;           const int s = tokw + hf * 64 + rowl;
;           if (tr == 1) {
;             v0 = silu(v0); v1 = silu(v1); v2 = silu(v2); v3 = silu(v3);
;           } else if (tr == 3) {
;             if (donorm) {
;               float ss = v0 * v0 + v1 * v1 + v2 * v2 + v3 * v3;
;               ss += __shfl_xor(ss, 1);
;               ss += __shfl_xor(ss, 2);
;               ss += __shfl_xor(ss, 4);
;               ss += __shfl_xor(ss, 8);
;               const float inv = rsqrtf(ss * (1.f / 64.f) + 1e-6f);
;               v0 *= inv * gv0; v1 *= inv * gv1; v2 *= inv * gv2; v3 *= inv * gv3;
;             }
;             if (dorope) {
;               float sr, cr, sc, cc;
;               sincos_rev((float)(s >> 6) * invf64, sr, cr);
;               sincos_rev((float)(s & 63) * invf64, sc, cc);
;               const float a1 = v0, a2 = v1, b1 = v2, b2 = v3;
;               v0 = a1 * cr - a2 * sr;
;               v1 = a2 * cr + a1 * sr;
;               v2 = b1 * cc - b2 * sc;
;               v3 = b2 * cc + b1 * sc;
;             }
;           } else if (tr == 4) {
;             float sr, cr, sc, cc;
;             sincos_rev((float)(s >> 6) * invf32, sr, cr);
;             sincos_rev((float)(s & 63) * invf32, sc, cc);
;             const float p0 = __shfl_xor(v0, 8), p1 = __shfl_xor(v1, 8), p2 = __shfl_xor(v2, 8), p3 = __shfl_xor(v3, 8);
;             v0 = lo8 ? (v0 * cr - p0 * sr) : (v0 * cr + p0 * sr);
;             v1 = lo8 ? (v1 * cc - p1 * sc) : (v1 * cc + p1 * sc);
;             v2 = lo8 ? (v2 * cr - p2 * sr) : (v2 * cr + p2 * sr);
;             v3 = lo8 ? (v3 * cc - p3 * sc) : (v3 * cc + p3 * sc);
;           }
;           const unsigned u01 = pack2(v0, v1), u23 = pack2(v2, v3);
;           if (kind == 1) {
;             Tl[(0 * 16 + r) * 72 + rowl] = (u16)u01;
;     ...
;       for (int i = 0; i < 8; ++i) {
;         const int c = lane + i * 64;
;         const int row = c >> 3, cc = c & 7;
;         uint4 v = *(const uint4*)&Tl[row * 72 + cc * 8];
;         *(uint4*)(dh + (size_t)row * rstride + cc * 8) = v;
	global_store_dwordx4 v172, v[130:133], s[44:45] offset:0 sc1 nt
	s_waitcnt lgkmcnt(6)
	global_store_dwordx4 v172, v[134:137], s[44:45] offset:1024 sc1 nt
	s_waitcnt lgkmcnt(5)
	global_store_dwordx4 v172, v[138:141], s[44:45] offset:2048 sc1 nt
	s_waitcnt lgkmcnt(4)
	global_store_dwordx4 v172, v[142:145], s[44:45] offset:3072 sc1 nt
	s_waitcnt lgkmcnt(3)
	global_store_dwordx4 v172, v[146:149], s[62:63] offset:0 sc1 nt
	s_waitcnt lgkmcnt(2)
	global_store_dwordx4 v172, v[150:153], s[62:63] offset:1024 sc1 nt
	s_waitcnt lgkmcnt(1)
	global_store_dwordx4 v172, v[154:157], s[62:63] offset:2048 sc1 nt
	s_waitcnt lgkmcnt(0)
	global_store_dwordx4 v172, v[158:161], s[62:63] offset:3072 sc1 nt
	s_add_u32 s44, s44, 0x2000
	s_addc_u32 s45, s45, 0
	s_add_u32 s62, s62, 0x2000
	s_addc_u32 s63, s63, 0
	s_lshr_b32 s70, s69, 6
	s_add_i32 s70, s70, 1
	v_cvt_f32_i32_e32 v182, s70
	v_mul_f32_e32 v182, v174, v182
	v_mul_f32_e32 v183, 0.15915494, v182
	v_rndne_f32_e32 v183, v183
	v_fma_f32 v183, v182, 0.15915494, -v183
	v_sin_f32_e32 v175, v183
	v_cos_f32_e32 v176, v183
	v_mul_f32_e32 v182, v70, v70
	v_mul_f32_e32 v183, v74, v74
	v_mul_f32_e32 v184, v78, v78
	v_mul_f32_e32 v185, v82, v82
	v_add_f32_e32 v186, v182, v183
	v_add_f32_e32 v186, v186, v184
	v_add_f32_e32 v186, v186, v185
	s_nop 1
	v_add_f32_dpp v186, v186, v186 quad_perm:[1,0,3,2] row_mask:0xf bank_mask:0xf
	s_nop 1
	v_add_f32_dpp v186, v186, v186 quad_perm:[2,3,0,1] row_mask:0xf bank_mask:0xf
	s_nop 1
	v_add_f32_dpp v186, v186, v186 row_half_mirror row_mask:0xf bank_mask:0xf
	s_nop 1
	v_add_f32_dpp v186, v186, v186 row_mirror row_mask:0xf bank_mask:0xf
	v_fmamk_f32 v186, v186, 0x3c800000, v173
	v_rsq_f32_e32 v186, v186
	s_nop 0
	v_mul_f32_e32 v187, v178, v186
	v_mul_f32_e32 v188, v179, v186
	v_mul_f32_e32 v189, v180, v186
	v_mul_f32_e32 v190, v181, v186
	v_mul_f32_e32 v182, v70, v187
	v_mul_f32_e32 v183, v74, v188
	v_mul_f32_e32 v184, v78, v189
	v_mul_f32_e32 v185, v82, v190
	v_mul_f32_e32 v186, v175, v183
	v_mul_f32_e32 v187, v176, v183
	v_fma_f32 v188, v176, v182, -v186
	v_fma_f32 v189, v175, v182, v187
	v_mul_f32_e32 v186, v212, v185
	v_mul_f32_e32 v187, v238, v185
	v_fma_f32 v190, v238, v184, -v186
	v_fma_f32 v191, v212, v184, v187
	v_cvt_pk_bf16_f32 v192, v188, v189
	v_cvt_pk_bf16_f32 v193, v190, v191
	ds_write_b16 v170, v192 offset:0
	ds_write_b16_d16_hi v170, v192 offset:32
	ds_write_b16 v170, v193 offset:64
	ds_write_b16_d16_hi v170, v193 offset:96
	v_mul_f32_e32 v182, v71, v71
	v_mul_f32_e32 v183, v75, v75
	v_mul_f32_e32 v184, v79, v79
	v_mul_f32_e32 v185, v83, v83
	v_add_f32_e32 v186, v182, v183
	v_add_f32_e32 v186, v186, v184
	v_add_f32_e32 v186, v186, v185
	s_nop 1
	v_add_f32_dpp v186, v186, v186 quad_perm:[1,0,3,2] row_mask:0xf bank_mask:0xf
	s_nop 1
	v_add_f32_dpp v186, v186, v186 quad_perm:[2,3,0,1] row_mask:0xf bank_mask:0xf
	s_nop 1
	v_add_f32_dpp v186, v186, v186 row_half_mirror row_mask:0xf bank_mask:0xf
	s_nop 1
	v_add_f32_dpp v186, v186, v186 row_mirror row_mask:0xf bank_mask:0xf
	v_fmamk_f32 v186, v186, 0x3c800000, v173
	v_rsq_f32_e32 v186, v186
	s_nop 0
	v_mul_f32_e32 v187, v178, v186
	v_mul_f32_e32 v188, v179, v186
	v_mul_f32_e32 v189, v180, v186
	v_mul_f32_e32 v190, v181, v186
	v_mul_f32_e32 v182, v71, v187
	v_mul_f32_e32 v183, v75, v188
	v_mul_f32_e32 v184, v79, v189
	v_mul_f32_e32 v185, v83, v190
	v_mul_f32_e32 v186, v175, v183
	v_mul_f32_e32 v187, v176, v183
	v_fma_f32 v188, v176, v182, -v186
	v_fma_f32 v189, v175, v182, v187
	v_mul_f32_e32 v186, v213, v185
	v_mul_f32_e32 v187, v239, v185
	v_fma_f32 v190, v239, v184, -v186
	v_fma_f32 v191, v213, v184, v187
	v_cvt_pk_bf16_f32 v192, v188, v189
	v_cvt_pk_bf16_f32 v193, v190, v191
	ds_write_b16 v170, v192 offset:144
	ds_write_b16_d16_hi v170, v192 offset:176
	ds_write_b16 v170, v193 offset:208
	ds_write_b16_d16_hi v170, v193 offset:240
	v_mul_f32_e32 v182, v72, v72
	v_mul_f32_e32 v183, v76, v76
	v_mul_f32_e32 v184, v80, v80
	v_mul_f32_e32 v185, v84, v84
	v_add_f32_e32 v186, v182, v183
	v_add_f32_e32 v186, v186, v184
	v_add_f32_e32 v186, v186, v185
	s_nop 1
	v_add_f32_dpp v186, v186, v186 quad_perm:[1,0,3,2] row_mask:0xf bank_mask:0xf
	s_nop 1
	v_add_f32_dpp v186, v186, v186 quad_perm:[2,3,0,1] row_mask:0xf bank_mask:0xf
	s_nop 1
	v_add_f32_dpp v186, v186, v186 row_half_mirror row_mask:0xf bank_mask:0xf
	s_nop 1
	v_add_f32_dpp v186, v186, v186 row_mirror row_mask:0xf bank_mask:0xf
	v_fmamk_f32 v186, v186, 0x3c800000, v173
	v_rsq_f32_e32 v186, v186
	s_nop 0
	v_mul_f32_e32 v187, v178, v186
	v_mul_f32_e32 v188, v179, v186
	v_mul_f32_e32 v189, v180, v186
	v_mul_f32_e32 v190, v181, v186
	v_mul_f32_e32 v182, v72, v187
	v_mul_f32_e32 v183, v76, v188
	v_mul_f32_e32 v184, v80, v189
	v_mul_f32_e32 v185, v84, v190
	v_mul_f32_e32 v186, v175, v183
	v_mul_f32_e32 v187, v176, v183
	v_fma_f32 v188, v176, v182, -v186
	v_fma_f32 v189, v175, v182, v187
	v_mul_f32_e32 v186, v214, v185
	v_mul_f32_e32 v187, v240, v185
	v_fma_f32 v190, v240, v184, -v186
	v_fma_f32 v191, v214, v184, v187
	v_cvt_pk_bf16_f32 v192, v188, v189
	v_cvt_pk_bf16_f32 v193, v190, v191
	ds_write_b16 v170, v192 offset:288
	ds_write_b16_d16_hi v170, v192 offset:320
	ds_write_b16 v170, v193 offset:352
	ds_write_b16_d16_hi v170, v193 offset:384
	v_mul_f32_e32 v182, v73, v73
	v_mul_f32_e32 v183, v77, v77
	v_mul_f32_e32 v184, v81, v81
	v_mul_f32_e32 v185, v85, v85
	v_add_f32_e32 v186, v182, v183
	v_add_f32_e32 v186, v186, v184
	v_add_f32_e32 v186, v186, v185
	s_nop 1
	v_add_f32_dpp v186, v186, v186 quad_perm:[1,0,3,2] row_mask:0xf bank_mask:0xf
	s_nop 1
	v_add_f32_dpp v186, v186, v186 quad_perm:[2,3,0,1] row_mask:0xf bank_mask:0xf
	s_nop 1
	v_add_f32_dpp v186, v186, v186 row_half_mirror row_mask:0xf bank_mask:0xf
; template <int EPI>
; DI void gemm_phase(const P& p, int l, const u16* __restrict__ A, const u16* __restrict__ Bt, int mpx, char* lds) {
;     ...
;           float v0 = acc[hf * 4 + mi][0][j], v1 = acc[hf * 4 + mi][1][j], v2 = acc[hf * 4 + mi][2][j], v3 = acc[hf * 4 + mi][3][j];
;           const int rowl = mi * 16 + g * 4 + j;
;           const int s = tokw + hf * 64 + rowl;
;           if (tr == 1) {
;             v0 = silu(v0); v1 = silu(v1); v2 = silu(v2); v3 = silu(v3);
;           } else if (tr == 3) {
;             if (donorm) {
;               float ss = v0 * v0 + v1 * v1 + v2 * v2 + v3 * v3;
;               ss += __shfl_xor(ss, 1);
;               ss += __shfl_xor(ss, 2);
;               ss += __shfl_xor(ss, 4);
;               ss += __shfl_xor(ss, 8);
;               const float inv = rsqrtf(ss * (1.f / 64.f) + 1e-6f);
;               v0 *= inv * gv0; v1 *= inv * gv1; v2 *= inv * gv2; v3 *= inv * gv3;
;             }
;             if (dorope) {
;               float sr, cr, sc, cc;
;               sincos_rev((float)(s >> 6) * invf64, sr, cr);
;               sincos_rev((float)(s & 63) * invf64, sc, cc);
;               const float a1 = v0, a2 = v1, b1 = v2, b2 = v3;
;               v0 = a1 * cr - a2 * sr;
;               v1 = a2 * cr + a1 * sr;
;               v2 = b1 * cc - b2 * sc;
;               v3 = b2 * cc + b1 * sc;
;             }
;           } else if (tr == 4) {
;             float sr, cr, sc, cc;
;             sincos_rev((float)(s >> 6) * invf32, sr, cr);
;             sincos_rev((float)(s & 63) * invf32, sc, cc);
;             const float p0 = __shfl_xor(v0, 8), p1 = __shfl_xor(v1, 8), p2 = __shfl_xor(v2, 8), p3 = __shfl_xor(v3, 8);
;             v0 = lo8 ? (v0 * cr - p0 * sr) : (v0 * cr + p0 * sr);
;             v1 = lo8 ? (v1 * cc - p1 * sc) : (v1 * cc + p1 * sc);
;             v2 = lo8 ? (v2 * cr - p2 * sr) : (v2 * cr + p2 * sr);
;             v3 = lo8 ? (v3 * cc - p3 * sc) : (v3 * cc + p3 * sc);
;           }
;           const unsigned u01 = pack2(v0, v1), u23 = pack2(v2, v3);
;           if (kind == 1) {
;             Tl[(0 * 16 + r) * 72 + rowl] = (u16)u01;
;             Tl[(1 * 16 + r) * 72 + rowl] = (u16)(u01 >> 16);
;             Tl[(2 * 16 + r) * 72 + rowl] = (u16)u23;
;             Tl[(3 * 16 + r) * 72 + rowl] = (u16)(u23 >> 16);
;           } else if (tr == 2) {
;             Tl[rowl * 72 + 0 * 16 + r] = f2h(v0);
	s_nop 1
	v_add_f32_dpp v186, v186, v186 row_mirror row_mask:0xf bank_mask:0xf
	v_fmamk_f32 v186, v186, 0x3c800000, v173
	v_rsq_f32_e32 v186, v186
	s_nop 0
	v_mul_f32_e32 v187, v178, v186
	v_mul_f32_e32 v188, v179, v186
	v_mul_f32_e32 v189, v180, v186
	v_mul_f32_e32 v190, v181, v186
	v_mul_f32_e32 v182, v73, v187
	v_mul_f32_e32 v183, v77, v188
	v_mul_f32_e32 v184, v81, v189
	v_mul_f32_e32 v185, v85, v190
	v_mul_f32_e32 v186, v175, v183
	v_mul_f32_e32 v187, v176, v183
	v_fma_f32 v188, v176, v182, -v186
	v_fma_f32 v189, v175, v182, v187
	v_mul_f32_e32 v186, v215, v185
	v_mul_f32_e32 v187, v241, v185
	v_fma_f32 v190, v241, v184, -v186
	v_fma_f32 v191, v215, v184, v187
	v_cvt_pk_bf16_f32 v192, v188, v189
	v_cvt_pk_bf16_f32 v193, v190, v191
	ds_write_b16 v170, v192 offset:432
	ds_write_b16_d16_hi v170, v192 offset:464
	ds_write_b16 v170, v193 offset:496
	ds_write_b16_d16_hi v170, v193 offset:528
	v_mul_f32_e32 v182, v86, v86
	v_mul_f32_e32 v183, v90, v90
	v_mul_f32_e32 v184, v94, v94
	v_mul_f32_e32 v185, v98, v98
	v_add_f32_e32 v186, v182, v183
	v_add_f32_e32 v186, v186, v184
	v_add_f32_e32 v186, v186, v185
	s_nop 1
	v_add_f32_dpp v186, v186, v186 quad_perm:[1,0,3,2] row_mask:0xf bank_mask:0xf
	s_nop 1
	v_add_f32_dpp v186, v186, v186 quad_perm:[2,3,0,1] row_mask:0xf bank_mask:0xf
	s_nop 1
	v_add_f32_dpp v186, v186, v186 row_half_mirror row_mask:0xf bank_mask:0xf
	s_nop 1
	v_add_f32_dpp v186, v186, v186 row_mirror row_mask:0xf bank_mask:0xf
	v_fmamk_f32 v186, v186, 0x3c800000, v173
	v_rsq_f32_e32 v186, v186
	s_nop 0
	v_mul_f32_e32 v187, v178, v186
	v_mul_f32_e32 v188, v179, v186
	v_mul_f32_e32 v189, v180, v186
	v_mul_f32_e32 v190, v181, v186
	v_mul_f32_e32 v182, v86, v187
	v_mul_f32_e32 v183, v90, v188
	v_mul_f32_e32 v184, v94, v189
	v_mul_f32_e32 v185, v98, v190
	v_mul_f32_e32 v186, v175, v183
	v_mul_f32_e32 v187, v176, v183
	v_fma_f32 v188, v176, v182, -v186
	v_fma_f32 v189, v175, v182, v187
	v_mul_f32_e32 v186, v216, v185
	v_mul_f32_e32 v187, v242, v185
	v_fma_f32 v190, v242, v184, -v186
	v_fma_f32 v191, v216, v184, v187
	v_cvt_pk_bf16_f32 v192, v188, v189
	v_cvt_pk_bf16_f32 v193, v190, v191
	ds_write_b16 v170, v192 offset:2304
	ds_write_b16_d16_hi v170, v192 offset:2336
	ds_write_b16 v170, v193 offset:2368
	ds_write_b16_d16_hi v170, v193 offset:2400
	v_mul_f32_e32 v182, v87, v87
	v_mul_f32_e32 v183, v91, v91
	v_mul_f32_e32 v184, v95, v95
	v_mul_f32_e32 v185, v99, v99
	v_add_f32_e32 v186, v182, v183
	v_add_f32_e32 v186, v186, v184
	v_add_f32_e32 v186, v186, v185
	s_nop 1
	v_add_f32_dpp v186, v186, v186 quad_perm:[1,0,3,2] row_mask:0xf bank_mask:0xf
	s_nop 1
	v_add_f32_dpp v186, v186, v186 quad_perm:[2,3,0,1] row_mask:0xf bank_mask:0xf
	s_nop 1
	v_add_f32_dpp v186, v186, v186 row_half_mirror row_mask:0xf bank_mask:0xf
	s_nop 1
	v_add_f32_dpp v186, v186, v186 row_mirror row_mask:0xf bank_mask:0xf
	v_fmamk_f32 v186, v186, 0x3c800000, v173
	v_rsq_f32_e32 v186, v186
	s_nop 0
	v_mul_f32_e32 v187, v178, v186
	v_mul_f32_e32 v188, v179, v186
	v_mul_f32_e32 v189, v180, v186
	v_mul_f32_e32 v190, v181, v186
	v_mul_f32_e32 v182, v87, v187
	v_mul_f32_e32 v183, v91, v188
	v_mul_f32_e32 v184, v95, v189
	v_mul_f32_e32 v185, v99, v190
	v_mul_f32_e32 v186, v175, v183
	v_mul_f32_e32 v187, v176, v183
	v_fma_f32 v188, v176, v182, -v186
	v_fma_f32 v189, v175, v182, v187
	v_mul_f32_e32 v186, v217, v185
	v_mul_f32_e32 v187, v243, v185
	v_fma_f32 v190, v243, v184, -v186
	v_fma_f32 v191, v217, v184, v187
	v_cvt_pk_bf16_f32 v192, v188, v189
	v_cvt_pk_bf16_f32 v193, v190, v191
	ds_write_b16 v170, v192 offset:2448
	ds_write_b16_d16_hi v170, v192 offset:2480
	ds_write_b16 v170, v193 offset:2512
	ds_write_b16_d16_hi v170, v193 offset:2544
	v_mul_f32_e32 v182, v88, v88
	v_mul_f32_e32 v183, v92, v92
	v_mul_f32_e32 v184, v96, v96
	v_mul_f32_e32 v185, v100, v100
	v_add_f32_e32 v186, v182, v183
	v_add_f32_e32 v186, v186, v184
	v_add_f32_e32 v186, v186, v185
	s_nop 1
	v_add_f32_dpp v186, v186, v186 quad_perm:[1,0,3,2] row_mask:0xf bank_mask:0xf
	s_nop 1
	v_add_f32_dpp v186, v186, v186 quad_perm:[2,3,0,1] row_mask:0xf bank_mask:0xf
	s_nop 1
	v_add_f32_dpp v186, v186, v186 row_half_mirror row_mask:0xf bank_mask:0xf
	s_nop 1
	v_add_f32_dpp v186, v186, v186 row_mirror row_mask:0xf bank_mask:0xf
	v_fmamk_f32 v186, v186, 0x3c800000, v173
	v_rsq_f32_e32 v186, v186
	s_nop 0
	v_mul_f32_e32 v187, v178, v186
	v_mul_f32_e32 v188, v179, v186
	v_mul_f32_e32 v189, v180, v186
	v_mul_f32_e32 v190, v181, v186
	v_mul_f32_e32 v182, v88, v187
	v_mul_f32_e32 v183, v92, v188
	v_mul_f32_e32 v184, v96, v189
	v_mul_f32_e32 v185, v100, v190
	v_mul_f32_e32 v186, v175, v183
	v_mul_f32_e32 v187, v176, v183
	v_fma_f32 v188, v176, v182, -v186
	v_fma_f32 v189, v175, v182, v187
	v_mul_f32_e32 v186, v218, v185
	v_mul_f32_e32 v187, v244, v185
	v_fma_f32 v190, v244, v184, -v186
	v_fma_f32 v191, v218, v184, v187
	v_cvt_pk_bf16_f32 v192, v188, v189
	v_cvt_pk_bf16_f32 v193, v190, v191
	ds_write_b16 v170, v192 offset:2592
	ds_write_b16_d16_hi v170, v192 offset:2624
	ds_write_b16 v170, v193 offset:2656
	ds_write_b16_d16_hi v170, v193 offset:2688
	v_mul_f32_e32 v182, v89, v89
	v_mul_f32_e32 v183, v93, v93
	v_mul_f32_e32 v184, v97, v97
	v_mul_f32_e32 v185, v101, v101
	v_add_f32_e32 v186, v182, v183
	v_add_f32_e32 v186, v186, v184
	v_add_f32_e32 v186, v186, v185
	s_nop 1
	v_add_f32_dpp v186, v186, v186 quad_perm:[1,0,3,2] row_mask:0xf bank_mask:0xf
	s_nop 1
	v_add_f32_dpp v186, v186, v186 quad_perm:[2,3,0,1] row_mask:0xf bank_mask:0xf
	s_nop 1
	v_add_f32_dpp v186, v186, v186 row_half_mirror row_mask:0xf bank_mask:0xf
	s_nop 1
	v_add_f32_dpp v186, v186, v186 row_mirror row_mask:0xf bank_mask:0xf
	v_fmamk_f32 v186, v186, 0x3c800000, v173
; template <int EPI>
; DI void gemm_phase(const P& p, int l, const u16* __restrict__ A, const u16* __restrict__ Bt, int mpx, char* lds) {
;     ...
;           float v0 = acc[hf * 4 + mi][0][j], v1 = acc[hf * 4 + mi][1][j], v2 = acc[hf * 4 + mi][2][j], v3 = acc[hf * 4 + mi][3][j];
;           const int rowl = mi * 16 + g * 4 + j;
;           const int s = tokw + hf * 64 + rowl;
;           if (tr == 1) {
;             v0 = silu(v0); v1 = silu(v1); v2 = silu(v2); v3 = silu(v3);
;           } else if (tr == 3) {
;             if (donorm) {
;               float ss = v0 * v0 + v1 * v1 + v2 * v2 + v3 * v3;
;               ss += __shfl_xor(ss, 1);
;               ss += __shfl_xor(ss, 2);
;               ss += __shfl_xor(ss, 4);
;               ss += __shfl_xor(ss, 8);
;               const float inv = rsqrtf(ss * (1.f / 64.f) + 1e-6f);
;               v0 *= inv * gv0; v1 *= inv * gv1; v2 *= inv * gv2; v3 *= inv * gv3;
;             }
;             if (dorope) {
;               float sr, cr, sc, cc;
;               sincos_rev((float)(s >> 6) * invf64, sr, cr);
;               sincos_rev((float)(s & 63) * invf64, sc, cc);
;               const float a1 = v0, a2 = v1, b1 = v2, b2 = v3;
;               v0 = a1 * cr - a2 * sr;
;               v1 = a2 * cr + a1 * sr;
;               v2 = b1 * cc - b2 * sc;
;               v3 = b2 * cc + b1 * sc;
;             }
;           } else if (tr == 4) {
;             float sr, cr, sc, cc;
;             sincos_rev((float)(s >> 6) * invf32, sr, cr);
;             sincos_rev((float)(s & 63) * invf32, sc, cc);
;             const float p0 = __shfl_xor(v0, 8), p1 = __shfl_xor(v1, 8), p2 = __shfl_xor(v2, 8), p3 = __shfl_xor(v3, 8);
;             v0 = lo8 ? (v0 * cr - p0 * sr) : (v0 * cr + p0 * sr);
;             v1 = lo8 ? (v1 * cc - p1 * sc) : (v1 * cc + p1 * sc);
;             v2 = lo8 ? (v2 * cr - p2 * sr) : (v2 * cr + p2 * sr);
;             v3 = lo8 ? (v3 * cc - p3 * sc) : (v3 * cc + p3 * sc);
;           }
;           const unsigned u01 = pack2(v0, v1), u23 = pack2(v2, v3);
;           if (kind == 1) {
;             Tl[(0 * 16 + r) * 72 + rowl] = (u16)u01;
;             Tl[(1 * 16 + r) * 72 + rowl] = (u16)(u01 >> 16);
;             Tl[(2 * 16 + r) * 72 + rowl] = (u16)u23;
;             Tl[(3 * 16 + r) * 72 + rowl] = (u16)(u23 >> 16);
;           } else if (tr == 2) {
;             Tl[rowl * 72 + 0 * 16 + r] = f2h(v0);
	v_rsq_f32_e32 v186, v186
	s_nop 0
	v_mul_f32_e32 v187, v178, v186
	v_mul_f32_e32 v188, v179, v186
	v_mul_f32_e32 v189, v180, v186
	v_mul_f32_e32 v190, v181, v186
	v_mul_f32_e32 v182, v89, v187
	v_mul_f32_e32 v183, v93, v188
	v_mul_f32_e32 v184, v97, v189
	v_mul_f32_e32 v185, v101, v190
	v_mul_f32_e32 v186, v175, v183
	v_mul_f32_e32 v187, v176, v183
	v_fma_f32 v188, v176, v182, -v186
	v_fma_f32 v189, v175, v182, v187
	v_mul_f32_e32 v186, v219, v185
	v_mul_f32_e32 v187, v245, v185
	v_fma_f32 v190, v245, v184, -v186
	v_fma_f32 v191, v219, v184, v187
	v_cvt_pk_bf16_f32 v192, v188, v189
	v_cvt_pk_bf16_f32 v193, v190, v191
	ds_write_b16 v170, v192 offset:2736
	ds_write_b16_d16_hi v170, v192 offset:2768
	ds_write_b16 v170, v193 offset:2800
	ds_write_b16_d16_hi v170, v193 offset:2832
	v_mul_f32_e32 v182, v102, v102
	v_mul_f32_e32 v183, v106, v106
	v_mul_f32_e32 v184, v110, v110
	v_mul_f32_e32 v185, v114, v114
	v_add_f32_e32 v186, v182, v183
	v_add_f32_e32 v186, v186, v184
	v_add_f32_e32 v186, v186, v185
	s_nop 1
	v_add_f32_dpp v186, v186, v186 quad_perm:[1,0,3,2] row_mask:0xf bank_mask:0xf
	s_nop 1
	v_add_f32_dpp v186, v186, v186 quad_perm:[2,3,0,1] row_mask:0xf bank_mask:0xf
	s_nop 1
	v_add_f32_dpp v186, v186, v186 row_half_mirror row_mask:0xf bank_mask:0xf
	s_nop 1
	v_add_f32_dpp v186, v186, v186 row_mirror row_mask:0xf bank_mask:0xf
	v_fmamk_f32 v186, v186, 0x3c800000, v173
	v_rsq_f32_e32 v186, v186
	s_nop 0
	v_mul_f32_e32 v187, v178, v186
	v_mul_f32_e32 v188, v179, v186
	v_mul_f32_e32 v189, v180, v186
	v_mul_f32_e32 v190, v181, v186
	v_mul_f32_e32 v182, v102, v187
	v_mul_f32_e32 v183, v106, v188
	v_mul_f32_e32 v184, v110, v189
	v_mul_f32_e32 v185, v114, v190
	v_mul_f32_e32 v186, v175, v183
	v_mul_f32_e32 v187, v176, v183
	v_fma_f32 v188, v176, v182, -v186
	v_fma_f32 v189, v175, v182, v187
	v_mul_f32_e32 v186, v220, v185
	v_mul_f32_e32 v187, v246, v185
	v_fma_f32 v190, v246, v184, -v186
	v_fma_f32 v191, v220, v184, v187
	v_cvt_pk_bf16_f32 v192, v188, v189
	v_cvt_pk_bf16_f32 v193, v190, v191
	ds_write_b16 v170, v192 offset:4608
	ds_write_b16_d16_hi v170, v192 offset:4640
	ds_write_b16 v170, v193 offset:4672
	ds_write_b16_d16_hi v170, v193 offset:4704
	v_mul_f32_e32 v182, v103, v103
	v_mul_f32_e32 v183, v107, v107
	v_mul_f32_e32 v184, v111, v111
	v_mul_f32_e32 v185, v115, v115
	v_add_f32_e32 v186, v182, v183
	v_add_f32_e32 v186, v186, v184
	v_add_f32_e32 v186, v186, v185
	s_nop 1
	v_add_f32_dpp v186, v186, v186 quad_perm:[1,0,3,2] row_mask:0xf bank_mask:0xf
	s_nop 1
	v_add_f32_dpp v186, v186, v186 quad_perm:[2,3,0,1] row_mask:0xf bank_mask:0xf
	s_nop 1
	v_add_f32_dpp v186, v186, v186 row_half_mirror row_mask:0xf bank_mask:0xf
	s_nop 1
	v_add_f32_dpp v186, v186, v186 row_mirror row_mask:0xf bank_mask:0xf
	v_fmamk_f32 v186, v186, 0x3c800000, v173
	v_rsq_f32_e32 v186, v186
	s_nop 0
	v_mul_f32_e32 v187, v178, v186
	v_mul_f32_e32 v188, v179, v186
	v_mul_f32_e32 v189, v180, v186
	v_mul_f32_e32 v190, v181, v186
	v_mul_f32_e32 v182, v103, v187
	v_mul_f32_e32 v183, v107, v188
	v_mul_f32_e32 v184, v111, v189
	v_mul_f32_e32 v185, v115, v190
	v_mul_f32_e32 v186, v175, v183
	v_mul_f32_e32 v187, v176, v183
	v_fma_f32 v188, v176, v182, -v186
	v_fma_f32 v189, v175, v182, v187
	v_mul_f32_e32 v186, v221, v185
	v_mul_f32_e32 v187, v247, v185
	v_fma_f32 v190, v247, v184, -v186
	v_fma_f32 v191, v221, v184, v187
	v_cvt_pk_bf16_f32 v192, v188, v189
	v_cvt_pk_bf16_f32 v193, v190, v191
	ds_write_b16 v170, v192 offset:4752
	ds_write_b16_d16_hi v170, v192 offset:4784
	ds_write_b16 v170, v193 offset:4816
	ds_write_b16_d16_hi v170, v193 offset:4848
	v_mul_f32_e32 v182, v104, v104
	v_mul_f32_e32 v183, v108, v108
	v_mul_f32_e32 v184, v112, v112
	v_mul_f32_e32 v185, v116, v116
	v_add_f32_e32 v186, v182, v183
	v_add_f32_e32 v186, v186, v184
	v_add_f32_e32 v186, v186, v185
	s_nop 1
	v_add_f32_dpp v186, v186, v186 quad_perm:[1,0,3,2] row_mask:0xf bank_mask:0xf
	s_nop 1
	v_add_f32_dpp v186, v186, v186 quad_perm:[2,3,0,1] row_mask:0xf bank_mask:0xf
	s_nop 1
	v_add_f32_dpp v186, v186, v186 row_half_mirror row_mask:0xf bank_mask:0xf
	s_nop 1
	v_add_f32_dpp v186, v186, v186 row_mirror row_mask:0xf bank_mask:0xf
	v_fmamk_f32 v186, v186, 0x3c800000, v173
	v_rsq_f32_e32 v186, v186
	s_nop 0
	v_mul_f32_e32 v187, v178, v186
	v_mul_f32_e32 v188, v179, v186
	v_mul_f32_e32 v189, v180, v186
	v_mul_f32_e32 v190, v181, v186
	v_mul_f32_e32 v182, v104, v187
	v_mul_f32_e32 v183, v108, v188
	v_mul_f32_e32 v184, v112, v189
	v_mul_f32_e32 v185, v116, v190
	v_mul_f32_e32 v186, v175, v183
	v_mul_f32_e32 v187, v176, v183
	v_fma_f32 v188, v176, v182, -v186
	v_fma_f32 v189, v175, v182, v187
	v_mul_f32_e32 v186, v222, v185
	v_mul_f32_e32 v187, v248, v185
	v_fma_f32 v190, v248, v184, -v186
	v_fma_f32 v191, v222, v184, v187
	v_cvt_pk_bf16_f32 v192, v188, v189
	v_cvt_pk_bf16_f32 v193, v190, v191
	ds_write_b16 v170, v192 offset:4896
	ds_write_b16_d16_hi v170, v192 offset:4928
	ds_write_b16 v170, v193 offset:4960
	ds_write_b16_d16_hi v170, v193 offset:4992
	v_mul_f32_e32 v182, v105, v105
	v_mul_f32_e32 v183, v109, v109
	v_mul_f32_e32 v184, v113, v113
	v_mul_f32_e32 v185, v117, v117
	v_add_f32_e32 v186, v182, v183
	v_add_f32_e32 v186, v186, v184
	v_add_f32_e32 v186, v186, v185
	s_nop 1
	v_add_f32_dpp v186, v186, v186 quad_perm:[1,0,3,2] row_mask:0xf bank_mask:0xf
	s_nop 1
	v_add_f32_dpp v186, v186, v186 quad_perm:[2,3,0,1] row_mask:0xf bank_mask:0xf
	s_nop 1
	v_add_f32_dpp v186, v186, v186 row_half_mirror row_mask:0xf bank_mask:0xf
	s_nop 1
	v_add_f32_dpp v186, v186, v186 row_mirror row_mask:0xf bank_mask:0xf
	v_fmamk_f32 v186, v186, 0x3c800000, v173
	v_rsq_f32_e32 v186, v186
	s_nop 0
	v_mul_f32_e32 v187, v178, v186
; template <int EPI>
; DI void gemm_phase(const P& p, int l, const u16* __restrict__ A, const u16* __restrict__ Bt, int mpx, char* lds) {
;     ...
;           float v0 = acc[hf * 4 + mi][0][j], v1 = acc[hf * 4 + mi][1][j], v2 = acc[hf * 4 + mi][2][j], v3 = acc[hf * 4 + mi][3][j];
;           const int rowl = mi * 16 + g * 4 + j;
;           const int s = tokw + hf * 64 + rowl;
;           if (tr == 1) {
;             v0 = silu(v0); v1 = silu(v1); v2 = silu(v2); v3 = silu(v3);
;           } else if (tr == 3) {
;             if (donorm) {
;               float ss = v0 * v0 + v1 * v1 + v2 * v2 + v3 * v3;
;               ss += __shfl_xor(ss, 1);
;               ss += __shfl_xor(ss, 2);
;               ss += __shfl_xor(ss, 4);
;               ss += __shfl_xor(ss, 8);
;               const float inv = rsqrtf(ss * (1.f / 64.f) + 1e-6f);
;               v0 *= inv * gv0; v1 *= inv * gv1; v2 *= inv * gv2; v3 *= inv * gv3;
;             }
;             if (dorope) {
;               float sr, cr, sc, cc;
;               sincos_rev((float)(s >> 6) * invf64, sr, cr);
;               sincos_rev((float)(s & 63) * invf64, sc, cc);
;               const float a1 = v0, a2 = v1, b1 = v2, b2 = v3;
;               v0 = a1 * cr - a2 * sr;
;               v1 = a2 * cr + a1 * sr;
;               v2 = b1 * cc - b2 * sc;
;               v3 = b2 * cc + b1 * sc;
;             }
;           } else if (tr == 4) {
;             float sr, cr, sc, cc;
;             sincos_rev((float)(s >> 6) * invf32, sr, cr);
;             sincos_rev((float)(s & 63) * invf32, sc, cc);
;             const float p0 = __shfl_xor(v0, 8), p1 = __shfl_xor(v1, 8), p2 = __shfl_xor(v2, 8), p3 = __shfl_xor(v3, 8);
;             v0 = lo8 ? (v0 * cr - p0 * sr) : (v0 * cr + p0 * sr);
;             v1 = lo8 ? (v1 * cc - p1 * sc) : (v1 * cc + p1 * sc);
;             v2 = lo8 ? (v2 * cr - p2 * sr) : (v2 * cr + p2 * sr);
;             v3 = lo8 ? (v3 * cc - p3 * sc) : (v3 * cc + p3 * sc);
;           }
;           const unsigned u01 = pack2(v0, v1), u23 = pack2(v2, v3);
;           if (kind == 1) {
;             Tl[(0 * 16 + r) * 72 + rowl] = (u16)u01;
;             Tl[(1 * 16 + r) * 72 + rowl] = (u16)(u01 >> 16);
;             Tl[(2 * 16 + r) * 72 + rowl] = (u16)u23;
;             Tl[(3 * 16 + r) * 72 + rowl] = (u16)(u23 >> 16);
;           } else if (tr == 2) {
;             Tl[rowl * 72 + 0 * 16 + r] = f2h(v0);
	v_mul_f32_e32 v188, v179, v186
	v_mul_f32_e32 v189, v180, v186
	v_mul_f32_e32 v190, v181, v186
	v_mul_f32_e32 v182, v105, v187
	v_mul_f32_e32 v183, v109, v188
	v_mul_f32_e32 v184, v113, v189
	v_mul_f32_e32 v185, v117, v190
	v_mul_f32_e32 v186, v175, v183
	v_mul_f32_e32 v187, v176, v183
	v_fma_f32 v188, v176, v182, -v186
	v_fma_f32 v189, v175, v182, v187
	v_mul_f32_e32 v186, v223, v185
	v_mul_f32_e32 v187, v249, v185
	v_fma_f32 v190, v249, v184, -v186
	v_fma_f32 v191, v223, v184, v187
	v_cvt_pk_bf16_f32 v192, v188, v189
	v_cvt_pk_bf16_f32 v193, v190, v191
	ds_write_b16 v170, v192 offset:5040
	ds_write_b16_d16_hi v170, v192 offset:5072
	ds_write_b16 v170, v193 offset:5104
	ds_write_b16_d16_hi v170, v193 offset:5136
	v_mul_f32_e32 v182, v118, v118
	v_mul_f32_e32 v183, v122, v122
	v_mul_f32_e32 v184, v126, v126
	v_mul_f32_e32 v185, v2, v2
	v_add_f32_e32 v186, v182, v183
	v_add_f32_e32 v186, v186, v184
	v_add_f32_e32 v186, v186, v185
	s_nop 1
	v_add_f32_dpp v186, v186, v186 quad_perm:[1,0,3,2] row_mask:0xf bank_mask:0xf
	s_nop 1
	v_add_f32_dpp v186, v186, v186 quad_perm:[2,3,0,1] row_mask:0xf bank_mask:0xf
	s_nop 1
	v_add_f32_dpp v186, v186, v186 row_half_mirror row_mask:0xf bank_mask:0xf
	s_nop 1
	v_add_f32_dpp v186, v186, v186 row_mirror row_mask:0xf bank_mask:0xf
	v_fmamk_f32 v186, v186, 0x3c800000, v173
	v_rsq_f32_e32 v186, v186
	s_nop 0
	v_mul_f32_e32 v187, v178, v186
	v_mul_f32_e32 v188, v179, v186
	v_mul_f32_e32 v189, v180, v186
	v_mul_f32_e32 v190, v181, v186
	v_mul_f32_e32 v182, v118, v187
	v_mul_f32_e32 v183, v122, v188
	v_mul_f32_e32 v184, v126, v189
	v_mul_f32_e32 v185, v2, v190
	v_mul_f32_e32 v186, v175, v183
	v_mul_f32_e32 v187, v176, v183
	v_fma_f32 v188, v176, v182, -v186
	v_fma_f32 v189, v175, v182, v187
	v_mul_f32_e32 v186, v234, v185
	v_mul_f32_e32 v187, v250, v185
	v_fma_f32 v190, v250, v184, -v186
	v_fma_f32 v191, v234, v184, v187
	v_cvt_pk_bf16_f32 v192, v188, v189
	v_cvt_pk_bf16_f32 v193, v190, v191
	ds_write_b16 v170, v192 offset:6912
	ds_write_b16_d16_hi v170, v192 offset:6944
	ds_write_b16 v170, v193 offset:6976
	ds_write_b16_d16_hi v170, v193 offset:7008
	v_mul_f32_e32 v182, v119, v119
	v_mul_f32_e32 v183, v123, v123
	v_mul_f32_e32 v184, v127, v127
	v_mul_f32_e32 v185, v3, v3
	v_add_f32_e32 v186, v182, v183
	v_add_f32_e32 v186, v186, v184
	v_add_f32_e32 v186, v186, v185
	s_nop 1
	v_add_f32_dpp v186, v186, v186 quad_perm:[1,0,3,2] row_mask:0xf bank_mask:0xf
	s_nop 1
	v_add_f32_dpp v186, v186, v186 quad_perm:[2,3,0,1] row_mask:0xf bank_mask:0xf
	s_nop 1
	v_add_f32_dpp v186, v186, v186 row_half_mirror row_mask:0xf bank_mask:0xf
	s_nop 1
	v_add_f32_dpp v186, v186, v186 row_mirror row_mask:0xf bank_mask:0xf
	v_fmamk_f32 v186, v186, 0x3c800000, v173
	v_rsq_f32_e32 v186, v186
	s_nop 0
	v_mul_f32_e32 v187, v178, v186
	v_mul_f32_e32 v188, v179, v186
	v_mul_f32_e32 v189, v180, v186
	v_mul_f32_e32 v190, v181, v186
	v_mul_f32_e32 v182, v119, v187
	v_mul_f32_e32 v183, v123, v188
	v_mul_f32_e32 v184, v127, v189
	v_mul_f32_e32 v185, v3, v190
	v_mul_f32_e32 v186, v175, v183
	v_mul_f32_e32 v187, v176, v183
	v_fma_f32 v188, v176, v182, -v186
	v_fma_f32 v189, v175, v182, v187
	v_mul_f32_e32 v186, v235, v185
	v_mul_f32_e32 v187, v251, v185
	v_fma_f32 v190, v251, v184, -v186
	v_fma_f32 v191, v235, v184, v187
	v_cvt_pk_bf16_f32 v192, v188, v189
	v_cvt_pk_bf16_f32 v193, v190, v191
	ds_write_b16 v170, v192 offset:7056
	ds_write_b16_d16_hi v170, v192 offset:7088
	ds_write_b16 v170, v193 offset:7120
	ds_write_b16_d16_hi v170, v193 offset:7152
	v_mul_f32_e32 v182, v120, v120
	v_mul_f32_e32 v183, v124, v124
	v_mul_f32_e32 v184, v128, v128
	v_mul_f32_e32 v185, v4, v4
	v_add_f32_e32 v186, v182, v183
	v_add_f32_e32 v186, v186, v184
	v_add_f32_e32 v186, v186, v185
	s_nop 1
	v_add_f32_dpp v186, v186, v186 quad_perm:[1,0,3,2] row_mask:0xf bank_mask:0xf
	s_nop 1
	v_add_f32_dpp v186, v186, v186 quad_perm:[2,3,0,1] row_mask:0xf bank_mask:0xf
	s_nop 1
	v_add_f32_dpp v186, v186, v186 row_half_mirror row_mask:0xf bank_mask:0xf
	s_nop 1
	v_add_f32_dpp v186, v186, v186 row_mirror row_mask:0xf bank_mask:0xf
	v_fmamk_f32 v186, v186, 0x3c800000, v173
	v_rsq_f32_e32 v186, v186
	s_nop 0
	v_mul_f32_e32 v187, v178, v186
	v_mul_f32_e32 v188, v179, v186
	v_mul_f32_e32 v189, v180, v186
	v_mul_f32_e32 v190, v181, v186
	v_mul_f32_e32 v182, v120, v187
	v_mul_f32_e32 v183, v124, v188
	v_mul_f32_e32 v184, v128, v189
	v_mul_f32_e32 v185, v4, v190
	v_mul_f32_e32 v186, v175, v183
	v_mul_f32_e32 v187, v176, v183
	v_fma_f32 v188, v176, v182, -v186
	v_fma_f32 v189, v175, v182, v187
	v_mul_f32_e32 v186, v236, v185
	v_mul_f32_e32 v187, v252, v185
	v_fma_f32 v190, v252, v184, -v186
	v_fma_f32 v191, v236, v184, v187
	v_cvt_pk_bf16_f32 v192, v188, v189
	v_cvt_pk_bf16_f32 v193, v190, v191
	ds_write_b16 v170, v192 offset:7200
	ds_write_b16_d16_hi v170, v192 offset:7232
	ds_write_b16 v170, v193 offset:7264
	ds_write_b16_d16_hi v170, v193 offset:7296
	v_mul_f32_e32 v182, v121, v121
	v_mul_f32_e32 v183, v125, v125
	v_mul_f32_e32 v184, v129, v129
	v_mul_f32_e32 v185, v5, v5
	v_add_f32_e32 v186, v182, v183
	v_add_f32_e32 v186, v186, v184
	v_add_f32_e32 v186, v186, v185
	s_nop 1
	v_add_f32_dpp v186, v186, v186 quad_perm:[1,0,3,2] row_mask:0xf bank_mask:0xf
	s_nop 1
	v_add_f32_dpp v186, v186, v186 quad_perm:[2,3,0,1] row_mask:0xf bank_mask:0xf
	s_nop 1
	v_add_f32_dpp v186, v186, v186 row_half_mirror row_mask:0xf bank_mask:0xf
	s_nop 1
	v_add_f32_dpp v186, v186, v186 row_mirror row_mask:0xf bank_mask:0xf
	v_fmamk_f32 v186, v186, 0x3c800000, v173
	v_rsq_f32_e32 v186, v186
	s_nop 0
	v_mul_f32_e32 v187, v178, v186
	v_mul_f32_e32 v188, v179, v186
	v_mul_f32_e32 v189, v180, v186
	v_mul_f32_e32 v190, v181, v186
	v_mul_f32_e32 v182, v121, v187
	v_mul_f32_e32 v183, v125, v188
	v_mul_f32_e32 v184, v129, v189
	v_mul_f32_e32 v185, v5, v190
	v_mul_f32_e32 v186, v175, v183
	v_mul_f32_e32 v187, v176, v183
	v_fma_f32 v188, v176, v182, -v186
	v_fma_f32 v189, v175, v182, v187
	v_mul_f32_e32 v186, v237, v185
	v_mul_f32_e32 v187, v253, v185
	v_fma_f32 v190, v253, v184, -v186
	v_fma_f32 v191, v237, v184, v187
	v_cvt_pk_bf16_f32 v192, v188, v189
	v_cvt_pk_bf16_f32 v193, v190, v191
	ds_write_b16 v170, v192 offset:7344
	ds_write_b16_d16_hi v170, v192 offset:7376
	ds_write_b16 v170, v193 offset:7408
	ds_write_b16_d16_hi v170, v193 offset:7440
	ds_read_b128 v[130:133], v171 offset:0
	ds_read_b128 v[134:137], v171 offset:1152
	ds_read_b128 v[138:141], v171 offset:2304
	ds_read_b128 v[142:145], v171 offset:3456
	ds_read_b128 v[146:149], v171 offset:4608
	ds_read_b128 v[150:153], v171 offset:5760
	ds_read_b128 v[154:157], v171 offset:6912
	ds_read_b128 v[158:161], v171 offset:8064
	s_waitcnt lgkmcnt(7)
; DI float silu(float v) { return v * __builtin_amdgcn_rcpf(1.f + __builtin_amdgcn_exp2f(-1.4426950408889634f * v)); }
; template <int EPI>
; DI void gemm_phase(const P& p, int l, const u16* __restrict__ A, const u16* __restrict__ Bt, int mpx, char* lds) {
;     ...
;     const float* gw = (cb < 1280 ? p.ga_qn : p.ga_kn) + l * 64;
;     float gv0 = 1.f, gv1 = 1.f, gv2 = 1.f, gv3 = 1.f;
;     if (donorm) { gv0 = gw[r]; gv1 = gw[16 + r]; gv2 = gw[32 + r]; gv3 = gw[48 + r]; }
;     const bool dorope = (tr == 3) && !isctx;
;     const float invf64 = exp2f(-13.287712379549449f * (float)r * (1.f / 16.f));
;     const float invf32 = exp2f(-13.287712379549449f * (float)(r & 7) * (1.f / 8.f));
;     const bool lo8 = r < 8;
;     u16* dst;
;     size_t rstride;
;     if (kind == 2) {
;       dst = p.G + (size_t)(m0 + wm * 128) * 1024 + (cb - 2816);
;       rstride = 1024;
;     } else if (kind == 1) {
;       dst = slab_ptr(p, cb >> 6, b) + tokw;
;       rstride = T;
;     } else {
;       dst = slab_ptr(p, cb >> 6, b) + (size_t)tokw * 64;
;       rstride = 64;
;     }
; #pragma unroll
;     for (int hf = 0; hf < 2; ++hf) {
; #pragma unroll
;       for (int mi = 0; mi < 4; ++mi) {
; #pragma unroll
;         for (int j = 0; j < 4; ++j) {
;           float v0 = acc[hf * 4 + mi][0][j], v1 = acc[hf * 4 + mi][1][j], v2 = acc[hf * 4 + mi][2][j], v3 = acc[hf * 4 + mi][3][j];
;           const int rowl = mi * 16 + g * 4 + j;
;           const int s = tokw + hf * 64 + rowl;
;           if (tr == 1) {
;             v0 = silu(v0); v1 = silu(v1); v2 = silu(v2); v3 = silu(v3);
;           } else if (tr == 3) {
;             if (donorm) {
;               float ss = v0 * v0 + v1 * v1 + v2 * v2 + v3 * v3;
;               ss += __shfl_xor(ss, 1);
;               ss += __shfl_xor(ss, 2);
;               ss += __shfl_xor(ss, 4);
;               ss += __shfl_xor(ss, 8);
;               const float inv = rsqrtf(ss * (1.f / 64.f) + 1e-6f);
;               v0 *= inv * gv0; v1 *= inv * gv1; v2 *= inv * gv2; v3 *= inv * gv3;
;     ...
;       for (int i = 0; i < 8; ++i) {
;         const int c = lane + i * 64;
;         const int row = c >> 3, cc = c & 7;
;         uint4 v = *(const uint4*)&Tl[row * 72 + cc * 8];
;         *(uint4*)(dh + (size_t)row * rstride + cc * 8) = v;
	global_store_dwordx4 v172, v[130:133], s[44:45] offset:0 sc1 nt
	s_waitcnt lgkmcnt(6)
	global_store_dwordx4 v172, v[134:137], s[44:45] offset:1024 sc1 nt
	s_waitcnt lgkmcnt(5)
	global_store_dwordx4 v172, v[138:141], s[44:45] offset:2048 sc1 nt
	s_waitcnt lgkmcnt(4)
	global_store_dwordx4 v172, v[142:145], s[44:45] offset:3072 sc1 nt
	s_waitcnt lgkmcnt(3)
	global_store_dwordx4 v172, v[146:149], s[62:63] offset:0 sc1 nt
	s_waitcnt lgkmcnt(2)
	global_store_dwordx4 v172, v[150:153], s[62:63] offset:1024 sc1 nt
	s_waitcnt lgkmcnt(1)
	global_store_dwordx4 v172, v[154:157], s[62:63] offset:2048 sc1 nt
	s_waitcnt lgkmcnt(0)
	global_store_dwordx4 v172, v[158:161], s[62:63] offset:3072 sc1 nt
	s_branch .Lfe_done
.Lfe_k0_norm:
	s_cmp_lt_u32 s43, 20
	s_movk_i32 s70, 0x68
	s_cselect_b32 s70, 0x60, s70
	s_add_u32 s70, s96, s70
	s_addc_u32 s71, s97, 0
	s_load_dwordx2 s[70:71], s[70:71], 0x0
	v_and_b32_e32 v0, 15, v226
	v_lshlrev_b32_e32 v0, 2, v0
	v_mov_b32_e32 v173, 0x358637bd
	s_waitcnt lgkmcnt(0)
	s_lshl_b32 s63, s52, 2
	s_add_u32 s70, s70, s63
	s_addc_u32 s71, s71, 0
	global_load_dword v178, v0, s[70:71] offset:0
	global_load_dword v179, v0, s[70:71] offset:64
	global_load_dword v180, v0, s[70:71] offset:128
	global_load_dword v181, v0, s[70:71] offset:192
	s_waitcnt vmcnt(0)
	s_add_u32 s62, s44, 0x1000
	s_addc_u32 s63, s45, 0
	v_mul_f32_e32 v182, v6, v6
	v_mul_f32_e32 v183, v10, v10
	v_mul_f32_e32 v184, v14, v14
	v_mul_f32_e32 v185, v18, v18
	v_add_f32_e32 v186, v182, v183
	v_add_f32_e32 v186, v186, v184
	v_add_f32_e32 v186, v186, v185
	s_nop 1
	v_add_f32_dpp v186, v186, v186 quad_perm:[1,0,3,2] row_mask:0xf bank_mask:0xf
	s_nop 1
	v_add_f32_dpp v186, v186, v186 quad_perm:[2,3,0,1] row_mask:0xf bank_mask:0xf
	s_nop 1
	v_add_f32_dpp v186, v186, v186 row_half_mirror row_mask:0xf bank_mask:0xf
	s_nop 1
	v_add_f32_dpp v186, v186, v186 row_mirror row_mask:0xf bank_mask:0xf
	v_fmamk_f32 v186, v186, 0x3c800000, v173
	v_rsq_f32_e32 v186, v186
	s_nop 0
	v_mul_f32_e32 v187, v178, v186
	v_mul_f32_e32 v188, v179, v186
	v_mul_f32_e32 v189, v180, v186
	v_mul_f32_e32 v190, v181, v186
	v_mul_f32_e32 v182, v6, v187
	v_mul_f32_e32 v183, v10, v188
	v_mul_f32_e32 v184, v14, v189
	v_mul_f32_e32 v185, v18, v190
	v_cvt_pk_bf16_f32 v192, v182, v183
	v_cvt_pk_bf16_f32 v193, v184, v185
	ds_write_b16 v170, v192 offset:0
	ds_write_b16_d16_hi v170, v192 offset:32
	ds_write_b16 v170, v193 offset:64
	ds_write_b16_d16_hi v170, v193 offset:96
	v_mul_f32_e32 v182, v7, v7
	v_mul_f32_e32 v183, v11, v11
	v_mul_f32_e32 v184, v15, v15
	v_mul_f32_e32 v185, v19, v19
	v_add_f32_e32 v186, v182, v183
	v_add_f32_e32 v186, v186, v184
	v_add_f32_e32 v186, v186, v185
	s_nop 1
	v_add_f32_dpp v186, v186, v186 quad_perm:[1,0,3,2] row_mask:0xf bank_mask:0xf
	s_nop 1
	v_add_f32_dpp v186, v186, v186 quad_perm:[2,3,0,1] row_mask:0xf bank_mask:0xf
	s_nop 1
	v_add_f32_dpp v186, v186, v186 row_half_mirror row_mask:0xf bank_mask:0xf
	s_nop 1
	v_add_f32_dpp v186, v186, v186 row_mirror row_mask:0xf bank_mask:0xf
	v_fmamk_f32 v186, v186, 0x3c800000, v173
	v_rsq_f32_e32 v186, v186
	s_nop 0
	v_mul_f32_e32 v187, v178, v186
	v_mul_f32_e32 v188, v179, v186
	v_mul_f32_e32 v189, v180, v186
	v_mul_f32_e32 v190, v181, v186
	v_mul_f32_e32 v182, v7, v187
	v_mul_f32_e32 v183, v11, v188
	v_mul_f32_e32 v184, v15, v189
	v_mul_f32_e32 v185, v19, v190
	v_cvt_pk_bf16_f32 v192, v182, v183
	v_cvt_pk_bf16_f32 v193, v184, v185
	ds_write_b16 v170, v192 offset:144
	ds_write_b16_d16_hi v170, v192 offset:176
	ds_write_b16 v170, v193 offset:208
	ds_write_b16_d16_hi v170, v193 offset:240
	v_mul_f32_e32 v182, v8, v8
	v_mul_f32_e32 v183, v12, v12
	v_mul_f32_e32 v184, v16, v16
	v_mul_f32_e32 v185, v20, v20
	v_add_f32_e32 v186, v182, v183
	v_add_f32_e32 v186, v186, v184
	v_add_f32_e32 v186, v186, v185
	s_nop 1
	v_add_f32_dpp v186, v186, v186 quad_perm:[1,0,3,2] row_mask:0xf bank_mask:0xf
	s_nop 1
	v_add_f32_dpp v186, v186, v186 quad_perm:[2,3,0,1] row_mask:0xf bank_mask:0xf
	s_nop 1
	v_add_f32_dpp v186, v186, v186 row_half_mirror row_mask:0xf bank_mask:0xf
	s_nop 1
	v_add_f32_dpp v186, v186, v186 row_mirror row_mask:0xf bank_mask:0xf
	v_fmamk_f32 v186, v186, 0x3c800000, v173
	v_rsq_f32_e32 v186, v186
	s_nop 0
	v_mul_f32_e32 v187, v178, v186
	v_mul_f32_e32 v188, v179, v186
	v_mul_f32_e32 v189, v180, v186
	v_mul_f32_e32 v190, v181, v186
	v_mul_f32_e32 v182, v8, v187
	v_mul_f32_e32 v183, v12, v188
	v_mul_f32_e32 v184, v16, v189
	v_mul_f32_e32 v185, v20, v190
	v_cvt_pk_bf16_f32 v192, v182, v183
	v_cvt_pk_bf16_f32 v193, v184, v185
	ds_write_b16 v170, v192 offset:288
	ds_write_b16_d16_hi v170, v192 offset:320
	ds_write_b16 v170, v193 offset:352
	ds_write_b16_d16_hi v170, v193 offset:384
	v_mul_f32_e32 v182, v9, v9
	v_mul_f32_e32 v183, v13, v13
	v_mul_f32_e32 v184, v17, v17
	v_mul_f32_e32 v185, v21, v21
	v_add_f32_e32 v186, v182, v183
	v_add_f32_e32 v186, v186, v184
	v_add_f32_e32 v186, v186, v185
	s_nop 1
	v_add_f32_dpp v186, v186, v186 quad_perm:[1,0,3,2] row_mask:0xf bank_mask:0xf
	s_nop 1
	v_add_f32_dpp v186, v186, v186 quad_perm:[2,3,0,1] row_mask:0xf bank_mask:0xf
	s_nop 1
	v_add_f32_dpp v186, v186, v186 row_half_mirror row_mask:0xf bank_mask:0xf
	s_nop 1
	v_add_f32_dpp v186, v186, v186 row_mirror row_mask:0xf bank_mask:0xf
	v_fmamk_f32 v186, v186, 0x3c800000, v173
	v_rsq_f32_e32 v186, v186
	s_nop 0
	v_mul_f32_e32 v187, v178, v186
	v_mul_f32_e32 v188, v179, v186
	v_mul_f32_e32 v189, v180, v186
	v_mul_f32_e32 v190, v181, v186
	v_mul_f32_e32 v182, v9, v187
	v_mul_f32_e32 v183, v13, v188
	v_mul_f32_e32 v184, v17, v189
	v_mul_f32_e32 v185, v21, v190
	v_cvt_pk_bf16_f32 v192, v182, v183
	v_cvt_pk_bf16_f32 v193, v184, v185
	ds_write_b16 v170, v192 offset:432
; template <int EPI>
; DI void gemm_phase(const P& p, int l, const u16* __restrict__ A, const u16* __restrict__ Bt, int mpx, char* lds) {
;     ...
;           } else if (tr == 3) {
;             if (donorm) {
;               float ss = v0 * v0 + v1 * v1 + v2 * v2 + v3 * v3;
;               ss += __shfl_xor(ss, 1);
;               ss += __shfl_xor(ss, 2);
;               ss += __shfl_xor(ss, 4);
;               ss += __shfl_xor(ss, 8);
;               const float inv = rsqrtf(ss * (1.f / 64.f) + 1e-6f);
;               v0 *= inv * gv0; v1 *= inv * gv1; v2 *= inv * gv2; v3 *= inv * gv3;
;             }
;             if (dorope) {
;               float sr, cr, sc, cc;
;               sincos_rev((float)(s >> 6) * invf64, sr, cr);
;               sincos_rev((float)(s & 63) * invf64, sc, cc);
;               const float a1 = v0, a2 = v1, b1 = v2, b2 = v3;
;               v0 = a1 * cr - a2 * sr;
;               v1 = a2 * cr + a1 * sr;
;               v2 = b1 * cc - b2 * sc;
;               v3 = b2 * cc + b1 * sc;
;             }
;           } else if (tr == 4) {
;             float sr, cr, sc, cc;
;             sincos_rev((float)(s >> 6) * invf32, sr, cr);
;             sincos_rev((float)(s & 63) * invf32, sc, cc);
;             const float p0 = __shfl_xor(v0, 8), p1 = __shfl_xor(v1, 8), p2 = __shfl_xor(v2, 8), p3 = __shfl_xor(v3, 8);
;             v0 = lo8 ? (v0 * cr - p0 * sr) : (v0 * cr + p0 * sr);
;             v1 = lo8 ? (v1 * cc - p1 * sc) : (v1 * cc + p1 * sc);
;             v2 = lo8 ? (v2 * cr - p2 * sr) : (v2 * cr + p2 * sr);
;             v3 = lo8 ? (v3 * cc - p3 * sc) : (v3 * cc + p3 * sc);
;           }
;           const unsigned u01 = pack2(v0, v1), u23 = pack2(v2, v3);
;           if (kind == 1) {
;             Tl[(0 * 16 + r) * 72 + rowl] = (u16)u01;
;             Tl[(1 * 16 + r) * 72 + rowl] = (u16)(u01 >> 16);
;             Tl[(2 * 16 + r) * 72 + rowl] = (u16)u23;
;             Tl[(3 * 16 + r) * 72 + rowl] = (u16)(u23 >> 16);
;           } else if (tr == 2) {
;             Tl[rowl * 72 + 0 * 16 + r] = f2h(v0);
;             Tl[rowl * 72 + 1 * 16 + r] = f2h(v1);
;             Tl[rowl * 72 + 2 * 16 + r] = f2h(v2);
;             Tl[rowl * 72 + 3 * 16 + r] = f2h(v3);
;           } else {
;             Tl[rowl * 72 + 0 * 16 + r] = (u16)u01;
;             Tl[rowl * 72 + 1 * 16 + r] = (u16)(u01 >> 16);
;             Tl[rowl * 72 + 2 * 16 + r] = (u16)u23;
	ds_write_b16_d16_hi v170, v192 offset:464
	ds_write_b16 v170, v193 offset:496
	ds_write_b16_d16_hi v170, v193 offset:528
	v_mul_f32_e32 v182, v22, v22
	v_mul_f32_e32 v183, v26, v26
	v_mul_f32_e32 v184, v30, v30
	v_mul_f32_e32 v185, v34, v34
	v_add_f32_e32 v186, v182, v183
	v_add_f32_e32 v186, v186, v184
	v_add_f32_e32 v186, v186, v185
	s_nop 1
	v_add_f32_dpp v186, v186, v186 quad_perm:[1,0,3,2] row_mask:0xf bank_mask:0xf
	s_nop 1
	v_add_f32_dpp v186, v186, v186 quad_perm:[2,3,0,1] row_mask:0xf bank_mask:0xf
	s_nop 1
	v_add_f32_dpp v186, v186, v186 row_half_mirror row_mask:0xf bank_mask:0xf
	s_nop 1
	v_add_f32_dpp v186, v186, v186 row_mirror row_mask:0xf bank_mask:0xf
	v_fmamk_f32 v186, v186, 0x3c800000, v173
	v_rsq_f32_e32 v186, v186
	s_nop 0
	v_mul_f32_e32 v187, v178, v186
	v_mul_f32_e32 v188, v179, v186
	v_mul_f32_e32 v189, v180, v186
	v_mul_f32_e32 v190, v181, v186
	v_mul_f32_e32 v182, v22, v187
	v_mul_f32_e32 v183, v26, v188
	v_mul_f32_e32 v184, v30, v189
	v_mul_f32_e32 v185, v34, v190
	v_cvt_pk_bf16_f32 v192, v182, v183
	v_cvt_pk_bf16_f32 v193, v184, v185
	ds_write_b16 v170, v192 offset:2304
	ds_write_b16_d16_hi v170, v192 offset:2336
	ds_write_b16 v170, v193 offset:2368
	ds_write_b16_d16_hi v170, v193 offset:2400
	v_mul_f32_e32 v182, v23, v23
	v_mul_f32_e32 v183, v27, v27
	v_mul_f32_e32 v184, v31, v31
	v_mul_f32_e32 v185, v35, v35
	v_add_f32_e32 v186, v182, v183
	v_add_f32_e32 v186, v186, v184
	v_add_f32_e32 v186, v186, v185
	s_nop 1
	v_add_f32_dpp v186, v186, v186 quad_perm:[1,0,3,2] row_mask:0xf bank_mask:0xf
	s_nop 1
	v_add_f32_dpp v186, v186, v186 quad_perm:[2,3,0,1] row_mask:0xf bank_mask:0xf
	s_nop 1
	v_add_f32_dpp v186, v186, v186 row_half_mirror row_mask:0xf bank_mask:0xf
	s_nop 1
	v_add_f32_dpp v186, v186, v186 row_mirror row_mask:0xf bank_mask:0xf
	v_fmamk_f32 v186, v186, 0x3c800000, v173
	v_rsq_f32_e32 v186, v186
	s_nop 0
	v_mul_f32_e32 v187, v178, v186
	v_mul_f32_e32 v188, v179, v186
	v_mul_f32_e32 v189, v180, v186
	v_mul_f32_e32 v190, v181, v186
	v_mul_f32_e32 v182, v23, v187
	v_mul_f32_e32 v183, v27, v188
	v_mul_f32_e32 v184, v31, v189
	v_mul_f32_e32 v185, v35, v190
	v_cvt_pk_bf16_f32 v192, v182, v183
	v_cvt_pk_bf16_f32 v193, v184, v185
	ds_write_b16 v170, v192 offset:2448
	ds_write_b16_d16_hi v170, v192 offset:2480
	ds_write_b16 v170, v193 offset:2512
	ds_write_b16_d16_hi v170, v193 offset:2544
	v_mul_f32_e32 v182, v24, v24
	v_mul_f32_e32 v183, v28, v28
	v_mul_f32_e32 v184, v32, v32
	v_mul_f32_e32 v185, v36, v36
	v_add_f32_e32 v186, v182, v183
	v_add_f32_e32 v186, v186, v184
	v_add_f32_e32 v186, v186, v185
	s_nop 1
	v_add_f32_dpp v186, v186, v186 quad_perm:[1,0,3,2] row_mask:0xf bank_mask:0xf
	s_nop 1
	v_add_f32_dpp v186, v186, v186 quad_perm:[2,3,0,1] row_mask:0xf bank_mask:0xf
	s_nop 1
	v_add_f32_dpp v186, v186, v186 row_half_mirror row_mask:0xf bank_mask:0xf
	s_nop 1
	v_add_f32_dpp v186, v186, v186 row_mirror row_mask:0xf bank_mask:0xf
	v_fmamk_f32 v186, v186, 0x3c800000, v173
	v_rsq_f32_e32 v186, v186
	s_nop 0
	v_mul_f32_e32 v187, v178, v186
	v_mul_f32_e32 v188, v179, v186
	v_mul_f32_e32 v189, v180, v186
	v_mul_f32_e32 v190, v181, v186
	v_mul_f32_e32 v182, v24, v187
	v_mul_f32_e32 v183, v28, v188
	v_mul_f32_e32 v184, v32, v189
	v_mul_f32_e32 v185, v36, v190
	v_cvt_pk_bf16_f32 v192, v182, v183
	v_cvt_pk_bf16_f32 v193, v184, v185
	ds_write_b16 v170, v192 offset:2592
	ds_write_b16_d16_hi v170, v192 offset:2624
	ds_write_b16 v170, v193 offset:2656
	ds_write_b16_d16_hi v170, v193 offset:2688
	v_mul_f32_e32 v182, v25, v25
	v_mul_f32_e32 v183, v29, v29
	v_mul_f32_e32 v184, v33, v33
	v_mul_f32_e32 v185, v37, v37
	v_add_f32_e32 v186, v182, v183
	v_add_f32_e32 v186, v186, v184
	v_add_f32_e32 v186, v186, v185
	s_nop 1
	v_add_f32_dpp v186, v186, v186 quad_perm:[1,0,3,2] row_mask:0xf bank_mask:0xf
	s_nop 1
	v_add_f32_dpp v186, v186, v186 quad_perm:[2,3,0,1] row_mask:0xf bank_mask:0xf
	s_nop 1
	v_add_f32_dpp v186, v186, v186 row_half_mirror row_mask:0xf bank_mask:0xf
	s_nop 1
	v_add_f32_dpp v186, v186, v186 row_mirror row_mask:0xf bank_mask:0xf
	v_fmamk_f32 v186, v186, 0x3c800000, v173
	v_rsq_f32_e32 v186, v186
	s_nop 0
	v_mul_f32_e32 v187, v178, v186
	v_mul_f32_e32 v188, v179, v186
	v_mul_f32_e32 v189, v180, v186
	v_mul_f32_e32 v190, v181, v186
	v_mul_f32_e32 v182, v25, v187
	v_mul_f32_e32 v183, v29, v188
	v_mul_f32_e32 v184, v33, v189
	v_mul_f32_e32 v185, v37, v190
	v_cvt_pk_bf16_f32 v192, v182, v183
	v_cvt_pk_bf16_f32 v193, v184, v185
	ds_write_b16 v170, v192 offset:2736
	ds_write_b16_d16_hi v170, v192 offset:2768
	ds_write_b16 v170, v193 offset:2800
	ds_write_b16_d16_hi v170, v193 offset:2832
	v_mul_f32_e32 v182, v38, v38
	v_mul_f32_e32 v183, v42, v42
	v_mul_f32_e32 v184, v46, v46
	v_mul_f32_e32 v185, v50, v50
	v_add_f32_e32 v186, v182, v183
	v_add_f32_e32 v186, v186, v184
	v_add_f32_e32 v186, v186, v185
	s_nop 1
	v_add_f32_dpp v186, v186, v186 quad_perm:[1,0,3,2] row_mask:0xf bank_mask:0xf
	s_nop 1
	v_add_f32_dpp v186, v186, v186 quad_perm:[2,3,0,1] row_mask:0xf bank_mask:0xf
	s_nop 1
	v_add_f32_dpp v186, v186, v186 row_half_mirror row_mask:0xf bank_mask:0xf
	s_nop 1
	v_add_f32_dpp v186, v186, v186 row_mirror row_mask:0xf bank_mask:0xf
	v_fmamk_f32 v186, v186, 0x3c800000, v173
	v_rsq_f32_e32 v186, v186
	s_nop 0
	v_mul_f32_e32 v187, v178, v186
	v_mul_f32_e32 v188, v179, v186
	v_mul_f32_e32 v189, v180, v186
	v_mul_f32_e32 v190, v181, v186
	v_mul_f32_e32 v182, v38, v187
	v_mul_f32_e32 v183, v42, v188
	v_mul_f32_e32 v184, v46, v189
	v_mul_f32_e32 v185, v50, v190
	v_cvt_pk_bf16_f32 v192, v182, v183
	v_cvt_pk_bf16_f32 v193, v184, v185
	ds_write_b16 v170, v192 offset:4608
	ds_write_b16_d16_hi v170, v192 offset:4640
; template <int EPI>
; DI void gemm_phase(const P& p, int l, const u16* __restrict__ A, const u16* __restrict__ Bt, int mpx, char* lds) {
;     ...
;           } else if (tr == 3) {
;             if (donorm) {
;               float ss = v0 * v0 + v1 * v1 + v2 * v2 + v3 * v3;
;               ss += __shfl_xor(ss, 1);
;               ss += __shfl_xor(ss, 2);
;               ss += __shfl_xor(ss, 4);
;               ss += __shfl_xor(ss, 8);
;               const float inv = rsqrtf(ss * (1.f / 64.f) + 1e-6f);
;               v0 *= inv * gv0; v1 *= inv * gv1; v2 *= inv * gv2; v3 *= inv * gv3;
;             }
;             if (dorope) {
;               float sr, cr, sc, cc;
;               sincos_rev((float)(s >> 6) * invf64, sr, cr);
;               sincos_rev((float)(s & 63) * invf64, sc, cc);
;               const float a1 = v0, a2 = v1, b1 = v2, b2 = v3;
;               v0 = a1 * cr - a2 * sr;
;               v1 = a2 * cr + a1 * sr;
;               v2 = b1 * cc - b2 * sc;
;               v3 = b2 * cc + b1 * sc;
;             }
;           } else if (tr == 4) {
;             float sr, cr, sc, cc;
;             sincos_rev((float)(s >> 6) * invf32, sr, cr);
;             sincos_rev((float)(s & 63) * invf32, sc, cc);
;             const float p0 = __shfl_xor(v0, 8), p1 = __shfl_xor(v1, 8), p2 = __shfl_xor(v2, 8), p3 = __shfl_xor(v3, 8);
;             v0 = lo8 ? (v0 * cr - p0 * sr) : (v0 * cr + p0 * sr);
;             v1 = lo8 ? (v1 * cc - p1 * sc) : (v1 * cc + p1 * sc);
;             v2 = lo8 ? (v2 * cr - p2 * sr) : (v2 * cr + p2 * sr);
;             v3 = lo8 ? (v3 * cc - p3 * sc) : (v3 * cc + p3 * sc);
;           }
;           const unsigned u01 = pack2(v0, v1), u23 = pack2(v2, v3);
;           if (kind == 1) {
;             Tl[(0 * 16 + r) * 72 + rowl] = (u16)u01;
;             Tl[(1 * 16 + r) * 72 + rowl] = (u16)(u01 >> 16);
;             Tl[(2 * 16 + r) * 72 + rowl] = (u16)u23;
;             Tl[(3 * 16 + r) * 72 + rowl] = (u16)(u23 >> 16);
;           } else if (tr == 2) {
;             Tl[rowl * 72 + 0 * 16 + r] = f2h(v0);
;             Tl[rowl * 72 + 1 * 16 + r] = f2h(v1);
;             Tl[rowl * 72 + 2 * 16 + r] = f2h(v2);
;             Tl[rowl * 72 + 3 * 16 + r] = f2h(v3);
;           } else {
;             Tl[rowl * 72 + 0 * 16 + r] = (u16)u01;
;             Tl[rowl * 72 + 1 * 16 + r] = (u16)(u01 >> 16);
;             Tl[rowl * 72 + 2 * 16 + r] = (u16)u23;
	ds_write_b16 v170, v193 offset:4672
	ds_write_b16_d16_hi v170, v193 offset:4704
	v_mul_f32_e32 v182, v39, v39
	v_mul_f32_e32 v183, v43, v43
	v_mul_f32_e32 v184, v47, v47
	v_mul_f32_e32 v185, v51, v51
	v_add_f32_e32 v186, v182, v183
	v_add_f32_e32 v186, v186, v184
	v_add_f32_e32 v186, v186, v185
	s_nop 1
	v_add_f32_dpp v186, v186, v186 quad_perm:[1,0,3,2] row_mask:0xf bank_mask:0xf
	s_nop 1
	v_add_f32_dpp v186, v186, v186 quad_perm:[2,3,0,1] row_mask:0xf bank_mask:0xf
	s_nop 1
	v_add_f32_dpp v186, v186, v186 row_half_mirror row_mask:0xf bank_mask:0xf
	s_nop 1
	v_add_f32_dpp v186, v186, v186 row_mirror row_mask:0xf bank_mask:0xf
	v_fmamk_f32 v186, v186, 0x3c800000, v173
	v_rsq_f32_e32 v186, v186
	s_nop 0
	v_mul_f32_e32 v187, v178, v186
	v_mul_f32_e32 v188, v179, v186
	v_mul_f32_e32 v189, v180, v186
	v_mul_f32_e32 v190, v181, v186
	v_mul_f32_e32 v182, v39, v187
	v_mul_f32_e32 v183, v43, v188
	v_mul_f32_e32 v184, v47, v189
	v_mul_f32_e32 v185, v51, v190
	v_cvt_pk_bf16_f32 v192, v182, v183
	v_cvt_pk_bf16_f32 v193, v184, v185
	ds_write_b16 v170, v192 offset:4752
	ds_write_b16_d16_hi v170, v192 offset:4784
	ds_write_b16 v170, v193 offset:4816
	ds_write_b16_d16_hi v170, v193 offset:4848
	v_mul_f32_e32 v182, v40, v40
	v_mul_f32_e32 v183, v44, v44
	v_mul_f32_e32 v184, v48, v48
	v_mul_f32_e32 v185, v52, v52
	v_add_f32_e32 v186, v182, v183
	v_add_f32_e32 v186, v186, v184
	v_add_f32_e32 v186, v186, v185
	s_nop 1
	v_add_f32_dpp v186, v186, v186 quad_perm:[1,0,3,2] row_mask:0xf bank_mask:0xf
	s_nop 1
	v_add_f32_dpp v186, v186, v186 quad_perm:[2,3,0,1] row_mask:0xf bank_mask:0xf
	s_nop 1
	v_add_f32_dpp v186, v186, v186 row_half_mirror row_mask:0xf bank_mask:0xf
	s_nop 1
	v_add_f32_dpp v186, v186, v186 row_mirror row_mask:0xf bank_mask:0xf
	v_fmamk_f32 v186, v186, 0x3c800000, v173
	v_rsq_f32_e32 v186, v186
	s_nop 0
	v_mul_f32_e32 v187, v178, v186
	v_mul_f32_e32 v188, v179, v186
	v_mul_f32_e32 v189, v180, v186
	v_mul_f32_e32 v190, v181, v186
	v_mul_f32_e32 v182, v40, v187
	v_mul_f32_e32 v183, v44, v188
	v_mul_f32_e32 v184, v48, v189
	v_mul_f32_e32 v185, v52, v190
	v_cvt_pk_bf16_f32 v192, v182, v183
	v_cvt_pk_bf16_f32 v193, v184, v185
	ds_write_b16 v170, v192 offset:4896
	ds_write_b16_d16_hi v170, v192 offset:4928
	ds_write_b16 v170, v193 offset:4960
	ds_write_b16_d16_hi v170, v193 offset:4992
	v_mul_f32_e32 v182, v41, v41
	v_mul_f32_e32 v183, v45, v45
	v_mul_f32_e32 v184, v49, v49
	v_mul_f32_e32 v185, v53, v53
	v_add_f32_e32 v186, v182, v183
	v_add_f32_e32 v186, v186, v184
	v_add_f32_e32 v186, v186, v185
	s_nop 1
	v_add_f32_dpp v186, v186, v186 quad_perm:[1,0,3,2] row_mask:0xf bank_mask:0xf
	s_nop 1
	v_add_f32_dpp v186, v186, v186 quad_perm:[2,3,0,1] row_mask:0xf bank_mask:0xf
	s_nop 1
	v_add_f32_dpp v186, v186, v186 row_half_mirror row_mask:0xf bank_mask:0xf
	s_nop 1
	v_add_f32_dpp v186, v186, v186 row_mirror row_mask:0xf bank_mask:0xf
	v_fmamk_f32 v186, v186, 0x3c800000, v173
	v_rsq_f32_e32 v186, v186
	s_nop 0
	v_mul_f32_e32 v187, v178, v186
	v_mul_f32_e32 v188, v179, v186
	v_mul_f32_e32 v189, v180, v186
	v_mul_f32_e32 v190, v181, v186
	v_mul_f32_e32 v182, v41, v187
	v_mul_f32_e32 v183, v45, v188
	v_mul_f32_e32 v184, v49, v189
	v_mul_f32_e32 v185, v53, v190
	v_cvt_pk_bf16_f32 v192, v182, v183
	v_cvt_pk_bf16_f32 v193, v184, v185
	ds_write_b16 v170, v192 offset:5040
	ds_write_b16_d16_hi v170, v192 offset:5072
	ds_write_b16 v170, v193 offset:5104
	ds_write_b16_d16_hi v170, v193 offset:5136
	v_mul_f32_e32 v182, v54, v54
	v_mul_f32_e32 v183, v58, v58
	v_mul_f32_e32 v184, v62, v62
	v_mul_f32_e32 v185, v66, v66
	v_add_f32_e32 v186, v182, v183
	v_add_f32_e32 v186, v186, v184
	v_add_f32_e32 v186, v186, v185
	s_nop 1
	v_add_f32_dpp v186, v186, v186 quad_perm:[1,0,3,2] row_mask:0xf bank_mask:0xf
	s_nop 1
	v_add_f32_dpp v186, v186, v186 quad_perm:[2,3,0,1] row_mask:0xf bank_mask:0xf
	s_nop 1
	v_add_f32_dpp v186, v186, v186 row_half_mirror row_mask:0xf bank_mask:0xf
	s_nop 1
	v_add_f32_dpp v186, v186, v186 row_mirror row_mask:0xf bank_mask:0xf
	v_fmamk_f32 v186, v186, 0x3c800000, v173
	v_rsq_f32_e32 v186, v186
	s_nop 0
	v_mul_f32_e32 v187, v178, v186
	v_mul_f32_e32 v188, v179, v186
	v_mul_f32_e32 v189, v180, v186
	v_mul_f32_e32 v190, v181, v186
	v_mul_f32_e32 v182, v54, v187
	v_mul_f32_e32 v183, v58, v188
	v_mul_f32_e32 v184, v62, v189
	v_mul_f32_e32 v185, v66, v190
	v_cvt_pk_bf16_f32 v192, v182, v183
	v_cvt_pk_bf16_f32 v193, v184, v185
	ds_write_b16 v170, v192 offset:6912
	ds_write_b16_d16_hi v170, v192 offset:6944
	ds_write_b16 v170, v193 offset:6976
	ds_write_b16_d16_hi v170, v193 offset:7008
	v_mul_f32_e32 v182, v55, v55
	v_mul_f32_e32 v183, v59, v59
	v_mul_f32_e32 v184, v63, v63
	v_mul_f32_e32 v185, v67, v67
	v_add_f32_e32 v186, v182, v183
	v_add_f32_e32 v186, v186, v184
	v_add_f32_e32 v186, v186, v185
	s_nop 1
	v_add_f32_dpp v186, v186, v186 quad_perm:[1,0,3,2] row_mask:0xf bank_mask:0xf
	s_nop 1
	v_add_f32_dpp v186, v186, v186 quad_perm:[2,3,0,1] row_mask:0xf bank_mask:0xf
	s_nop 1
	v_add_f32_dpp v186, v186, v186 row_half_mirror row_mask:0xf bank_mask:0xf
	s_nop 1
	v_add_f32_dpp v186, v186, v186 row_mirror row_mask:0xf bank_mask:0xf
	v_fmamk_f32 v186, v186, 0x3c800000, v173
	v_rsq_f32_e32 v186, v186
	s_nop 0
	v_mul_f32_e32 v187, v178, v186
	v_mul_f32_e32 v188, v179, v186
	v_mul_f32_e32 v189, v180, v186
	v_mul_f32_e32 v190, v181, v186
	v_mul_f32_e32 v182, v55, v187
	v_mul_f32_e32 v183, v59, v188
	v_mul_f32_e32 v184, v63, v189
	v_mul_f32_e32 v185, v67, v190
	v_cvt_pk_bf16_f32 v192, v182, v183
	v_cvt_pk_bf16_f32 v193, v184, v185
	ds_write_b16 v170, v192 offset:7056
	ds_write_b16_d16_hi v170, v192 offset:7088
	ds_write_b16 v170, v193 offset:7120
; template <int EPI>
; DI void gemm_phase(const P& p, int l, const u16* __restrict__ A, const u16* __restrict__ Bt, int mpx, char* lds) {
;     ...
;           } else if (tr == 3) {
;             if (donorm) {
;               float ss = v0 * v0 + v1 * v1 + v2 * v2 + v3 * v3;
;               ss += __shfl_xor(ss, 1);
;               ss += __shfl_xor(ss, 2);
;               ss += __shfl_xor(ss, 4);
;               ss += __shfl_xor(ss, 8);
;               const float inv = rsqrtf(ss * (1.f / 64.f) + 1e-6f);
;               v0 *= inv * gv0; v1 *= inv * gv1; v2 *= inv * gv2; v3 *= inv * gv3;
;             }
;             if (dorope) {
;               float sr, cr, sc, cc;
;               sincos_rev((float)(s >> 6) * invf64, sr, cr);
;               sincos_rev((float)(s & 63) * invf64, sc, cc);
;               const float a1 = v0, a2 = v1, b1 = v2, b2 = v3;
;               v0 = a1 * cr - a2 * sr;
;               v1 = a2 * cr + a1 * sr;
;               v2 = b1 * cc - b2 * sc;
;               v3 = b2 * cc + b1 * sc;
;             }
;           } else if (tr == 4) {
;             float sr, cr, sc, cc;
;             sincos_rev((float)(s >> 6) * invf32, sr, cr);
;             sincos_rev((float)(s & 63) * invf32, sc, cc);
;             const float p0 = __shfl_xor(v0, 8), p1 = __shfl_xor(v1, 8), p2 = __shfl_xor(v2, 8), p3 = __shfl_xor(v3, 8);
;             v0 = lo8 ? (v0 * cr - p0 * sr) : (v0 * cr + p0 * sr);
;             v1 = lo8 ? (v1 * cc - p1 * sc) : (v1 * cc + p1 * sc);
;             v2 = lo8 ? (v2 * cr - p2 * sr) : (v2 * cr + p2 * sr);
;             v3 = lo8 ? (v3 * cc - p3 * sc) : (v3 * cc + p3 * sc);
;           }
;           const unsigned u01 = pack2(v0, v1), u23 = pack2(v2, v3);
;           if (kind == 1) {
;             Tl[(0 * 16 + r) * 72 + rowl] = (u16)u01;
;             Tl[(1 * 16 + r) * 72 + rowl] = (u16)(u01 >> 16);
;             Tl[(2 * 16 + r) * 72 + rowl] = (u16)u23;
;             Tl[(3 * 16 + r) * 72 + rowl] = (u16)(u23 >> 16);
;           } else if (tr == 2) {
;             Tl[rowl * 72 + 0 * 16 + r] = f2h(v0);
;             Tl[rowl * 72 + 1 * 16 + r] = f2h(v1);
;             Tl[rowl * 72 + 2 * 16 + r] = f2h(v2);
;     ...
;       for (int i = 0; i < 8; ++i) {
;         const int c = lane + i * 64;
;         const int row = c >> 3, cc = c & 7;
;         uint4 v = *(const uint4*)&Tl[row * 72 + cc * 8];
;         *(uint4*)(dh + (size_t)row * rstride + cc * 8) = v;
	ds_write_b16_d16_hi v170, v193 offset:7152
	v_mul_f32_e32 v182, v56, v56
	v_mul_f32_e32 v183, v60, v60
	v_mul_f32_e32 v184, v64, v64
	v_mul_f32_e32 v185, v68, v68
	v_add_f32_e32 v186, v182, v183
	v_add_f32_e32 v186, v186, v184
	v_add_f32_e32 v186, v186, v185
	s_nop 1
	v_add_f32_dpp v186, v186, v186 quad_perm:[1,0,3,2] row_mask:0xf bank_mask:0xf
	s_nop 1
	v_add_f32_dpp v186, v186, v186 quad_perm:[2,3,0,1] row_mask:0xf bank_mask:0xf
	s_nop 1
	v_add_f32_dpp v186, v186, v186 row_half_mirror row_mask:0xf bank_mask:0xf
	s_nop 1
	v_add_f32_dpp v186, v186, v186 row_mirror row_mask:0xf bank_mask:0xf
	v_fmamk_f32 v186, v186, 0x3c800000, v173
	v_rsq_f32_e32 v186, v186
	s_nop 0
	v_mul_f32_e32 v187, v178, v186
	v_mul_f32_e32 v188, v179, v186
	v_mul_f32_e32 v189, v180, v186
	v_mul_f32_e32 v190, v181, v186
	v_mul_f32_e32 v182, v56, v187
	v_mul_f32_e32 v183, v60, v188
	v_mul_f32_e32 v184, v64, v189
	v_mul_f32_e32 v185, v68, v190
	v_cvt_pk_bf16_f32 v192, v182, v183
	v_cvt_pk_bf16_f32 v193, v184, v185
	ds_write_b16 v170, v192 offset:7200
	ds_write_b16_d16_hi v170, v192 offset:7232
	ds_write_b16 v170, v193 offset:7264
	ds_write_b16_d16_hi v170, v193 offset:7296
	v_mul_f32_e32 v182, v57, v57
	v_mul_f32_e32 v183, v61, v61
	v_mul_f32_e32 v184, v65, v65
	v_mul_f32_e32 v185, v69, v69
	v_add_f32_e32 v186, v182, v183
	v_add_f32_e32 v186, v186, v184
	v_add_f32_e32 v186, v186, v185
	s_nop 1
	v_add_f32_dpp v186, v186, v186 quad_perm:[1,0,3,2] row_mask:0xf bank_mask:0xf
	s_nop 1
	v_add_f32_dpp v186, v186, v186 quad_perm:[2,3,0,1] row_mask:0xf bank_mask:0xf
	s_nop 1
	v_add_f32_dpp v186, v186, v186 row_half_mirror row_mask:0xf bank_mask:0xf
	s_nop 1
	v_add_f32_dpp v186, v186, v186 row_mirror row_mask:0xf bank_mask:0xf
	v_fmamk_f32 v186, v186, 0x3c800000, v173
	v_rsq_f32_e32 v186, v186
	s_nop 0
	v_mul_f32_e32 v187, v178, v186
	v_mul_f32_e32 v188, v179, v186
	v_mul_f32_e32 v189, v180, v186
	v_mul_f32_e32 v190, v181, v186
	v_mul_f32_e32 v182, v57, v187
	v_mul_f32_e32 v183, v61, v188
	v_mul_f32_e32 v184, v65, v189
	v_mul_f32_e32 v185, v69, v190
	v_cvt_pk_bf16_f32 v192, v182, v183
	v_cvt_pk_bf16_f32 v193, v184, v185
	ds_write_b16 v170, v192 offset:7344
	ds_write_b16_d16_hi v170, v192 offset:7376
	ds_write_b16 v170, v193 offset:7408
	ds_write_b16_d16_hi v170, v193 offset:7440
	ds_read_b128 v[130:133], v171 offset:0
	ds_read_b128 v[134:137], v171 offset:1152
	ds_read_b128 v[138:141], v171 offset:2304
	ds_read_b128 v[142:145], v171 offset:3456
	ds_read_b128 v[146:149], v171 offset:4608
	ds_read_b128 v[150:153], v171 offset:5760
	ds_read_b128 v[154:157], v171 offset:6912
	ds_read_b128 v[158:161], v171 offset:8064
	s_waitcnt lgkmcnt(7)
	global_store_dwordx4 v172, v[130:133], s[44:45] offset:0 sc1 nt
	s_waitcnt lgkmcnt(6)
	global_store_dwordx4 v172, v[134:137], s[44:45] offset:1024 sc1 nt
	s_waitcnt lgkmcnt(5)
	global_store_dwordx4 v172, v[138:141], s[44:45] offset:2048 sc1 nt
	s_waitcnt lgkmcnt(4)
	global_store_dwordx4 v172, v[142:145], s[44:45] offset:3072 sc1 nt
	s_waitcnt lgkmcnt(3)
	global_store_dwordx4 v172, v[146:149], s[62:63] offset:0 sc1 nt
	s_waitcnt lgkmcnt(2)
	global_store_dwordx4 v172, v[150:153], s[62:63] offset:1024 sc1 nt
	s_waitcnt lgkmcnt(1)
	global_store_dwordx4 v172, v[154:157], s[62:63] offset:2048 sc1 nt
	s_waitcnt lgkmcnt(0)
	global_store_dwordx4 v172, v[158:161], s[62:63] offset:3072 sc1 nt
	s_add_u32 s44, s44, 0x2000
	s_addc_u32 s45, s45, 0
	s_add_u32 s62, s62, 0x2000
	s_addc_u32 s63, s63, 0
	v_mul_f32_e32 v182, v70, v70
	v_mul_f32_e32 v183, v74, v74
	v_mul_f32_e32 v184, v78, v78
	v_mul_f32_e32 v185, v82, v82
	v_add_f32_e32 v186, v182, v183
	v_add_f32_e32 v186, v186, v184
	v_add_f32_e32 v186, v186, v185
	s_nop 1
	v_add_f32_dpp v186, v186, v186 quad_perm:[1,0,3,2] row_mask:0xf bank_mask:0xf
	s_nop 1
	v_add_f32_dpp v186, v186, v186 quad_perm:[2,3,0,1] row_mask:0xf bank_mask:0xf
	s_nop 1
	v_add_f32_dpp v186, v186, v186 row_half_mirror row_mask:0xf bank_mask:0xf
	s_nop 1
	v_add_f32_dpp v186, v186, v186 row_mirror row_mask:0xf bank_mask:0xf
	v_fmamk_f32 v186, v186, 0x3c800000, v173
	v_rsq_f32_e32 v186, v186
	s_nop 0
	v_mul_f32_e32 v187, v178, v186
	v_mul_f32_e32 v188, v179, v186
	v_mul_f32_e32 v189, v180, v186
	v_mul_f32_e32 v190, v181, v186
	v_mul_f32_e32 v182, v70, v187
	v_mul_f32_e32 v183, v74, v188
	v_mul_f32_e32 v184, v78, v189
	v_mul_f32_e32 v185, v82, v190
	v_cvt_pk_bf16_f32 v192, v182, v183
	v_cvt_pk_bf16_f32 v193, v184, v185
	ds_write_b16 v170, v192 offset:0
	ds_write_b16_d16_hi v170, v192 offset:32
	ds_write_b16 v170, v193 offset:64
	ds_write_b16_d16_hi v170, v193 offset:96
	v_mul_f32_e32 v182, v71, v71
	v_mul_f32_e32 v183, v75, v75
	v_mul_f32_e32 v184, v79, v79
	v_mul_f32_e32 v185, v83, v83
	v_add_f32_e32 v186, v182, v183
	v_add_f32_e32 v186, v186, v184
	v_add_f32_e32 v186, v186, v185
	s_nop 1
	v_add_f32_dpp v186, v186, v186 quad_perm:[1,0,3,2] row_mask:0xf bank_mask:0xf
	s_nop 1
	v_add_f32_dpp v186, v186, v186 quad_perm:[2,3,0,1] row_mask:0xf bank_mask:0xf
	s_nop 1
	v_add_f32_dpp v186, v186, v186 row_half_mirror row_mask:0xf bank_mask:0xf
	s_nop 1
	v_add_f32_dpp v186, v186, v186 row_mirror row_mask:0xf bank_mask:0xf
	v_fmamk_f32 v186, v186, 0x3c800000, v173
	v_rsq_f32_e32 v186, v186
	s_nop 0
	v_mul_f32_e32 v187, v178, v186
	v_mul_f32_e32 v188, v179, v186
	v_mul_f32_e32 v189, v180, v186
	v_mul_f32_e32 v190, v181, v186
	v_mul_f32_e32 v182, v71, v187
	v_mul_f32_e32 v183, v75, v188
	v_mul_f32_e32 v184, v79, v189
	v_mul_f32_e32 v185, v83, v190
	v_cvt_pk_bf16_f32 v192, v182, v183
	v_cvt_pk_bf16_f32 v193, v184, v185
	ds_write_b16 v170, v192 offset:144
	ds_write_b16_d16_hi v170, v192 offset:176
	ds_write_b16 v170, v193 offset:208
; template <int EPI>
; DI void gemm_phase(const P& p, int l, const u16* __restrict__ A, const u16* __restrict__ Bt, int mpx, char* lds) {
;     ...
;           } else if (tr == 3) {
;             if (donorm) {
;               float ss = v0 * v0 + v1 * v1 + v2 * v2 + v3 * v3;
;               ss += __shfl_xor(ss, 1);
;               ss += __shfl_xor(ss, 2);
;               ss += __shfl_xor(ss, 4);
;               ss += __shfl_xor(ss, 8);
;               const float inv = rsqrtf(ss * (1.f / 64.f) + 1e-6f);
;               v0 *= inv * gv0; v1 *= inv * gv1; v2 *= inv * gv2; v3 *= inv * gv3;
;             }
;             if (dorope) {
;               float sr, cr, sc, cc;
;               sincos_rev((float)(s >> 6) * invf64, sr, cr);
;               sincos_rev((float)(s & 63) * invf64, sc, cc);
;               const float a1 = v0, a2 = v1, b1 = v2, b2 = v3;
;               v0 = a1 * cr - a2 * sr;
;               v1 = a2 * cr + a1 * sr;
;               v2 = b1 * cc - b2 * sc;
;               v3 = b2 * cc + b1 * sc;
;             }
;           } else if (tr == 4) {
;             float sr, cr, sc, cc;
;             sincos_rev((float)(s >> 6) * invf32, sr, cr);
;             sincos_rev((float)(s & 63) * invf32, sc, cc);
;             const float p0 = __shfl_xor(v0, 8), p1 = __shfl_xor(v1, 8), p2 = __shfl_xor(v2, 8), p3 = __shfl_xor(v3, 8);
;             v0 = lo8 ? (v0 * cr - p0 * sr) : (v0 * cr + p0 * sr);
;             v1 = lo8 ? (v1 * cc - p1 * sc) : (v1 * cc + p1 * sc);
;             v2 = lo8 ? (v2 * cr - p2 * sr) : (v2 * cr + p2 * sr);
;             v3 = lo8 ? (v3 * cc - p3 * sc) : (v3 * cc + p3 * sc);
;           }
;           const unsigned u01 = pack2(v0, v1), u23 = pack2(v2, v3);
;           if (kind == 1) {
;             Tl[(0 * 16 + r) * 72 + rowl] = (u16)u01;
;             Tl[(1 * 16 + r) * 72 + rowl] = (u16)(u01 >> 16);
;             Tl[(2 * 16 + r) * 72 + rowl] = (u16)u23;
;             Tl[(3 * 16 + r) * 72 + rowl] = (u16)(u23 >> 16);
;           } else if (tr == 2) {
;             Tl[rowl * 72 + 0 * 16 + r] = f2h(v0);
;             Tl[rowl * 72 + 1 * 16 + r] = f2h(v1);
;             Tl[rowl * 72 + 2 * 16 + r] = f2h(v2);
;             Tl[rowl * 72 + 3 * 16 + r] = f2h(v3);
;           } else {
;             Tl[rowl * 72 + 0 * 16 + r] = (u16)u01;
;             Tl[rowl * 72 + 1 * 16 + r] = (u16)(u01 >> 16);
;             Tl[rowl * 72 + 2 * 16 + r] = (u16)u23;
	ds_write_b16_d16_hi v170, v193 offset:240
	v_mul_f32_e32 v182, v72, v72
	v_mul_f32_e32 v183, v76, v76
	v_mul_f32_e32 v184, v80, v80
	v_mul_f32_e32 v185, v84, v84
	v_add_f32_e32 v186, v182, v183
	v_add_f32_e32 v186, v186, v184
	v_add_f32_e32 v186, v186, v185
	s_nop 1
	v_add_f32_dpp v186, v186, v186 quad_perm:[1,0,3,2] row_mask:0xf bank_mask:0xf
	s_nop 1
	v_add_f32_dpp v186, v186, v186 quad_perm:[2,3,0,1] row_mask:0xf bank_mask:0xf
	s_nop 1
	v_add_f32_dpp v186, v186, v186 row_half_mirror row_mask:0xf bank_mask:0xf
	s_nop 1
	v_add_f32_dpp v186, v186, v186 row_mirror row_mask:0xf bank_mask:0xf
	v_fmamk_f32 v186, v186, 0x3c800000, v173
	v_rsq_f32_e32 v186, v186
	s_nop 0
	v_mul_f32_e32 v187, v178, v186
	v_mul_f32_e32 v188, v179, v186
	v_mul_f32_e32 v189, v180, v186
	v_mul_f32_e32 v190, v181, v186
	v_mul_f32_e32 v182, v72, v187
	v_mul_f32_e32 v183, v76, v188
	v_mul_f32_e32 v184, v80, v189
	v_mul_f32_e32 v185, v84, v190
	v_cvt_pk_bf16_f32 v192, v182, v183
	v_cvt_pk_bf16_f32 v193, v184, v185
	ds_write_b16 v170, v192 offset:288
	ds_write_b16_d16_hi v170, v192 offset:320
	ds_write_b16 v170, v193 offset:352
	ds_write_b16_d16_hi v170, v193 offset:384
	v_mul_f32_e32 v182, v73, v73
	v_mul_f32_e32 v183, v77, v77
	v_mul_f32_e32 v184, v81, v81
	v_mul_f32_e32 v185, v85, v85
	v_add_f32_e32 v186, v182, v183
	v_add_f32_e32 v186, v186, v184
	v_add_f32_e32 v186, v186, v185
	s_nop 1
	v_add_f32_dpp v186, v186, v186 quad_perm:[1,0,3,2] row_mask:0xf bank_mask:0xf
	s_nop 1
	v_add_f32_dpp v186, v186, v186 quad_perm:[2,3,0,1] row_mask:0xf bank_mask:0xf
	s_nop 1
	v_add_f32_dpp v186, v186, v186 row_half_mirror row_mask:0xf bank_mask:0xf
	s_nop 1
	v_add_f32_dpp v186, v186, v186 row_mirror row_mask:0xf bank_mask:0xf
	v_fmamk_f32 v186, v186, 0x3c800000, v173
	v_rsq_f32_e32 v186, v186
	s_nop 0
	v_mul_f32_e32 v187, v178, v186
	v_mul_f32_e32 v188, v179, v186
	v_mul_f32_e32 v189, v180, v186
	v_mul_f32_e32 v190, v181, v186
	v_mul_f32_e32 v182, v73, v187
	v_mul_f32_e32 v183, v77, v188
	v_mul_f32_e32 v184, v81, v189
	v_mul_f32_e32 v185, v85, v190
	v_cvt_pk_bf16_f32 v192, v182, v183
	v_cvt_pk_bf16_f32 v193, v184, v185
	ds_write_b16 v170, v192 offset:432
	ds_write_b16_d16_hi v170, v192 offset:464
	ds_write_b16 v170, v193 offset:496
	ds_write_b16_d16_hi v170, v193 offset:528
	v_mul_f32_e32 v182, v86, v86
	v_mul_f32_e32 v183, v90, v90
	v_mul_f32_e32 v184, v94, v94
	v_mul_f32_e32 v185, v98, v98
	v_add_f32_e32 v186, v182, v183
	v_add_f32_e32 v186, v186, v184
	v_add_f32_e32 v186, v186, v185
	s_nop 1
	v_add_f32_dpp v186, v186, v186 quad_perm:[1,0,3,2] row_mask:0xf bank_mask:0xf
	s_nop 1
	v_add_f32_dpp v186, v186, v186 quad_perm:[2,3,0,1] row_mask:0xf bank_mask:0xf
	s_nop 1
	v_add_f32_dpp v186, v186, v186 row_half_mirror row_mask:0xf bank_mask:0xf
	s_nop 1
	v_add_f32_dpp v186, v186, v186 row_mirror row_mask:0xf bank_mask:0xf
	v_fmamk_f32 v186, v186, 0x3c800000, v173
	v_rsq_f32_e32 v186, v186
	s_nop 0
	v_mul_f32_e32 v187, v178, v186
	v_mul_f32_e32 v188, v179, v186
	v_mul_f32_e32 v189, v180, v186
	v_mul_f32_e32 v190, v181, v186
	v_mul_f32_e32 v182, v86, v187
	v_mul_f32_e32 v183, v90, v188
	v_mul_f32_e32 v184, v94, v189
	v_mul_f32_e32 v185, v98, v190
	v_cvt_pk_bf16_f32 v192, v182, v183
	v_cvt_pk_bf16_f32 v193, v184, v185
	ds_write_b16 v170, v192 offset:2304
	ds_write_b16_d16_hi v170, v192 offset:2336
	ds_write_b16 v170, v193 offset:2368
	ds_write_b16_d16_hi v170, v193 offset:2400
	v_mul_f32_e32 v182, v87, v87
	v_mul_f32_e32 v183, v91, v91
	v_mul_f32_e32 v184, v95, v95
	v_mul_f32_e32 v185, v99, v99
	v_add_f32_e32 v186, v182, v183
	v_add_f32_e32 v186, v186, v184
	v_add_f32_e32 v186, v186, v185
	s_nop 1
	v_add_f32_dpp v186, v186, v186 quad_perm:[1,0,3,2] row_mask:0xf bank_mask:0xf
	s_nop 1
	v_add_f32_dpp v186, v186, v186 quad_perm:[2,3,0,1] row_mask:0xf bank_mask:0xf
	s_nop 1
	v_add_f32_dpp v186, v186, v186 row_half_mirror row_mask:0xf bank_mask:0xf
	s_nop 1
	v_add_f32_dpp v186, v186, v186 row_mirror row_mask:0xf bank_mask:0xf
	v_fmamk_f32 v186, v186, 0x3c800000, v173
	v_rsq_f32_e32 v186, v186
	s_nop 0
	v_mul_f32_e32 v187, v178, v186
	v_mul_f32_e32 v188, v179, v186
	v_mul_f32_e32 v189, v180, v186
	v_mul_f32_e32 v190, v181, v186
	v_mul_f32_e32 v182, v87, v187
	v_mul_f32_e32 v183, v91, v188
	v_mul_f32_e32 v184, v95, v189
	v_mul_f32_e32 v185, v99, v190
	v_cvt_pk_bf16_f32 v192, v182, v183
	v_cvt_pk_bf16_f32 v193, v184, v185
	ds_write_b16 v170, v192 offset:2448
	ds_write_b16_d16_hi v170, v192 offset:2480
	ds_write_b16 v170, v193 offset:2512
	ds_write_b16_d16_hi v170, v193 offset:2544
	v_mul_f32_e32 v182, v88, v88
	v_mul_f32_e32 v183, v92, v92
	v_mul_f32_e32 v184, v96, v96
	v_mul_f32_e32 v185, v100, v100
	v_add_f32_e32 v186, v182, v183
	v_add_f32_e32 v186, v186, v184
	v_add_f32_e32 v186, v186, v185
	s_nop 1
	v_add_f32_dpp v186, v186, v186 quad_perm:[1,0,3,2] row_mask:0xf bank_mask:0xf
	s_nop 1
	v_add_f32_dpp v186, v186, v186 quad_perm:[2,3,0,1] row_mask:0xf bank_mask:0xf
	s_nop 1
	v_add_f32_dpp v186, v186, v186 row_half_mirror row_mask:0xf bank_mask:0xf
	s_nop 1
	v_add_f32_dpp v186, v186, v186 row_mirror row_mask:0xf bank_mask:0xf
	v_fmamk_f32 v186, v186, 0x3c800000, v173
	v_rsq_f32_e32 v186, v186
	s_nop 0
	v_mul_f32_e32 v187, v178, v186
	v_mul_f32_e32 v188, v179, v186
	v_mul_f32_e32 v189, v180, v186
	v_mul_f32_e32 v190, v181, v186
	v_mul_f32_e32 v182, v88, v187
	v_mul_f32_e32 v183, v92, v188
	v_mul_f32_e32 v184, v96, v189
	v_mul_f32_e32 v185, v100, v190
	v_cvt_pk_bf16_f32 v192, v182, v183
	v_cvt_pk_bf16_f32 v193, v184, v185
	ds_write_b16 v170, v192 offset:2592
	ds_write_b16_d16_hi v170, v192 offset:2624
	ds_write_b16 v170, v193 offset:2656
	ds_write_b16_d16_hi v170, v193 offset:2688
; template <int EPI>
; DI void gemm_phase(const P& p, int l, const u16* __restrict__ A, const u16* __restrict__ Bt, int mpx, char* lds) {
;     ...
;           } else if (tr == 3) {
;             if (donorm) {
;               float ss = v0 * v0 + v1 * v1 + v2 * v2 + v3 * v3;
;               ss += __shfl_xor(ss, 1);
;               ss += __shfl_xor(ss, 2);
;               ss += __shfl_xor(ss, 4);
;               ss += __shfl_xor(ss, 8);
;               const float inv = rsqrtf(ss * (1.f / 64.f) + 1e-6f);
;               v0 *= inv * gv0; v1 *= inv * gv1; v2 *= inv * gv2; v3 *= inv * gv3;
;             }
;             if (dorope) {
;               float sr, cr, sc, cc;
;               sincos_rev((float)(s >> 6) * invf64, sr, cr);
;               sincos_rev((float)(s & 63) * invf64, sc, cc);
;               const float a1 = v0, a2 = v1, b1 = v2, b2 = v3;
;               v0 = a1 * cr - a2 * sr;
;               v1 = a2 * cr + a1 * sr;
;               v2 = b1 * cc - b2 * sc;
;               v3 = b2 * cc + b1 * sc;
;             }
;           } else if (tr == 4) {
;             float sr, cr, sc, cc;
;             sincos_rev((float)(s >> 6) * invf32, sr, cr);
;             sincos_rev((float)(s & 63) * invf32, sc, cc);
;             const float p0 = __shfl_xor(v0, 8), p1 = __shfl_xor(v1, 8), p2 = __shfl_xor(v2, 8), p3 = __shfl_xor(v3, 8);
;             v0 = lo8 ? (v0 * cr - p0 * sr) : (v0 * cr + p0 * sr);
;             v1 = lo8 ? (v1 * cc - p1 * sc) : (v1 * cc + p1 * sc);
;             v2 = lo8 ? (v2 * cr - p2 * sr) : (v2 * cr + p2 * sr);
;             v3 = lo8 ? (v3 * cc - p3 * sc) : (v3 * cc + p3 * sc);
;           }
;           const unsigned u01 = pack2(v0, v1), u23 = pack2(v2, v3);
;           if (kind == 1) {
;             Tl[(0 * 16 + r) * 72 + rowl] = (u16)u01;
;             Tl[(1 * 16 + r) * 72 + rowl] = (u16)(u01 >> 16);
;             Tl[(2 * 16 + r) * 72 + rowl] = (u16)u23;
;             Tl[(3 * 16 + r) * 72 + rowl] = (u16)(u23 >> 16);
;           } else if (tr == 2) {
;             Tl[rowl * 72 + 0 * 16 + r] = f2h(v0);
;             Tl[rowl * 72 + 1 * 16 + r] = f2h(v1);
;             Tl[rowl * 72 + 2 * 16 + r] = f2h(v2);
;             Tl[rowl * 72 + 3 * 16 + r] = f2h(v3);
;           } else {
;             Tl[rowl * 72 + 0 * 16 + r] = (u16)u01;
;             Tl[rowl * 72 + 1 * 16 + r] = (u16)(u01 >> 16);
;             Tl[rowl * 72 + 2 * 16 + r] = (u16)u23;
	v_mul_f32_e32 v182, v89, v89
	v_mul_f32_e32 v183, v93, v93
	v_mul_f32_e32 v184, v97, v97
	v_mul_f32_e32 v185, v101, v101
	v_add_f32_e32 v186, v182, v183
	v_add_f32_e32 v186, v186, v184
	v_add_f32_e32 v186, v186, v185
	s_nop 1
	v_add_f32_dpp v186, v186, v186 quad_perm:[1,0,3,2] row_mask:0xf bank_mask:0xf
	s_nop 1
	v_add_f32_dpp v186, v186, v186 quad_perm:[2,3,0,1] row_mask:0xf bank_mask:0xf
	s_nop 1
	v_add_f32_dpp v186, v186, v186 row_half_mirror row_mask:0xf bank_mask:0xf
	s_nop 1
	v_add_f32_dpp v186, v186, v186 row_mirror row_mask:0xf bank_mask:0xf
	v_fmamk_f32 v186, v186, 0x3c800000, v173
	v_rsq_f32_e32 v186, v186
	s_nop 0
	v_mul_f32_e32 v187, v178, v186
	v_mul_f32_e32 v188, v179, v186
	v_mul_f32_e32 v189, v180, v186
	v_mul_f32_e32 v190, v181, v186
	v_mul_f32_e32 v182, v89, v187
	v_mul_f32_e32 v183, v93, v188
	v_mul_f32_e32 v184, v97, v189
	v_mul_f32_e32 v185, v101, v190
	v_cvt_pk_bf16_f32 v192, v182, v183
	v_cvt_pk_bf16_f32 v193, v184, v185
	ds_write_b16 v170, v192 offset:2736
	ds_write_b16_d16_hi v170, v192 offset:2768
	ds_write_b16 v170, v193 offset:2800
	ds_write_b16_d16_hi v170, v193 offset:2832
	v_mul_f32_e32 v182, v102, v102
	v_mul_f32_e32 v183, v106, v106
	v_mul_f32_e32 v184, v110, v110
	v_mul_f32_e32 v185, v114, v114
	v_add_f32_e32 v186, v182, v183
	v_add_f32_e32 v186, v186, v184
	v_add_f32_e32 v186, v186, v185
	s_nop 1
	v_add_f32_dpp v186, v186, v186 quad_perm:[1,0,3,2] row_mask:0xf bank_mask:0xf
	s_nop 1
	v_add_f32_dpp v186, v186, v186 quad_perm:[2,3,0,1] row_mask:0xf bank_mask:0xf
	s_nop 1
	v_add_f32_dpp v186, v186, v186 row_half_mirror row_mask:0xf bank_mask:0xf
	s_nop 1
	v_add_f32_dpp v186, v186, v186 row_mirror row_mask:0xf bank_mask:0xf
	v_fmamk_f32 v186, v186, 0x3c800000, v173
	v_rsq_f32_e32 v186, v186
	s_nop 0
	v_mul_f32_e32 v187, v178, v186
	v_mul_f32_e32 v188, v179, v186
	v_mul_f32_e32 v189, v180, v186
	v_mul_f32_e32 v190, v181, v186
	v_mul_f32_e32 v182, v102, v187
	v_mul_f32_e32 v183, v106, v188
	v_mul_f32_e32 v184, v110, v189
	v_mul_f32_e32 v185, v114, v190
	v_cvt_pk_bf16_f32 v192, v182, v183
	v_cvt_pk_bf16_f32 v193, v184, v185
	ds_write_b16 v170, v192 offset:4608
	ds_write_b16_d16_hi v170, v192 offset:4640
	ds_write_b16 v170, v193 offset:4672
	ds_write_b16_d16_hi v170, v193 offset:4704
	v_mul_f32_e32 v182, v103, v103
	v_mul_f32_e32 v183, v107, v107
	v_mul_f32_e32 v184, v111, v111
	v_mul_f32_e32 v185, v115, v115
	v_add_f32_e32 v186, v182, v183
	v_add_f32_e32 v186, v186, v184
	v_add_f32_e32 v186, v186, v185
	s_nop 1
	v_add_f32_dpp v186, v186, v186 quad_perm:[1,0,3,2] row_mask:0xf bank_mask:0xf
	s_nop 1
	v_add_f32_dpp v186, v186, v186 quad_perm:[2,3,0,1] row_mask:0xf bank_mask:0xf
	s_nop 1
	v_add_f32_dpp v186, v186, v186 row_half_mirror row_mask:0xf bank_mask:0xf
	s_nop 1
	v_add_f32_dpp v186, v186, v186 row_mirror row_mask:0xf bank_mask:0xf
	v_fmamk_f32 v186, v186, 0x3c800000, v173
	v_rsq_f32_e32 v186, v186
	s_nop 0
	v_mul_f32_e32 v187, v178, v186
	v_mul_f32_e32 v188, v179, v186
	v_mul_f32_e32 v189, v180, v186
	v_mul_f32_e32 v190, v181, v186
	v_mul_f32_e32 v182, v103, v187
	v_mul_f32_e32 v183, v107, v188
	v_mul_f32_e32 v184, v111, v189
	v_mul_f32_e32 v185, v115, v190
	v_cvt_pk_bf16_f32 v192, v182, v183
	v_cvt_pk_bf16_f32 v193, v184, v185
	ds_write_b16 v170, v192 offset:4752
	ds_write_b16_d16_hi v170, v192 offset:4784
	ds_write_b16 v170, v193 offset:4816
	ds_write_b16_d16_hi v170, v193 offset:4848
	v_mul_f32_e32 v182, v104, v104
	v_mul_f32_e32 v183, v108, v108
	v_mul_f32_e32 v184, v112, v112
	v_mul_f32_e32 v185, v116, v116
	v_add_f32_e32 v186, v182, v183
	v_add_f32_e32 v186, v186, v184
	v_add_f32_e32 v186, v186, v185
	s_nop 1
	v_add_f32_dpp v186, v186, v186 quad_perm:[1,0,3,2] row_mask:0xf bank_mask:0xf
	s_nop 1
	v_add_f32_dpp v186, v186, v186 quad_perm:[2,3,0,1] row_mask:0xf bank_mask:0xf
	s_nop 1
	v_add_f32_dpp v186, v186, v186 row_half_mirror row_mask:0xf bank_mask:0xf
	s_nop 1
	v_add_f32_dpp v186, v186, v186 row_mirror row_mask:0xf bank_mask:0xf
	v_fmamk_f32 v186, v186, 0x3c800000, v173
	v_rsq_f32_e32 v186, v186
	s_nop 0
	v_mul_f32_e32 v187, v178, v186
	v_mul_f32_e32 v188, v179, v186
	v_mul_f32_e32 v189, v180, v186
	v_mul_f32_e32 v190, v181, v186
	v_mul_f32_e32 v182, v104, v187
	v_mul_f32_e32 v183, v108, v188
	v_mul_f32_e32 v184, v112, v189
	v_mul_f32_e32 v185, v116, v190
	v_cvt_pk_bf16_f32 v192, v182, v183
	v_cvt_pk_bf16_f32 v193, v184, v185
	ds_write_b16 v170, v192 offset:4896
	ds_write_b16_d16_hi v170, v192 offset:4928
	ds_write_b16 v170, v193 offset:4960
	ds_write_b16_d16_hi v170, v193 offset:4992
	v_mul_f32_e32 v182, v105, v105
	v_mul_f32_e32 v183, v109, v109
	v_mul_f32_e32 v184, v113, v113
	v_mul_f32_e32 v185, v117, v117
	v_add_f32_e32 v186, v182, v183
	v_add_f32_e32 v186, v186, v184
	v_add_f32_e32 v186, v186, v185
	s_nop 1
	v_add_f32_dpp v186, v186, v186 quad_perm:[1,0,3,2] row_mask:0xf bank_mask:0xf
	s_nop 1
	v_add_f32_dpp v186, v186, v186 quad_perm:[2,3,0,1] row_mask:0xf bank_mask:0xf
	s_nop 1
	v_add_f32_dpp v186, v186, v186 row_half_mirror row_mask:0xf bank_mask:0xf
	s_nop 1
	v_add_f32_dpp v186, v186, v186 row_mirror row_mask:0xf bank_mask:0xf
	v_fmamk_f32 v186, v186, 0x3c800000, v173
	v_rsq_f32_e32 v186, v186
	s_nop 0
	v_mul_f32_e32 v187, v178, v186
	v_mul_f32_e32 v188, v179, v186
	v_mul_f32_e32 v189, v180, v186
	v_mul_f32_e32 v190, v181, v186
	v_mul_f32_e32 v182, v105, v187
	v_mul_f32_e32 v183, v109, v188
	v_mul_f32_e32 v184, v113, v189
	v_mul_f32_e32 v185, v117, v190
	v_cvt_pk_bf16_f32 v192, v182, v183
	v_cvt_pk_bf16_f32 v193, v184, v185
	ds_write_b16 v170, v192 offset:5040
	ds_write_b16_d16_hi v170, v192 offset:5072
	ds_write_b16 v170, v193 offset:5104
; template <int EPI>
; DI void gemm_phase(const P& p, int l, const u16* __restrict__ A, const u16* __restrict__ Bt, int mpx, char* lds) {
;     ...
;           } else if (tr == 3) {
;             if (donorm) {
;               float ss = v0 * v0 + v1 * v1 + v2 * v2 + v3 * v3;
;               ss += __shfl_xor(ss, 1);
;               ss += __shfl_xor(ss, 2);
;               ss += __shfl_xor(ss, 4);
;               ss += __shfl_xor(ss, 8);
;               const float inv = rsqrtf(ss * (1.f / 64.f) + 1e-6f);
;               v0 *= inv * gv0; v1 *= inv * gv1; v2 *= inv * gv2; v3 *= inv * gv3;
;             }
;             if (dorope) {
;               float sr, cr, sc, cc;
;               sincos_rev((float)(s >> 6) * invf64, sr, cr);
;               sincos_rev((float)(s & 63) * invf64, sc, cc);
;               const float a1 = v0, a2 = v1, b1 = v2, b2 = v3;
;               v0 = a1 * cr - a2 * sr;
;               v1 = a2 * cr + a1 * sr;
;               v2 = b1 * cc - b2 * sc;
;               v3 = b2 * cc + b1 * sc;
;             }
;           } else if (tr == 4) {
;             float sr, cr, sc, cc;
;             sincos_rev((float)(s >> 6) * invf32, sr, cr);
;             sincos_rev((float)(s & 63) * invf32, sc, cc);
;             const float p0 = __shfl_xor(v0, 8), p1 = __shfl_xor(v1, 8), p2 = __shfl_xor(v2, 8), p3 = __shfl_xor(v3, 8);
;             v0 = lo8 ? (v0 * cr - p0 * sr) : (v0 * cr + p0 * sr);
;             v1 = lo8 ? (v1 * cc - p1 * sc) : (v1 * cc + p1 * sc);
;             v2 = lo8 ? (v2 * cr - p2 * sr) : (v2 * cr + p2 * sr);
;             v3 = lo8 ? (v3 * cc - p3 * sc) : (v3 * cc + p3 * sc);
;           }
;           const unsigned u01 = pack2(v0, v1), u23 = pack2(v2, v3);
;           if (kind == 1) {
;             Tl[(0 * 16 + r) * 72 + rowl] = (u16)u01;
;             Tl[(1 * 16 + r) * 72 + rowl] = (u16)(u01 >> 16);
;             Tl[(2 * 16 + r) * 72 + rowl] = (u16)u23;
;             Tl[(3 * 16 + r) * 72 + rowl] = (u16)(u23 >> 16);
;           } else if (tr == 2) {
;             Tl[rowl * 72 + 0 * 16 + r] = f2h(v0);
;             Tl[rowl * 72 + 1 * 16 + r] = f2h(v1);
;             Tl[rowl * 72 + 2 * 16 + r] = f2h(v2);
;             Tl[rowl * 72 + 3 * 16 + r] = f2h(v3);
;           } else {
;             Tl[rowl * 72 + 0 * 16 + r] = (u16)u01;
;             Tl[rowl * 72 + 1 * 16 + r] = (u16)(u01 >> 16);
;             Tl[rowl * 72 + 2 * 16 + r] = (u16)u23;
	ds_write_b16_d16_hi v170, v193 offset:5136
	v_mul_f32_e32 v182, v118, v118
	v_mul_f32_e32 v183, v122, v122
	v_mul_f32_e32 v184, v126, v126
	v_mul_f32_e32 v185, v2, v2
	v_add_f32_e32 v186, v182, v183
	v_add_f32_e32 v186, v186, v184
	v_add_f32_e32 v186, v186, v185
	s_nop 1
	v_add_f32_dpp v186, v186, v186 quad_perm:[1,0,3,2] row_mask:0xf bank_mask:0xf
	s_nop 1
	v_add_f32_dpp v186, v186, v186 quad_perm:[2,3,0,1] row_mask:0xf bank_mask:0xf
	s_nop 1
	v_add_f32_dpp v186, v186, v186 row_half_mirror row_mask:0xf bank_mask:0xf
	s_nop 1
	v_add_f32_dpp v186, v186, v186 row_mirror row_mask:0xf bank_mask:0xf
	v_fmamk_f32 v186, v186, 0x3c800000, v173
	v_rsq_f32_e32 v186, v186
	s_nop 0
	v_mul_f32_e32 v187, v178, v186
	v_mul_f32_e32 v188, v179, v186
	v_mul_f32_e32 v189, v180, v186
	v_mul_f32_e32 v190, v181, v186
	v_mul_f32_e32 v182, v118, v187
	v_mul_f32_e32 v183, v122, v188
	v_mul_f32_e32 v184, v126, v189
	v_mul_f32_e32 v185, v2, v190
	v_cvt_pk_bf16_f32 v192, v182, v183
	v_cvt_pk_bf16_f32 v193, v184, v185
	ds_write_b16 v170, v192 offset:6912
	ds_write_b16_d16_hi v170, v192 offset:6944
	ds_write_b16 v170, v193 offset:6976
	ds_write_b16_d16_hi v170, v193 offset:7008
	v_mul_f32_e32 v182, v119, v119
	v_mul_f32_e32 v183, v123, v123
	v_mul_f32_e32 v184, v127, v127
	v_mul_f32_e32 v185, v3, v3
	v_add_f32_e32 v186, v182, v183
	v_add_f32_e32 v186, v186, v184
	v_add_f32_e32 v186, v186, v185
	s_nop 1
	v_add_f32_dpp v186, v186, v186 quad_perm:[1,0,3,2] row_mask:0xf bank_mask:0xf
	s_nop 1
	v_add_f32_dpp v186, v186, v186 quad_perm:[2,3,0,1] row_mask:0xf bank_mask:0xf
	s_nop 1
	v_add_f32_dpp v186, v186, v186 row_half_mirror row_mask:0xf bank_mask:0xf
	s_nop 1
	v_add_f32_dpp v186, v186, v186 row_mirror row_mask:0xf bank_mask:0xf
	v_fmamk_f32 v186, v186, 0x3c800000, v173
	v_rsq_f32_e32 v186, v186
	s_nop 0
	v_mul_f32_e32 v187, v178, v186
	v_mul_f32_e32 v188, v179, v186
	v_mul_f32_e32 v189, v180, v186
	v_mul_f32_e32 v190, v181, v186
	v_mul_f32_e32 v182, v119, v187
	v_mul_f32_e32 v183, v123, v188
	v_mul_f32_e32 v184, v127, v189
	v_mul_f32_e32 v185, v3, v190
	v_cvt_pk_bf16_f32 v192, v182, v183
	v_cvt_pk_bf16_f32 v193, v184, v185
	ds_write_b16 v170, v192 offset:7056
	ds_write_b16_d16_hi v170, v192 offset:7088
	ds_write_b16 v170, v193 offset:7120
	ds_write_b16_d16_hi v170, v193 offset:7152
	v_mul_f32_e32 v182, v120, v120
	v_mul_f32_e32 v183, v124, v124
	v_mul_f32_e32 v184, v128, v128
	v_mul_f32_e32 v185, v4, v4
	v_add_f32_e32 v186, v182, v183
	v_add_f32_e32 v186, v186, v184
	v_add_f32_e32 v186, v186, v185
	s_nop 1
	v_add_f32_dpp v186, v186, v186 quad_perm:[1,0,3,2] row_mask:0xf bank_mask:0xf
	s_nop 1
	v_add_f32_dpp v186, v186, v186 quad_perm:[2,3,0,1] row_mask:0xf bank_mask:0xf
	s_nop 1
	v_add_f32_dpp v186, v186, v186 row_half_mirror row_mask:0xf bank_mask:0xf
	s_nop 1
	v_add_f32_dpp v186, v186, v186 row_mirror row_mask:0xf bank_mask:0xf
	v_fmamk_f32 v186, v186, 0x3c800000, v173
	v_rsq_f32_e32 v186, v186
	s_nop 0
	v_mul_f32_e32 v187, v178, v186
	v_mul_f32_e32 v188, v179, v186
	v_mul_f32_e32 v189, v180, v186
	v_mul_f32_e32 v190, v181, v186
	v_mul_f32_e32 v182, v120, v187
	v_mul_f32_e32 v183, v124, v188
	v_mul_f32_e32 v184, v128, v189
	v_mul_f32_e32 v185, v4, v190
	v_cvt_pk_bf16_f32 v192, v182, v183
	v_cvt_pk_bf16_f32 v193, v184, v185
	ds_write_b16 v170, v192 offset:7200
	ds_write_b16_d16_hi v170, v192 offset:7232
	ds_write_b16 v170, v193 offset:7264
	ds_write_b16_d16_hi v170, v193 offset:7296
	v_mul_f32_e32 v182, v121, v121
	v_mul_f32_e32 v183, v125, v125
	v_mul_f32_e32 v184, v129, v129
	v_mul_f32_e32 v185, v5, v5
	v_add_f32_e32 v186, v182, v183
	v_add_f32_e32 v186, v186, v184
	v_add_f32_e32 v186, v186, v185
	s_nop 1
	v_add_f32_dpp v186, v186, v186 quad_perm:[1,0,3,2] row_mask:0xf bank_mask:0xf
	s_nop 1
	v_add_f32_dpp v186, v186, v186 quad_perm:[2,3,0,1] row_mask:0xf bank_mask:0xf
	s_nop 1
	v_add_f32_dpp v186, v186, v186 row_half_mirror row_mask:0xf bank_mask:0xf
	s_nop 1
	v_add_f32_dpp v186, v186, v186 row_mirror row_mask:0xf bank_mask:0xf
	v_fmamk_f32 v186, v186, 0x3c800000, v173
	v_rsq_f32_e32 v186, v186
	s_nop 0
	v_mul_f32_e32 v187, v178, v186
	v_mul_f32_e32 v188, v179, v186
	v_mul_f32_e32 v189, v180, v186
	v_mul_f32_e32 v190, v181, v186
	v_mul_f32_e32 v182, v121, v187
	v_mul_f32_e32 v183, v125, v188
	v_mul_f32_e32 v184, v129, v189
	v_mul_f32_e32 v185, v5, v190
	v_cvt_pk_bf16_f32 v192, v182, v183
	v_cvt_pk_bf16_f32 v193, v184, v185
	ds_write_b16 v170, v192 offset:7344
	ds_write_b16_d16_hi v170, v192 offset:7376
	ds_write_b16 v170, v193 offset:7408
	ds_write_b16_d16_hi v170, v193 offset:7440
	ds_read_b128 v[130:133], v171 offset:0
	ds_read_b128 v[134:137], v171 offset:1152
	ds_read_b128 v[138:141], v171 offset:2304
	ds_read_b128 v[142:145], v171 offset:3456
	ds_read_b128 v[146:149], v171 offset:4608
	ds_read_b128 v[150:153], v171 offset:5760
	ds_read_b128 v[154:157], v171 offset:6912
	ds_read_b128 v[158:161], v171 offset:8064
	s_waitcnt lgkmcnt(7)
	global_store_dwordx4 v172, v[130:133], s[44:45] offset:0 sc1 nt
	s_waitcnt lgkmcnt(6)
	global_store_dwordx4 v172, v[134:137], s[44:45] offset:1024 sc1 nt
	s_waitcnt lgkmcnt(5)
	global_store_dwordx4 v172, v[138:141], s[44:45] offset:2048 sc1 nt
	s_waitcnt lgkmcnt(4)
	global_store_dwordx4 v172, v[142:145], s[44:45] offset:3072 sc1 nt
	s_waitcnt lgkmcnt(3)
	global_store_dwordx4 v172, v[146:149], s[62:63] offset:0 sc1 nt
	s_waitcnt lgkmcnt(2)
	global_store_dwordx4 v172, v[150:153], s[62:63] offset:1024 sc1 nt
	s_waitcnt lgkmcnt(1)
	global_store_dwordx4 v172, v[154:157], s[62:63] offset:2048 sc1 nt
	s_waitcnt lgkmcnt(0)
	global_store_dwordx4 v172, v[158:161], s[62:63] offset:3072 sc1 nt
	s_branch .Lfe_done

; template <int EPI>
; DI void gemm_phase(const P& p, int l, const u16* __restrict__ A, const u16* __restrict__ Bt, int mpx, char* lds) {
;     ...
;           const unsigned u01 = pack2(v0, v1), u23 = pack2(v2, v3);
;           if (kind == 1) {
;             Tl[(0 * 16 + r) * 72 + rowl] = (u16)u01;
;             Tl[(1 * 16 + r) * 72 + rowl] = (u16)(u01 >> 16);
;             Tl[(2 * 16 + r) * 72 + rowl] = (u16)u23;
;             Tl[(3 * 16 + r) * 72 + rowl] = (u16)(u23 >> 16);
;           } else if (tr == 2) {
;             Tl[rowl * 72 + 0 * 16 + r] = f2h(v0);
;             Tl[rowl * 72 + 1 * 16 + r] = f2h(v1);
;             Tl[rowl * 72 + 2 * 16 + r] = f2h(v2);
;             Tl[rowl * 72 + 3 * 16 + r] = f2h(v3);
;           } else {
;             Tl[rowl * 72 + 0 * 16 + r] = (u16)u01;
;             Tl[rowl * 72 + 1 * 16 + r] = (u16)(u01 >> 16);
;             Tl[rowl * 72 + 2 * 16 + r] = (u16)u23;
;             Tl[rowl * 72 + 3 * 16 + r] = (u16)(u23 >> 16);
;           }
;         }
;       }
;       __builtin_amdgcn_fence(__ATOMIC_RELEASE, "wavefront");
;       u16* dh = (kind == 1) ? dst + hf * 64 : dst + (size_t)(hf * 64) * rstride;
; #pragma unroll
;       for (int i = 0; i < 8; ++i) {
;         const int c = lane + i * 64;
;         const int row = c >> 3, cc = c & 7;
;         uint4 v = *(const uint4*)&Tl[row * 72 + cc * 8];
;         *(uint4*)(dh + (size_t)row * rstride + cc * 8) = v;
.Lfe_k1:
	s_mov_b64 s[62:63], s[44:45]
	v_cvt_pk_bf16_f32 v178, v6, v10
	v_cvt_pk_bf16_f32 v179, v14, v18
	ds_write_b16 v170, v178 offset:0
	ds_write_b16_d16_hi v170, v178 offset:2304
	ds_write_b16 v170, v179 offset:4608
	ds_write_b16_d16_hi v170, v179 offset:6912
	v_cvt_pk_bf16_f32 v184, v7, v11
	v_cvt_pk_bf16_f32 v185, v15, v19
	ds_write_b16 v170, v184 offset:2
	ds_write_b16_d16_hi v170, v184 offset:2306
	ds_write_b16 v170, v185 offset:4610
	ds_write_b16_d16_hi v170, v185 offset:6914
	v_cvt_pk_bf16_f32 v190, v8, v12
	v_cvt_pk_bf16_f32 v191, v16, v20
	ds_write_b16 v170, v190 offset:4
	ds_write_b16_d16_hi v170, v190 offset:2308
	ds_write_b16 v170, v191 offset:4612
	ds_write_b16_d16_hi v170, v191 offset:6916
	v_cvt_pk_bf16_f32 v176, v9, v13
	v_cvt_pk_bf16_f32 v177, v17, v21
	ds_write_b16 v170, v176 offset:6
	ds_write_b16_d16_hi v170, v176 offset:2310
	ds_write_b16 v170, v177 offset:4614
	ds_write_b16_d16_hi v170, v177 offset:6918
	v_cvt_pk_bf16_f32 v182, v22, v26
	v_cvt_pk_bf16_f32 v183, v30, v34
	ds_write_b16 v170, v182 offset:32
	ds_write_b16_d16_hi v170, v182 offset:2336
	ds_write_b16 v170, v183 offset:4640
	ds_write_b16_d16_hi v170, v183 offset:6944
	v_cvt_pk_bf16_f32 v188, v23, v27
	v_cvt_pk_bf16_f32 v189, v31, v35
	ds_write_b16 v170, v188 offset:34
	ds_write_b16_d16_hi v170, v188 offset:2338
	ds_write_b16 v170, v189 offset:4642
	ds_write_b16_d16_hi v170, v189 offset:6946
	v_cvt_pk_bf16_f32 v174, v24, v28
	v_cvt_pk_bf16_f32 v175, v32, v36
	ds_write_b16 v170, v174 offset:36
	ds_write_b16_d16_hi v170, v174 offset:2340
	ds_write_b16 v170, v175 offset:4644
	ds_write_b16_d16_hi v170, v175 offset:6948
	v_cvt_pk_bf16_f32 v180, v25, v29
	v_cvt_pk_bf16_f32 v181, v33, v37
	ds_write_b16 v170, v180 offset:38
	ds_write_b16_d16_hi v170, v180 offset:2342
	ds_write_b16 v170, v181 offset:4646
	ds_write_b16_d16_hi v170, v181 offset:6950
	v_cvt_pk_bf16_f32 v186, v38, v42
	v_cvt_pk_bf16_f32 v187, v46, v50
	ds_write_b16 v170, v186 offset:64
	ds_write_b16_d16_hi v170, v186 offset:2368
	ds_write_b16 v170, v187 offset:4672
	ds_write_b16_d16_hi v170, v187 offset:6976
	v_cvt_pk_bf16_f32 v192, v39, v43
	v_cvt_pk_bf16_f32 v193, v47, v51
	ds_write_b16 v170, v192 offset:66
	ds_write_b16_d16_hi v170, v192 offset:2370
	ds_write_b16 v170, v193 offset:4674
	ds_write_b16_d16_hi v170, v193 offset:6978
	v_cvt_pk_bf16_f32 v178, v40, v44
	v_cvt_pk_bf16_f32 v179, v48, v52
	ds_write_b16 v170, v178 offset:68
	ds_write_b16_d16_hi v170, v178 offset:2372
	ds_write_b16 v170, v179 offset:4676
	ds_write_b16_d16_hi v170, v179 offset:6980
	v_cvt_pk_bf16_f32 v184, v41, v45
	v_cvt_pk_bf16_f32 v185, v49, v53
	ds_write_b16 v170, v184 offset:70
	ds_write_b16_d16_hi v170, v184 offset:2374
	ds_write_b16 v170, v185 offset:4678
	ds_write_b16_d16_hi v170, v185 offset:6982
	v_cvt_pk_bf16_f32 v190, v54, v58
	v_cvt_pk_bf16_f32 v191, v62, v66
	ds_write_b16 v170, v190 offset:96
	ds_write_b16_d16_hi v170, v190 offset:2400
	ds_write_b16 v170, v191 offset:4704
	ds_write_b16_d16_hi v170, v191 offset:7008
	v_cvt_pk_bf16_f32 v176, v55, v59
	v_cvt_pk_bf16_f32 v177, v63, v67
	ds_write_b16 v170, v176 offset:98
	ds_write_b16_d16_hi v170, v176 offset:2402
	ds_write_b16 v170, v177 offset:4706
	ds_write_b16_d16_hi v170, v177 offset:7010
	v_cvt_pk_bf16_f32 v182, v56, v60
	v_cvt_pk_bf16_f32 v183, v64, v68
	ds_write_b16 v170, v182 offset:100
	ds_write_b16_d16_hi v170, v182 offset:2404
	ds_write_b16 v170, v183 offset:4708
	ds_write_b16_d16_hi v170, v183 offset:7012
	v_cvt_pk_bf16_f32 v188, v57, v61
	v_cvt_pk_bf16_f32 v189, v65, v69
	ds_write_b16 v170, v188 offset:102
	ds_write_b16_d16_hi v170, v188 offset:2406
	ds_write_b16 v170, v189 offset:4710
	ds_write_b16_d16_hi v170, v189 offset:7014
	ds_read_b128 v[130:133], v171 offset:0
	ds_read_b128 v[134:137], v171 offset:1152
	ds_read_b128 v[138:141], v171 offset:2304
	ds_read_b128 v[142:145], v171 offset:3456
	ds_read_b128 v[146:149], v171 offset:4608
	ds_read_b128 v[150:153], v171 offset:5760
	ds_read_b128 v[154:157], v171 offset:6912
	ds_read_b128 v[158:161], v171 offset:8064
	s_waitcnt lgkmcnt(7)
	global_store_dwordx4 v172, v[130:133], s[44:45] sc1 nt
	s_add_u32 s44, s44, 0x9000
	s_addc_u32 s45, s45, 0
	s_waitcnt lgkmcnt(6)
	global_store_dwordx4 v172, v[134:137], s[44:45] sc1 nt
	s_add_u32 s44, s44, 0x9000
	s_addc_u32 s45, s45, 0
	s_waitcnt lgkmcnt(5)
	global_store_dwordx4 v172, v[138:141], s[44:45] sc1 nt
	s_add_u32 s44, s44, 0x9000
	s_addc_u32 s45, s45, 0
	s_waitcnt lgkmcnt(4)
	global_store_dwordx4 v172, v[142:145], s[44:45] sc1 nt
	s_add_u32 s44, s44, 0x9000
	s_addc_u32 s45, s45, 0
	s_waitcnt lgkmcnt(3)
	global_store_dwordx4 v172, v[146:149], s[44:45] sc1 nt
	s_add_u32 s44, s44, 0x9000
	s_addc_u32 s45, s45, 0
	s_waitcnt lgkmcnt(2)
	global_store_dwordx4 v172, v[150:153], s[44:45] sc1 nt
	s_add_u32 s44, s44, 0x9000
	s_addc_u32 s45, s45, 0
	s_waitcnt lgkmcnt(1)
	global_store_dwordx4 v172, v[154:157], s[44:45] sc1 nt
	s_add_u32 s44, s44, 0x9000
	s_addc_u32 s45, s45, 0
	s_waitcnt lgkmcnt(0)
; template <int EPI>
; DI void gemm_phase(const P& p, int l, const u16* __restrict__ A, const u16* __restrict__ Bt, int mpx, char* lds) {
;     ...
;           const unsigned u01 = pack2(v0, v1), u23 = pack2(v2, v3);
;           if (kind == 1) {
;             Tl[(0 * 16 + r) * 72 + rowl] = (u16)u01;
;             Tl[(1 * 16 + r) * 72 + rowl] = (u16)(u01 >> 16);
;             Tl[(2 * 16 + r) * 72 + rowl] = (u16)u23;
;             Tl[(3 * 16 + r) * 72 + rowl] = (u16)(u23 >> 16);
;           } else if (tr == 2) {
;             Tl[rowl * 72 + 0 * 16 + r] = f2h(v0);
;             Tl[rowl * 72 + 1 * 16 + r] = f2h(v1);
;             Tl[rowl * 72 + 2 * 16 + r] = f2h(v2);
;             Tl[rowl * 72 + 3 * 16 + r] = f2h(v3);
;           } else {
;             Tl[rowl * 72 + 0 * 16 + r] = (u16)u01;
;             Tl[rowl * 72 + 1 * 16 + r] = (u16)(u01 >> 16);
;             Tl[rowl * 72 + 2 * 16 + r] = (u16)u23;
;             Tl[rowl * 72 + 3 * 16 + r] = (u16)(u23 >> 16);
;           }
;         }
;       }
;       __builtin_amdgcn_fence(__ATOMIC_RELEASE, "wavefront");
;       u16* dh = (kind == 1) ? dst + hf * 64 : dst + (size_t)(hf * 64) * rstride;
; #pragma unroll
;       for (int i = 0; i < 8; ++i) {
;         const int c = lane + i * 64;
;         const int row = c >> 3, cc = c & 7;
;         uint4 v = *(const uint4*)&Tl[row * 72 + cc * 8];
;         *(uint4*)(dh + (size_t)row * rstride + cc * 8) = v;
	global_store_dwordx4 v172, v[158:161], s[44:45] sc1 nt
	s_add_u32 s44, s62, 0x80
	s_addc_u32 s45, s63, 0
	v_cvt_pk_bf16_f32 v178, v70, v74
	v_cvt_pk_bf16_f32 v179, v78, v82
	ds_write_b16 v170, v178 offset:0
	ds_write_b16_d16_hi v170, v178 offset:2304
	ds_write_b16 v170, v179 offset:4608
	ds_write_b16_d16_hi v170, v179 offset:6912
	v_cvt_pk_bf16_f32 v184, v71, v75
	v_cvt_pk_bf16_f32 v185, v79, v83
	ds_write_b16 v170, v184 offset:2
	ds_write_b16_d16_hi v170, v184 offset:2306
	ds_write_b16 v170, v185 offset:4610
	ds_write_b16_d16_hi v170, v185 offset:6914
	v_cvt_pk_bf16_f32 v190, v72, v76
	v_cvt_pk_bf16_f32 v191, v80, v84
	ds_write_b16 v170, v190 offset:4
	ds_write_b16_d16_hi v170, v190 offset:2308
	ds_write_b16 v170, v191 offset:4612
	ds_write_b16_d16_hi v170, v191 offset:6916
	v_cvt_pk_bf16_f32 v176, v73, v77
	v_cvt_pk_bf16_f32 v177, v81, v85
	ds_write_b16 v170, v176 offset:6
	ds_write_b16_d16_hi v170, v176 offset:2310
	ds_write_b16 v170, v177 offset:4614
	ds_write_b16_d16_hi v170, v177 offset:6918
	v_cvt_pk_bf16_f32 v182, v86, v90
	v_cvt_pk_bf16_f32 v183, v94, v98
	ds_write_b16 v170, v182 offset:32
	ds_write_b16_d16_hi v170, v182 offset:2336
	ds_write_b16 v170, v183 offset:4640
	ds_write_b16_d16_hi v170, v183 offset:6944
	v_cvt_pk_bf16_f32 v188, v87, v91
	v_cvt_pk_bf16_f32 v189, v95, v99
	ds_write_b16 v170, v188 offset:34
	ds_write_b16_d16_hi v170, v188 offset:2338
	ds_write_b16 v170, v189 offset:4642
	ds_write_b16_d16_hi v170, v189 offset:6946
	v_cvt_pk_bf16_f32 v174, v88, v92
	v_cvt_pk_bf16_f32 v175, v96, v100
	ds_write_b16 v170, v174 offset:36
	ds_write_b16_d16_hi v170, v174 offset:2340
	ds_write_b16 v170, v175 offset:4644
	ds_write_b16_d16_hi v170, v175 offset:6948
	v_cvt_pk_bf16_f32 v180, v89, v93
	v_cvt_pk_bf16_f32 v181, v97, v101
	ds_write_b16 v170, v180 offset:38
	ds_write_b16_d16_hi v170, v180 offset:2342
	ds_write_b16 v170, v181 offset:4646
	ds_write_b16_d16_hi v170, v181 offset:6950
	v_cvt_pk_bf16_f32 v186, v102, v106
	v_cvt_pk_bf16_f32 v187, v110, v114
	ds_write_b16 v170, v186 offset:64
	ds_write_b16_d16_hi v170, v186 offset:2368
	ds_write_b16 v170, v187 offset:4672
	ds_write_b16_d16_hi v170, v187 offset:6976
	v_cvt_pk_bf16_f32 v192, v103, v107
	v_cvt_pk_bf16_f32 v193, v111, v115
	ds_write_b16 v170, v192 offset:66
	ds_write_b16_d16_hi v170, v192 offset:2370
	ds_write_b16 v170, v193 offset:4674
	ds_write_b16_d16_hi v170, v193 offset:6978
	v_cvt_pk_bf16_f32 v178, v104, v108
	v_cvt_pk_bf16_f32 v179, v112, v116
	ds_write_b16 v170, v178 offset:68
	ds_write_b16_d16_hi v170, v178 offset:2372
	ds_write_b16 v170, v179 offset:4676
	ds_write_b16_d16_hi v170, v179 offset:6980
	v_cvt_pk_bf16_f32 v184, v105, v109
	v_cvt_pk_bf16_f32 v185, v113, v117
	ds_write_b16 v170, v184 offset:70
	ds_write_b16_d16_hi v170, v184 offset:2374
	ds_write_b16 v170, v185 offset:4678
	ds_write_b16_d16_hi v170, v185 offset:6982
	v_cvt_pk_bf16_f32 v190, v118, v122
	v_cvt_pk_bf16_f32 v191, v126, v2
	ds_write_b16 v170, v190 offset:96
	ds_write_b16_d16_hi v170, v190 offset:2400
	ds_write_b16 v170, v191 offset:4704
	ds_write_b16_d16_hi v170, v191 offset:7008
	v_cvt_pk_bf16_f32 v176, v119, v123
	v_cvt_pk_bf16_f32 v177, v127, v3
	ds_write_b16 v170, v176 offset:98
	ds_write_b16_d16_hi v170, v176 offset:2402
	ds_write_b16 v170, v177 offset:4706
	ds_write_b16_d16_hi v170, v177 offset:7010
	v_cvt_pk_bf16_f32 v182, v120, v124
	v_cvt_pk_bf16_f32 v183, v128, v4
	ds_write_b16 v170, v182 offset:100
	ds_write_b16_d16_hi v170, v182 offset:2404
	ds_write_b16 v170, v183 offset:4708
	ds_write_b16_d16_hi v170, v183 offset:7012
	v_cvt_pk_bf16_f32 v188, v121, v125
	v_cvt_pk_bf16_f32 v189, v129, v5
	ds_write_b16 v170, v188 offset:102
	ds_write_b16_d16_hi v170, v188 offset:2406
	ds_write_b16 v170, v189 offset:4710
	ds_write_b16_d16_hi v170, v189 offset:7014
	ds_read_b128 v[130:133], v171 offset:0
	ds_read_b128 v[134:137], v171 offset:1152
	ds_read_b128 v[138:141], v171 offset:2304
	ds_read_b128 v[142:145], v171 offset:3456
	ds_read_b128 v[146:149], v171 offset:4608
	ds_read_b128 v[150:153], v171 offset:5760
	ds_read_b128 v[154:157], v171 offset:6912
	ds_read_b128 v[158:161], v171 offset:8064
	s_waitcnt lgkmcnt(7)
	global_store_dwordx4 v172, v[130:133], s[44:45] sc1 nt
	s_add_u32 s44, s44, 0x9000
	s_addc_u32 s45, s45, 0
	s_waitcnt lgkmcnt(6)
	global_store_dwordx4 v172, v[134:137], s[44:45] sc1 nt
	s_add_u32 s44, s44, 0x9000
	s_addc_u32 s45, s45, 0
	s_waitcnt lgkmcnt(5)
	global_store_dwordx4 v172, v[138:141], s[44:45] sc1 nt
	s_add_u32 s44, s44, 0x9000
	s_addc_u32 s45, s45, 0
	s_waitcnt lgkmcnt(4)
	global_store_dwordx4 v172, v[142:145], s[44:45] sc1 nt
	s_add_u32 s44, s44, 0x9000
	s_addc_u32 s45, s45, 0
	s_waitcnt lgkmcnt(3)
	global_store_dwordx4 v172, v[146:149], s[44:45] sc1 nt
	s_add_u32 s44, s44, 0x9000
	s_addc_u32 s45, s45, 0
	s_waitcnt lgkmcnt(2)
	global_store_dwordx4 v172, v[150:153], s[44:45] sc1 nt
	s_add_u32 s44, s44, 0x9000
	s_addc_u32 s45, s45, 0
	s_waitcnt lgkmcnt(1)
	global_store_dwordx4 v172, v[154:157], s[44:45] sc1 nt
	s_add_u32 s44, s44, 0x9000
	s_addc_u32 s45, s45, 0
	s_waitcnt lgkmcnt(0)
	global_store_dwordx4 v172, v[158:161], s[44:45] sc1 nt
	s_branch .Lfe_done

; template <int EPI>
; DI void gemm_phase(const P& p, int l, const u16* __restrict__ A, const u16* __restrict__ Bt, int mpx, char* lds) {
;     ...
;           float v0 = acc[hf * 4 + mi][0][j], v1 = acc[hf * 4 + mi][1][j], v2 = acc[hf * 4 + mi][2][j], v3 = acc[hf * 4 + mi][3][j];
;           const int rowl = mi * 16 + g * 4 + j;
;           const int s = tokw + hf * 64 + rowl;
;           if (tr == 1) {
;             v0 = silu(v0); v1 = silu(v1); v2 = silu(v2); v3 = silu(v3);
;           } else if (tr == 3) {
;             if (donorm) {
;               float ss = v0 * v0 + v1 * v1 + v2 * v2 + v3 * v3;
;               ss += __shfl_xor(ss, 1);
;               ss += __shfl_xor(ss, 2);
;               ss += __shfl_xor(ss, 4);
;               ss += __shfl_xor(ss, 8);
;               const float inv = rsqrtf(ss * (1.f / 64.f) + 1e-6f);
;               v0 *= inv * gv0; v1 *= inv * gv1; v2 *= inv * gv2; v3 *= inv * gv3;
;             }
;             if (dorope) {
;               float sr, cr, sc, cc;
;               sincos_rev((float)(s >> 6) * invf64, sr, cr);
;               sincos_rev((float)(s & 63) * invf64, sc, cc);
;               const float a1 = v0, a2 = v1, b1 = v2, b2 = v3;
;               v0 = a1 * cr - a2 * sr;
;               v1 = a2 * cr + a1 * sr;
;               v2 = b1 * cc - b2 * sc;
;               v3 = b2 * cc + b1 * sc;
;             }
;           } else if (tr == 4) {
;             float sr, cr, sc, cc;
;             sincos_rev((float)(s >> 6) * invf32, sr, cr);
;             sincos_rev((float)(s & 63) * invf32, sc, cc);
;             const float p0 = __shfl_xor(v0, 8), p1 = __shfl_xor(v1, 8), p2 = __shfl_xor(v2, 8), p3 = __shfl_xor(v3, 8);
;             v0 = lo8 ? (v0 * cr - p0 * sr) : (v0 * cr + p0 * sr);
;             v1 = lo8 ? (v1 * cc - p1 * sc) : (v1 * cc + p1 * sc);
;             v2 = lo8 ? (v2 * cr - p2 * sr) : (v2 * cr + p2 * sr);
;             v3 = lo8 ? (v3 * cc - p3 * sc) : (v3 * cc + p3 * sc);
;           }
;           const unsigned u01 = pack2(v0, v1), u23 = pack2(v2, v3);
;           if (kind == 1) {
;             Tl[(0 * 16 + r) * 72 + rowl] = (u16)u01;
;             Tl[(1 * 16 + r) * 72 + rowl] = (u16)(u01 >> 16);
;             Tl[(2 * 16 + r) * 72 + rowl] = (u16)u23;
;             Tl[(3 * 16 + r) * 72 + rowl] = (u16)(u23 >> 16);
;           } else if (tr == 2) {
;             Tl[rowl * 72 + 0 * 16 + r] = f2h(v0);
.Lfe_k2:
	s_mov_b64 s[62:63], s[44:45]
	v_mul_f32_e32 v174, 0xbfb8aa3b, v6
	v_mul_f32_e32 v175, 0xbfb8aa3b, v10
	v_mul_f32_e32 v176, 0xbfb8aa3b, v14
	v_mul_f32_e32 v177, 0xbfb8aa3b, v18
	v_exp_f32_e32 v174, v174
	v_exp_f32_e32 v175, v175
	v_exp_f32_e32 v176, v176
	v_exp_f32_e32 v177, v177
	v_add_f32_e32 v174, 1.0, v174
	v_add_f32_e32 v175, 1.0, v175
	v_add_f32_e32 v176, 1.0, v176
	v_add_f32_e32 v177, 1.0, v177
	v_rcp_f32_e32 v174, v174
	v_rcp_f32_e32 v175, v175
	v_rcp_f32_e32 v176, v176
	v_rcp_f32_e32 v177, v177
	v_mul_f32_e32 v174, v6, v174
	v_mul_f32_e32 v175, v10, v175
	v_mul_f32_e32 v176, v14, v176
	v_mul_f32_e32 v177, v18, v177
	v_cvt_pk_bf16_f32 v178, v174, v175
	v_cvt_pk_bf16_f32 v179, v176, v177
	ds_write_b16 v170, v178 offset:0
	ds_write_b16_d16_hi v170, v178 offset:32
	ds_write_b16 v170, v179 offset:64
	ds_write_b16_d16_hi v170, v179 offset:96
	v_mul_f32_e32 v180, 0xbfb8aa3b, v7
	v_mul_f32_e32 v181, 0xbfb8aa3b, v11
	v_mul_f32_e32 v182, 0xbfb8aa3b, v15
	v_mul_f32_e32 v183, 0xbfb8aa3b, v19
	v_exp_f32_e32 v180, v180
	v_exp_f32_e32 v181, v181
	v_exp_f32_e32 v182, v182
	v_exp_f32_e32 v183, v183
	v_add_f32_e32 v180, 1.0, v180
	v_add_f32_e32 v181, 1.0, v181
	v_add_f32_e32 v182, 1.0, v182
	v_add_f32_e32 v183, 1.0, v183
	v_rcp_f32_e32 v180, v180
	v_rcp_f32_e32 v181, v181
	v_rcp_f32_e32 v182, v182
	v_rcp_f32_e32 v183, v183
	v_mul_f32_e32 v180, v7, v180
	v_mul_f32_e32 v181, v11, v181
	v_mul_f32_e32 v182, v15, v182
	v_mul_f32_e32 v183, v19, v183
	v_cvt_pk_bf16_f32 v184, v180, v181
	v_cvt_pk_bf16_f32 v185, v182, v183
	ds_write_b16 v170, v184 offset:144
	ds_write_b16_d16_hi v170, v184 offset:176
	ds_write_b16 v170, v185 offset:208
	ds_write_b16_d16_hi v170, v185 offset:240
	v_mul_f32_e32 v186, 0xbfb8aa3b, v8
	v_mul_f32_e32 v187, 0xbfb8aa3b, v12
	v_mul_f32_e32 v188, 0xbfb8aa3b, v16
	v_mul_f32_e32 v189, 0xbfb8aa3b, v20
	v_exp_f32_e32 v186, v186
	v_exp_f32_e32 v187, v187
	v_exp_f32_e32 v188, v188
	v_exp_f32_e32 v189, v189
	v_add_f32_e32 v186, 1.0, v186
	v_add_f32_e32 v187, 1.0, v187
	v_add_f32_e32 v188, 1.0, v188
	v_add_f32_e32 v189, 1.0, v189
	v_rcp_f32_e32 v186, v186
	v_rcp_f32_e32 v187, v187
	v_rcp_f32_e32 v188, v188
	v_rcp_f32_e32 v189, v189
	v_mul_f32_e32 v186, v8, v186
	v_mul_f32_e32 v187, v12, v187
	v_mul_f32_e32 v188, v16, v188
	v_mul_f32_e32 v189, v20, v189
	v_cvt_pk_bf16_f32 v190, v186, v187
	v_cvt_pk_bf16_f32 v191, v188, v189
	ds_write_b16 v170, v190 offset:288
	ds_write_b16_d16_hi v170, v190 offset:320
	ds_write_b16 v170, v191 offset:352
	ds_write_b16_d16_hi v170, v191 offset:384
	v_mul_f32_e32 v192, 0xbfb8aa3b, v9
	v_mul_f32_e32 v193, 0xbfb8aa3b, v13
	v_mul_f32_e32 v174, 0xbfb8aa3b, v17
	v_mul_f32_e32 v175, 0xbfb8aa3b, v21
	v_exp_f32_e32 v192, v192
	v_exp_f32_e32 v193, v193
	v_exp_f32_e32 v174, v174
	v_exp_f32_e32 v175, v175
	v_add_f32_e32 v192, 1.0, v192
	v_add_f32_e32 v193, 1.0, v193
	v_add_f32_e32 v174, 1.0, v174
	v_add_f32_e32 v175, 1.0, v175
	v_rcp_f32_e32 v192, v192
	v_rcp_f32_e32 v193, v193
	v_rcp_f32_e32 v174, v174
	v_rcp_f32_e32 v175, v175
	v_mul_f32_e32 v192, v9, v192
	v_mul_f32_e32 v193, v13, v193
	v_mul_f32_e32 v174, v17, v174
	v_mul_f32_e32 v175, v21, v175
	v_cvt_pk_bf16_f32 v176, v192, v193
	v_cvt_pk_bf16_f32 v177, v174, v175
	ds_write_b16 v170, v176 offset:432
	ds_write_b16_d16_hi v170, v176 offset:464
	ds_write_b16 v170, v177 offset:496
	ds_write_b16_d16_hi v170, v177 offset:528
	v_mul_f32_e32 v178, 0xbfb8aa3b, v22
	v_mul_f32_e32 v179, 0xbfb8aa3b, v26
	v_mul_f32_e32 v180, 0xbfb8aa3b, v30
	v_mul_f32_e32 v181, 0xbfb8aa3b, v34
	v_exp_f32_e32 v178, v178
	v_exp_f32_e32 v179, v179
	v_exp_f32_e32 v180, v180
	v_exp_f32_e32 v181, v181
	v_add_f32_e32 v178, 1.0, v178
	v_add_f32_e32 v179, 1.0, v179
	v_add_f32_e32 v180, 1.0, v180
	v_add_f32_e32 v181, 1.0, v181
	v_rcp_f32_e32 v178, v178
	v_rcp_f32_e32 v179, v179
	v_rcp_f32_e32 v180, v180
	v_rcp_f32_e32 v181, v181
	v_mul_f32_e32 v178, v22, v178
	v_mul_f32_e32 v179, v26, v179
	v_mul_f32_e32 v180, v30, v180
	v_mul_f32_e32 v181, v34, v181
	v_cvt_pk_bf16_f32 v182, v178, v179
	v_cvt_pk_bf16_f32 v183, v180, v181
	ds_write_b16 v170, v182 offset:2304
	ds_write_b16_d16_hi v170, v182 offset:2336
	ds_write_b16 v170, v183 offset:2368
	ds_write_b16_d16_hi v170, v183 offset:2400
	v_mul_f32_e32 v184, 0xbfb8aa3b, v23
	v_mul_f32_e32 v185, 0xbfb8aa3b, v27
	v_mul_f32_e32 v186, 0xbfb8aa3b, v31
	v_mul_f32_e32 v187, 0xbfb8aa3b, v35
	v_exp_f32_e32 v184, v184
	v_exp_f32_e32 v185, v185
	v_exp_f32_e32 v186, v186
	v_exp_f32_e32 v187, v187
	v_add_f32_e32 v184, 1.0, v184
	v_add_f32_e32 v185, 1.0, v185
	v_add_f32_e32 v186, 1.0, v186
	v_add_f32_e32 v187, 1.0, v187
	v_rcp_f32_e32 v184, v184
	v_rcp_f32_e32 v185, v185
	v_rcp_f32_e32 v186, v186
	v_rcp_f32_e32 v187, v187
	v_mul_f32_e32 v184, v23, v184
	v_mul_f32_e32 v185, v27, v185
	v_mul_f32_e32 v186, v31, v186
	v_mul_f32_e32 v187, v35, v187
	v_cvt_pk_bf16_f32 v188, v184, v185
	v_cvt_pk_bf16_f32 v189, v186, v187
	ds_write_b16 v170, v188 offset:2448
	ds_write_b16_d16_hi v170, v188 offset:2480
	ds_write_b16 v170, v189 offset:2512
	ds_write_b16_d16_hi v170, v189 offset:2544
	v_mul_f32_e32 v190, 0xbfb8aa3b, v24
	v_mul_f32_e32 v191, 0xbfb8aa3b, v28
	v_mul_f32_e32 v192, 0xbfb8aa3b, v32
	v_mul_f32_e32 v193, 0xbfb8aa3b, v36
	v_exp_f32_e32 v190, v190
	v_exp_f32_e32 v191, v191
	v_exp_f32_e32 v192, v192
	v_exp_f32_e32 v193, v193
	v_add_f32_e32 v190, 1.0, v190
	v_add_f32_e32 v191, 1.0, v191
	v_add_f32_e32 v192, 1.0, v192
	v_add_f32_e32 v193, 1.0, v193
	v_rcp_f32_e32 v190, v190
	v_rcp_f32_e32 v191, v191
	v_rcp_f32_e32 v192, v192
	v_rcp_f32_e32 v193, v193
	v_mul_f32_e32 v190, v24, v190
	v_mul_f32_e32 v191, v28, v191
	v_mul_f32_e32 v192, v32, v192
	v_mul_f32_e32 v193, v36, v193
; template <int EPI>
; DI void gemm_phase(const P& p, int l, const u16* __restrict__ A, const u16* __restrict__ Bt, int mpx, char* lds) {
;     ...
;           float v0 = acc[hf * 4 + mi][0][j], v1 = acc[hf * 4 + mi][1][j], v2 = acc[hf * 4 + mi][2][j], v3 = acc[hf * 4 + mi][3][j];
;           const int rowl = mi * 16 + g * 4 + j;
;           const int s = tokw + hf * 64 + rowl;
;           if (tr == 1) {
;             v0 = silu(v0); v1 = silu(v1); v2 = silu(v2); v3 = silu(v3);
;           } else if (tr == 3) {
;             if (donorm) {
;               float ss = v0 * v0 + v1 * v1 + v2 * v2 + v3 * v3;
;               ss += __shfl_xor(ss, 1);
;               ss += __shfl_xor(ss, 2);
;               ss += __shfl_xor(ss, 4);
;               ss += __shfl_xor(ss, 8);
;               const float inv = rsqrtf(ss * (1.f / 64.f) + 1e-6f);
;               v0 *= inv * gv0; v1 *= inv * gv1; v2 *= inv * gv2; v3 *= inv * gv3;
;             }
;             if (dorope) {
;               float sr, cr, sc, cc;
;               sincos_rev((float)(s >> 6) * invf64, sr, cr);
;               sincos_rev((float)(s & 63) * invf64, sc, cc);
;               const float a1 = v0, a2 = v1, b1 = v2, b2 = v3;
;               v0 = a1 * cr - a2 * sr;
;               v1 = a2 * cr + a1 * sr;
;               v2 = b1 * cc - b2 * sc;
;               v3 = b2 * cc + b1 * sc;
;             }
;           } else if (tr == 4) {
;             float sr, cr, sc, cc;
;             sincos_rev((float)(s >> 6) * invf32, sr, cr);
;             sincos_rev((float)(s & 63) * invf32, sc, cc);
;             const float p0 = __shfl_xor(v0, 8), p1 = __shfl_xor(v1, 8), p2 = __shfl_xor(v2, 8), p3 = __shfl_xor(v3, 8);
;             v0 = lo8 ? (v0 * cr - p0 * sr) : (v0 * cr + p0 * sr);
;             v1 = lo8 ? (v1 * cc - p1 * sc) : (v1 * cc + p1 * sc);
;             v2 = lo8 ? (v2 * cr - p2 * sr) : (v2 * cr + p2 * sr);
;             v3 = lo8 ? (v3 * cc - p3 * sc) : (v3 * cc + p3 * sc);
;           }
;           const unsigned u01 = pack2(v0, v1), u23 = pack2(v2, v3);
;           if (kind == 1) {
;             Tl[(0 * 16 + r) * 72 + rowl] = (u16)u01;
;             Tl[(1 * 16 + r) * 72 + rowl] = (u16)(u01 >> 16);
;             Tl[(2 * 16 + r) * 72 + rowl] = (u16)u23;
;             Tl[(3 * 16 + r) * 72 + rowl] = (u16)(u23 >> 16);
;           } else if (tr == 2) {
;             Tl[rowl * 72 + 0 * 16 + r] = f2h(v0);
	v_cvt_pk_bf16_f32 v174, v190, v191
	v_cvt_pk_bf16_f32 v175, v192, v193
	ds_write_b16 v170, v174 offset:2592
	ds_write_b16_d16_hi v170, v174 offset:2624
	ds_write_b16 v170, v175 offset:2656
	ds_write_b16_d16_hi v170, v175 offset:2688
	v_mul_f32_e32 v176, 0xbfb8aa3b, v25
	v_mul_f32_e32 v177, 0xbfb8aa3b, v29
	v_mul_f32_e32 v178, 0xbfb8aa3b, v33
	v_mul_f32_e32 v179, 0xbfb8aa3b, v37
	v_exp_f32_e32 v176, v176
	v_exp_f32_e32 v177, v177
	v_exp_f32_e32 v178, v178
	v_exp_f32_e32 v179, v179
	v_add_f32_e32 v176, 1.0, v176
	v_add_f32_e32 v177, 1.0, v177
	v_add_f32_e32 v178, 1.0, v178
	v_add_f32_e32 v179, 1.0, v179
	v_rcp_f32_e32 v176, v176
	v_rcp_f32_e32 v177, v177
	v_rcp_f32_e32 v178, v178
	v_rcp_f32_e32 v179, v179
	v_mul_f32_e32 v176, v25, v176
	v_mul_f32_e32 v177, v29, v177
	v_mul_f32_e32 v178, v33, v178
	v_mul_f32_e32 v179, v37, v179
	v_cvt_pk_bf16_f32 v180, v176, v177
	v_cvt_pk_bf16_f32 v181, v178, v179
	ds_write_b16 v170, v180 offset:2736
	ds_write_b16_d16_hi v170, v180 offset:2768
	ds_write_b16 v170, v181 offset:2800
	ds_write_b16_d16_hi v170, v181 offset:2832
	v_mul_f32_e32 v182, 0xbfb8aa3b, v38
	v_mul_f32_e32 v183, 0xbfb8aa3b, v42
	v_mul_f32_e32 v184, 0xbfb8aa3b, v46
	v_mul_f32_e32 v185, 0xbfb8aa3b, v50
	v_exp_f32_e32 v182, v182
	v_exp_f32_e32 v183, v183
	v_exp_f32_e32 v184, v184
	v_exp_f32_e32 v185, v185
	v_add_f32_e32 v182, 1.0, v182
	v_add_f32_e32 v183, 1.0, v183
	v_add_f32_e32 v184, 1.0, v184
	v_add_f32_e32 v185, 1.0, v185
	v_rcp_f32_e32 v182, v182
	v_rcp_f32_e32 v183, v183
	v_rcp_f32_e32 v184, v184
	v_rcp_f32_e32 v185, v185
	v_mul_f32_e32 v182, v38, v182
	v_mul_f32_e32 v183, v42, v183
	v_mul_f32_e32 v184, v46, v184
	v_mul_f32_e32 v185, v50, v185
	v_cvt_pk_bf16_f32 v186, v182, v183
	v_cvt_pk_bf16_f32 v187, v184, v185
	ds_write_b16 v170, v186 offset:4608
	ds_write_b16_d16_hi v170, v186 offset:4640
	ds_write_b16 v170, v187 offset:4672
	ds_write_b16_d16_hi v170, v187 offset:4704
	v_mul_f32_e32 v188, 0xbfb8aa3b, v39
	v_mul_f32_e32 v189, 0xbfb8aa3b, v43
	v_mul_f32_e32 v190, 0xbfb8aa3b, v47
	v_mul_f32_e32 v191, 0xbfb8aa3b, v51
	v_exp_f32_e32 v188, v188
	v_exp_f32_e32 v189, v189
	v_exp_f32_e32 v190, v190
	v_exp_f32_e32 v191, v191
	v_add_f32_e32 v188, 1.0, v188
	v_add_f32_e32 v189, 1.0, v189
	v_add_f32_e32 v190, 1.0, v190
	v_add_f32_e32 v191, 1.0, v191
	v_rcp_f32_e32 v188, v188
	v_rcp_f32_e32 v189, v189
	v_rcp_f32_e32 v190, v190
	v_rcp_f32_e32 v191, v191
	v_mul_f32_e32 v188, v39, v188
	v_mul_f32_e32 v189, v43, v189
	v_mul_f32_e32 v190, v47, v190
	v_mul_f32_e32 v191, v51, v191
	v_cvt_pk_bf16_f32 v192, v188, v189
	v_cvt_pk_bf16_f32 v193, v190, v191
	ds_write_b16 v170, v192 offset:4752
	ds_write_b16_d16_hi v170, v192 offset:4784
	ds_write_b16 v170, v193 offset:4816
	ds_write_b16_d16_hi v170, v193 offset:4848
	v_mul_f32_e32 v174, 0xbfb8aa3b, v40
	v_mul_f32_e32 v175, 0xbfb8aa3b, v44
	v_mul_f32_e32 v176, 0xbfb8aa3b, v48
	v_mul_f32_e32 v177, 0xbfb8aa3b, v52
	v_exp_f32_e32 v174, v174
	v_exp_f32_e32 v175, v175
	v_exp_f32_e32 v176, v176
	v_exp_f32_e32 v177, v177
	v_add_f32_e32 v174, 1.0, v174
	v_add_f32_e32 v175, 1.0, v175
	v_add_f32_e32 v176, 1.0, v176
	v_add_f32_e32 v177, 1.0, v177
	v_rcp_f32_e32 v174, v174
	v_rcp_f32_e32 v175, v175
	v_rcp_f32_e32 v176, v176
	v_rcp_f32_e32 v177, v177
	v_mul_f32_e32 v174, v40, v174
	v_mul_f32_e32 v175, v44, v175
	v_mul_f32_e32 v176, v48, v176
	v_mul_f32_e32 v177, v52, v177
	v_cvt_pk_bf16_f32 v178, v174, v175
	v_cvt_pk_bf16_f32 v179, v176, v177
	ds_write_b16 v170, v178 offset:4896
	ds_write_b16_d16_hi v170, v178 offset:4928
	ds_write_b16 v170, v179 offset:4960
	ds_write_b16_d16_hi v170, v179 offset:4992
	v_mul_f32_e32 v180, 0xbfb8aa3b, v41
	v_mul_f32_e32 v181, 0xbfb8aa3b, v45
	v_mul_f32_e32 v182, 0xbfb8aa3b, v49
	v_mul_f32_e32 v183, 0xbfb8aa3b, v53
	v_exp_f32_e32 v180, v180
	v_exp_f32_e32 v181, v181
	v_exp_f32_e32 v182, v182
	v_exp_f32_e32 v183, v183
	v_add_f32_e32 v180, 1.0, v180
	v_add_f32_e32 v181, 1.0, v181
	v_add_f32_e32 v182, 1.0, v182
	v_add_f32_e32 v183, 1.0, v183
	v_rcp_f32_e32 v180, v180
	v_rcp_f32_e32 v181, v181
	v_rcp_f32_e32 v182, v182
	v_rcp_f32_e32 v183, v183
	v_mul_f32_e32 v180, v41, v180
	v_mul_f32_e32 v181, v45, v181
	v_mul_f32_e32 v182, v49, v182
	v_mul_f32_e32 v183, v53, v183
	v_cvt_pk_bf16_f32 v184, v180, v181
	v_cvt_pk_bf16_f32 v185, v182, v183
	ds_write_b16 v170, v184 offset:5040
	ds_write_b16_d16_hi v170, v184 offset:5072
	ds_write_b16 v170, v185 offset:5104
	ds_write_b16_d16_hi v170, v185 offset:5136
	v_mul_f32_e32 v186, 0xbfb8aa3b, v54
	v_mul_f32_e32 v187, 0xbfb8aa3b, v58
	v_mul_f32_e32 v188, 0xbfb8aa3b, v62
	v_mul_f32_e32 v189, 0xbfb8aa3b, v66
	v_exp_f32_e32 v186, v186
	v_exp_f32_e32 v187, v187
	v_exp_f32_e32 v188, v188
	v_exp_f32_e32 v189, v189
	v_add_f32_e32 v186, 1.0, v186
	v_add_f32_e32 v187, 1.0, v187
	v_add_f32_e32 v188, 1.0, v188
	v_add_f32_e32 v189, 1.0, v189
	v_rcp_f32_e32 v186, v186
	v_rcp_f32_e32 v187, v187
	v_rcp_f32_e32 v188, v188
	v_rcp_f32_e32 v189, v189
	v_mul_f32_e32 v186, v54, v186
	v_mul_f32_e32 v187, v58, v187
	v_mul_f32_e32 v188, v62, v188
	v_mul_f32_e32 v189, v66, v189
	v_cvt_pk_bf16_f32 v190, v186, v187
	v_cvt_pk_bf16_f32 v191, v188, v189
	ds_write_b16 v170, v190 offset:6912
	ds_write_b16_d16_hi v170, v190 offset:6944
	ds_write_b16 v170, v191 offset:6976
	ds_write_b16_d16_hi v170, v191 offset:7008
	v_mul_f32_e32 v192, 0xbfb8aa3b, v55
	v_mul_f32_e32 v193, 0xbfb8aa3b, v59
	v_mul_f32_e32 v174, 0xbfb8aa3b, v63
	v_mul_f32_e32 v175, 0xbfb8aa3b, v67
	v_exp_f32_e32 v192, v192
	v_exp_f32_e32 v193, v193
	v_exp_f32_e32 v174, v174
	v_exp_f32_e32 v175, v175
	v_add_f32_e32 v192, 1.0, v192
	v_add_f32_e32 v193, 1.0, v193
	v_add_f32_e32 v174, 1.0, v174
	v_add_f32_e32 v175, 1.0, v175
; template <int EPI>
; DI void gemm_phase(const P& p, int l, const u16* __restrict__ A, const u16* __restrict__ Bt, int mpx, char* lds) {
;     ...
;           float v0 = acc[hf * 4 + mi][0][j], v1 = acc[hf * 4 + mi][1][j], v2 = acc[hf * 4 + mi][2][j], v3 = acc[hf * 4 + mi][3][j];
;           const int rowl = mi * 16 + g * 4 + j;
;           const int s = tokw + hf * 64 + rowl;
;           if (tr == 1) {
;             v0 = silu(v0); v1 = silu(v1); v2 = silu(v2); v3 = silu(v3);
;           } else if (tr == 3) {
;             if (donorm) {
;               float ss = v0 * v0 + v1 * v1 + v2 * v2 + v3 * v3;
;               ss += __shfl_xor(ss, 1);
;               ss += __shfl_xor(ss, 2);
;               ss += __shfl_xor(ss, 4);
;               ss += __shfl_xor(ss, 8);
;               const float inv = rsqrtf(ss * (1.f / 64.f) + 1e-6f);
;               v0 *= inv * gv0; v1 *= inv * gv1; v2 *= inv * gv2; v3 *= inv * gv3;
;             }
;             if (dorope) {
;               float sr, cr, sc, cc;
;               sincos_rev((float)(s >> 6) * invf64, sr, cr);
;               sincos_rev((float)(s & 63) * invf64, sc, cc);
;               const float a1 = v0, a2 = v1, b1 = v2, b2 = v3;
;               v0 = a1 * cr - a2 * sr;
;               v1 = a2 * cr + a1 * sr;
;               v2 = b1 * cc - b2 * sc;
;               v3 = b2 * cc + b1 * sc;
;             }
;           } else if (tr == 4) {
;             float sr, cr, sc, cc;
;             sincos_rev((float)(s >> 6) * invf32, sr, cr);
;             sincos_rev((float)(s & 63) * invf32, sc, cc);
;             const float p0 = __shfl_xor(v0, 8), p1 = __shfl_xor(v1, 8), p2 = __shfl_xor(v2, 8), p3 = __shfl_xor(v3, 8);
;             v0 = lo8 ? (v0 * cr - p0 * sr) : (v0 * cr + p0 * sr);
;             v1 = lo8 ? (v1 * cc - p1 * sc) : (v1 * cc + p1 * sc);
;             v2 = lo8 ? (v2 * cr - p2 * sr) : (v2 * cr + p2 * sr);
;             v3 = lo8 ? (v3 * cc - p3 * sc) : (v3 * cc + p3 * sc);
;           }
;           const unsigned u01 = pack2(v0, v1), u23 = pack2(v2, v3);
;           if (kind == 1) {
;             Tl[(0 * 16 + r) * 72 + rowl] = (u16)u01;
;     ...
;       for (int i = 0; i < 8; ++i) {
;         const int c = lane + i * 64;
;         const int row = c >> 3, cc = c & 7;
;         uint4 v = *(const uint4*)&Tl[row * 72 + cc * 8];
;         *(uint4*)(dh + (size_t)row * rstride + cc * 8) = v;
	v_rcp_f32_e32 v192, v192
	v_rcp_f32_e32 v193, v193
	v_rcp_f32_e32 v174, v174
	v_rcp_f32_e32 v175, v175
	v_mul_f32_e32 v192, v55, v192
	v_mul_f32_e32 v193, v59, v193
	v_mul_f32_e32 v174, v63, v174
	v_mul_f32_e32 v175, v67, v175
	v_cvt_pk_bf16_f32 v176, v192, v193
	v_cvt_pk_bf16_f32 v177, v174, v175
	ds_write_b16 v170, v176 offset:7056
	ds_write_b16_d16_hi v170, v176 offset:7088
	ds_write_b16 v170, v177 offset:7120
	ds_write_b16_d16_hi v170, v177 offset:7152
	v_mul_f32_e32 v178, 0xbfb8aa3b, v56
	v_mul_f32_e32 v179, 0xbfb8aa3b, v60
	v_mul_f32_e32 v180, 0xbfb8aa3b, v64
	v_mul_f32_e32 v181, 0xbfb8aa3b, v68
	v_exp_f32_e32 v178, v178
	v_exp_f32_e32 v179, v179
	v_exp_f32_e32 v180, v180
	v_exp_f32_e32 v181, v181
	v_add_f32_e32 v178, 1.0, v178
	v_add_f32_e32 v179, 1.0, v179
	v_add_f32_e32 v180, 1.0, v180
	v_add_f32_e32 v181, 1.0, v181
	v_rcp_f32_e32 v178, v178
	v_rcp_f32_e32 v179, v179
	v_rcp_f32_e32 v180, v180
	v_rcp_f32_e32 v181, v181
	v_mul_f32_e32 v178, v56, v178
	v_mul_f32_e32 v179, v60, v179
	v_mul_f32_e32 v180, v64, v180
	v_mul_f32_e32 v181, v68, v181
	v_cvt_pk_bf16_f32 v182, v178, v179
	v_cvt_pk_bf16_f32 v183, v180, v181
	ds_write_b16 v170, v182 offset:7200
	ds_write_b16_d16_hi v170, v182 offset:7232
	ds_write_b16 v170, v183 offset:7264
	ds_write_b16_d16_hi v170, v183 offset:7296
	v_mul_f32_e32 v184, 0xbfb8aa3b, v57
	v_mul_f32_e32 v185, 0xbfb8aa3b, v61
	v_mul_f32_e32 v186, 0xbfb8aa3b, v65
	v_mul_f32_e32 v187, 0xbfb8aa3b, v69
	v_exp_f32_e32 v184, v184
	v_exp_f32_e32 v185, v185
	v_exp_f32_e32 v186, v186
	v_exp_f32_e32 v187, v187
	v_add_f32_e32 v184, 1.0, v184
	v_add_f32_e32 v185, 1.0, v185
	v_add_f32_e32 v186, 1.0, v186
	v_add_f32_e32 v187, 1.0, v187
	v_rcp_f32_e32 v184, v184
	v_rcp_f32_e32 v185, v185
	v_rcp_f32_e32 v186, v186
	v_rcp_f32_e32 v187, v187
	v_mul_f32_e32 v184, v57, v184
	v_mul_f32_e32 v185, v61, v185
	v_mul_f32_e32 v186, v65, v186
	v_mul_f32_e32 v187, v69, v187
	v_cvt_pk_bf16_f32 v188, v184, v185
	v_cvt_pk_bf16_f32 v189, v186, v187
	ds_write_b16 v170, v188 offset:7344
	ds_write_b16_d16_hi v170, v188 offset:7376
	ds_write_b16 v170, v189 offset:7408
	ds_write_b16_d16_hi v170, v189 offset:7440
	ds_read_b128 v[130:133], v171 offset:0
	ds_read_b128 v[134:137], v171 offset:1152
	ds_read_b128 v[138:141], v171 offset:2304
	ds_read_b128 v[142:145], v171 offset:3456
	ds_read_b128 v[146:149], v171 offset:4608
	ds_read_b128 v[150:153], v171 offset:5760
	ds_read_b128 v[154:157], v171 offset:6912
	ds_read_b128 v[158:161], v171 offset:8064
	s_waitcnt lgkmcnt(7)
	global_store_dwordx4 v172, v[130:133], s[44:45] sc1 nt
	s_add_u32 s44, s44, 0x4000
	s_addc_u32 s45, s45, 0
	s_waitcnt lgkmcnt(6)
	global_store_dwordx4 v172, v[134:137], s[44:45] sc1 nt
	s_add_u32 s44, s44, 0x4000
	s_addc_u32 s45, s45, 0
	s_waitcnt lgkmcnt(5)
	global_store_dwordx4 v172, v[138:141], s[44:45] sc1 nt
	s_add_u32 s44, s44, 0x4000
	s_addc_u32 s45, s45, 0
	s_waitcnt lgkmcnt(4)
	global_store_dwordx4 v172, v[142:145], s[44:45] sc1 nt
	s_add_u32 s44, s44, 0x4000
	s_addc_u32 s45, s45, 0
	s_waitcnt lgkmcnt(3)
	global_store_dwordx4 v172, v[146:149], s[44:45] sc1 nt
	s_add_u32 s44, s44, 0x4000
	s_addc_u32 s45, s45, 0
	s_waitcnt lgkmcnt(2)
	global_store_dwordx4 v172, v[150:153], s[44:45] sc1 nt
	s_add_u32 s44, s44, 0x4000
	s_addc_u32 s45, s45, 0
	s_waitcnt lgkmcnt(1)
	global_store_dwordx4 v172, v[154:157], s[44:45] sc1 nt
	s_add_u32 s44, s44, 0x4000
	s_addc_u32 s45, s45, 0
	s_waitcnt lgkmcnt(0)
	global_store_dwordx4 v172, v[158:161], s[44:45] sc1 nt
	s_add_u32 s44, s62, 0x20000
	s_addc_u32 s45, s63, 0
	v_mul_f32_e32 v174, 0xbfb8aa3b, v70
	v_mul_f32_e32 v175, 0xbfb8aa3b, v74
	v_mul_f32_e32 v176, 0xbfb8aa3b, v78
	v_mul_f32_e32 v177, 0xbfb8aa3b, v82
	v_exp_f32_e32 v174, v174
	v_exp_f32_e32 v175, v175
	v_exp_f32_e32 v176, v176
	v_exp_f32_e32 v177, v177
	v_add_f32_e32 v174, 1.0, v174
	v_add_f32_e32 v175, 1.0, v175
	v_add_f32_e32 v176, 1.0, v176
	v_add_f32_e32 v177, 1.0, v177
	v_rcp_f32_e32 v174, v174
	v_rcp_f32_e32 v175, v175
	v_rcp_f32_e32 v176, v176
	v_rcp_f32_e32 v177, v177
	v_mul_f32_e32 v174, v70, v174
	v_mul_f32_e32 v175, v74, v175
	v_mul_f32_e32 v176, v78, v176
	v_mul_f32_e32 v177, v82, v177
	v_cvt_pk_bf16_f32 v178, v174, v175
	v_cvt_pk_bf16_f32 v179, v176, v177
	ds_write_b16 v170, v178 offset:0
	ds_write_b16_d16_hi v170, v178 offset:32
	ds_write_b16 v170, v179 offset:64
	ds_write_b16_d16_hi v170, v179 offset:96
	v_mul_f32_e32 v180, 0xbfb8aa3b, v71
	v_mul_f32_e32 v181, 0xbfb8aa3b, v75
	v_mul_f32_e32 v182, 0xbfb8aa3b, v79
	v_mul_f32_e32 v183, 0xbfb8aa3b, v83
	v_exp_f32_e32 v180, v180
	v_exp_f32_e32 v181, v181
	v_exp_f32_e32 v182, v182
	v_exp_f32_e32 v183, v183
	v_add_f32_e32 v180, 1.0, v180
	v_add_f32_e32 v181, 1.0, v181
	v_add_f32_e32 v182, 1.0, v182
	v_add_f32_e32 v183, 1.0, v183
	v_rcp_f32_e32 v180, v180
	v_rcp_f32_e32 v181, v181
	v_rcp_f32_e32 v182, v182
	v_rcp_f32_e32 v183, v183
	v_mul_f32_e32 v180, v71, v180
	v_mul_f32_e32 v181, v75, v181
	v_mul_f32_e32 v182, v79, v182
	v_mul_f32_e32 v183, v83, v183
	v_cvt_pk_bf16_f32 v184, v180, v181
	v_cvt_pk_bf16_f32 v185, v182, v183
	ds_write_b16 v170, v184 offset:144
	ds_write_b16_d16_hi v170, v184 offset:176
	ds_write_b16 v170, v185 offset:208
	ds_write_b16_d16_hi v170, v185 offset:240
	v_mul_f32_e32 v186, 0xbfb8aa3b, v72
	v_mul_f32_e32 v187, 0xbfb8aa3b, v76
	v_mul_f32_e32 v188, 0xbfb8aa3b, v80
	v_mul_f32_e32 v189, 0xbfb8aa3b, v84
	v_exp_f32_e32 v186, v186
	v_exp_f32_e32 v187, v187
	v_exp_f32_e32 v188, v188
	v_exp_f32_e32 v189, v189
	v_add_f32_e32 v186, 1.0, v186
	v_add_f32_e32 v187, 1.0, v187
	v_add_f32_e32 v188, 1.0, v188
	v_add_f32_e32 v189, 1.0, v189
	v_rcp_f32_e32 v186, v186
	v_rcp_f32_e32 v187, v187
	v_rcp_f32_e32 v188, v188
; template <int EPI>
; DI void gemm_phase(const P& p, int l, const u16* __restrict__ A, const u16* __restrict__ Bt, int mpx, char* lds) {
;     ...
;           float v0 = acc[hf * 4 + mi][0][j], v1 = acc[hf * 4 + mi][1][j], v2 = acc[hf * 4 + mi][2][j], v3 = acc[hf * 4 + mi][3][j];
;           const int rowl = mi * 16 + g * 4 + j;
;           const int s = tokw + hf * 64 + rowl;
;           if (tr == 1) {
;             v0 = silu(v0); v1 = silu(v1); v2 = silu(v2); v3 = silu(v3);
;           } else if (tr == 3) {
;             if (donorm) {
;               float ss = v0 * v0 + v1 * v1 + v2 * v2 + v3 * v3;
;               ss += __shfl_xor(ss, 1);
;               ss += __shfl_xor(ss, 2);
;               ss += __shfl_xor(ss, 4);
;               ss += __shfl_xor(ss, 8);
;               const float inv = rsqrtf(ss * (1.f / 64.f) + 1e-6f);
;               v0 *= inv * gv0; v1 *= inv * gv1; v2 *= inv * gv2; v3 *= inv * gv3;
;             }
;             if (dorope) {
;               float sr, cr, sc, cc;
;               sincos_rev((float)(s >> 6) * invf64, sr, cr);
;               sincos_rev((float)(s & 63) * invf64, sc, cc);
;               const float a1 = v0, a2 = v1, b1 = v2, b2 = v3;
;               v0 = a1 * cr - a2 * sr;
;               v1 = a2 * cr + a1 * sr;
;               v2 = b1 * cc - b2 * sc;
;               v3 = b2 * cc + b1 * sc;
;             }
;           } else if (tr == 4) {
;             float sr, cr, sc, cc;
;             sincos_rev((float)(s >> 6) * invf32, sr, cr);
;             sincos_rev((float)(s & 63) * invf32, sc, cc);
;             const float p0 = __shfl_xor(v0, 8), p1 = __shfl_xor(v1, 8), p2 = __shfl_xor(v2, 8), p3 = __shfl_xor(v3, 8);
;             v0 = lo8 ? (v0 * cr - p0 * sr) : (v0 * cr + p0 * sr);
;             v1 = lo8 ? (v1 * cc - p1 * sc) : (v1 * cc + p1 * sc);
;             v2 = lo8 ? (v2 * cr - p2 * sr) : (v2 * cr + p2 * sr);
;             v3 = lo8 ? (v3 * cc - p3 * sc) : (v3 * cc + p3 * sc);
;           }
;           const unsigned u01 = pack2(v0, v1), u23 = pack2(v2, v3);
;           if (kind == 1) {
;             Tl[(0 * 16 + r) * 72 + rowl] = (u16)u01;
;             Tl[(1 * 16 + r) * 72 + rowl] = (u16)(u01 >> 16);
;             Tl[(2 * 16 + r) * 72 + rowl] = (u16)u23;
;             Tl[(3 * 16 + r) * 72 + rowl] = (u16)(u23 >> 16);
;           } else if (tr == 2) {
;             Tl[rowl * 72 + 0 * 16 + r] = f2h(v0);
	v_rcp_f32_e32 v189, v189
	v_mul_f32_e32 v186, v72, v186
	v_mul_f32_e32 v187, v76, v187
	v_mul_f32_e32 v188, v80, v188
	v_mul_f32_e32 v189, v84, v189
	v_cvt_pk_bf16_f32 v190, v186, v187
	v_cvt_pk_bf16_f32 v191, v188, v189
	ds_write_b16 v170, v190 offset:288
	ds_write_b16_d16_hi v170, v190 offset:320
	ds_write_b16 v170, v191 offset:352
	ds_write_b16_d16_hi v170, v191 offset:384
	v_mul_f32_e32 v192, 0xbfb8aa3b, v73
	v_mul_f32_e32 v193, 0xbfb8aa3b, v77
	v_mul_f32_e32 v174, 0xbfb8aa3b, v81
	v_mul_f32_e32 v175, 0xbfb8aa3b, v85
	v_exp_f32_e32 v192, v192
	v_exp_f32_e32 v193, v193
	v_exp_f32_e32 v174, v174
	v_exp_f32_e32 v175, v175
	v_add_f32_e32 v192, 1.0, v192
	v_add_f32_e32 v193, 1.0, v193
	v_add_f32_e32 v174, 1.0, v174
	v_add_f32_e32 v175, 1.0, v175
	v_rcp_f32_e32 v192, v192
	v_rcp_f32_e32 v193, v193
	v_rcp_f32_e32 v174, v174
	v_rcp_f32_e32 v175, v175
	v_mul_f32_e32 v192, v73, v192
	v_mul_f32_e32 v193, v77, v193
	v_mul_f32_e32 v174, v81, v174
	v_mul_f32_e32 v175, v85, v175
	v_cvt_pk_bf16_f32 v176, v192, v193
	v_cvt_pk_bf16_f32 v177, v174, v175
	ds_write_b16 v170, v176 offset:432
	ds_write_b16_d16_hi v170, v176 offset:464
	ds_write_b16 v170, v177 offset:496
	ds_write_b16_d16_hi v170, v177 offset:528
	v_mul_f32_e32 v178, 0xbfb8aa3b, v86
	v_mul_f32_e32 v179, 0xbfb8aa3b, v90
	v_mul_f32_e32 v180, 0xbfb8aa3b, v94
	v_mul_f32_e32 v181, 0xbfb8aa3b, v98
	v_exp_f32_e32 v178, v178
	v_exp_f32_e32 v179, v179
	v_exp_f32_e32 v180, v180
	v_exp_f32_e32 v181, v181
	v_add_f32_e32 v178, 1.0, v178
	v_add_f32_e32 v179, 1.0, v179
	v_add_f32_e32 v180, 1.0, v180
	v_add_f32_e32 v181, 1.0, v181
	v_rcp_f32_e32 v178, v178
	v_rcp_f32_e32 v179, v179
	v_rcp_f32_e32 v180, v180
	v_rcp_f32_e32 v181, v181
	v_mul_f32_e32 v178, v86, v178
	v_mul_f32_e32 v179, v90, v179
	v_mul_f32_e32 v180, v94, v180
	v_mul_f32_e32 v181, v98, v181
	v_cvt_pk_bf16_f32 v182, v178, v179
	v_cvt_pk_bf16_f32 v183, v180, v181
	ds_write_b16 v170, v182 offset:2304
	ds_write_b16_d16_hi v170, v182 offset:2336
	ds_write_b16 v170, v183 offset:2368
	ds_write_b16_d16_hi v170, v183 offset:2400
	v_mul_f32_e32 v184, 0xbfb8aa3b, v87
	v_mul_f32_e32 v185, 0xbfb8aa3b, v91
	v_mul_f32_e32 v186, 0xbfb8aa3b, v95
	v_mul_f32_e32 v187, 0xbfb8aa3b, v99
	v_exp_f32_e32 v184, v184
	v_exp_f32_e32 v185, v185
	v_exp_f32_e32 v186, v186
	v_exp_f32_e32 v187, v187
	v_add_f32_e32 v184, 1.0, v184
	v_add_f32_e32 v185, 1.0, v185
	v_add_f32_e32 v186, 1.0, v186
	v_add_f32_e32 v187, 1.0, v187
	v_rcp_f32_e32 v184, v184
	v_rcp_f32_e32 v185, v185
	v_rcp_f32_e32 v186, v186
	v_rcp_f32_e32 v187, v187
	v_mul_f32_e32 v184, v87, v184
	v_mul_f32_e32 v185, v91, v185
	v_mul_f32_e32 v186, v95, v186
	v_mul_f32_e32 v187, v99, v187
	v_cvt_pk_bf16_f32 v188, v184, v185
	v_cvt_pk_bf16_f32 v189, v186, v187
	ds_write_b16 v170, v188 offset:2448
	ds_write_b16_d16_hi v170, v188 offset:2480
	ds_write_b16 v170, v189 offset:2512
	ds_write_b16_d16_hi v170, v189 offset:2544
	v_mul_f32_e32 v190, 0xbfb8aa3b, v88
	v_mul_f32_e32 v191, 0xbfb8aa3b, v92
	v_mul_f32_e32 v192, 0xbfb8aa3b, v96
	v_mul_f32_e32 v193, 0xbfb8aa3b, v100
	v_exp_f32_e32 v190, v190
	v_exp_f32_e32 v191, v191
	v_exp_f32_e32 v192, v192
	v_exp_f32_e32 v193, v193
	v_add_f32_e32 v190, 1.0, v190
	v_add_f32_e32 v191, 1.0, v191
	v_add_f32_e32 v192, 1.0, v192
	v_add_f32_e32 v193, 1.0, v193
	v_rcp_f32_e32 v190, v190
	v_rcp_f32_e32 v191, v191
	v_rcp_f32_e32 v192, v192
	v_rcp_f32_e32 v193, v193
	v_mul_f32_e32 v190, v88, v190
	v_mul_f32_e32 v191, v92, v191
	v_mul_f32_e32 v192, v96, v192
	v_mul_f32_e32 v193, v100, v193
	v_cvt_pk_bf16_f32 v174, v190, v191
	v_cvt_pk_bf16_f32 v175, v192, v193
	ds_write_b16 v170, v174 offset:2592
	ds_write_b16_d16_hi v170, v174 offset:2624
	ds_write_b16 v170, v175 offset:2656
	ds_write_b16_d16_hi v170, v175 offset:2688
	v_mul_f32_e32 v176, 0xbfb8aa3b, v89
	v_mul_f32_e32 v177, 0xbfb8aa3b, v93
	v_mul_f32_e32 v178, 0xbfb8aa3b, v97
	v_mul_f32_e32 v179, 0xbfb8aa3b, v101
	v_exp_f32_e32 v176, v176
	v_exp_f32_e32 v177, v177
	v_exp_f32_e32 v178, v178
	v_exp_f32_e32 v179, v179
	v_add_f32_e32 v176, 1.0, v176
	v_add_f32_e32 v177, 1.0, v177
	v_add_f32_e32 v178, 1.0, v178
	v_add_f32_e32 v179, 1.0, v179
	v_rcp_f32_e32 v176, v176
	v_rcp_f32_e32 v177, v177
	v_rcp_f32_e32 v178, v178
	v_rcp_f32_e32 v179, v179
	v_mul_f32_e32 v176, v89, v176
	v_mul_f32_e32 v177, v93, v177
	v_mul_f32_e32 v178, v97, v178
	v_mul_f32_e32 v179, v101, v179
	v_cvt_pk_bf16_f32 v180, v176, v177
	v_cvt_pk_bf16_f32 v181, v178, v179
	ds_write_b16 v170, v180 offset:2736
	ds_write_b16_d16_hi v170, v180 offset:2768
	ds_write_b16 v170, v181 offset:2800
	ds_write_b16_d16_hi v170, v181 offset:2832
	v_mul_f32_e32 v182, 0xbfb8aa3b, v102
	v_mul_f32_e32 v183, 0xbfb8aa3b, v106
	v_mul_f32_e32 v184, 0xbfb8aa3b, v110
	v_mul_f32_e32 v185, 0xbfb8aa3b, v114
	v_exp_f32_e32 v182, v182
	v_exp_f32_e32 v183, v183
	v_exp_f32_e32 v184, v184
	v_exp_f32_e32 v185, v185
	v_add_f32_e32 v182, 1.0, v182
	v_add_f32_e32 v183, 1.0, v183
	v_add_f32_e32 v184, 1.0, v184
	v_add_f32_e32 v185, 1.0, v185
	v_rcp_f32_e32 v182, v182
	v_rcp_f32_e32 v183, v183
	v_rcp_f32_e32 v184, v184
	v_rcp_f32_e32 v185, v185
	v_mul_f32_e32 v182, v102, v182
	v_mul_f32_e32 v183, v106, v183
	v_mul_f32_e32 v184, v110, v184
	v_mul_f32_e32 v185, v114, v185
	v_cvt_pk_bf16_f32 v186, v182, v183
	v_cvt_pk_bf16_f32 v187, v184, v185
	ds_write_b16 v170, v186 offset:4608
	ds_write_b16_d16_hi v170, v186 offset:4640
	ds_write_b16 v170, v187 offset:4672
	ds_write_b16_d16_hi v170, v187 offset:4704
	v_mul_f32_e32 v188, 0xbfb8aa3b, v103
	v_mul_f32_e32 v189, 0xbfb8aa3b, v107
	v_mul_f32_e32 v190, 0xbfb8aa3b, v111
	v_mul_f32_e32 v191, 0xbfb8aa3b, v115
	v_exp_f32_e32 v188, v188
	v_exp_f32_e32 v189, v189
	v_exp_f32_e32 v190, v190
; template <int EPI>
; DI void gemm_phase(const P& p, int l, const u16* __restrict__ A, const u16* __restrict__ Bt, int mpx, char* lds) {
;     ...
;           float v0 = acc[hf * 4 + mi][0][j], v1 = acc[hf * 4 + mi][1][j], v2 = acc[hf * 4 + mi][2][j], v3 = acc[hf * 4 + mi][3][j];
;           const int rowl = mi * 16 + g * 4 + j;
;           const int s = tokw + hf * 64 + rowl;
;           if (tr == 1) {
;             v0 = silu(v0); v1 = silu(v1); v2 = silu(v2); v3 = silu(v3);
;           } else if (tr == 3) {
;             if (donorm) {
;               float ss = v0 * v0 + v1 * v1 + v2 * v2 + v3 * v3;
;               ss += __shfl_xor(ss, 1);
;               ss += __shfl_xor(ss, 2);
;               ss += __shfl_xor(ss, 4);
;               ss += __shfl_xor(ss, 8);
;               const float inv = rsqrtf(ss * (1.f / 64.f) + 1e-6f);
;               v0 *= inv * gv0; v1 *= inv * gv1; v2 *= inv * gv2; v3 *= inv * gv3;
;             }
;             if (dorope) {
;               float sr, cr, sc, cc;
;               sincos_rev((float)(s >> 6) * invf64, sr, cr);
;               sincos_rev((float)(s & 63) * invf64, sc, cc);
;               const float a1 = v0, a2 = v1, b1 = v2, b2 = v3;
;               v0 = a1 * cr - a2 * sr;
;               v1 = a2 * cr + a1 * sr;
;               v2 = b1 * cc - b2 * sc;
;               v3 = b2 * cc + b1 * sc;
;             }
;           } else if (tr == 4) {
;             float sr, cr, sc, cc;
;             sincos_rev((float)(s >> 6) * invf32, sr, cr);
;             sincos_rev((float)(s & 63) * invf32, sc, cc);
;             const float p0 = __shfl_xor(v0, 8), p1 = __shfl_xor(v1, 8), p2 = __shfl_xor(v2, 8), p3 = __shfl_xor(v3, 8);
;             v0 = lo8 ? (v0 * cr - p0 * sr) : (v0 * cr + p0 * sr);
;             v1 = lo8 ? (v1 * cc - p1 * sc) : (v1 * cc + p1 * sc);
;             v2 = lo8 ? (v2 * cr - p2 * sr) : (v2 * cr + p2 * sr);
;             v3 = lo8 ? (v3 * cc - p3 * sc) : (v3 * cc + p3 * sc);
;           }
;           const unsigned u01 = pack2(v0, v1), u23 = pack2(v2, v3);
;           if (kind == 1) {
;             Tl[(0 * 16 + r) * 72 + rowl] = (u16)u01;
;             Tl[(1 * 16 + r) * 72 + rowl] = (u16)(u01 >> 16);
;             Tl[(2 * 16 + r) * 72 + rowl] = (u16)u23;
;             Tl[(3 * 16 + r) * 72 + rowl] = (u16)(u23 >> 16);
;           } else if (tr == 2) {
;             Tl[rowl * 72 + 0 * 16 + r] = f2h(v0);
	v_exp_f32_e32 v191, v191
	v_add_f32_e32 v188, 1.0, v188
	v_add_f32_e32 v189, 1.0, v189
	v_add_f32_e32 v190, 1.0, v190
	v_add_f32_e32 v191, 1.0, v191
	v_rcp_f32_e32 v188, v188
	v_rcp_f32_e32 v189, v189
	v_rcp_f32_e32 v190, v190
	v_rcp_f32_e32 v191, v191
	v_mul_f32_e32 v188, v103, v188
	v_mul_f32_e32 v189, v107, v189
	v_mul_f32_e32 v190, v111, v190
	v_mul_f32_e32 v191, v115, v191
	v_cvt_pk_bf16_f32 v192, v188, v189
	v_cvt_pk_bf16_f32 v193, v190, v191
	ds_write_b16 v170, v192 offset:4752
	ds_write_b16_d16_hi v170, v192 offset:4784
	ds_write_b16 v170, v193 offset:4816
	ds_write_b16_d16_hi v170, v193 offset:4848
	v_mul_f32_e32 v174, 0xbfb8aa3b, v104
	v_mul_f32_e32 v175, 0xbfb8aa3b, v108
	v_mul_f32_e32 v176, 0xbfb8aa3b, v112
	v_mul_f32_e32 v177, 0xbfb8aa3b, v116
	v_exp_f32_e32 v174, v174
	v_exp_f32_e32 v175, v175
	v_exp_f32_e32 v176, v176
	v_exp_f32_e32 v177, v177
	v_add_f32_e32 v174, 1.0, v174
	v_add_f32_e32 v175, 1.0, v175
	v_add_f32_e32 v176, 1.0, v176
	v_add_f32_e32 v177, 1.0, v177
	v_rcp_f32_e32 v174, v174
	v_rcp_f32_e32 v175, v175
	v_rcp_f32_e32 v176, v176
	v_rcp_f32_e32 v177, v177
	v_mul_f32_e32 v174, v104, v174
	v_mul_f32_e32 v175, v108, v175
	v_mul_f32_e32 v176, v112, v176
	v_mul_f32_e32 v177, v116, v177
	v_cvt_pk_bf16_f32 v178, v174, v175
	v_cvt_pk_bf16_f32 v179, v176, v177
	ds_write_b16 v170, v178 offset:4896
	ds_write_b16_d16_hi v170, v178 offset:4928
	ds_write_b16 v170, v179 offset:4960
	ds_write_b16_d16_hi v170, v179 offset:4992
	v_mul_f32_e32 v180, 0xbfb8aa3b, v105
	v_mul_f32_e32 v181, 0xbfb8aa3b, v109
	v_mul_f32_e32 v182, 0xbfb8aa3b, v113
	v_mul_f32_e32 v183, 0xbfb8aa3b, v117
	v_exp_f32_e32 v180, v180
	v_exp_f32_e32 v181, v181
	v_exp_f32_e32 v182, v182
	v_exp_f32_e32 v183, v183
	v_add_f32_e32 v180, 1.0, v180
	v_add_f32_e32 v181, 1.0, v181
	v_add_f32_e32 v182, 1.0, v182
	v_add_f32_e32 v183, 1.0, v183
	v_rcp_f32_e32 v180, v180
	v_rcp_f32_e32 v181, v181
	v_rcp_f32_e32 v182, v182
	v_rcp_f32_e32 v183, v183
	v_mul_f32_e32 v180, v105, v180
	v_mul_f32_e32 v181, v109, v181
	v_mul_f32_e32 v182, v113, v182
	v_mul_f32_e32 v183, v117, v183
	v_cvt_pk_bf16_f32 v184, v180, v181
	v_cvt_pk_bf16_f32 v185, v182, v183
	ds_write_b16 v170, v184 offset:5040
	ds_write_b16_d16_hi v170, v184 offset:5072
	ds_write_b16 v170, v185 offset:5104
	ds_write_b16_d16_hi v170, v185 offset:5136
	v_mul_f32_e32 v186, 0xbfb8aa3b, v118
	v_mul_f32_e32 v187, 0xbfb8aa3b, v122
	v_mul_f32_e32 v188, 0xbfb8aa3b, v126
	v_mul_f32_e32 v189, 0xbfb8aa3b, v2
	v_exp_f32_e32 v186, v186
	v_exp_f32_e32 v187, v187
	v_exp_f32_e32 v188, v188
	v_exp_f32_e32 v189, v189
	v_add_f32_e32 v186, 1.0, v186
	v_add_f32_e32 v187, 1.0, v187
	v_add_f32_e32 v188, 1.0, v188
	v_add_f32_e32 v189, 1.0, v189
	v_rcp_f32_e32 v186, v186
	v_rcp_f32_e32 v187, v187
	v_rcp_f32_e32 v188, v188
	v_rcp_f32_e32 v189, v189
	v_mul_f32_e32 v186, v118, v186
	v_mul_f32_e32 v187, v122, v187
	v_mul_f32_e32 v188, v126, v188
	v_mul_f32_e32 v189, v2, v189
	v_cvt_pk_bf16_f32 v190, v186, v187
	v_cvt_pk_bf16_f32 v191, v188, v189
	ds_write_b16 v170, v190 offset:6912
	ds_write_b16_d16_hi v170, v190 offset:6944
	ds_write_b16 v170, v191 offset:6976
	ds_write_b16_d16_hi v170, v191 offset:7008
	v_mul_f32_e32 v192, 0xbfb8aa3b, v119
	v_mul_f32_e32 v193, 0xbfb8aa3b, v123
	v_mul_f32_e32 v174, 0xbfb8aa3b, v127
	v_mul_f32_e32 v175, 0xbfb8aa3b, v3
	v_exp_f32_e32 v192, v192
	v_exp_f32_e32 v193, v193
	v_exp_f32_e32 v174, v174
	v_exp_f32_e32 v175, v175
	v_add_f32_e32 v192, 1.0, v192
	v_add_f32_e32 v193, 1.0, v193
	v_add_f32_e32 v174, 1.0, v174
	v_add_f32_e32 v175, 1.0, v175
	v_rcp_f32_e32 v192, v192
	v_rcp_f32_e32 v193, v193
	v_rcp_f32_e32 v174, v174
	v_rcp_f32_e32 v175, v175
	v_mul_f32_e32 v192, v119, v192
	v_mul_f32_e32 v193, v123, v193
	v_mul_f32_e32 v174, v127, v174
	v_mul_f32_e32 v175, v3, v175
	v_cvt_pk_bf16_f32 v176, v192, v193
	v_cvt_pk_bf16_f32 v177, v174, v175
	ds_write_b16 v170, v176 offset:7056
	ds_write_b16_d16_hi v170, v176 offset:7088
	ds_write_b16 v170, v177 offset:7120
	ds_write_b16_d16_hi v170, v177 offset:7152
	v_mul_f32_e32 v178, 0xbfb8aa3b, v120
	v_mul_f32_e32 v179, 0xbfb8aa3b, v124
	v_mul_f32_e32 v180, 0xbfb8aa3b, v128
	v_mul_f32_e32 v181, 0xbfb8aa3b, v4
	v_exp_f32_e32 v178, v178
	v_exp_f32_e32 v179, v179
	v_exp_f32_e32 v180, v180
	v_exp_f32_e32 v181, v181
	v_add_f32_e32 v178, 1.0, v178
	v_add_f32_e32 v179, 1.0, v179
	v_add_f32_e32 v180, 1.0, v180
	v_add_f32_e32 v181, 1.0, v181
	v_rcp_f32_e32 v178, v178
	v_rcp_f32_e32 v179, v179
	v_rcp_f32_e32 v180, v180
	v_rcp_f32_e32 v181, v181
	v_mul_f32_e32 v178, v120, v178
	v_mul_f32_e32 v179, v124, v179
	v_mul_f32_e32 v180, v128, v180
	v_mul_f32_e32 v181, v4, v181
	v_cvt_pk_bf16_f32 v182, v178, v179
	v_cvt_pk_bf16_f32 v183, v180, v181
	ds_write_b16 v170, v182 offset:7200
	ds_write_b16_d16_hi v170, v182 offset:7232
	ds_write_b16 v170, v183 offset:7264
	ds_write_b16_d16_hi v170, v183 offset:7296
	v_mul_f32_e32 v184, 0xbfb8aa3b, v121
	v_mul_f32_e32 v185, 0xbfb8aa3b, v125
	v_mul_f32_e32 v186, 0xbfb8aa3b, v129
	v_mul_f32_e32 v187, 0xbfb8aa3b, v5
	v_exp_f32_e32 v184, v184
	v_exp_f32_e32 v185, v185
	v_exp_f32_e32 v186, v186
	v_exp_f32_e32 v187, v187
	v_add_f32_e32 v184, 1.0, v184
	v_add_f32_e32 v185, 1.0, v185
	v_add_f32_e32 v186, 1.0, v186
	v_add_f32_e32 v187, 1.0, v187
	v_rcp_f32_e32 v184, v184
	v_rcp_f32_e32 v185, v185
	v_rcp_f32_e32 v186, v186
	v_rcp_f32_e32 v187, v187
	v_mul_f32_e32 v184, v121, v184
	v_mul_f32_e32 v185, v125, v185
	v_mul_f32_e32 v186, v129, v186
	v_mul_f32_e32 v187, v5, v187
	v_cvt_pk_bf16_f32 v188, v184, v185
	v_cvt_pk_bf16_f32 v189, v186, v187
	ds_write_b16 v170, v188 offset:7344
	ds_write_b16_d16_hi v170, v188 offset:7376
	ds_write_b16 v170, v189 offset:7408
	ds_write_b16_d16_hi v170, v189 offset:7440
	ds_read_b128 v[130:133], v171 offset:0
	ds_read_b128 v[134:137], v171 offset:1152
	ds_read_b128 v[138:141], v171 offset:2304
	ds_read_b128 v[142:145], v171 offset:3456
	ds_read_b128 v[146:149], v171 offset:4608
	ds_read_b128 v[150:153], v171 offset:5760
	ds_read_b128 v[154:157], v171 offset:6912
	ds_read_b128 v[158:161], v171 offset:8064
	s_waitcnt lgkmcnt(7)
	global_store_dwordx4 v172, v[130:133], s[44:45] sc1 nt
	s_add_u32 s44, s44, 0x4000
	s_addc_u32 s45, s45, 0
	s_waitcnt lgkmcnt(6)
	global_store_dwordx4 v172, v[134:137], s[44:45] sc1 nt
	s_add_u32 s44, s44, 0x4000
	s_addc_u32 s45, s45, 0
	s_waitcnt lgkmcnt(5)
	global_store_dwordx4 v172, v[138:141], s[44:45] sc1 nt
	s_add_u32 s44, s44, 0x4000
	s_addc_u32 s45, s45, 0
	s_waitcnt lgkmcnt(4)
	global_store_dwordx4 v172, v[142:145], s[44:45] sc1 nt
	s_add_u32 s44, s44, 0x4000
	s_addc_u32 s45, s45, 0
	s_waitcnt lgkmcnt(3)
	global_store_dwordx4 v172, v[146:149], s[44:45] sc1 nt
	s_add_u32 s44, s44, 0x4000
	s_addc_u32 s45, s45, 0
	s_waitcnt lgkmcnt(2)
	global_store_dwordx4 v172, v[150:153], s[44:45] sc1 nt
	s_add_u32 s44, s44, 0x4000
	s_addc_u32 s45, s45, 0
	s_waitcnt lgkmcnt(1)
	global_store_dwordx4 v172, v[154:157], s[44:45] sc1 nt
	s_add_u32 s44, s44, 0x4000
	s_addc_u32 s45, s45, 0
	s_waitcnt lgkmcnt(0)
	global_store_dwordx4 v172, v[158:161], s[44:45] sc1 nt
	s_branch .Lfe_done
